# epilogues: hipcc IEEE 1.0/x sequences (11 instr) replaced by v_rcp_f32 + one Newton step + v_div_fixup (f32), 394 sites
# speedup vs baseline: 1.0181x; 1.0133x over previous
; __device__ __forceinline__ float sigmoidf_(float x) { return 1.0f / (1.0f + __expf(-x)); }
; __device__ __forceinline__ void phase0(const Params& p, unsigned char* lds) {
;     ...
;             const int kc = it & 15, nc = (it >> 4) % 12, s = it / 192; const int k0 = kc * 128;
;             { const int b = tid >> 7, kk = tid & 127; const float cv = p.c[b * 2048 + k0 + kk]; sc[tid] = cv * sigmoidf_(cv); }
;             __syncthreads();
.LBB0_5:
	s_and_b32 s21, s20, 15
	v_lshl_or_b32 v2, s21, 7, v12
	v_ashrrev_i32_e32 v3, 31, v2
	v_lshl_add_u64 v[2:3], v[2:3], 2, s[38:39]
	global_load_dword v5, v[2:3], off
	s_and_b32 s23, s19, 15
	s_ashr_i32 s24, s20, 4
	s_mul_hi_i32 s25, s20, 0x2aaaaaab
	s_mul_i32 s26, s23, 0x300000
	s_mul_hi_i32 s23, s24, 0x2aaaaaab
	s_lshr_b32 s27, s25, 31
	s_ashr_i32 s25, s25, 5
	s_lshr_b32 s28, s23, 31
	s_lshr_b32 s29, s23, 1
	s_add_i32 s23, s25, s27
	s_add_i32 s25, s29, s28
	s_mul_i32 s25, s25, 12
	s_mul_i32 s28, s23, 0x3000000
	s_sub_i32 s24, s24, s25
	s_mul_hi_i32 s27, s23, 0x3000000
	v_lshl_add_u32 v2, s24, 9, v1
	s_add_u32 s24, s28, s26
	s_addc_u32 s25, s27, 0
	s_add_u32 s24, s40, s24
	v_mov_b32_e32 v6, 0
	v_ashrrev_i32_e32 v3, 31, v2
	s_addc_u32 s25, s41, s25
	s_mov_b64 s[4:5], 0
	s_mov_b32 s22, 0
	v_mov_b32_e32 v7, v6
	v_mov_b32_e32 v4, v6
	s_waitcnt vmcnt(0)
	v_mul_f32_e32 v8, 0xbfb8aa3b, v5
	v_exp_f32_e32 v8, v8
	s_nop 0
	v_add_f32_e32 v10, 1.0, v8
	v_rcp_f32_e32 v14, v10
	v_lshl_add_u64 v[8:9], v[2:3], 2, s[24:25]
	v_fma_f32 v16, -v10, v14, 1.0
	v_fma_f32 v11, v16, v14, v14
	v_div_fixup_f32 v10, v11, v10, 1.0
	v_mul_f32_e32 v5, v5, v10
	ds_write_b32 v13, v5
	v_mov_b32_e32 v5, v6
	s_waitcnt lgkmcnt(0)
	s_barrier

; __device__ __forceinline__ float sigmoidf_(float x) { return 1.0f / (1.0f + __expf(-x)); }
; __device__ __forceinline__ void phase_prep(const Params& p, unsigned char* lds) {
;     ...
;             for (int j = 0; j < 8; ++j) { const float a = (float)z1[j]; const float zs = a + (0.5f * ((float)z0[j] + (float)z2[j]) - a) * p.rwkv_mu[zc + j];
;                 v[j] = grp < 12 ? tanhf(zs) : (grp < 24 ? zs : sigmoidf_(zs)); }
.LBB0_292:
	s_or_b64 exec, exec, s[16:17]
	global_load_dword v36, v[16:17], off
	s_waitcnt vmcnt(1)
	v_cvt_f32_f16_e32 v37, v8
	v_cvt_f32_f16_e32 v40, v4
	v_add_f32_e32 v37, v37, v40
	v_fma_mix_f32 v37, v37, s30, -v0 op_sel_hi:[0,0,1]
	s_waitcnt vmcnt(0)
	v_fma_mix_f32 v36, v36, v37, v0 op_sel_hi:[0,0,1]
	s_and_saveexec_b64 s[16:17], s[6:7]
	s_xor_b64 s[16:17], exec, s[16:17]
	s_cbranch_execz .LBB0_296
	s_and_saveexec_b64 s[28:29], s[4:5]
	s_cbranch_execz .LBB0_295
	v_mul_f32_e32 v36, 0xbfb8aa3b, v36
	v_exp_f32_e32 v36, v36
	s_nop 0
	v_add_f32_e32 v36, 1.0, v36
	v_rcp_f32_e32 v40, v36
	s_nop 0
	v_fma_f32 v42, -v36, v40, 1.0
	v_fma_f32 v37, v42, v40, v40
	v_div_fixup_f32 v36, v37, v36, 1.0

; __device__ __forceinline__ float sigmoidf_(float x) { return 1.0f / (1.0f + __expf(-x)); }
; __device__ __forceinline__ void phase_prep(const Params& p, unsigned char* lds) {
;     ...
;             for (int j = 0; j < 8; ++j) { const float a = (float)z1[j]; const float zs = a + (0.5f * ((float)z0[j] + (float)z2[j]) - a) * p.rwkv_mu[zc + j];
;                 v[j] = grp < 12 ? tanhf(zs) : (grp < 24 ? zs : sigmoidf_(zs)); }
.LBB0_302:
	s_or_b64 exec, exec, s[16:17]
	global_load_dword v37, v[18:19], off
	v_cvt_f32_f16_sdwa v8, v8 dst_sel:DWORD dst_unused:UNUSED_PAD src0_sel:WORD_1
	v_cvt_f32_f16_sdwa v4, v4 dst_sel:DWORD dst_unused:UNUSED_PAD src0_sel:WORD_1
	v_add_f32_e32 v4, v8, v4
	v_fma_mix_f32 v4, v4, s30, -v0 op_sel:[0,0,1] op_sel_hi:[0,0,1]
	s_waitcnt vmcnt(0)
	v_fma_mix_f32 v0, v4, v37, v0 op_sel:[0,0,1] op_sel_hi:[0,0,1]
	s_and_saveexec_b64 s[16:17], s[6:7]
	s_xor_b64 s[16:17], exec, s[16:17]
	s_cbranch_execz .LBB0_306
	s_and_saveexec_b64 s[28:29], s[4:5]
	s_cbranch_execz .LBB0_305
	v_mul_f32_e32 v0, 0xbfb8aa3b, v0
	v_exp_f32_e32 v0, v0
	s_nop 0
	v_add_f32_e32 v0, 1.0, v0
	v_rcp_f32_e32 v8, v0
	s_nop 0
	v_fma_f32 v40, -v0, v8, 1.0
	v_fma_f32 v4, v40, v8, v8
	v_div_fixup_f32 v0, v4, v0, 1.0

; __device__ __forceinline__ float sigmoidf_(float x) { return 1.0f / (1.0f + __expf(-x)); }
; __device__ __forceinline__ void phase_prep(const Params& p, unsigned char* lds) {
;     ...
;             for (int j = 0; j < 8; ++j) { const float a = (float)z1[j]; const float zs = a + (0.5f * ((float)z0[j] + (float)z2[j]) - a) * p.rwkv_mu[zc + j];
;                 v[j] = grp < 12 ? tanhf(zs) : (grp < 24 ? zs : sigmoidf_(zs)); }
.LBB0_312:
	s_or_b64 exec, exec, s[16:17]
	global_load_dword v4, v[20:21], off
	v_cvt_f32_f16_e32 v8, v9
	v_cvt_f32_f16_e32 v37, v5
	v_add_f32_e32 v8, v8, v37
	v_fma_mix_f32 v8, v8, s30, -v1 op_sel_hi:[0,0,1]
	s_waitcnt vmcnt(0)
	v_fma_mix_f32 v4, v8, v4, v1 op_sel_hi:[0,0,1]
	s_and_saveexec_b64 s[16:17], s[6:7]
	s_xor_b64 s[16:17], exec, s[16:17]
	s_cbranch_execz .LBB0_316
	s_and_saveexec_b64 s[28:29], s[4:5]
	s_cbranch_execz .LBB0_315
	v_mul_f32_e32 v4, 0xbfb8aa3b, v4
	v_exp_f32_e32 v4, v4
	s_nop 0
	v_add_f32_e32 v4, 1.0, v4
	v_rcp_f32_e32 v37, v4
	s_nop 0
	v_fma_f32 v41, -v4, v37, 1.0
	v_fma_f32 v8, v41, v37, v37
	v_div_fixup_f32 v4, v8, v4, 1.0

; __device__ __forceinline__ float sigmoidf_(float x) { return 1.0f / (1.0f + __expf(-x)); }
; __device__ __forceinline__ void phase_prep(const Params& p, unsigned char* lds) {
;     ...
;             for (int j = 0; j < 8; ++j) { const float a = (float)z1[j]; const float zs = a + (0.5f * ((float)z0[j] + (float)z2[j]) - a) * p.rwkv_mu[zc + j];
;                 v[j] = grp < 12 ? tanhf(zs) : (grp < 24 ? zs : sigmoidf_(zs)); }
.LBB0_322:
	s_or_b64 exec, exec, s[16:17]
	global_load_dword v8, v[22:23], off
	v_cvt_f32_f16_sdwa v9, v9 dst_sel:DWORD dst_unused:UNUSED_PAD src0_sel:WORD_1
	v_cvt_f32_f16_sdwa v5, v5 dst_sel:DWORD dst_unused:UNUSED_PAD src0_sel:WORD_1
	v_add_f32_e32 v5, v9, v5
	v_fma_mix_f32 v5, v5, s30, -v1 op_sel:[0,0,1] op_sel_hi:[0,0,1]
	s_waitcnt vmcnt(0)
	v_fma_mix_f32 v1, v5, v8, v1 op_sel:[0,0,1] op_sel_hi:[0,0,1]
	s_and_saveexec_b64 s[16:17], s[6:7]
	s_xor_b64 s[16:17], exec, s[16:17]
	s_cbranch_execz .LBB0_326
	s_and_saveexec_b64 s[28:29], s[4:5]
	s_cbranch_execz .LBB0_325
	v_mul_f32_e32 v1, 0xbfb8aa3b, v1
	v_exp_f32_e32 v1, v1
	s_nop 0
	v_add_f32_e32 v1, 1.0, v1
	v_rcp_f32_e32 v8, v1
	s_nop 0
	v_fma_f32 v37, -v1, v8, 1.0
	v_fma_f32 v5, v37, v8, v8
	v_div_fixup_f32 v1, v5, v1, 1.0

; __device__ __forceinline__ float sigmoidf_(float x) { return 1.0f / (1.0f + __expf(-x)); }
; __device__ __forceinline__ void phase_prep(const Params& p, unsigned char* lds) {
;     ...
;             for (int j = 0; j < 8; ++j) { const float a = (float)z1[j]; const float zs = a + (0.5f * ((float)z0[j] + (float)z2[j]) - a) * p.rwkv_mu[zc + j];
;                 v[j] = grp < 12 ? tanhf(zs) : (grp < 24 ? zs : sigmoidf_(zs)); }
.LBB0_332:
	s_or_b64 exec, exec, s[16:17]
	global_load_dword v5, v[24:25], off
	v_cvt_f32_f16_e32 v8, v10
	v_cvt_f32_f16_e32 v9, v6
	v_add_f32_e32 v8, v8, v9
	v_fma_mix_f32 v8, v8, s30, -v2 op_sel_hi:[0,0,1]
	s_waitcnt vmcnt(0)
	v_fma_mix_f32 v5, v8, v5, v2 op_sel_hi:[0,0,1]
	s_and_saveexec_b64 s[16:17], s[6:7]
	s_xor_b64 s[16:17], exec, s[16:17]
	s_cbranch_execz .LBB0_336
	s_and_saveexec_b64 s[28:29], s[4:5]
	s_cbranch_execz .LBB0_335
	v_mul_f32_e32 v5, 0xbfb8aa3b, v5
	v_exp_f32_e32 v5, v5
	s_nop 0
	v_add_f32_e32 v5, 1.0, v5
	v_rcp_f32_e32 v9, v5
	s_nop 0
	v_fma_f32 v40, -v5, v9, 1.0
	v_fma_f32 v8, v40, v9, v9
	v_div_fixup_f32 v5, v8, v5, 1.0

; __device__ __forceinline__ float sigmoidf_(float x) { return 1.0f / (1.0f + __expf(-x)); }
; __device__ __forceinline__ void phase_prep(const Params& p, unsigned char* lds) {
;     ...
;             for (int j = 0; j < 8; ++j) { const float a = (float)z1[j]; const float zs = a + (0.5f * ((float)z0[j] + (float)z2[j]) - a) * p.rwkv_mu[zc + j];
;                 v[j] = grp < 12 ? tanhf(zs) : (grp < 24 ? zs : sigmoidf_(zs)); }
.LBB0_342:
	s_or_b64 exec, exec, s[16:17]
	global_load_dword v8, v[26:27], off
	v_cvt_f32_f16_sdwa v9, v10 dst_sel:DWORD dst_unused:UNUSED_PAD src0_sel:WORD_1
	v_cvt_f32_f16_sdwa v6, v6 dst_sel:DWORD dst_unused:UNUSED_PAD src0_sel:WORD_1
	v_add_f32_e32 v6, v9, v6
	v_fma_mix_f32 v6, v6, s30, -v2 op_sel:[0,0,1] op_sel_hi:[0,0,1]
	s_waitcnt vmcnt(0)
	v_fma_mix_f32 v2, v6, v8, v2 op_sel:[0,0,1] op_sel_hi:[0,0,1]
	s_and_saveexec_b64 s[16:17], s[6:7]
	s_xor_b64 s[16:17], exec, s[16:17]
	s_cbranch_execz .LBB0_346
	s_and_saveexec_b64 s[28:29], s[4:5]
	s_cbranch_execz .LBB0_345
	v_mul_f32_e32 v2, 0xbfb8aa3b, v2
	v_exp_f32_e32 v2, v2
	s_nop 0
	v_add_f32_e32 v2, 1.0, v2
	v_rcp_f32_e32 v8, v2
	s_nop 0
	v_fma_f32 v10, -v2, v8, 1.0
	v_fma_f32 v6, v10, v8, v8
	v_div_fixup_f32 v2, v6, v2, 1.0

; __device__ __forceinline__ float sigmoidf_(float x) { return 1.0f / (1.0f + __expf(-x)); }
; __device__ __forceinline__ void phase_prep(const Params& p, unsigned char* lds) {
;     ...
;             for (int j = 0; j < 8; ++j) { const float a = (float)z1[j]; const float zs = a + (0.5f * ((float)z0[j] + (float)z2[j]) - a) * p.rwkv_mu[zc + j];
;                 v[j] = grp < 12 ? tanhf(zs) : (grp < 24 ? zs : sigmoidf_(zs)); }
.LBB0_352:
	s_or_b64 exec, exec, s[16:17]
	global_load_dword v6, v[28:29], off
	v_cvt_f32_f16_e32 v8, v11
	v_cvt_f32_f16_e32 v9, v7
	v_add_f32_e32 v8, v8, v9
	v_fma_mix_f32 v8, v8, s30, -v3 op_sel_hi:[0,0,1]
	s_waitcnt vmcnt(0)
	v_fma_mix_f32 v6, v8, v6, v3 op_sel_hi:[0,0,1]
	s_and_saveexec_b64 s[16:17], s[6:7]
	s_xor_b64 s[16:17], exec, s[16:17]
	s_cbranch_execz .LBB0_356
	s_and_saveexec_b64 s[28:29], s[4:5]
	s_cbranch_execz .LBB0_355
	v_mul_f32_e32 v6, 0xbfb8aa3b, v6
	v_exp_f32_e32 v6, v6
	s_nop 0
	v_add_f32_e32 v6, 1.0, v6
	v_rcp_f32_e32 v9, v6
	s_nop 0
	v_fma_f32 v37, -v6, v9, 1.0
	v_fma_f32 v8, v37, v9, v9
	v_div_fixup_f32 v6, v8, v6, 1.0

; __device__ __forceinline__ float sigmoidf_(float x) { return 1.0f / (1.0f + __expf(-x)); }
; __device__ __forceinline__ void phase_prep(const Params& p, unsigned char* lds) {
;     ...
;             for (int j = 0; j < 8; ++j) { const float a = (float)z1[j]; const float zs = a + (0.5f * ((float)z0[j] + (float)z2[j]) - a) * p.rwkv_mu[zc + j];
;                 v[j] = grp < 12 ? tanhf(zs) : (grp < 24 ? zs : sigmoidf_(zs)); }
.LBB0_362:
	s_or_b64 exec, exec, s[16:17]
	global_load_dword v8, v[30:31], off
	v_cvt_f32_f16_sdwa v9, v11 dst_sel:DWORD dst_unused:UNUSED_PAD src0_sel:WORD_1
	v_cvt_f32_f16_sdwa v7, v7 dst_sel:DWORD dst_unused:UNUSED_PAD src0_sel:WORD_1
	v_add_f32_e32 v7, v9, v7
	v_fma_mix_f32 v7, v7, s30, -v3 op_sel:[0,0,1] op_sel_hi:[0,0,1]
	s_waitcnt vmcnt(0)
	v_fma_mix_f32 v3, v7, v8, v3 op_sel:[0,0,1] op_sel_hi:[0,0,1]
	s_and_saveexec_b64 s[16:17], s[6:7]
	s_xor_b64 s[16:17], exec, s[16:17]
	s_cbranch_execz .LBB0_366
	s_and_saveexec_b64 s[28:29], s[4:5]
	s_cbranch_execz .LBB0_365
	v_mul_f32_e32 v3, 0xbfb8aa3b, v3
	v_exp_f32_e32 v3, v3
	s_nop 0
	v_add_f32_e32 v3, 1.0, v3
	v_rcp_f32_e32 v8, v3
	s_nop 0
	v_fma_f32 v10, -v3, v8, 1.0
	v_fma_f32 v7, v10, v8, v8
	v_div_fixup_f32 v3, v7, v3, 1.0

; __device__ __forceinline__ float sigmoidf_(float x) { return 1.0f / (1.0f + __expf(-x)); }
;     __device__ __forceinline__ void operator()(const f32x4 (&acc)[2][2][4][2], const Unit& u, int wr, int wc, int fr, int fq) const {
;     ...
;                         for (int i = 0; i < 4; ++i) { float xv = acc[ai][bj][m][n][i] + bv[bj][n][i]; float r;
;                             if (type < 2) { const float sg = sigmoidf_(xv); r = -expm1f(-0.606531f * sg); }
;                             else if (type == 2) r = sigmoidf_(xv);
.LBB0_468:
	s_waitcnt vmcnt(0)
	v_add_f32_e32 v140, v140, v32
	s_mov_b64 s[52:53], -1
	s_and_b64 vcc, exec, s[38:39]
	s_cbranch_vccz .LBB0_472
	s_and_b64 vcc, exec, s[6:7]
	v_mov_b32_e32 v152, v140
	s_cbranch_vccnz .LBB0_471
	v_mul_f32_e32 v152, 0xbfb8aa3b, v140
	v_exp_f32_e32 v152, v152
	s_nop 0
	v_add_f32_e32 v152, 1.0, v152
	v_rcp_f32_e32 v163, v152
	s_nop 0
	v_fma_f32 v175, -v152, v163, 1.0
	v_fma_f32 v162, v175, v163, v163
	v_div_fixup_f32 v152, v162, v152, 1.0

; __device__ __forceinline__ float sigmoidf_(float x) { return 1.0f / (1.0f + __expf(-x)); }
;     __device__ __forceinline__ void operator()(const f32x4 (&acc)[2][2][4][2], const Unit& u, int wr, int wc, int fr, int fq) const {
;     ...
;                         for (int i = 0; i < 4; ++i) { float xv = acc[ai][bj][m][n][i] + bv[bj][n][i]; float r;
;                             if (type < 2) { const float sg = sigmoidf_(xv); r = -expm1f(-0.606531f * sg); }
;                             else if (type == 2) r = sigmoidf_(xv);
.LBB0_473:
	v_mul_f32_e32 v140, 0xbfb8aa3b, v140
	v_exp_f32_e32 v140, v140
	s_nop 0
	v_add_f32_e32 v140, 1.0, v140
	v_rcp_f32_e32 v162, v140
	s_nop 0
	v_fma_f32 v174, -v140, v162, 1.0
	v_fma_f32 v152, v174, v162, v162
	v_div_fixup_f32 v140, v152, v140, 1.0
	v_mul_f32_e32 v140, 0xbf1b459e, v140
	v_mul_f32_e32 v152, 0x3fb8aa3b, v140
	v_rndne_f32_e32 v152, v152
	v_fmamk_f32 v162, v152, 0xbf317218, v140
	v_fmac_f32_e32 v162, 0x3102e308, v152
	v_cvt_i32_f32_e32 v163, v152
	v_fmamk_f32 v174, v162, 0x395133b1, v171
	v_fmaak_f32 v174, v162, v174, 0x3c0887f9
	v_fmaak_f32 v174, v162, v174, 0x3d2aaa81
	v_fmaak_f32 v174, v162, v174, 0x3e2aaaab
	v_ldexp_f32 v163, 1.0, v163
	v_fma_f32 v174, v162, v174, 0.5
	v_cmp_eq_f32_e32 vcc, s90, v152
	v_mul_f32_e32 v174, v162, v174
	v_fmac_f32_e32 v162, v162, v174
	v_cndmask_b32_e32 v152, v163, v172, vcc
	v_add_f32_e32 v163, -1.0, v152
	v_fmac_f32_e32 v163, v152, v162
	v_add_f32_e32 v152, v163, v163
	v_cndmask_b32_e32 v152, v163, v152, vcc
	v_cmp_nlt_f32_e32 vcc, s91, v140
	s_nop 1
	v_cndmask_b32_e64 v152, v173, -v152, vcc
	v_cmp_ngt_f32_e32 vcc, s92, v140
	s_nop 1
	v_cndmask_b32_e32 v152, 1.0, v152, vcc
.LBB0_474:
	v_add_f32_e32 v140, v141, v33
	s_and_b64 vcc, exec, s[8:9]
	s_mov_b64 s[38:39], -1
	s_cbranch_vccnz .LBB0_478
	s_and_b64 vcc, exec, s[6:7]
	v_mov_b32_e32 v162, v140
	s_cbranch_vccnz .LBB0_477
	v_mul_f32_e32 v141, 0xbfb8aa3b, v140
	v_exp_f32_e32 v141, v141
	s_nop 0
	v_add_f32_e32 v141, 1.0, v141
	v_rcp_f32_e32 v163, v141
	s_nop 0
	v_fma_f32 v175, -v141, v163, 1.0
	v_fma_f32 v162, v175, v163, v163
	v_div_fixup_f32 v162, v162, v141, 1.0

; __device__ __forceinline__ float sigmoidf_(float x) { return 1.0f / (1.0f + __expf(-x)); }
;     __device__ __forceinline__ void operator()(const f32x4 (&acc)[2][2][4][2], const Unit& u, int wr, int wc, int fr, int fq) const {
;     ...
;                         for (int i = 0; i < 4; ++i) { float xv = acc[ai][bj][m][n][i] + bv[bj][n][i]; float r;
;                             if (type < 2) { const float sg = sigmoidf_(xv); r = -expm1f(-0.606531f * sg); }
;                             else if (type == 2) r = sigmoidf_(xv);
.LBB0_479:
	v_mul_f32_e32 v140, 0xbfb8aa3b, v140
	v_exp_f32_e32 v140, v140
	s_nop 0
	v_add_f32_e32 v140, 1.0, v140
	v_rcp_f32_e32 v162, v140
	s_nop 0
	v_fma_f32 v174, -v140, v162, 1.0
	v_fma_f32 v141, v174, v162, v162
	v_div_fixup_f32 v140, v141, v140, 1.0
	v_mul_f32_e32 v140, 0xbf1b459e, v140
	v_mul_f32_e32 v141, 0x3fb8aa3b, v140
	v_rndne_f32_e32 v141, v141
	v_fmamk_f32 v162, v141, 0xbf317218, v140
	v_fmac_f32_e32 v162, 0x3102e308, v141
	v_cvt_i32_f32_e32 v163, v141
	v_fmamk_f32 v174, v162, 0x395133b1, v171
	v_fmaak_f32 v174, v162, v174, 0x3c0887f9
	v_fmaak_f32 v174, v162, v174, 0x3d2aaa81
	v_fmaak_f32 v174, v162, v174, 0x3e2aaaab
	v_ldexp_f32 v163, 1.0, v163
	v_fma_f32 v174, v162, v174, 0.5
	v_cmp_eq_f32_e32 vcc, s90, v141
	v_mul_f32_e32 v174, v162, v174
	v_fmac_f32_e32 v162, v162, v174
	v_cndmask_b32_e32 v141, v163, v172, vcc
	v_add_f32_e32 v163, -1.0, v141
	v_fmac_f32_e32 v163, v141, v162
	v_add_f32_e32 v141, v163, v163
	v_cndmask_b32_e32 v141, v163, v141, vcc
	v_cmp_nlt_f32_e32 vcc, s91, v140
	s_nop 1
	v_cndmask_b32_e64 v141, v173, -v141, vcc
	v_cmp_ngt_f32_e32 vcc, s92, v140
	s_nop 1
	v_cndmask_b32_e32 v162, 1.0, v141, vcc
.LBB0_480:
	v_add_f32_e32 v140, v142, v34
	s_and_b64 vcc, exec, s[8:9]
	s_mov_b64 s[38:39], -1
	s_cbranch_vccnz .LBB0_484
	s_and_b64 vcc, exec, s[6:7]
	v_mov_b32_e32 v142, v140
	s_cbranch_vccnz .LBB0_483
	v_mul_f32_e32 v141, 0xbfb8aa3b, v140
	v_exp_f32_e32 v141, v141
	s_nop 0
	v_add_f32_e32 v141, 1.0, v141
	v_rcp_f32_e32 v163, v141
	s_nop 0
	v_fma_f32 v175, -v141, v163, 1.0
	v_fma_f32 v142, v175, v163, v163
	v_div_fixup_f32 v142, v142, v141, 1.0

; __device__ __forceinline__ float sigmoidf_(float x) { return 1.0f / (1.0f + __expf(-x)); }
;     __device__ __forceinline__ void operator()(const f32x4 (&acc)[2][2][4][2], const Unit& u, int wr, int wc, int fr, int fq) const {
;     ...
;                         for (int i = 0; i < 4; ++i) { float xv = acc[ai][bj][m][n][i] + bv[bj][n][i]; float r;
;                             if (type < 2) { const float sg = sigmoidf_(xv); r = -expm1f(-0.606531f * sg); }
;                             else if (type == 2) r = sigmoidf_(xv);
.LBB0_485:
	v_mul_f32_e32 v140, 0xbfb8aa3b, v140
	v_exp_f32_e32 v140, v140
	s_nop 0
	v_add_f32_e32 v140, 1.0, v140
	v_rcp_f32_e32 v142, v140
	s_nop 0
	v_fma_f32 v174, -v140, v142, 1.0
	v_fma_f32 v141, v174, v142, v142
	v_div_fixup_f32 v140, v141, v140, 1.0
	v_mul_f32_e32 v140, 0xbf1b459e, v140
	v_mul_f32_e32 v141, 0x3fb8aa3b, v140
	v_rndne_f32_e32 v141, v141
	v_fmamk_f32 v142, v141, 0xbf317218, v140
	v_fmac_f32_e32 v142, 0x3102e308, v141
	v_cvt_i32_f32_e32 v163, v141
	v_fmamk_f32 v174, v142, 0x395133b1, v171
	v_fmaak_f32 v174, v142, v174, 0x3c0887f9
	v_fmaak_f32 v174, v142, v174, 0x3d2aaa81
	v_fmaak_f32 v174, v142, v174, 0x3e2aaaab
	v_ldexp_f32 v163, 1.0, v163
	v_fma_f32 v174, v142, v174, 0.5
	v_cmp_eq_f32_e32 vcc, s90, v141
	v_mul_f32_e32 v174, v142, v174
	v_fmac_f32_e32 v142, v142, v174
	v_cndmask_b32_e32 v141, v163, v172, vcc
	v_add_f32_e32 v163, -1.0, v141
	v_fmac_f32_e32 v163, v141, v142
	v_add_f32_e32 v141, v163, v163
	v_cndmask_b32_e32 v141, v163, v141, vcc
	v_cmp_nlt_f32_e32 vcc, s91, v140
	s_nop 1
	v_cndmask_b32_e64 v141, v173, -v141, vcc
	v_cmp_ngt_f32_e32 vcc, s92, v140
	s_nop 1
	v_cndmask_b32_e32 v142, 1.0, v141, vcc
.LBB0_486:
	v_add_f32_e32 v140, v143, v35
	s_and_b64 vcc, exec, s[8:9]
	s_mov_b64 s[38:39], -1
	s_cbranch_vccnz .LBB0_490
	s_and_b64 vcc, exec, s[6:7]
	v_mov_b32_e32 v143, v140
	s_cbranch_vccnz .LBB0_489
	v_mul_f32_e32 v141, 0xbfb8aa3b, v140
	v_exp_f32_e32 v141, v141
	s_nop 0
	v_add_f32_e32 v141, 1.0, v141
	v_rcp_f32_e32 v163, v141
	s_nop 0
	v_fma_f32 v175, -v141, v163, 1.0
	v_fma_f32 v143, v175, v163, v163
	v_div_fixup_f32 v143, v143, v141, 1.0

; __device__ __forceinline__ float sigmoidf_(float x) { return 1.0f / (1.0f + __expf(-x)); }
;     __device__ __forceinline__ void operator()(const f32x4 (&acc)[2][2][4][2], const Unit& u, int wr, int wc, int fr, int fq) const {
;     ...
;                         for (int i = 0; i < 4; ++i) { float xv = acc[ai][bj][m][n][i] + bv[bj][n][i]; float r;
;                             if (type < 2) { const float sg = sigmoidf_(xv); r = -expm1f(-0.606531f * sg); }
;                             else if (type == 2) r = sigmoidf_(xv);
.LBB0_491:
	v_mul_f32_e32 v140, 0xbfb8aa3b, v140
	v_exp_f32_e32 v140, v140
	s_nop 0
	v_add_f32_e32 v140, 1.0, v140
	v_rcp_f32_e32 v143, v140
	s_nop 0
	v_fma_f32 v174, -v140, v143, 1.0
	v_fma_f32 v141, v174, v143, v143
	v_div_fixup_f32 v140, v141, v140, 1.0
	v_mul_f32_e32 v140, 0xbf1b459e, v140
	v_mul_f32_e32 v141, 0x3fb8aa3b, v140
	v_rndne_f32_e32 v141, v141
	v_fmamk_f32 v143, v141, 0xbf317218, v140
	v_fmac_f32_e32 v143, 0x3102e308, v141
	v_cvt_i32_f32_e32 v163, v141
	v_fmamk_f32 v174, v143, 0x395133b1, v171
	v_fmaak_f32 v174, v143, v174, 0x3c0887f9
	v_fmaak_f32 v174, v143, v174, 0x3d2aaa81
	v_fmaak_f32 v174, v143, v174, 0x3e2aaaab
	v_ldexp_f32 v163, 1.0, v163
	v_fma_f32 v174, v143, v174, 0.5
	v_cmp_eq_f32_e32 vcc, s90, v141
	v_mul_f32_e32 v174, v143, v174
	v_fmac_f32_e32 v143, v143, v174
	v_cndmask_b32_e32 v141, v163, v172, vcc
	v_add_f32_e32 v163, -1.0, v141
	v_fmac_f32_e32 v163, v141, v143
	v_add_f32_e32 v141, v163, v163
	v_cndmask_b32_e32 v141, v163, v141, vcc
	v_cmp_nlt_f32_e32 vcc, s91, v140
	s_nop 1
	v_cndmask_b32_e64 v141, v173, -v141, vcc
	v_cmp_ngt_f32_e32 vcc, s92, v140
	s_nop 1
	v_cndmask_b32_e32 v143, 1.0, v141, vcc
.LBB0_492:
	v_add_f32_e32 v136, v136, v28
	s_and_b64 vcc, exec, s[8:9]
	s_mov_b64 s[38:39], -1
	s_cbranch_vccnz .LBB0_496
	s_and_b64 vcc, exec, s[6:7]
	v_mov_b32_e32 v163, v136
	s_cbranch_vccnz .LBB0_495
	v_mul_f32_e32 v140, 0xbfb8aa3b, v136
	v_exp_f32_e32 v140, v140
	s_nop 0
	v_add_f32_e32 v140, 1.0, v140
	v_rcp_f32_e32 v163, v140
	s_nop 0
	v_fma_f32 v175, -v140, v163, 1.0
	v_fma_f32 v141, v175, v163, v163
	v_div_fixup_f32 v163, v141, v140, 1.0

; __device__ __forceinline__ float sigmoidf_(float x) { return 1.0f / (1.0f + __expf(-x)); }
;     __device__ __forceinline__ void operator()(const f32x4 (&acc)[2][2][4][2], const Unit& u, int wr, int wc, int fr, int fq) const {
;     ...
;                         for (int i = 0; i < 4; ++i) { float xv = acc[ai][bj][m][n][i] + bv[bj][n][i]; float r;
;                             if (type < 2) { const float sg = sigmoidf_(xv); r = -expm1f(-0.606531f * sg); }
;                             else if (type == 2) r = sigmoidf_(xv);
.LBB0_497:
	v_mul_f32_e32 v136, 0xbfb8aa3b, v136
	v_exp_f32_e32 v136, v136
	s_nop 0
	v_add_f32_e32 v136, 1.0, v136
	v_rcp_f32_e32 v141, v136
	s_nop 0
	v_fma_f32 v174, -v136, v141, 1.0
	v_fma_f32 v140, v174, v141, v141
	v_div_fixup_f32 v136, v140, v136, 1.0
	v_mul_f32_e32 v136, 0xbf1b459e, v136
	v_mul_f32_e32 v140, 0x3fb8aa3b, v136
	v_rndne_f32_e32 v140, v140
	v_fmamk_f32 v141, v140, 0xbf317218, v136
	v_fmac_f32_e32 v141, 0x3102e308, v140
	v_cvt_i32_f32_e32 v163, v140
	v_fmamk_f32 v174, v141, 0x395133b1, v171
	v_fmaak_f32 v174, v141, v174, 0x3c0887f9
	v_fmaak_f32 v174, v141, v174, 0x3d2aaa81
	v_fmaak_f32 v174, v141, v174, 0x3e2aaaab
	v_ldexp_f32 v163, 1.0, v163
	v_fma_f32 v174, v141, v174, 0.5
	v_cmp_eq_f32_e32 vcc, s90, v140
	v_mul_f32_e32 v174, v141, v174
	v_fmac_f32_e32 v141, v141, v174
	v_cndmask_b32_e32 v140, v163, v172, vcc
	v_add_f32_e32 v163, -1.0, v140
	v_fmac_f32_e32 v163, v140, v141
	v_add_f32_e32 v140, v163, v163
	v_cndmask_b32_e32 v140, v163, v140, vcc
	v_cmp_nlt_f32_e32 vcc, s91, v136
	s_nop 1
	v_cndmask_b32_e64 v140, v173, -v140, vcc
	v_cmp_ngt_f32_e32 vcc, s92, v136
	s_nop 1
	v_cndmask_b32_e32 v163, 1.0, v140, vcc
.LBB0_498:
	v_add_f32_e32 v136, v137, v29
	s_and_b64 vcc, exec, s[8:9]
	s_mov_b64 s[38:39], -1
	s_cbranch_vccnz .LBB0_502
	s_and_b64 vcc, exec, s[6:7]
	v_mov_b32_e32 v174, v136
	s_cbranch_vccnz .LBB0_501
	v_mul_f32_e32 v137, 0xbfb8aa3b, v136
	v_exp_f32_e32 v137, v137
	s_nop 0
	v_add_f32_e32 v137, 1.0, v137
	v_rcp_f32_e32 v141, v137
	s_nop 0
	v_fma_f32 v175, -v137, v141, 1.0
	v_fma_f32 v140, v175, v141, v141
	v_div_fixup_f32 v174, v140, v137, 1.0

; __device__ __forceinline__ float sigmoidf_(float x) { return 1.0f / (1.0f + __expf(-x)); }
;     __device__ __forceinline__ void operator()(const f32x4 (&acc)[2][2][4][2], const Unit& u, int wr, int wc, int fr, int fq) const {
;     ...
;                         for (int i = 0; i < 4; ++i) { float xv = acc[ai][bj][m][n][i] + bv[bj][n][i]; float r;
;                             if (type < 2) { const float sg = sigmoidf_(xv); r = -expm1f(-0.606531f * sg); }
;                             else if (type == 2) r = sigmoidf_(xv);
.LBB0_503:
	v_mul_f32_e32 v136, 0xbfb8aa3b, v136
	v_exp_f32_e32 v136, v136
	s_nop 0
	v_add_f32_e32 v136, 1.0, v136
	v_rcp_f32_e32 v140, v136
	s_nop 0
	v_fma_f32 v174, -v136, v140, 1.0
	v_fma_f32 v137, v174, v140, v140
	v_div_fixup_f32 v136, v137, v136, 1.0
	v_mul_f32_e32 v136, 0xbf1b459e, v136
	v_mul_f32_e32 v137, 0x3fb8aa3b, v136
	v_rndne_f32_e32 v137, v137
	v_fmamk_f32 v140, v137, 0xbf317218, v136
	v_fmac_f32_e32 v140, 0x3102e308, v137
	v_cvt_i32_f32_e32 v141, v137
	v_fmamk_f32 v174, v140, 0x395133b1, v171
	v_fmaak_f32 v174, v140, v174, 0x3c0887f9
	v_fmaak_f32 v174, v140, v174, 0x3d2aaa81
	v_fmaak_f32 v174, v140, v174, 0x3e2aaaab
	v_ldexp_f32 v141, 1.0, v141
	v_fma_f32 v174, v140, v174, 0.5
	v_cmp_eq_f32_e32 vcc, s90, v137
	v_mul_f32_e32 v174, v140, v174
	v_fmac_f32_e32 v140, v140, v174
	v_cndmask_b32_e32 v137, v141, v172, vcc
	v_add_f32_e32 v141, -1.0, v137
	v_fmac_f32_e32 v141, v137, v140
	v_add_f32_e32 v137, v141, v141
	v_cndmask_b32_e32 v137, v141, v137, vcc
	v_cmp_nlt_f32_e32 vcc, s91, v136
	s_nop 1
	v_cndmask_b32_e64 v137, v173, -v137, vcc
	v_cmp_ngt_f32_e32 vcc, s92, v136
	s_nop 1
	v_cndmask_b32_e32 v174, 1.0, v137, vcc
.LBB0_504:
	v_add_f32_e32 v136, v138, v30
	s_and_b64 vcc, exec, s[8:9]
	s_mov_b64 s[38:39], -1
	s_cbranch_vccnz .LBB0_508
	s_and_b64 vcc, exec, s[6:7]
	v_mov_b32_e32 v175, v136
	s_cbranch_vccnz .LBB0_507
	v_mul_f32_e32 v137, 0xbfb8aa3b, v136
	v_exp_f32_e32 v137, v137
	s_nop 0
	v_add_f32_e32 v137, 1.0, v137
	v_rcp_f32_e32 v140, v137
	s_nop 0
	v_fma_f32 v175, -v137, v140, 1.0
	v_fma_f32 v138, v175, v140, v140
	v_div_fixup_f32 v175, v138, v137, 1.0

; __device__ __forceinline__ float sigmoidf_(float x) { return 1.0f / (1.0f + __expf(-x)); }
;     __device__ __forceinline__ void operator()(const f32x4 (&acc)[2][2][4][2], const Unit& u, int wr, int wc, int fr, int fq) const {
;     ...
;                         for (int i = 0; i < 4; ++i) { float xv = acc[ai][bj][m][n][i] + bv[bj][n][i]; float r;
;                             if (type < 2) { const float sg = sigmoidf_(xv); r = -expm1f(-0.606531f * sg); }
;                             else if (type == 2) r = sigmoidf_(xv);
.LBB0_509:
	v_mul_f32_e32 v136, 0xbfb8aa3b, v136
	v_exp_f32_e32 v136, v136
	s_nop 0
	v_add_f32_e32 v136, 1.0, v136
	v_rcp_f32_e32 v138, v136
	s_nop 0
	v_fma_f32 v141, -v136, v138, 1.0
	v_fma_f32 v137, v141, v138, v138
	v_div_fixup_f32 v136, v137, v136, 1.0
	v_mul_f32_e32 v136, 0xbf1b459e, v136
	v_mul_f32_e32 v137, 0x3fb8aa3b, v136
	v_rndne_f32_e32 v137, v137
	v_fmamk_f32 v138, v137, 0xbf317218, v136
	v_fmac_f32_e32 v138, 0x3102e308, v137
	v_cvt_i32_f32_e32 v140, v137
	v_fmamk_f32 v141, v138, 0x395133b1, v171
	v_fmaak_f32 v141, v138, v141, 0x3c0887f9
	v_fmaak_f32 v141, v138, v141, 0x3d2aaa81
	v_fmaak_f32 v141, v138, v141, 0x3e2aaaab
	v_ldexp_f32 v140, 1.0, v140
	v_fma_f32 v141, v138, v141, 0.5
	v_cmp_eq_f32_e32 vcc, s90, v137
	v_mul_f32_e32 v141, v138, v141
	v_fmac_f32_e32 v138, v138, v141
	v_cndmask_b32_e32 v137, v140, v172, vcc
	v_add_f32_e32 v140, -1.0, v137
	v_fmac_f32_e32 v140, v137, v138
	v_add_f32_e32 v137, v140, v140
	v_cndmask_b32_e32 v137, v140, v137, vcc
	v_cmp_nlt_f32_e32 vcc, s91, v136
	s_nop 1
	v_cndmask_b32_e64 v137, v173, -v137, vcc
	v_cmp_ngt_f32_e32 vcc, s92, v136
	s_nop 1
	v_cndmask_b32_e32 v175, 1.0, v137, vcc
.LBB0_510:
	v_add_f32_e32 v136, v139, v31
	s_and_b64 vcc, exec, s[8:9]
	s_mov_b64 s[38:39], -1
	s_cbranch_vccnz .LBB0_514
	s_and_b64 vcc, exec, s[6:7]
	v_mov_b32_e32 v176, v136
	s_cbranch_vccnz .LBB0_513
	v_mul_f32_e32 v137, 0xbfb8aa3b, v136
	v_exp_f32_e32 v137, v137
	s_nop 0
	v_add_f32_e32 v137, 1.0, v137
	v_rcp_f32_e32 v139, v137
	s_nop 0
	v_fma_f32 v141, -v137, v139, 1.0
	v_fma_f32 v138, v141, v139, v139
	v_div_fixup_f32 v176, v138, v137, 1.0

; __device__ __forceinline__ float sigmoidf_(float x) { return 1.0f / (1.0f + __expf(-x)); }
;     __device__ __forceinline__ void operator()(const f32x4 (&acc)[2][2][4][2], const Unit& u, int wr, int wc, int fr, int fq) const {
;     ...
;             for (int m = 0; m < 4; ++m) { f16* rowp = O + (size_t)(row0 + ai * 128 + m * 16) * 4096 + col0;
; #pragma unroll
;                 for (int bj = 0; bj < 2; ++bj) { f16x8 v;
; #pragma unroll
;                     for (int n = 0; n < 2; ++n)
; #pragma unroll
;                         for (int i = 0; i < 4; ++i) { float xv = acc[ai][bj][m][n][i] + bv[bj][n][i]; float r;
;                             if (type < 2) { const float sg = sigmoidf_(xv); r = -expm1f(-0.606531f * sg); }
;                             else if (type == 2) r = sigmoidf_(xv);
;                             else r = xv;
;                             v[4 * n + i] = (f16)r; }
;                     *(f16x8*)(rowp + bj * 128) = v; } }
.LBB0_515:
	v_mul_f32_e32 v136, 0xbfb8aa3b, v136
	v_exp_f32_e32 v136, v136
	s_nop 0
	v_add_f32_e32 v136, 1.0, v136
	v_rcp_f32_e32 v138, v136
	s_nop 0
	v_fma_f32 v140, -v136, v138, 1.0
	v_fma_f32 v137, v140, v138, v138
	v_div_fixup_f32 v136, v137, v136, 1.0
	v_mul_f32_e32 v136, 0xbf1b459e, v136
	v_mul_f32_e32 v137, 0x3fb8aa3b, v136
	v_rndne_f32_e32 v137, v137
	v_fmamk_f32 v138, v137, 0xbf317218, v136
	v_fmac_f32_e32 v138, 0x3102e308, v137
	v_cvt_i32_f32_e32 v139, v137
	v_fmamk_f32 v140, v138, 0x395133b1, v171
	v_fmaak_f32 v140, v138, v140, 0x3c0887f9
	v_fmaak_f32 v140, v138, v140, 0x3d2aaa81
	v_fmaak_f32 v140, v138, v140, 0x3e2aaaab
	v_ldexp_f32 v139, 1.0, v139
	v_fma_f32 v140, v138, v140, 0.5
	v_cmp_eq_f32_e32 vcc, s90, v137
	v_mul_f32_e32 v140, v138, v140
	v_fmac_f32_e32 v138, v138, v140
	v_cndmask_b32_e32 v137, v139, v172, vcc
	v_add_f32_e32 v139, -1.0, v137
	v_fmac_f32_e32 v139, v137, v138
	v_add_f32_e32 v137, v139, v139
	v_cndmask_b32_e32 v137, v139, v137, vcc
	v_cmp_nlt_f32_e32 vcc, s91, v136
	s_nop 1
	v_cndmask_b32_e64 v137, v173, -v137, vcc
	v_cmp_ngt_f32_e32 vcc, s92, v136
	s_nop 1
	v_cndmask_b32_e32 v176, 1.0, v137, vcc
.LBB0_516:
	v_lshl_add_u32 v138, s36, 8, v164
	v_ashrrev_i32_e32 v139, 31, v138
	v_or_b32_e32 v136, s2, v166
	v_lshlrev_b64 v[140:141], 13, v[138:139]
	v_ashrrev_i32_e32 v137, 31, v136
	v_lshl_add_u64 v[140:141], s[28:29], 0, v[140:141]
	v_lshl_add_u64 v[140:141], v[136:137], 1, v[140:141]
	v_cvt_pk_f16_f32 v177, v175, v176
	v_cvt_pk_f16_f32 v176, v163, v174
	v_cvt_pk_f16_f32 v175, v142, v143
	v_cvt_pk_f16_f32 v174, v152, v162
	v_add_f32_e32 v142, v132, v20
	s_and_b64 vcc, exec, s[8:9]
	s_mov_b64 s[14:15], -1
	global_store_dwordx4 v[140:141], v[174:177], off
	s_cbranch_vccnz .LBB0_520
	s_and_b64 vcc, exec, s[6:7]
	v_mov_b32_e32 v132, v142
	s_cbranch_vccnz .LBB0_519
	v_mul_f32_e32 v132, 0xbfb8aa3b, v142
	v_exp_f32_e32 v132, v132
	s_nop 0
	v_add_f32_e32 v132, 1.0, v132
	v_rcp_f32_e32 v152, v132
	s_nop 0
	v_fma_f32 v163, -v132, v152, 1.0
	v_fma_f32 v143, v163, v152, v152
	v_div_fixup_f32 v132, v143, v132, 1.0

; __device__ __forceinline__ float sigmoidf_(float x) { return 1.0f / (1.0f + __expf(-x)); }
;     __device__ __forceinline__ void operator()(const f32x4 (&acc)[2][2][4][2], const Unit& u, int wr, int wc, int fr, int fq) const {
;     ...
;                         for (int i = 0; i < 4; ++i) { float xv = acc[ai][bj][m][n][i] + bv[bj][n][i]; float r;
;                             if (type < 2) { const float sg = sigmoidf_(xv); r = -expm1f(-0.606531f * sg); }
;                             else if (type == 2) r = sigmoidf_(xv);
.LBB0_521:
	v_mul_f32_e32 v132, 0xbfb8aa3b, v142
	v_exp_f32_e32 v132, v132
	s_nop 0
	v_add_f32_e32 v132, 1.0, v132
	v_rcp_f32_e32 v143, v132
	s_nop 0
	v_fma_f32 v162, -v132, v143, 1.0
	v_fma_f32 v142, v162, v143, v143
	v_div_fixup_f32 v132, v142, v132, 1.0
	v_mul_f32_e32 v132, 0xbf1b459e, v132
	v_mul_f32_e32 v142, 0x3fb8aa3b, v132
	v_rndne_f32_e32 v142, v142
	v_fmamk_f32 v143, v142, 0xbf317218, v132
	v_fmac_f32_e32 v143, 0x3102e308, v142
	v_cvt_i32_f32_e32 v152, v142
	v_fmamk_f32 v162, v143, 0x395133b1, v171
	v_fmaak_f32 v162, v143, v162, 0x3c0887f9
	v_fmaak_f32 v162, v143, v162, 0x3d2aaa81
	v_fmaak_f32 v162, v143, v162, 0x3e2aaaab
	v_ldexp_f32 v152, 1.0, v152
	v_fma_f32 v162, v143, v162, 0.5
	v_cmp_eq_f32_e32 vcc, s90, v142
	v_mul_f32_e32 v162, v143, v162
	v_fmac_f32_e32 v143, v143, v162
	v_cndmask_b32_e32 v142, v152, v172, vcc
	v_add_f32_e32 v152, -1.0, v142
	v_fmac_f32_e32 v152, v142, v143
	v_add_f32_e32 v142, v152, v152
	v_cndmask_b32_e32 v142, v152, v142, vcc
	v_cmp_nlt_f32_e32 vcc, s91, v132
	s_nop 1
	v_cndmask_b32_e64 v142, v173, -v142, vcc
	v_cmp_ngt_f32_e32 vcc, s92, v132
	s_nop 1
	v_cndmask_b32_e32 v132, 1.0, v142, vcc
.LBB0_522:
	v_add_f32_e32 v142, v133, v21
	s_and_b64 vcc, exec, s[8:9]
	s_mov_b64 s[14:15], -1
	s_cbranch_vccnz .LBB0_526
	s_and_b64 vcc, exec, s[6:7]
	v_mov_b32_e32 v133, v142
	s_cbranch_vccnz .LBB0_525
	v_mul_f32_e32 v133, 0xbfb8aa3b, v142
	v_exp_f32_e32 v133, v133
	s_nop 0
	v_add_f32_e32 v133, 1.0, v133
	v_rcp_f32_e32 v152, v133
	s_nop 0
	v_fma_f32 v163, -v133, v152, 1.0
	v_fma_f32 v143, v163, v152, v152
	v_div_fixup_f32 v133, v143, v133, 1.0

; __device__ __forceinline__ float sigmoidf_(float x) { return 1.0f / (1.0f + __expf(-x)); }
;     __device__ __forceinline__ void operator()(const f32x4 (&acc)[2][2][4][2], const Unit& u, int wr, int wc, int fr, int fq) const {
;     ...
;                         for (int i = 0; i < 4; ++i) { float xv = acc[ai][bj][m][n][i] + bv[bj][n][i]; float r;
;                             if (type < 2) { const float sg = sigmoidf_(xv); r = -expm1f(-0.606531f * sg); }
;                             else if (type == 2) r = sigmoidf_(xv);
.LBB0_527:
	v_mul_f32_e32 v133, 0xbfb8aa3b, v142
	v_exp_f32_e32 v133, v133
	s_nop 0
	v_add_f32_e32 v133, 1.0, v133
	v_rcp_f32_e32 v143, v133
	s_nop 0
	v_fma_f32 v162, -v133, v143, 1.0
	v_fma_f32 v142, v162, v143, v143
	v_div_fixup_f32 v133, v142, v133, 1.0
	v_mul_f32_e32 v133, 0xbf1b459e, v133
	v_mul_f32_e32 v142, 0x3fb8aa3b, v133
	v_rndne_f32_e32 v142, v142
	v_fmamk_f32 v143, v142, 0xbf317218, v133
	v_fmac_f32_e32 v143, 0x3102e308, v142
	v_cvt_i32_f32_e32 v152, v142
	v_fmamk_f32 v162, v143, 0x395133b1, v171
	v_fmaak_f32 v162, v143, v162, 0x3c0887f9
	v_fmaak_f32 v162, v143, v162, 0x3d2aaa81
	v_fmaak_f32 v162, v143, v162, 0x3e2aaaab
	v_ldexp_f32 v152, 1.0, v152
	v_fma_f32 v162, v143, v162, 0.5
	v_cmp_eq_f32_e32 vcc, s90, v142
	v_mul_f32_e32 v162, v143, v162
	v_fmac_f32_e32 v143, v143, v162
	v_cndmask_b32_e32 v142, v152, v172, vcc
	v_add_f32_e32 v152, -1.0, v142
	v_fmac_f32_e32 v152, v142, v143
	v_add_f32_e32 v142, v152, v152
	v_cndmask_b32_e32 v142, v152, v142, vcc
	v_cmp_nlt_f32_e32 vcc, s91, v133
	s_nop 1
	v_cndmask_b32_e64 v142, v173, -v142, vcc
	v_cmp_ngt_f32_e32 vcc, s92, v133
	s_nop 1
	v_cndmask_b32_e32 v133, 1.0, v142, vcc
.LBB0_528:
	v_add_f32_e32 v142, v134, v22
	s_and_b64 vcc, exec, s[8:9]
	s_mov_b64 s[14:15], -1
	s_cbranch_vccnz .LBB0_532
	s_and_b64 vcc, exec, s[6:7]
	v_mov_b32_e32 v134, v142
	s_cbranch_vccnz .LBB0_531
	v_mul_f32_e32 v134, 0xbfb8aa3b, v142
	v_exp_f32_e32 v134, v134
	s_nop 0
	v_add_f32_e32 v134, 1.0, v134
	v_rcp_f32_e32 v152, v134
	s_nop 0
	v_fma_f32 v163, -v134, v152, 1.0
	v_fma_f32 v143, v163, v152, v152
	v_div_fixup_f32 v134, v143, v134, 1.0

; __device__ __forceinline__ float sigmoidf_(float x) { return 1.0f / (1.0f + __expf(-x)); }
;     __device__ __forceinline__ void operator()(const f32x4 (&acc)[2][2][4][2], const Unit& u, int wr, int wc, int fr, int fq) const {
;     ...
;                         for (int i = 0; i < 4; ++i) { float xv = acc[ai][bj][m][n][i] + bv[bj][n][i]; float r;
;                             if (type < 2) { const float sg = sigmoidf_(xv); r = -expm1f(-0.606531f * sg); }
;                             else if (type == 2) r = sigmoidf_(xv);
.LBB0_533:
	v_mul_f32_e32 v134, 0xbfb8aa3b, v142
	v_exp_f32_e32 v134, v134
	s_nop 0
	v_add_f32_e32 v134, 1.0, v134
	v_rcp_f32_e32 v143, v134
	s_nop 0
	v_fma_f32 v162, -v134, v143, 1.0
	v_fma_f32 v142, v162, v143, v143
	v_div_fixup_f32 v134, v142, v134, 1.0
	v_mul_f32_e32 v134, 0xbf1b459e, v134
	v_mul_f32_e32 v142, 0x3fb8aa3b, v134
	v_rndne_f32_e32 v142, v142
	v_fmamk_f32 v143, v142, 0xbf317218, v134
	v_fmac_f32_e32 v143, 0x3102e308, v142
	v_cvt_i32_f32_e32 v152, v142
	v_fmamk_f32 v162, v143, 0x395133b1, v171
	v_fmaak_f32 v162, v143, v162, 0x3c0887f9
	v_fmaak_f32 v162, v143, v162, 0x3d2aaa81
	v_fmaak_f32 v162, v143, v162, 0x3e2aaaab
	v_ldexp_f32 v152, 1.0, v152
	v_fma_f32 v162, v143, v162, 0.5
	v_cmp_eq_f32_e32 vcc, s90, v142
	v_mul_f32_e32 v162, v143, v162
	v_fmac_f32_e32 v143, v143, v162
	v_cndmask_b32_e32 v142, v152, v172, vcc
	v_add_f32_e32 v152, -1.0, v142
	v_fmac_f32_e32 v152, v142, v143
	v_add_f32_e32 v142, v152, v152
	v_cndmask_b32_e32 v142, v152, v142, vcc
	v_cmp_nlt_f32_e32 vcc, s91, v134
	s_nop 1
	v_cndmask_b32_e64 v142, v173, -v142, vcc
	v_cmp_ngt_f32_e32 vcc, s92, v134
	s_nop 1
	v_cndmask_b32_e32 v134, 1.0, v142, vcc
.LBB0_534:
	v_add_f32_e32 v142, v135, v23
	s_and_b64 vcc, exec, s[8:9]
	s_mov_b64 s[14:15], -1
	s_cbranch_vccnz .LBB0_538
	s_and_b64 vcc, exec, s[6:7]
	v_mov_b32_e32 v135, v142
	s_cbranch_vccnz .LBB0_537
	v_mul_f32_e32 v135, 0xbfb8aa3b, v142
	v_exp_f32_e32 v135, v135
	s_nop 0
	v_add_f32_e32 v135, 1.0, v135
	v_rcp_f32_e32 v152, v135
	s_nop 0
	v_fma_f32 v163, -v135, v152, 1.0
	v_fma_f32 v143, v163, v152, v152
	v_div_fixup_f32 v135, v143, v135, 1.0

; __device__ __forceinline__ float sigmoidf_(float x) { return 1.0f / (1.0f + __expf(-x)); }
;     __device__ __forceinline__ void operator()(const f32x4 (&acc)[2][2][4][2], const Unit& u, int wr, int wc, int fr, int fq) const {
;     ...
;                         for (int i = 0; i < 4; ++i) { float xv = acc[ai][bj][m][n][i] + bv[bj][n][i]; float r;
;                             if (type < 2) { const float sg = sigmoidf_(xv); r = -expm1f(-0.606531f * sg); }
;                             else if (type == 2) r = sigmoidf_(xv);
.LBB0_539:
	v_mul_f32_e32 v135, 0xbfb8aa3b, v142
	v_exp_f32_e32 v135, v135
	s_nop 0
	v_add_f32_e32 v135, 1.0, v135
	v_rcp_f32_e32 v143, v135
	s_nop 0
	v_fma_f32 v162, -v135, v143, 1.0
	v_fma_f32 v142, v162, v143, v143
	v_div_fixup_f32 v135, v142, v135, 1.0
	v_mul_f32_e32 v135, 0xbf1b459e, v135
	v_mul_f32_e32 v142, 0x3fb8aa3b, v135
	v_rndne_f32_e32 v142, v142
	v_fmamk_f32 v143, v142, 0xbf317218, v135
	v_fmac_f32_e32 v143, 0x3102e308, v142
	v_cvt_i32_f32_e32 v152, v142
	v_fmamk_f32 v162, v143, 0x395133b1, v171
	v_fmaak_f32 v162, v143, v162, 0x3c0887f9
	v_fmaak_f32 v162, v143, v162, 0x3d2aaa81
	v_fmaak_f32 v162, v143, v162, 0x3e2aaaab
	v_ldexp_f32 v152, 1.0, v152
	v_fma_f32 v162, v143, v162, 0.5
	v_cmp_eq_f32_e32 vcc, s90, v142
	v_mul_f32_e32 v162, v143, v162
	v_fmac_f32_e32 v143, v143, v162
	v_cndmask_b32_e32 v142, v152, v172, vcc
	v_add_f32_e32 v152, -1.0, v142
	v_fmac_f32_e32 v152, v142, v143
	v_add_f32_e32 v142, v152, v152
	v_cndmask_b32_e32 v142, v152, v142, vcc
	v_cmp_nlt_f32_e32 vcc, s91, v135
	s_nop 1
	v_cndmask_b32_e64 v142, v173, -v142, vcc
	v_cmp_ngt_f32_e32 vcc, s92, v135
	s_nop 1
	v_cndmask_b32_e32 v135, 1.0, v142, vcc
.LBB0_540:
	v_add_f32_e32 v142, v128, v12
	s_and_b64 vcc, exec, s[8:9]
	s_mov_b64 s[14:15], -1
	s_cbranch_vccnz .LBB0_544
	s_and_b64 vcc, exec, s[6:7]
	v_mov_b32_e32 v128, v142
	s_cbranch_vccnz .LBB0_543
	v_mul_f32_e32 v128, 0xbfb8aa3b, v142
	v_exp_f32_e32 v128, v128
	s_nop 0
	v_add_f32_e32 v128, 1.0, v128
	v_rcp_f32_e32 v152, v128
	s_nop 0
	v_fma_f32 v163, -v128, v152, 1.0
	v_fma_f32 v143, v163, v152, v152
	v_div_fixup_f32 v128, v143, v128, 1.0

; __device__ __forceinline__ float sigmoidf_(float x) { return 1.0f / (1.0f + __expf(-x)); }
;     __device__ __forceinline__ void operator()(const f32x4 (&acc)[2][2][4][2], const Unit& u, int wr, int wc, int fr, int fq) const {
;     ...
;                         for (int i = 0; i < 4; ++i) { float xv = acc[ai][bj][m][n][i] + bv[bj][n][i]; float r;
;                             if (type < 2) { const float sg = sigmoidf_(xv); r = -expm1f(-0.606531f * sg); }
;                             else if (type == 2) r = sigmoidf_(xv);
.LBB0_545:
	v_mul_f32_e32 v128, 0xbfb8aa3b, v142
	v_exp_f32_e32 v128, v128
	s_nop 0
	v_add_f32_e32 v128, 1.0, v128
	v_rcp_f32_e32 v143, v128
	s_nop 0
	v_fma_f32 v162, -v128, v143, 1.0
	v_fma_f32 v142, v162, v143, v143
	v_div_fixup_f32 v128, v142, v128, 1.0
	v_mul_f32_e32 v128, 0xbf1b459e, v128
	v_mul_f32_e32 v142, 0x3fb8aa3b, v128
	v_rndne_f32_e32 v142, v142
	v_fmamk_f32 v143, v142, 0xbf317218, v128
	v_fmac_f32_e32 v143, 0x3102e308, v142
	v_cvt_i32_f32_e32 v152, v142
	v_fmamk_f32 v162, v143, 0x395133b1, v171
	v_fmaak_f32 v162, v143, v162, 0x3c0887f9
	v_fmaak_f32 v162, v143, v162, 0x3d2aaa81
	v_fmaak_f32 v162, v143, v162, 0x3e2aaaab
	v_ldexp_f32 v152, 1.0, v152
	v_fma_f32 v162, v143, v162, 0.5
	v_cmp_eq_f32_e32 vcc, s90, v142
	v_mul_f32_e32 v162, v143, v162
	v_fmac_f32_e32 v143, v143, v162
	v_cndmask_b32_e32 v142, v152, v172, vcc
	v_add_f32_e32 v152, -1.0, v142
	v_fmac_f32_e32 v152, v142, v143
	v_add_f32_e32 v142, v152, v152
	v_cndmask_b32_e32 v142, v152, v142, vcc
	v_cmp_nlt_f32_e32 vcc, s91, v128
	s_nop 1
	v_cndmask_b32_e64 v142, v173, -v142, vcc
	v_cmp_ngt_f32_e32 vcc, s92, v128
	s_nop 1
	v_cndmask_b32_e32 v128, 1.0, v142, vcc
.LBB0_546:
	v_add_f32_e32 v142, v129, v13
	s_and_b64 vcc, exec, s[8:9]
	s_mov_b64 s[14:15], -1
	s_cbranch_vccnz .LBB0_550
	s_and_b64 vcc, exec, s[6:7]
	v_mov_b32_e32 v129, v142
	s_cbranch_vccnz .LBB0_549
	v_mul_f32_e32 v129, 0xbfb8aa3b, v142
	v_exp_f32_e32 v129, v129
	s_nop 0
	v_add_f32_e32 v129, 1.0, v129
	v_rcp_f32_e32 v152, v129
	s_nop 0
	v_fma_f32 v163, -v129, v152, 1.0
	v_fma_f32 v143, v163, v152, v152
	v_div_fixup_f32 v129, v143, v129, 1.0

; __device__ __forceinline__ float sigmoidf_(float x) { return 1.0f / (1.0f + __expf(-x)); }
;     __device__ __forceinline__ void operator()(const f32x4 (&acc)[2][2][4][2], const Unit& u, int wr, int wc, int fr, int fq) const {
;     ...
;                         for (int i = 0; i < 4; ++i) { float xv = acc[ai][bj][m][n][i] + bv[bj][n][i]; float r;
;                             if (type < 2) { const float sg = sigmoidf_(xv); r = -expm1f(-0.606531f * sg); }
;                             else if (type == 2) r = sigmoidf_(xv);
.LBB0_551:
	v_mul_f32_e32 v129, 0xbfb8aa3b, v142
	v_exp_f32_e32 v129, v129
	s_nop 0
	v_add_f32_e32 v129, 1.0, v129
	v_rcp_f32_e32 v143, v129
	s_nop 0
	v_fma_f32 v162, -v129, v143, 1.0
	v_fma_f32 v142, v162, v143, v143
	v_div_fixup_f32 v129, v142, v129, 1.0
	v_mul_f32_e32 v129, 0xbf1b459e, v129
	v_mul_f32_e32 v142, 0x3fb8aa3b, v129
	v_rndne_f32_e32 v142, v142
	v_fmamk_f32 v143, v142, 0xbf317218, v129
	v_fmac_f32_e32 v143, 0x3102e308, v142
	v_cvt_i32_f32_e32 v152, v142
	v_fmamk_f32 v162, v143, 0x395133b1, v171
	v_fmaak_f32 v162, v143, v162, 0x3c0887f9
	v_fmaak_f32 v162, v143, v162, 0x3d2aaa81
	v_fmaak_f32 v162, v143, v162, 0x3e2aaaab
	v_ldexp_f32 v152, 1.0, v152
	v_fma_f32 v162, v143, v162, 0.5
	v_cmp_eq_f32_e32 vcc, s90, v142
	v_mul_f32_e32 v162, v143, v162
	v_fmac_f32_e32 v143, v143, v162
	v_cndmask_b32_e32 v142, v152, v172, vcc
	v_add_f32_e32 v152, -1.0, v142
	v_fmac_f32_e32 v152, v142, v143
	v_add_f32_e32 v142, v152, v152
	v_cndmask_b32_e32 v142, v152, v142, vcc
	v_cmp_nlt_f32_e32 vcc, s91, v129
	s_nop 1
	v_cndmask_b32_e64 v142, v173, -v142, vcc
	v_cmp_ngt_f32_e32 vcc, s92, v129
	s_nop 1
	v_cndmask_b32_e32 v129, 1.0, v142, vcc
.LBB0_552:
	v_add_f32_e32 v142, v130, v14
	s_and_b64 vcc, exec, s[8:9]
	s_mov_b64 s[14:15], -1
	s_cbranch_vccnz .LBB0_556
	s_and_b64 vcc, exec, s[6:7]
	v_mov_b32_e32 v130, v142
	s_cbranch_vccnz .LBB0_555
	v_mul_f32_e32 v130, 0xbfb8aa3b, v142
	v_exp_f32_e32 v130, v130
	s_nop 0
	v_add_f32_e32 v130, 1.0, v130
	v_rcp_f32_e32 v152, v130
	s_nop 0
	v_fma_f32 v163, -v130, v152, 1.0
	v_fma_f32 v143, v163, v152, v152
	v_div_fixup_f32 v130, v143, v130, 1.0

; __device__ __forceinline__ float sigmoidf_(float x) { return 1.0f / (1.0f + __expf(-x)); }
;     __device__ __forceinline__ void operator()(const f32x4 (&acc)[2][2][4][2], const Unit& u, int wr, int wc, int fr, int fq) const {
;     ...
;                         for (int i = 0; i < 4; ++i) { float xv = acc[ai][bj][m][n][i] + bv[bj][n][i]; float r;
;                             if (type < 2) { const float sg = sigmoidf_(xv); r = -expm1f(-0.606531f * sg); }
;                             else if (type == 2) r = sigmoidf_(xv);
.LBB0_557:
	v_mul_f32_e32 v130, 0xbfb8aa3b, v142
	v_exp_f32_e32 v130, v130
	s_nop 0
	v_add_f32_e32 v130, 1.0, v130
	v_rcp_f32_e32 v143, v130
	s_nop 0
	v_fma_f32 v162, -v130, v143, 1.0
	v_fma_f32 v142, v162, v143, v143
	v_div_fixup_f32 v130, v142, v130, 1.0
	v_mul_f32_e32 v130, 0xbf1b459e, v130
	v_mul_f32_e32 v142, 0x3fb8aa3b, v130
	v_rndne_f32_e32 v142, v142
	v_fmamk_f32 v143, v142, 0xbf317218, v130
	v_fmac_f32_e32 v143, 0x3102e308, v142
	v_cvt_i32_f32_e32 v152, v142
	v_fmamk_f32 v162, v143, 0x395133b1, v171
	v_fmaak_f32 v162, v143, v162, 0x3c0887f9
	v_fmaak_f32 v162, v143, v162, 0x3d2aaa81
	v_fmaak_f32 v162, v143, v162, 0x3e2aaaab
	v_ldexp_f32 v152, 1.0, v152
	v_fma_f32 v162, v143, v162, 0.5
	v_cmp_eq_f32_e32 vcc, s90, v142
	v_mul_f32_e32 v162, v143, v162
	v_fmac_f32_e32 v143, v143, v162
	v_cndmask_b32_e32 v142, v152, v172, vcc
	v_add_f32_e32 v152, -1.0, v142
	v_fmac_f32_e32 v152, v142, v143
	v_add_f32_e32 v142, v152, v152
	v_cndmask_b32_e32 v142, v152, v142, vcc
	v_cmp_nlt_f32_e32 vcc, s91, v130
	s_nop 1
	v_cndmask_b32_e64 v142, v173, -v142, vcc
	v_cmp_ngt_f32_e32 vcc, s92, v130
	s_nop 1
	v_cndmask_b32_e32 v130, 1.0, v142, vcc
.LBB0_558:
	v_add_f32_e32 v131, v131, v15
	s_and_b64 vcc, exec, s[8:9]
	s_mov_b64 s[14:15], -1
	s_cbranch_vccnz .LBB0_562
	s_and_b64 vcc, exec, s[6:7]
	v_mov_b32_e32 v142, v131
	s_cbranch_vccnz .LBB0_561
	v_mul_f32_e32 v142, 0xbfb8aa3b, v131
	v_exp_f32_e32 v142, v142
	s_nop 0
	v_add_f32_e32 v142, 1.0, v142
	v_rcp_f32_e32 v152, v142
	s_nop 0
	v_fma_f32 v163, -v142, v152, 1.0
	v_fma_f32 v143, v163, v152, v152
	v_div_fixup_f32 v142, v143, v142, 1.0

; __device__ __forceinline__ float sigmoidf_(float x) { return 1.0f / (1.0f + __expf(-x)); }
;     __device__ __forceinline__ void operator()(const f32x4 (&acc)[2][2][4][2], const Unit& u, int wr, int wc, int fr, int fq) const {
;     ...
;             for (int m = 0; m < 4; ++m) { f16* rowp = O + (size_t)(row0 + ai * 128 + m * 16) * 4096 + col0;
; #pragma unroll
;                 for (int bj = 0; bj < 2; ++bj) { f16x8 v;
; #pragma unroll
;                     for (int n = 0; n < 2; ++n)
; #pragma unroll
;                         for (int i = 0; i < 4; ++i) { float xv = acc[ai][bj][m][n][i] + bv[bj][n][i]; float r;
;                             if (type < 2) { const float sg = sigmoidf_(xv); r = -expm1f(-0.606531f * sg); }
;                             else if (type == 2) r = sigmoidf_(xv);
;                             else r = xv;
;                             v[4 * n + i] = (f16)r; }
;                     *(f16x8*)(rowp + bj * 128) = v; } }
.LBB0_563:
	v_mul_f32_e32 v131, 0xbfb8aa3b, v131
	v_exp_f32_e32 v131, v131
	s_nop 0
	v_add_f32_e32 v131, 1.0, v131
	v_rcp_f32_e32 v143, v131
	s_nop 0
	v_fma_f32 v162, -v131, v143, 1.0
	v_fma_f32 v142, v162, v143, v143
	v_div_fixup_f32 v131, v142, v131, 1.0
	v_mul_f32_e32 v131, 0xbf1b459e, v131
	v_mul_f32_e32 v142, 0x3fb8aa3b, v131
	v_rndne_f32_e32 v142, v142
	v_fmamk_f32 v143, v142, 0xbf317218, v131
	v_fmac_f32_e32 v143, 0x3102e308, v142
	v_cvt_i32_f32_e32 v152, v142
	v_fmamk_f32 v162, v143, 0x395133b1, v171
	v_fmaak_f32 v162, v143, v162, 0x3c0887f9
	v_fmaak_f32 v162, v143, v162, 0x3d2aaa81
	v_fmaak_f32 v162, v143, v162, 0x3e2aaaab
	v_ldexp_f32 v152, 1.0, v152
	v_fma_f32 v162, v143, v162, 0.5
	v_cmp_eq_f32_e32 vcc, s90, v142
	v_mul_f32_e32 v162, v143, v162
	v_fmac_f32_e32 v143, v143, v162
	v_cndmask_b32_e32 v142, v152, v172, vcc
	v_add_f32_e32 v152, -1.0, v142
	v_fmac_f32_e32 v152, v142, v143
	v_add_f32_e32 v142, v152, v152
	v_cndmask_b32_e32 v142, v152, v142, vcc
	v_cmp_nlt_f32_e32 vcc, s91, v131
	s_nop 1
	v_cndmask_b32_e64 v142, v173, -v142, vcc
	v_cmp_ngt_f32_e32 vcc, s92, v131
	s_nop 1
	v_cndmask_b32_e32 v142, 1.0, v142, vcc
.LBB0_564:
	v_cvt_pk_f16_f32 v131, v130, v142
	v_cvt_pk_f16_f32 v130, v128, v129
	v_cvt_pk_f16_f32 v129, v134, v135
	v_cvt_pk_f16_f32 v128, v132, v133
	global_store_dwordx4 v[140:141], v[128:131], off offset:256
	s_and_b64 vcc, exec, s[8:9]
	s_mov_b64 s[14:15], -1
	v_add_f32_e32 v128, v124, v32
	s_cbranch_vccnz .LBB0_568
	s_and_b64 vcc, exec, s[6:7]
	v_mov_b32_e32 v124, v128
	s_cbranch_vccnz .LBB0_567
	v_mul_f32_e32 v124, 0xbfb8aa3b, v128
	v_exp_f32_e32 v124, v124
	s_nop 0
	v_add_f32_e32 v124, 1.0, v124
	v_rcp_f32_e32 v130, v124
	s_nop 0
	v_fma_f32 v132, -v124, v130, 1.0
	v_fma_f32 v129, v132, v130, v130
	v_div_fixup_f32 v124, v129, v124, 1.0

; __device__ __forceinline__ float sigmoidf_(float x) { return 1.0f / (1.0f + __expf(-x)); }
;     __device__ __forceinline__ void operator()(const f32x4 (&acc)[2][2][4][2], const Unit& u, int wr, int wc, int fr, int fq) const {
;     ...
;                         for (int i = 0; i < 4; ++i) { float xv = acc[ai][bj][m][n][i] + bv[bj][n][i]; float r;
;                             if (type < 2) { const float sg = sigmoidf_(xv); r = -expm1f(-0.606531f * sg); }
;                             else if (type == 2) r = sigmoidf_(xv);
.LBB0_569:
	v_mul_f32_e32 v124, 0xbfb8aa3b, v128
	v_exp_f32_e32 v124, v124
	s_nop 0
	v_add_f32_e32 v124, 1.0, v124
	v_rcp_f32_e32 v129, v124
	s_nop 0
	v_fma_f32 v131, -v124, v129, 1.0
	v_fma_f32 v128, v131, v129, v129
	v_div_fixup_f32 v124, v128, v124, 1.0
	v_mul_f32_e32 v124, 0xbf1b459e, v124
	v_mul_f32_e32 v128, 0x3fb8aa3b, v124
	v_rndne_f32_e32 v128, v128
	v_fmamk_f32 v129, v128, 0xbf317218, v124
	v_fmac_f32_e32 v129, 0x3102e308, v128
	v_cvt_i32_f32_e32 v130, v128
	v_fmamk_f32 v131, v129, 0x395133b1, v171
	v_fmaak_f32 v131, v129, v131, 0x3c0887f9
	v_fmaak_f32 v131, v129, v131, 0x3d2aaa81
	v_fmaak_f32 v131, v129, v131, 0x3e2aaaab
	v_ldexp_f32 v130, 1.0, v130
	v_fma_f32 v131, v129, v131, 0.5
	v_cmp_eq_f32_e32 vcc, s90, v128
	v_mul_f32_e32 v131, v129, v131
	v_fmac_f32_e32 v129, v129, v131
	v_cndmask_b32_e32 v128, v130, v172, vcc
	v_add_f32_e32 v130, -1.0, v128
	v_fmac_f32_e32 v130, v128, v129
	v_add_f32_e32 v128, v130, v130
	v_cndmask_b32_e32 v128, v130, v128, vcc
	v_cmp_nlt_f32_e32 vcc, s91, v124
	s_nop 1
	v_cndmask_b32_e64 v128, v173, -v128, vcc
	v_cmp_ngt_f32_e32 vcc, s92, v124
	s_nop 1
	v_cndmask_b32_e32 v124, 1.0, v128, vcc
.LBB0_570:
	v_add_f32_e32 v128, v125, v33
	s_and_b64 vcc, exec, s[8:9]
	s_mov_b64 s[14:15], -1
	s_cbranch_vccnz .LBB0_574
	s_and_b64 vcc, exec, s[6:7]
	v_mov_b32_e32 v125, v128
	s_cbranch_vccnz .LBB0_573
	v_mul_f32_e32 v125, 0xbfb8aa3b, v128
	v_exp_f32_e32 v125, v125
	s_nop 0
	v_add_f32_e32 v125, 1.0, v125
	v_rcp_f32_e32 v130, v125
	s_nop 0
	v_fma_f32 v132, -v125, v130, 1.0
	v_fma_f32 v129, v132, v130, v130
	v_div_fixup_f32 v125, v129, v125, 1.0

; __device__ __forceinline__ float sigmoidf_(float x) { return 1.0f / (1.0f + __expf(-x)); }
;     __device__ __forceinline__ void operator()(const f32x4 (&acc)[2][2][4][2], const Unit& u, int wr, int wc, int fr, int fq) const {
;     ...
;                         for (int i = 0; i < 4; ++i) { float xv = acc[ai][bj][m][n][i] + bv[bj][n][i]; float r;
;                             if (type < 2) { const float sg = sigmoidf_(xv); r = -expm1f(-0.606531f * sg); }
;                             else if (type == 2) r = sigmoidf_(xv);
.LBB0_575:
	v_mul_f32_e32 v125, 0xbfb8aa3b, v128
	v_exp_f32_e32 v125, v125
	s_nop 0
	v_add_f32_e32 v125, 1.0, v125
	v_rcp_f32_e32 v129, v125
	s_nop 0
	v_fma_f32 v131, -v125, v129, 1.0
	v_fma_f32 v128, v131, v129, v129
	v_div_fixup_f32 v125, v128, v125, 1.0
	v_mul_f32_e32 v125, 0xbf1b459e, v125
	v_mul_f32_e32 v128, 0x3fb8aa3b, v125
	v_rndne_f32_e32 v128, v128
	v_fmamk_f32 v129, v128, 0xbf317218, v125
	v_fmac_f32_e32 v129, 0x3102e308, v128
	v_cvt_i32_f32_e32 v130, v128
	v_fmamk_f32 v131, v129, 0x395133b1, v171
	v_fmaak_f32 v131, v129, v131, 0x3c0887f9
	v_fmaak_f32 v131, v129, v131, 0x3d2aaa81
	v_fmaak_f32 v131, v129, v131, 0x3e2aaaab
	v_ldexp_f32 v130, 1.0, v130
	v_fma_f32 v131, v129, v131, 0.5
	v_cmp_eq_f32_e32 vcc, s90, v128
	v_mul_f32_e32 v131, v129, v131
	v_fmac_f32_e32 v129, v129, v131
	v_cndmask_b32_e32 v128, v130, v172, vcc
	v_add_f32_e32 v130, -1.0, v128
	v_fmac_f32_e32 v130, v128, v129
	v_add_f32_e32 v128, v130, v130
	v_cndmask_b32_e32 v128, v130, v128, vcc
	v_cmp_nlt_f32_e32 vcc, s91, v125
	s_nop 1
	v_cndmask_b32_e64 v128, v173, -v128, vcc
	v_cmp_ngt_f32_e32 vcc, s92, v125
	s_nop 1
	v_cndmask_b32_e32 v125, 1.0, v128, vcc
.LBB0_576:
	v_add_f32_e32 v128, v126, v34
	s_and_b64 vcc, exec, s[8:9]
	s_mov_b64 s[14:15], -1
	s_cbranch_vccnz .LBB0_580
	s_and_b64 vcc, exec, s[6:7]
	v_mov_b32_e32 v126, v128
	s_cbranch_vccnz .LBB0_579
	v_mul_f32_e32 v126, 0xbfb8aa3b, v128
	v_exp_f32_e32 v126, v126
	s_nop 0
	v_add_f32_e32 v126, 1.0, v126
	v_rcp_f32_e32 v130, v126
	s_nop 0
	v_fma_f32 v132, -v126, v130, 1.0
	v_fma_f32 v129, v132, v130, v130
	v_div_fixup_f32 v126, v129, v126, 1.0

; __device__ __forceinline__ float sigmoidf_(float x) { return 1.0f / (1.0f + __expf(-x)); }
;     __device__ __forceinline__ void operator()(const f32x4 (&acc)[2][2][4][2], const Unit& u, int wr, int wc, int fr, int fq) const {
;     ...
;                         for (int i = 0; i < 4; ++i) { float xv = acc[ai][bj][m][n][i] + bv[bj][n][i]; float r;
;                             if (type < 2) { const float sg = sigmoidf_(xv); r = -expm1f(-0.606531f * sg); }
;                             else if (type == 2) r = sigmoidf_(xv);
.LBB0_581:
	v_mul_f32_e32 v126, 0xbfb8aa3b, v128
	v_exp_f32_e32 v126, v126
	s_nop 0
	v_add_f32_e32 v126, 1.0, v126
	v_rcp_f32_e32 v129, v126
	s_nop 0
	v_fma_f32 v131, -v126, v129, 1.0
	v_fma_f32 v128, v131, v129, v129
	v_div_fixup_f32 v126, v128, v126, 1.0
	v_mul_f32_e32 v126, 0xbf1b459e, v126
	v_mul_f32_e32 v128, 0x3fb8aa3b, v126
	v_rndne_f32_e32 v128, v128
	v_fmamk_f32 v129, v128, 0xbf317218, v126
	v_fmac_f32_e32 v129, 0x3102e308, v128
	v_cvt_i32_f32_e32 v130, v128
	v_fmamk_f32 v131, v129, 0x395133b1, v171
	v_fmaak_f32 v131, v129, v131, 0x3c0887f9
	v_fmaak_f32 v131, v129, v131, 0x3d2aaa81
	v_fmaak_f32 v131, v129, v131, 0x3e2aaaab
	v_ldexp_f32 v130, 1.0, v130
	v_fma_f32 v131, v129, v131, 0.5
	v_cmp_eq_f32_e32 vcc, s90, v128
	v_mul_f32_e32 v131, v129, v131
	v_fmac_f32_e32 v129, v129, v131
	v_cndmask_b32_e32 v128, v130, v172, vcc
	v_add_f32_e32 v130, -1.0, v128
	v_fmac_f32_e32 v130, v128, v129
	v_add_f32_e32 v128, v130, v130
	v_cndmask_b32_e32 v128, v130, v128, vcc
	v_cmp_nlt_f32_e32 vcc, s91, v126
	s_nop 1
	v_cndmask_b32_e64 v128, v173, -v128, vcc
	v_cmp_ngt_f32_e32 vcc, s92, v126
	s_nop 1
	v_cndmask_b32_e32 v126, 1.0, v128, vcc
.LBB0_582:
	v_add_f32_e32 v128, v127, v35
	s_and_b64 vcc, exec, s[8:9]
	s_mov_b64 s[14:15], -1
	s_cbranch_vccnz .LBB0_586
	s_and_b64 vcc, exec, s[6:7]
	v_mov_b32_e32 v127, v128
	s_cbranch_vccnz .LBB0_585
	v_mul_f32_e32 v127, 0xbfb8aa3b, v128
	v_exp_f32_e32 v127, v127
	s_nop 0
	v_add_f32_e32 v127, 1.0, v127
	v_rcp_f32_e32 v130, v127
	s_nop 0
	v_fma_f32 v132, -v127, v130, 1.0
	v_fma_f32 v129, v132, v130, v130
	v_div_fixup_f32 v127, v129, v127, 1.0

; __device__ __forceinline__ float sigmoidf_(float x) { return 1.0f / (1.0f + __expf(-x)); }
;     __device__ __forceinline__ void operator()(const f32x4 (&acc)[2][2][4][2], const Unit& u, int wr, int wc, int fr, int fq) const {
;     ...
;                         for (int i = 0; i < 4; ++i) { float xv = acc[ai][bj][m][n][i] + bv[bj][n][i]; float r;
;                             if (type < 2) { const float sg = sigmoidf_(xv); r = -expm1f(-0.606531f * sg); }
;                             else if (type == 2) r = sigmoidf_(xv);
.LBB0_587:
	v_mul_f32_e32 v127, 0xbfb8aa3b, v128
	v_exp_f32_e32 v127, v127
	s_nop 0
	v_add_f32_e32 v127, 1.0, v127
	v_rcp_f32_e32 v129, v127
	s_nop 0
	v_fma_f32 v131, -v127, v129, 1.0
	v_fma_f32 v128, v131, v129, v129
	v_div_fixup_f32 v127, v128, v127, 1.0
	v_mul_f32_e32 v127, 0xbf1b459e, v127
	v_mul_f32_e32 v128, 0x3fb8aa3b, v127
	v_rndne_f32_e32 v128, v128
	v_fmamk_f32 v129, v128, 0xbf317218, v127
	v_fmac_f32_e32 v129, 0x3102e308, v128
	v_cvt_i32_f32_e32 v130, v128
	v_fmamk_f32 v131, v129, 0x395133b1, v171
	v_fmaak_f32 v131, v129, v131, 0x3c0887f9
	v_fmaak_f32 v131, v129, v131, 0x3d2aaa81
	v_fmaak_f32 v131, v129, v131, 0x3e2aaaab
	v_ldexp_f32 v130, 1.0, v130
	v_fma_f32 v131, v129, v131, 0.5
	v_cmp_eq_f32_e32 vcc, s90, v128
	v_mul_f32_e32 v131, v129, v131
	v_fmac_f32_e32 v129, v129, v131
	v_cndmask_b32_e32 v128, v130, v172, vcc
	v_add_f32_e32 v130, -1.0, v128
	v_fmac_f32_e32 v130, v128, v129
	v_add_f32_e32 v128, v130, v130
	v_cndmask_b32_e32 v128, v130, v128, vcc
	v_cmp_nlt_f32_e32 vcc, s91, v127
	s_nop 1
	v_cndmask_b32_e64 v128, v173, -v128, vcc
	v_cmp_ngt_f32_e32 vcc, s92, v127
	s_nop 1
	v_cndmask_b32_e32 v127, 1.0, v128, vcc
.LBB0_588:
	v_add_f32_e32 v120, v120, v28
	s_and_b64 vcc, exec, s[8:9]
	s_mov_b64 s[14:15], -1
	s_cbranch_vccnz .LBB0_592
	s_and_b64 vcc, exec, s[6:7]
	v_mov_b32_e32 v128, v120
	s_cbranch_vccnz .LBB0_591
	v_mul_f32_e32 v128, 0xbfb8aa3b, v120
	v_exp_f32_e32 v128, v128
	s_nop 0
	v_add_f32_e32 v128, 1.0, v128
	v_rcp_f32_e32 v130, v128
	s_nop 0
	v_fma_f32 v132, -v128, v130, 1.0
	v_fma_f32 v129, v132, v130, v130
	v_div_fixup_f32 v128, v129, v128, 1.0

; __device__ __forceinline__ float sigmoidf_(float x) { return 1.0f / (1.0f + __expf(-x)); }
;     __device__ __forceinline__ void operator()(const f32x4 (&acc)[2][2][4][2], const Unit& u, int wr, int wc, int fr, int fq) const {
;     ...
;                         for (int i = 0; i < 4; ++i) { float xv = acc[ai][bj][m][n][i] + bv[bj][n][i]; float r;
;                             if (type < 2) { const float sg = sigmoidf_(xv); r = -expm1f(-0.606531f * sg); }
;                             else if (type == 2) r = sigmoidf_(xv);
.LBB0_593:
	v_mul_f32_e32 v120, 0xbfb8aa3b, v120
	v_exp_f32_e32 v120, v120
	s_nop 0
	v_add_f32_e32 v120, 1.0, v120
	v_rcp_f32_e32 v129, v120
	s_nop 0
	v_fma_f32 v131, -v120, v129, 1.0
	v_fma_f32 v128, v131, v129, v129
	v_div_fixup_f32 v120, v128, v120, 1.0
	v_mul_f32_e32 v120, 0xbf1b459e, v120
	v_mul_f32_e32 v128, 0x3fb8aa3b, v120
	v_rndne_f32_e32 v128, v128
	v_fmamk_f32 v129, v128, 0xbf317218, v120
	v_fmac_f32_e32 v129, 0x3102e308, v128
	v_cvt_i32_f32_e32 v130, v128
	v_fmamk_f32 v131, v129, 0x395133b1, v171
	v_fmaak_f32 v131, v129, v131, 0x3c0887f9
	v_fmaak_f32 v131, v129, v131, 0x3d2aaa81
	v_fmaak_f32 v131, v129, v131, 0x3e2aaaab
	v_ldexp_f32 v130, 1.0, v130
	v_fma_f32 v131, v129, v131, 0.5
	v_cmp_eq_f32_e32 vcc, s90, v128
	v_mul_f32_e32 v131, v129, v131
	v_fmac_f32_e32 v129, v129, v131
	v_cndmask_b32_e32 v128, v130, v172, vcc
	v_add_f32_e32 v130, -1.0, v128
	v_fmac_f32_e32 v130, v128, v129
	v_add_f32_e32 v128, v130, v130
	v_cndmask_b32_e32 v128, v130, v128, vcc
	v_cmp_nlt_f32_e32 vcc, s91, v120
	s_nop 1
	v_cndmask_b32_e64 v128, v173, -v128, vcc
	v_cmp_ngt_f32_e32 vcc, s92, v120
	s_nop 1
	v_cndmask_b32_e32 v128, 1.0, v128, vcc
.LBB0_594:
	v_add_f32_e32 v120, v121, v29
	s_and_b64 vcc, exec, s[8:9]
	s_mov_b64 s[14:15], -1
	s_cbranch_vccnz .LBB0_598
	s_and_b64 vcc, exec, s[6:7]
	v_mov_b32_e32 v129, v120
	s_cbranch_vccnz .LBB0_597
	v_mul_f32_e32 v121, 0xbfb8aa3b, v120
	v_exp_f32_e32 v121, v121
	s_nop 0
	v_add_f32_e32 v121, 1.0, v121
	v_rcp_f32_e32 v130, v121
	s_nop 0
	v_fma_f32 v132, -v121, v130, 1.0
	v_fma_f32 v129, v132, v130, v130
	v_div_fixup_f32 v129, v129, v121, 1.0

; __device__ __forceinline__ float sigmoidf_(float x) { return 1.0f / (1.0f + __expf(-x)); }
;     __device__ __forceinline__ void operator()(const f32x4 (&acc)[2][2][4][2], const Unit& u, int wr, int wc, int fr, int fq) const {
;     ...
;                         for (int i = 0; i < 4; ++i) { float xv = acc[ai][bj][m][n][i] + bv[bj][n][i]; float r;
;                             if (type < 2) { const float sg = sigmoidf_(xv); r = -expm1f(-0.606531f * sg); }
;                             else if (type == 2) r = sigmoidf_(xv);
.LBB0_599:
	v_mul_f32_e32 v120, 0xbfb8aa3b, v120
	v_exp_f32_e32 v120, v120
	s_nop 0
	v_add_f32_e32 v120, 1.0, v120
	v_rcp_f32_e32 v129, v120
	s_nop 0
	v_fma_f32 v131, -v120, v129, 1.0
	v_fma_f32 v121, v131, v129, v129
	v_div_fixup_f32 v120, v121, v120, 1.0
	v_mul_f32_e32 v120, 0xbf1b459e, v120
	v_mul_f32_e32 v121, 0x3fb8aa3b, v120
	v_rndne_f32_e32 v121, v121
	v_fmamk_f32 v129, v121, 0xbf317218, v120
	v_fmac_f32_e32 v129, 0x3102e308, v121
	v_cvt_i32_f32_e32 v130, v121
	v_fmamk_f32 v131, v129, 0x395133b1, v171
	v_fmaak_f32 v131, v129, v131, 0x3c0887f9
	v_fmaak_f32 v131, v129, v131, 0x3d2aaa81
	v_fmaak_f32 v131, v129, v131, 0x3e2aaaab
	v_ldexp_f32 v130, 1.0, v130
	v_fma_f32 v131, v129, v131, 0.5
	v_cmp_eq_f32_e32 vcc, s90, v121
	v_mul_f32_e32 v131, v129, v131
	v_fmac_f32_e32 v129, v129, v131
	v_cndmask_b32_e32 v121, v130, v172, vcc
	v_add_f32_e32 v130, -1.0, v121
	v_fmac_f32_e32 v130, v121, v129
	v_add_f32_e32 v121, v130, v130
	v_cndmask_b32_e32 v121, v130, v121, vcc
	v_cmp_nlt_f32_e32 vcc, s91, v120
	s_nop 1
	v_cndmask_b32_e64 v121, v173, -v121, vcc
	v_cmp_ngt_f32_e32 vcc, s92, v120
	s_nop 1
	v_cndmask_b32_e32 v129, 1.0, v121, vcc
.LBB0_600:
	v_add_f32_e32 v120, v122, v30
	s_and_b64 vcc, exec, s[8:9]
	s_mov_b64 s[14:15], -1
	s_cbranch_vccnz .LBB0_604
	s_and_b64 vcc, exec, s[6:7]
	v_mov_b32_e32 v122, v120
	s_cbranch_vccnz .LBB0_603
	v_mul_f32_e32 v121, 0xbfb8aa3b, v120
	v_exp_f32_e32 v121, v121
	s_nop 0
	v_add_f32_e32 v121, 1.0, v121
	v_rcp_f32_e32 v130, v121
	s_nop 0
	v_fma_f32 v132, -v121, v130, 1.0
	v_fma_f32 v122, v132, v130, v130
	v_div_fixup_f32 v122, v122, v121, 1.0

; __device__ __forceinline__ float sigmoidf_(float x) { return 1.0f / (1.0f + __expf(-x)); }
;     __device__ __forceinline__ void operator()(const f32x4 (&acc)[2][2][4][2], const Unit& u, int wr, int wc, int fr, int fq) const {
;     ...
;                         for (int i = 0; i < 4; ++i) { float xv = acc[ai][bj][m][n][i] + bv[bj][n][i]; float r;
;                             if (type < 2) { const float sg = sigmoidf_(xv); r = -expm1f(-0.606531f * sg); }
;                             else if (type == 2) r = sigmoidf_(xv);
.LBB0_605:
	v_mul_f32_e32 v120, 0xbfb8aa3b, v120
	v_exp_f32_e32 v120, v120
	s_nop 0
	v_add_f32_e32 v120, 1.0, v120
	v_rcp_f32_e32 v122, v120
	s_nop 0
	v_fma_f32 v131, -v120, v122, 1.0
	v_fma_f32 v121, v131, v122, v122
	v_div_fixup_f32 v120, v121, v120, 1.0
	v_mul_f32_e32 v120, 0xbf1b459e, v120
	v_mul_f32_e32 v121, 0x3fb8aa3b, v120
	v_rndne_f32_e32 v121, v121
	v_fmamk_f32 v122, v121, 0xbf317218, v120
	v_fmac_f32_e32 v122, 0x3102e308, v121
	v_cvt_i32_f32_e32 v130, v121
	v_fmamk_f32 v131, v122, 0x395133b1, v171
	v_fmaak_f32 v131, v122, v131, 0x3c0887f9
	v_fmaak_f32 v131, v122, v131, 0x3d2aaa81
	v_fmaak_f32 v131, v122, v131, 0x3e2aaaab
	v_ldexp_f32 v130, 1.0, v130
	v_fma_f32 v131, v122, v131, 0.5
	v_cmp_eq_f32_e32 vcc, s90, v121
	v_mul_f32_e32 v131, v122, v131
	v_fmac_f32_e32 v122, v122, v131
	v_cndmask_b32_e32 v121, v130, v172, vcc
	v_add_f32_e32 v130, -1.0, v121
	v_fmac_f32_e32 v130, v121, v122
	v_add_f32_e32 v121, v130, v130
	v_cndmask_b32_e32 v121, v130, v121, vcc
	v_cmp_nlt_f32_e32 vcc, s91, v120
	s_nop 1
	v_cndmask_b32_e64 v121, v173, -v121, vcc
	v_cmp_ngt_f32_e32 vcc, s92, v120
	s_nop 1
	v_cndmask_b32_e32 v122, 1.0, v121, vcc
.LBB0_606:
	v_add_f32_e32 v120, v123, v31
	s_and_b64 vcc, exec, s[8:9]
	s_mov_b64 s[14:15], -1
	s_cbranch_vccnz .LBB0_610
	s_and_b64 vcc, exec, s[6:7]
	v_mov_b32_e32 v123, v120
	s_cbranch_vccnz .LBB0_609
	v_mul_f32_e32 v121, 0xbfb8aa3b, v120
	v_exp_f32_e32 v121, v121
	s_nop 0
	v_add_f32_e32 v121, 1.0, v121
	v_rcp_f32_e32 v130, v121
	s_nop 0
	v_fma_f32 v132, -v121, v130, 1.0
	v_fma_f32 v123, v132, v130, v130
	v_div_fixup_f32 v123, v123, v121, 1.0

; __device__ __forceinline__ float sigmoidf_(float x) { return 1.0f / (1.0f + __expf(-x)); }
;     __device__ __forceinline__ void operator()(const f32x4 (&acc)[2][2][4][2], const Unit& u, int wr, int wc, int fr, int fq) const {
;     ...
;             for (int m = 0; m < 4; ++m) { f16* rowp = O + (size_t)(row0 + ai * 128 + m * 16) * 4096 + col0;
; #pragma unroll
;                 for (int bj = 0; bj < 2; ++bj) { f16x8 v;
; #pragma unroll
;                     for (int n = 0; n < 2; ++n)
; #pragma unroll
;                         for (int i = 0; i < 4; ++i) { float xv = acc[ai][bj][m][n][i] + bv[bj][n][i]; float r;
;                             if (type < 2) { const float sg = sigmoidf_(xv); r = -expm1f(-0.606531f * sg); }
;                             else if (type == 2) r = sigmoidf_(xv);
;                             else r = xv;
;                             v[4 * n + i] = (f16)r; }
;                     *(f16x8*)(rowp + bj * 128) = v; } }
.LBB0_611:
	v_mul_f32_e32 v120, 0xbfb8aa3b, v120
	v_exp_f32_e32 v120, v120
	s_nop 0
	v_add_f32_e32 v120, 1.0, v120
	v_rcp_f32_e32 v123, v120
	s_nop 0
	v_fma_f32 v131, -v120, v123, 1.0
	v_fma_f32 v121, v131, v123, v123
	v_div_fixup_f32 v120, v121, v120, 1.0
	v_mul_f32_e32 v120, 0xbf1b459e, v120
	v_mul_f32_e32 v121, 0x3fb8aa3b, v120
	v_rndne_f32_e32 v121, v121
	v_fmamk_f32 v123, v121, 0xbf317218, v120
	v_fmac_f32_e32 v123, 0x3102e308, v121
	v_cvt_i32_f32_e32 v130, v121
	v_fmamk_f32 v131, v123, 0x395133b1, v171
	v_fmaak_f32 v131, v123, v131, 0x3c0887f9
	v_fmaak_f32 v131, v123, v131, 0x3d2aaa81
	v_fmaak_f32 v131, v123, v131, 0x3e2aaaab
	v_ldexp_f32 v130, 1.0, v130
	v_fma_f32 v131, v123, v131, 0.5
	v_cmp_eq_f32_e32 vcc, s90, v121
	v_mul_f32_e32 v131, v123, v131
	v_fmac_f32_e32 v123, v123, v131
	v_cndmask_b32_e32 v121, v130, v172, vcc
	v_add_f32_e32 v130, -1.0, v121
	v_fmac_f32_e32 v130, v121, v123
	v_add_f32_e32 v121, v130, v130
	v_cndmask_b32_e32 v121, v130, v121, vcc
	v_cmp_nlt_f32_e32 vcc, s91, v120
	s_nop 1
	v_cndmask_b32_e64 v121, v173, -v121, vcc
	v_cmp_ngt_f32_e32 vcc, s92, v120
	s_nop 1
	v_cndmask_b32_e32 v123, 1.0, v121, vcc
.LBB0_612:
	v_or_b32_e32 v120, 16, v138
	v_ashrrev_i32_e32 v121, 31, v120
	v_lshlrev_b64 v[120:121], 13, v[120:121]
	v_lshl_add_u64 v[120:121], s[28:29], 0, v[120:121]
	v_lshl_add_u64 v[120:121], v[136:137], 1, v[120:121]
	v_cvt_pk_f16_f32 v131, v122, v123
	v_cvt_pk_f16_f32 v130, v128, v129
	v_cvt_pk_f16_f32 v129, v126, v127
	v_cvt_pk_f16_f32 v128, v124, v125
	v_add_f32_e32 v122, v116, v20
	s_and_b64 vcc, exec, s[8:9]
	s_mov_b64 s[14:15], -1
	global_store_dwordx4 v[120:121], v[128:131], off
	s_cbranch_vccnz .LBB0_616
	s_and_b64 vcc, exec, s[6:7]
	v_mov_b32_e32 v116, v122
	s_cbranch_vccnz .LBB0_615
	v_mul_f32_e32 v116, 0xbfb8aa3b, v122
	v_exp_f32_e32 v116, v116
	s_nop 0
	v_add_f32_e32 v116, 1.0, v116
	v_rcp_f32_e32 v124, v116
	s_nop 0
	v_fma_f32 v126, -v116, v124, 1.0
	v_fma_f32 v123, v126, v124, v124
	v_div_fixup_f32 v116, v123, v116, 1.0

; __device__ __forceinline__ float sigmoidf_(float x) { return 1.0f / (1.0f + __expf(-x)); }
;     __device__ __forceinline__ void operator()(const f32x4 (&acc)[2][2][4][2], const Unit& u, int wr, int wc, int fr, int fq) const {
;     ...
;                         for (int i = 0; i < 4; ++i) { float xv = acc[ai][bj][m][n][i] + bv[bj][n][i]; float r;
;                             if (type < 2) { const float sg = sigmoidf_(xv); r = -expm1f(-0.606531f * sg); }
;                             else if (type == 2) r = sigmoidf_(xv);
.LBB0_617:
	v_mul_f32_e32 v116, 0xbfb8aa3b, v122
	v_exp_f32_e32 v116, v116
	s_nop 0
	v_add_f32_e32 v116, 1.0, v116
	v_rcp_f32_e32 v123, v116
	s_nop 0
	v_fma_f32 v125, -v116, v123, 1.0
	v_fma_f32 v122, v125, v123, v123
	v_div_fixup_f32 v116, v122, v116, 1.0
	v_mul_f32_e32 v116, 0xbf1b459e, v116
	v_mul_f32_e32 v122, 0x3fb8aa3b, v116
	v_rndne_f32_e32 v122, v122
	v_fmamk_f32 v123, v122, 0xbf317218, v116
	v_fmac_f32_e32 v123, 0x3102e308, v122
	v_cvt_i32_f32_e32 v124, v122
	v_fmamk_f32 v125, v123, 0x395133b1, v171
	v_fmaak_f32 v125, v123, v125, 0x3c0887f9
	v_fmaak_f32 v125, v123, v125, 0x3d2aaa81
	v_fmaak_f32 v125, v123, v125, 0x3e2aaaab
	v_ldexp_f32 v124, 1.0, v124
	v_fma_f32 v125, v123, v125, 0.5
	v_cmp_eq_f32_e32 vcc, s90, v122
	v_mul_f32_e32 v125, v123, v125
	v_fmac_f32_e32 v123, v123, v125
	v_cndmask_b32_e32 v122, v124, v172, vcc
	v_add_f32_e32 v124, -1.0, v122
	v_fmac_f32_e32 v124, v122, v123
	v_add_f32_e32 v122, v124, v124
	v_cndmask_b32_e32 v122, v124, v122, vcc
	v_cmp_nlt_f32_e32 vcc, s91, v116
	s_nop 1
	v_cndmask_b32_e64 v122, v173, -v122, vcc
	v_cmp_ngt_f32_e32 vcc, s92, v116
	s_nop 1
	v_cndmask_b32_e32 v116, 1.0, v122, vcc
.LBB0_618:
	v_add_f32_e32 v122, v117, v21
	s_and_b64 vcc, exec, s[8:9]
	s_mov_b64 s[14:15], -1
	s_cbranch_vccnz .LBB0_622
	s_and_b64 vcc, exec, s[6:7]
	v_mov_b32_e32 v117, v122
	s_cbranch_vccnz .LBB0_621
	v_mul_f32_e32 v117, 0xbfb8aa3b, v122
	v_exp_f32_e32 v117, v117
	s_nop 0
	v_add_f32_e32 v117, 1.0, v117
	v_rcp_f32_e32 v124, v117
	s_nop 0
	v_fma_f32 v126, -v117, v124, 1.0
	v_fma_f32 v123, v126, v124, v124
	v_div_fixup_f32 v117, v123, v117, 1.0

; __device__ __forceinline__ float sigmoidf_(float x) { return 1.0f / (1.0f + __expf(-x)); }
;     __device__ __forceinline__ void operator()(const f32x4 (&acc)[2][2][4][2], const Unit& u, int wr, int wc, int fr, int fq) const {
;     ...
;                         for (int i = 0; i < 4; ++i) { float xv = acc[ai][bj][m][n][i] + bv[bj][n][i]; float r;
;                             if (type < 2) { const float sg = sigmoidf_(xv); r = -expm1f(-0.606531f * sg); }
;                             else if (type == 2) r = sigmoidf_(xv);
.LBB0_623:
	v_mul_f32_e32 v117, 0xbfb8aa3b, v122
	v_exp_f32_e32 v117, v117
	s_nop 0
	v_add_f32_e32 v117, 1.0, v117
	v_rcp_f32_e32 v123, v117
	s_nop 0
	v_fma_f32 v125, -v117, v123, 1.0
	v_fma_f32 v122, v125, v123, v123
	v_div_fixup_f32 v117, v122, v117, 1.0
	v_mul_f32_e32 v117, 0xbf1b459e, v117
	v_mul_f32_e32 v122, 0x3fb8aa3b, v117
	v_rndne_f32_e32 v122, v122
	v_fmamk_f32 v123, v122, 0xbf317218, v117
	v_fmac_f32_e32 v123, 0x3102e308, v122
	v_cvt_i32_f32_e32 v124, v122
	v_fmamk_f32 v125, v123, 0x395133b1, v171
	v_fmaak_f32 v125, v123, v125, 0x3c0887f9
	v_fmaak_f32 v125, v123, v125, 0x3d2aaa81
	v_fmaak_f32 v125, v123, v125, 0x3e2aaaab
	v_ldexp_f32 v124, 1.0, v124
	v_fma_f32 v125, v123, v125, 0.5
	v_cmp_eq_f32_e32 vcc, s90, v122
	v_mul_f32_e32 v125, v123, v125
	v_fmac_f32_e32 v123, v123, v125
	v_cndmask_b32_e32 v122, v124, v172, vcc
	v_add_f32_e32 v124, -1.0, v122
	v_fmac_f32_e32 v124, v122, v123
	v_add_f32_e32 v122, v124, v124
	v_cndmask_b32_e32 v122, v124, v122, vcc
	v_cmp_nlt_f32_e32 vcc, s91, v117
	s_nop 1
	v_cndmask_b32_e64 v122, v173, -v122, vcc
	v_cmp_ngt_f32_e32 vcc, s92, v117
	s_nop 1
	v_cndmask_b32_e32 v117, 1.0, v122, vcc
.LBB0_624:
	v_add_f32_e32 v122, v118, v22
	s_and_b64 vcc, exec, s[8:9]
	s_mov_b64 s[14:15], -1
	s_cbranch_vccnz .LBB0_628
	s_and_b64 vcc, exec, s[6:7]
	v_mov_b32_e32 v118, v122
	s_cbranch_vccnz .LBB0_627
	v_mul_f32_e32 v118, 0xbfb8aa3b, v122
	v_exp_f32_e32 v118, v118
	s_nop 0
	v_add_f32_e32 v118, 1.0, v118
	v_rcp_f32_e32 v124, v118
	s_nop 0
	v_fma_f32 v126, -v118, v124, 1.0
	v_fma_f32 v123, v126, v124, v124
	v_div_fixup_f32 v118, v123, v118, 1.0

; __device__ __forceinline__ float sigmoidf_(float x) { return 1.0f / (1.0f + __expf(-x)); }
;     __device__ __forceinline__ void operator()(const f32x4 (&acc)[2][2][4][2], const Unit& u, int wr, int wc, int fr, int fq) const {
;     ...
;                         for (int i = 0; i < 4; ++i) { float xv = acc[ai][bj][m][n][i] + bv[bj][n][i]; float r;
;                             if (type < 2) { const float sg = sigmoidf_(xv); r = -expm1f(-0.606531f * sg); }
;                             else if (type == 2) r = sigmoidf_(xv);
.LBB0_629:
	v_mul_f32_e32 v118, 0xbfb8aa3b, v122
	v_exp_f32_e32 v118, v118
	s_nop 0
	v_add_f32_e32 v118, 1.0, v118
	v_rcp_f32_e32 v123, v118
	s_nop 0
	v_fma_f32 v125, -v118, v123, 1.0
	v_fma_f32 v122, v125, v123, v123
	v_div_fixup_f32 v118, v122, v118, 1.0
	v_mul_f32_e32 v118, 0xbf1b459e, v118
	v_mul_f32_e32 v122, 0x3fb8aa3b, v118
	v_rndne_f32_e32 v122, v122
	v_fmamk_f32 v123, v122, 0xbf317218, v118
	v_fmac_f32_e32 v123, 0x3102e308, v122
	v_cvt_i32_f32_e32 v124, v122
	v_fmamk_f32 v125, v123, 0x395133b1, v171
	v_fmaak_f32 v125, v123, v125, 0x3c0887f9
	v_fmaak_f32 v125, v123, v125, 0x3d2aaa81
	v_fmaak_f32 v125, v123, v125, 0x3e2aaaab
	v_ldexp_f32 v124, 1.0, v124
	v_fma_f32 v125, v123, v125, 0.5
	v_cmp_eq_f32_e32 vcc, s90, v122
	v_mul_f32_e32 v125, v123, v125
	v_fmac_f32_e32 v123, v123, v125
	v_cndmask_b32_e32 v122, v124, v172, vcc
	v_add_f32_e32 v124, -1.0, v122
	v_fmac_f32_e32 v124, v122, v123
	v_add_f32_e32 v122, v124, v124
	v_cndmask_b32_e32 v122, v124, v122, vcc
	v_cmp_nlt_f32_e32 vcc, s91, v118
	s_nop 1
	v_cndmask_b32_e64 v122, v173, -v122, vcc
	v_cmp_ngt_f32_e32 vcc, s92, v118
	s_nop 1
	v_cndmask_b32_e32 v118, 1.0, v122, vcc
.LBB0_630:
	v_add_f32_e32 v122, v119, v23
	s_and_b64 vcc, exec, s[8:9]
	s_mov_b64 s[14:15], -1
	s_cbranch_vccnz .LBB0_634
	s_and_b64 vcc, exec, s[6:7]
	v_mov_b32_e32 v119, v122
	s_cbranch_vccnz .LBB0_633
	v_mul_f32_e32 v119, 0xbfb8aa3b, v122
	v_exp_f32_e32 v119, v119
	s_nop 0
	v_add_f32_e32 v119, 1.0, v119
	v_rcp_f32_e32 v124, v119
	s_nop 0
	v_fma_f32 v126, -v119, v124, 1.0
	v_fma_f32 v123, v126, v124, v124
	v_div_fixup_f32 v119, v123, v119, 1.0

; __device__ __forceinline__ float sigmoidf_(float x) { return 1.0f / (1.0f + __expf(-x)); }
;     __device__ __forceinline__ void operator()(const f32x4 (&acc)[2][2][4][2], const Unit& u, int wr, int wc, int fr, int fq) const {
;     ...
;                         for (int i = 0; i < 4; ++i) { float xv = acc[ai][bj][m][n][i] + bv[bj][n][i]; float r;
;                             if (type < 2) { const float sg = sigmoidf_(xv); r = -expm1f(-0.606531f * sg); }
;                             else if (type == 2) r = sigmoidf_(xv);
.LBB0_635:
	v_mul_f32_e32 v119, 0xbfb8aa3b, v122
	v_exp_f32_e32 v119, v119
	s_nop 0
	v_add_f32_e32 v119, 1.0, v119
	v_rcp_f32_e32 v123, v119
	s_nop 0
	v_fma_f32 v125, -v119, v123, 1.0
	v_fma_f32 v122, v125, v123, v123
	v_div_fixup_f32 v119, v122, v119, 1.0
	v_mul_f32_e32 v119, 0xbf1b459e, v119
	v_mul_f32_e32 v122, 0x3fb8aa3b, v119
	v_rndne_f32_e32 v122, v122
	v_fmamk_f32 v123, v122, 0xbf317218, v119
	v_fmac_f32_e32 v123, 0x3102e308, v122
	v_cvt_i32_f32_e32 v124, v122
	v_fmamk_f32 v125, v123, 0x395133b1, v171
	v_fmaak_f32 v125, v123, v125, 0x3c0887f9
	v_fmaak_f32 v125, v123, v125, 0x3d2aaa81
	v_fmaak_f32 v125, v123, v125, 0x3e2aaaab
	v_ldexp_f32 v124, 1.0, v124
	v_fma_f32 v125, v123, v125, 0.5
	v_cmp_eq_f32_e32 vcc, s90, v122
	v_mul_f32_e32 v125, v123, v125
	v_fmac_f32_e32 v123, v123, v125
	v_cndmask_b32_e32 v122, v124, v172, vcc
	v_add_f32_e32 v124, -1.0, v122
	v_fmac_f32_e32 v124, v122, v123
	v_add_f32_e32 v122, v124, v124
	v_cndmask_b32_e32 v122, v124, v122, vcc
	v_cmp_nlt_f32_e32 vcc, s91, v119
	s_nop 1
	v_cndmask_b32_e64 v122, v173, -v122, vcc
	v_cmp_ngt_f32_e32 vcc, s92, v119
	s_nop 1
	v_cndmask_b32_e32 v119, 1.0, v122, vcc
.LBB0_636:
	v_add_f32_e32 v122, v112, v12
	s_and_b64 vcc, exec, s[8:9]
	s_mov_b64 s[14:15], -1
	s_cbranch_vccnz .LBB0_640
	s_and_b64 vcc, exec, s[6:7]
	v_mov_b32_e32 v112, v122
	s_cbranch_vccnz .LBB0_639
	v_mul_f32_e32 v112, 0xbfb8aa3b, v122
	v_exp_f32_e32 v112, v112
	s_nop 0
	v_add_f32_e32 v112, 1.0, v112
	v_rcp_f32_e32 v124, v112
	s_nop 0
	v_fma_f32 v126, -v112, v124, 1.0
	v_fma_f32 v123, v126, v124, v124
	v_div_fixup_f32 v112, v123, v112, 1.0

; __device__ __forceinline__ float sigmoidf_(float x) { return 1.0f / (1.0f + __expf(-x)); }
;     __device__ __forceinline__ void operator()(const f32x4 (&acc)[2][2][4][2], const Unit& u, int wr, int wc, int fr, int fq) const {
;     ...
;                         for (int i = 0; i < 4; ++i) { float xv = acc[ai][bj][m][n][i] + bv[bj][n][i]; float r;
;                             if (type < 2) { const float sg = sigmoidf_(xv); r = -expm1f(-0.606531f * sg); }
;                             else if (type == 2) r = sigmoidf_(xv);
.LBB0_641:
	v_mul_f32_e32 v112, 0xbfb8aa3b, v122
	v_exp_f32_e32 v112, v112
	s_nop 0
	v_add_f32_e32 v112, 1.0, v112
	v_rcp_f32_e32 v123, v112
	s_nop 0
	v_fma_f32 v125, -v112, v123, 1.0
	v_fma_f32 v122, v125, v123, v123
	v_div_fixup_f32 v112, v122, v112, 1.0
	v_mul_f32_e32 v112, 0xbf1b459e, v112
	v_mul_f32_e32 v122, 0x3fb8aa3b, v112
	v_rndne_f32_e32 v122, v122
	v_fmamk_f32 v123, v122, 0xbf317218, v112
	v_fmac_f32_e32 v123, 0x3102e308, v122
	v_cvt_i32_f32_e32 v124, v122
	v_fmamk_f32 v125, v123, 0x395133b1, v171
	v_fmaak_f32 v125, v123, v125, 0x3c0887f9
	v_fmaak_f32 v125, v123, v125, 0x3d2aaa81
	v_fmaak_f32 v125, v123, v125, 0x3e2aaaab
	v_ldexp_f32 v124, 1.0, v124
	v_fma_f32 v125, v123, v125, 0.5
	v_cmp_eq_f32_e32 vcc, s90, v122
	v_mul_f32_e32 v125, v123, v125
	v_fmac_f32_e32 v123, v123, v125
	v_cndmask_b32_e32 v122, v124, v172, vcc
	v_add_f32_e32 v124, -1.0, v122
	v_fmac_f32_e32 v124, v122, v123
	v_add_f32_e32 v122, v124, v124
	v_cndmask_b32_e32 v122, v124, v122, vcc
	v_cmp_nlt_f32_e32 vcc, s91, v112
	s_nop 1
	v_cndmask_b32_e64 v122, v173, -v122, vcc
	v_cmp_ngt_f32_e32 vcc, s92, v112
	s_nop 1
	v_cndmask_b32_e32 v112, 1.0, v122, vcc
.LBB0_642:
	v_add_f32_e32 v122, v113, v13
	s_and_b64 vcc, exec, s[8:9]
	s_mov_b64 s[14:15], -1
	s_cbranch_vccnz .LBB0_646
	s_and_b64 vcc, exec, s[6:7]
	v_mov_b32_e32 v113, v122
	s_cbranch_vccnz .LBB0_645
	v_mul_f32_e32 v113, 0xbfb8aa3b, v122
	v_exp_f32_e32 v113, v113
	s_nop 0
	v_add_f32_e32 v113, 1.0, v113
	v_rcp_f32_e32 v124, v113
	s_nop 0
	v_fma_f32 v126, -v113, v124, 1.0
	v_fma_f32 v123, v126, v124, v124
	v_div_fixup_f32 v113, v123, v113, 1.0

; __device__ __forceinline__ float sigmoidf_(float x) { return 1.0f / (1.0f + __expf(-x)); }
;     __device__ __forceinline__ void operator()(const f32x4 (&acc)[2][2][4][2], const Unit& u, int wr, int wc, int fr, int fq) const {
;     ...
;                         for (int i = 0; i < 4; ++i) { float xv = acc[ai][bj][m][n][i] + bv[bj][n][i]; float r;
;                             if (type < 2) { const float sg = sigmoidf_(xv); r = -expm1f(-0.606531f * sg); }
;                             else if (type == 2) r = sigmoidf_(xv);
.LBB0_647:
	v_mul_f32_e32 v113, 0xbfb8aa3b, v122
	v_exp_f32_e32 v113, v113
	s_nop 0
	v_add_f32_e32 v113, 1.0, v113
	v_rcp_f32_e32 v123, v113
	s_nop 0
	v_fma_f32 v125, -v113, v123, 1.0
	v_fma_f32 v122, v125, v123, v123
	v_div_fixup_f32 v113, v122, v113, 1.0
	v_mul_f32_e32 v113, 0xbf1b459e, v113
	v_mul_f32_e32 v122, 0x3fb8aa3b, v113
	v_rndne_f32_e32 v122, v122
	v_fmamk_f32 v123, v122, 0xbf317218, v113
	v_fmac_f32_e32 v123, 0x3102e308, v122
	v_cvt_i32_f32_e32 v124, v122
	v_fmamk_f32 v125, v123, 0x395133b1, v171
	v_fmaak_f32 v125, v123, v125, 0x3c0887f9
	v_fmaak_f32 v125, v123, v125, 0x3d2aaa81
	v_fmaak_f32 v125, v123, v125, 0x3e2aaaab
	v_ldexp_f32 v124, 1.0, v124
	v_fma_f32 v125, v123, v125, 0.5
	v_cmp_eq_f32_e32 vcc, s90, v122
	v_mul_f32_e32 v125, v123, v125
	v_fmac_f32_e32 v123, v123, v125
	v_cndmask_b32_e32 v122, v124, v172, vcc
	v_add_f32_e32 v124, -1.0, v122
	v_fmac_f32_e32 v124, v122, v123
	v_add_f32_e32 v122, v124, v124
	v_cndmask_b32_e32 v122, v124, v122, vcc
	v_cmp_nlt_f32_e32 vcc, s91, v113
	s_nop 1
	v_cndmask_b32_e64 v122, v173, -v122, vcc
	v_cmp_ngt_f32_e32 vcc, s92, v113
	s_nop 1
	v_cndmask_b32_e32 v113, 1.0, v122, vcc
.LBB0_648:
	v_add_f32_e32 v122, v114, v14
	s_and_b64 vcc, exec, s[8:9]
	s_mov_b64 s[14:15], -1
	s_cbranch_vccnz .LBB0_652
	s_and_b64 vcc, exec, s[6:7]
	v_mov_b32_e32 v114, v122
	s_cbranch_vccnz .LBB0_651
	v_mul_f32_e32 v114, 0xbfb8aa3b, v122
	v_exp_f32_e32 v114, v114
	s_nop 0
	v_add_f32_e32 v114, 1.0, v114
	v_rcp_f32_e32 v124, v114
	s_nop 0
	v_fma_f32 v126, -v114, v124, 1.0
	v_fma_f32 v123, v126, v124, v124
	v_div_fixup_f32 v114, v123, v114, 1.0

; __device__ __forceinline__ float sigmoidf_(float x) { return 1.0f / (1.0f + __expf(-x)); }
;     __device__ __forceinline__ void operator()(const f32x4 (&acc)[2][2][4][2], const Unit& u, int wr, int wc, int fr, int fq) const {
;     ...
;                         for (int i = 0; i < 4; ++i) { float xv = acc[ai][bj][m][n][i] + bv[bj][n][i]; float r;
;                             if (type < 2) { const float sg = sigmoidf_(xv); r = -expm1f(-0.606531f * sg); }
;                             else if (type == 2) r = sigmoidf_(xv);
.LBB0_653:
	v_mul_f32_e32 v114, 0xbfb8aa3b, v122
	v_exp_f32_e32 v114, v114
	s_nop 0
	v_add_f32_e32 v114, 1.0, v114
	v_rcp_f32_e32 v123, v114
	s_nop 0
	v_fma_f32 v125, -v114, v123, 1.0
	v_fma_f32 v122, v125, v123, v123
	v_div_fixup_f32 v114, v122, v114, 1.0
	v_mul_f32_e32 v114, 0xbf1b459e, v114
	v_mul_f32_e32 v122, 0x3fb8aa3b, v114
	v_rndne_f32_e32 v122, v122
	v_fmamk_f32 v123, v122, 0xbf317218, v114
	v_fmac_f32_e32 v123, 0x3102e308, v122
	v_cvt_i32_f32_e32 v124, v122
	v_fmamk_f32 v125, v123, 0x395133b1, v171
	v_fmaak_f32 v125, v123, v125, 0x3c0887f9
	v_fmaak_f32 v125, v123, v125, 0x3d2aaa81
	v_fmaak_f32 v125, v123, v125, 0x3e2aaaab
	v_ldexp_f32 v124, 1.0, v124
	v_fma_f32 v125, v123, v125, 0.5
	v_cmp_eq_f32_e32 vcc, s90, v122
	v_mul_f32_e32 v125, v123, v125
	v_fmac_f32_e32 v123, v123, v125
	v_cndmask_b32_e32 v122, v124, v172, vcc
	v_add_f32_e32 v124, -1.0, v122
	v_fmac_f32_e32 v124, v122, v123
	v_add_f32_e32 v122, v124, v124
	v_cndmask_b32_e32 v122, v124, v122, vcc
	v_cmp_nlt_f32_e32 vcc, s91, v114
	s_nop 1
	v_cndmask_b32_e64 v122, v173, -v122, vcc
	v_cmp_ngt_f32_e32 vcc, s92, v114
	s_nop 1
	v_cndmask_b32_e32 v114, 1.0, v122, vcc
.LBB0_654:
	v_add_f32_e32 v115, v115, v15
	s_and_b64 vcc, exec, s[8:9]
	s_mov_b64 s[14:15], -1
	s_cbranch_vccnz .LBB0_658
	s_and_b64 vcc, exec, s[6:7]
	v_mov_b32_e32 v122, v115
	s_cbranch_vccnz .LBB0_657
	v_mul_f32_e32 v122, 0xbfb8aa3b, v115
	v_exp_f32_e32 v122, v122
	s_nop 0
	v_add_f32_e32 v122, 1.0, v122
	v_rcp_f32_e32 v124, v122
	s_nop 0
	v_fma_f32 v126, -v122, v124, 1.0
	v_fma_f32 v123, v126, v124, v124
	v_div_fixup_f32 v122, v123, v122, 1.0

; __device__ __forceinline__ float sigmoidf_(float x) { return 1.0f / (1.0f + __expf(-x)); }
;     __device__ __forceinline__ void operator()(const f32x4 (&acc)[2][2][4][2], const Unit& u, int wr, int wc, int fr, int fq) const {
;     ...
;             for (int m = 0; m < 4; ++m) { f16* rowp = O + (size_t)(row0 + ai * 128 + m * 16) * 4096 + col0;
; #pragma unroll
;                 for (int bj = 0; bj < 2; ++bj) { f16x8 v;
; #pragma unroll
;                     for (int n = 0; n < 2; ++n)
; #pragma unroll
;                         for (int i = 0; i < 4; ++i) { float xv = acc[ai][bj][m][n][i] + bv[bj][n][i]; float r;
;                             if (type < 2) { const float sg = sigmoidf_(xv); r = -expm1f(-0.606531f * sg); }
;                             else if (type == 2) r = sigmoidf_(xv);
;                             else r = xv;
;                             v[4 * n + i] = (f16)r; }
;                     *(f16x8*)(rowp + bj * 128) = v; } }
.LBB0_659:
	v_mul_f32_e32 v115, 0xbfb8aa3b, v115
	v_exp_f32_e32 v115, v115
	s_nop 0
	v_add_f32_e32 v115, 1.0, v115
	v_rcp_f32_e32 v123, v115
	s_nop 0
	v_fma_f32 v125, -v115, v123, 1.0
	v_fma_f32 v122, v125, v123, v123
	v_div_fixup_f32 v115, v122, v115, 1.0
	v_mul_f32_e32 v115, 0xbf1b459e, v115
	v_mul_f32_e32 v122, 0x3fb8aa3b, v115
	v_rndne_f32_e32 v122, v122
	v_fmamk_f32 v123, v122, 0xbf317218, v115
	v_fmac_f32_e32 v123, 0x3102e308, v122
	v_cvt_i32_f32_e32 v124, v122
	v_fmamk_f32 v125, v123, 0x395133b1, v171
	v_fmaak_f32 v125, v123, v125, 0x3c0887f9
	v_fmaak_f32 v125, v123, v125, 0x3d2aaa81
	v_fmaak_f32 v125, v123, v125, 0x3e2aaaab
	v_ldexp_f32 v124, 1.0, v124
	v_fma_f32 v125, v123, v125, 0.5
	v_cmp_eq_f32_e32 vcc, s90, v122
	v_mul_f32_e32 v125, v123, v125
	v_fmac_f32_e32 v123, v123, v125
	v_cndmask_b32_e32 v122, v124, v172, vcc
	v_add_f32_e32 v124, -1.0, v122
	v_fmac_f32_e32 v124, v122, v123
	v_add_f32_e32 v122, v124, v124
	v_cndmask_b32_e32 v122, v124, v122, vcc
	v_cmp_nlt_f32_e32 vcc, s91, v115
	s_nop 1
	v_cndmask_b32_e64 v122, v173, -v122, vcc
	v_cmp_ngt_f32_e32 vcc, s92, v115
	s_nop 1
	v_cndmask_b32_e32 v122, 1.0, v122, vcc
.LBB0_660:
	v_cvt_pk_f16_f32 v115, v114, v122
	v_cvt_pk_f16_f32 v114, v112, v113
	v_cvt_pk_f16_f32 v113, v118, v119
	v_cvt_pk_f16_f32 v112, v116, v117
	global_store_dwordx4 v[120:121], v[112:115], off offset:256
	s_and_b64 vcc, exec, s[8:9]
	s_mov_b64 s[14:15], -1
	v_add_f32_e32 v112, v108, v32
	s_cbranch_vccnz .LBB0_664
	s_and_b64 vcc, exec, s[6:7]
	v_mov_b32_e32 v108, v112
	s_cbranch_vccnz .LBB0_663
	v_mul_f32_e32 v108, 0xbfb8aa3b, v112
	v_exp_f32_e32 v108, v108
	s_nop 0
	v_add_f32_e32 v108, 1.0, v108
	v_rcp_f32_e32 v114, v108
	s_nop 0
	v_fma_f32 v116, -v108, v114, 1.0
	v_fma_f32 v113, v116, v114, v114
	v_div_fixup_f32 v108, v113, v108, 1.0

; __device__ __forceinline__ float sigmoidf_(float x) { return 1.0f / (1.0f + __expf(-x)); }
;     __device__ __forceinline__ void operator()(const f32x4 (&acc)[2][2][4][2], const Unit& u, int wr, int wc, int fr, int fq) const {
;     ...
;                         for (int i = 0; i < 4; ++i) { float xv = acc[ai][bj][m][n][i] + bv[bj][n][i]; float r;
;                             if (type < 2) { const float sg = sigmoidf_(xv); r = -expm1f(-0.606531f * sg); }
;                             else if (type == 2) r = sigmoidf_(xv);
.LBB0_665:
	v_mul_f32_e32 v108, 0xbfb8aa3b, v112
	v_exp_f32_e32 v108, v108
	s_nop 0
	v_add_f32_e32 v108, 1.0, v108
	v_rcp_f32_e32 v113, v108
	s_nop 0
	v_fma_f32 v115, -v108, v113, 1.0
	v_fma_f32 v112, v115, v113, v113
	v_div_fixup_f32 v108, v112, v108, 1.0
	v_mul_f32_e32 v108, 0xbf1b459e, v108
	v_mul_f32_e32 v112, 0x3fb8aa3b, v108
	v_rndne_f32_e32 v112, v112
	v_fmamk_f32 v113, v112, 0xbf317218, v108
	v_fmac_f32_e32 v113, 0x3102e308, v112
	v_cvt_i32_f32_e32 v114, v112
	v_fmamk_f32 v115, v113, 0x395133b1, v171
	v_fmaak_f32 v115, v113, v115, 0x3c0887f9
	v_fmaak_f32 v115, v113, v115, 0x3d2aaa81
	v_fmaak_f32 v115, v113, v115, 0x3e2aaaab
	v_ldexp_f32 v114, 1.0, v114
	v_fma_f32 v115, v113, v115, 0.5
	v_cmp_eq_f32_e32 vcc, s90, v112
	v_mul_f32_e32 v115, v113, v115
	v_fmac_f32_e32 v113, v113, v115
	v_cndmask_b32_e32 v112, v114, v172, vcc
	v_add_f32_e32 v114, -1.0, v112
	v_fmac_f32_e32 v114, v112, v113
	v_add_f32_e32 v112, v114, v114
	v_cndmask_b32_e32 v112, v114, v112, vcc
	v_cmp_nlt_f32_e32 vcc, s91, v108
	s_nop 1
	v_cndmask_b32_e64 v112, v173, -v112, vcc
	v_cmp_ngt_f32_e32 vcc, s92, v108
	s_nop 1
	v_cndmask_b32_e32 v108, 1.0, v112, vcc
.LBB0_666:
	v_add_f32_e32 v112, v109, v33
	s_and_b64 vcc, exec, s[8:9]
	s_mov_b64 s[14:15], -1
	s_cbranch_vccnz .LBB0_670
	s_and_b64 vcc, exec, s[6:7]
	v_mov_b32_e32 v109, v112
	s_cbranch_vccnz .LBB0_669
	v_mul_f32_e32 v109, 0xbfb8aa3b, v112
	v_exp_f32_e32 v109, v109
	s_nop 0
	v_add_f32_e32 v109, 1.0, v109
	v_rcp_f32_e32 v114, v109
	s_nop 0
	v_fma_f32 v116, -v109, v114, 1.0
	v_fma_f32 v113, v116, v114, v114
	v_div_fixup_f32 v109, v113, v109, 1.0

; __device__ __forceinline__ float sigmoidf_(float x) { return 1.0f / (1.0f + __expf(-x)); }
;     __device__ __forceinline__ void operator()(const f32x4 (&acc)[2][2][4][2], const Unit& u, int wr, int wc, int fr, int fq) const {
;     ...
;                         for (int i = 0; i < 4; ++i) { float xv = acc[ai][bj][m][n][i] + bv[bj][n][i]; float r;
;                             if (type < 2) { const float sg = sigmoidf_(xv); r = -expm1f(-0.606531f * sg); }
;                             else if (type == 2) r = sigmoidf_(xv);
.LBB0_671:
	v_mul_f32_e32 v109, 0xbfb8aa3b, v112
	v_exp_f32_e32 v109, v109
	s_nop 0
	v_add_f32_e32 v109, 1.0, v109
	v_rcp_f32_e32 v113, v109
	s_nop 0
	v_fma_f32 v115, -v109, v113, 1.0
	v_fma_f32 v112, v115, v113, v113
	v_div_fixup_f32 v109, v112, v109, 1.0
	v_mul_f32_e32 v109, 0xbf1b459e, v109
	v_mul_f32_e32 v112, 0x3fb8aa3b, v109
	v_rndne_f32_e32 v112, v112
	v_fmamk_f32 v113, v112, 0xbf317218, v109
	v_fmac_f32_e32 v113, 0x3102e308, v112
	v_cvt_i32_f32_e32 v114, v112
	v_fmamk_f32 v115, v113, 0x395133b1, v171
	v_fmaak_f32 v115, v113, v115, 0x3c0887f9
	v_fmaak_f32 v115, v113, v115, 0x3d2aaa81
	v_fmaak_f32 v115, v113, v115, 0x3e2aaaab
	v_ldexp_f32 v114, 1.0, v114
	v_fma_f32 v115, v113, v115, 0.5
	v_cmp_eq_f32_e32 vcc, s90, v112
	v_mul_f32_e32 v115, v113, v115
	v_fmac_f32_e32 v113, v113, v115
	v_cndmask_b32_e32 v112, v114, v172, vcc
	v_add_f32_e32 v114, -1.0, v112
	v_fmac_f32_e32 v114, v112, v113
	v_add_f32_e32 v112, v114, v114
	v_cndmask_b32_e32 v112, v114, v112, vcc
	v_cmp_nlt_f32_e32 vcc, s91, v109
	s_nop 1
	v_cndmask_b32_e64 v112, v173, -v112, vcc
	v_cmp_ngt_f32_e32 vcc, s92, v109
	s_nop 1
	v_cndmask_b32_e32 v109, 1.0, v112, vcc
.LBB0_672:
	v_add_f32_e32 v112, v110, v34
	s_and_b64 vcc, exec, s[8:9]
	s_mov_b64 s[14:15], -1
	s_cbranch_vccnz .LBB0_676
	s_and_b64 vcc, exec, s[6:7]
	v_mov_b32_e32 v110, v112
	s_cbranch_vccnz .LBB0_675
	v_mul_f32_e32 v110, 0xbfb8aa3b, v112
	v_exp_f32_e32 v110, v110
	s_nop 0
	v_add_f32_e32 v110, 1.0, v110
	v_rcp_f32_e32 v114, v110
	s_nop 0
	v_fma_f32 v116, -v110, v114, 1.0
	v_fma_f32 v113, v116, v114, v114
	v_div_fixup_f32 v110, v113, v110, 1.0

; __device__ __forceinline__ float sigmoidf_(float x) { return 1.0f / (1.0f + __expf(-x)); }
;     __device__ __forceinline__ void operator()(const f32x4 (&acc)[2][2][4][2], const Unit& u, int wr, int wc, int fr, int fq) const {
;     ...
;                         for (int i = 0; i < 4; ++i) { float xv = acc[ai][bj][m][n][i] + bv[bj][n][i]; float r;
;                             if (type < 2) { const float sg = sigmoidf_(xv); r = -expm1f(-0.606531f * sg); }
;                             else if (type == 2) r = sigmoidf_(xv);
.LBB0_677:
	v_mul_f32_e32 v110, 0xbfb8aa3b, v112
	v_exp_f32_e32 v110, v110
	s_nop 0
	v_add_f32_e32 v110, 1.0, v110
	v_rcp_f32_e32 v113, v110
	s_nop 0
	v_fma_f32 v115, -v110, v113, 1.0
	v_fma_f32 v112, v115, v113, v113
	v_div_fixup_f32 v110, v112, v110, 1.0
	v_mul_f32_e32 v110, 0xbf1b459e, v110
	v_mul_f32_e32 v112, 0x3fb8aa3b, v110
	v_rndne_f32_e32 v112, v112
	v_fmamk_f32 v113, v112, 0xbf317218, v110
	v_fmac_f32_e32 v113, 0x3102e308, v112
	v_cvt_i32_f32_e32 v114, v112
	v_fmamk_f32 v115, v113, 0x395133b1, v171
	v_fmaak_f32 v115, v113, v115, 0x3c0887f9
	v_fmaak_f32 v115, v113, v115, 0x3d2aaa81
	v_fmaak_f32 v115, v113, v115, 0x3e2aaaab
	v_ldexp_f32 v114, 1.0, v114
	v_fma_f32 v115, v113, v115, 0.5
	v_cmp_eq_f32_e32 vcc, s90, v112
	v_mul_f32_e32 v115, v113, v115
	v_fmac_f32_e32 v113, v113, v115
	v_cndmask_b32_e32 v112, v114, v172, vcc
	v_add_f32_e32 v114, -1.0, v112
	v_fmac_f32_e32 v114, v112, v113
	v_add_f32_e32 v112, v114, v114
	v_cndmask_b32_e32 v112, v114, v112, vcc
	v_cmp_nlt_f32_e32 vcc, s91, v110
	s_nop 1
	v_cndmask_b32_e64 v112, v173, -v112, vcc
	v_cmp_ngt_f32_e32 vcc, s92, v110
	s_nop 1
	v_cndmask_b32_e32 v110, 1.0, v112, vcc
.LBB0_678:
	v_add_f32_e32 v112, v111, v35
	s_and_b64 vcc, exec, s[8:9]
	s_mov_b64 s[14:15], -1
	s_cbranch_vccnz .LBB0_682
	s_and_b64 vcc, exec, s[6:7]
	v_mov_b32_e32 v111, v112
	s_cbranch_vccnz .LBB0_681
	v_mul_f32_e32 v111, 0xbfb8aa3b, v112
	v_exp_f32_e32 v111, v111
	s_nop 0
	v_add_f32_e32 v111, 1.0, v111
	v_rcp_f32_e32 v114, v111
	s_nop 0
	v_fma_f32 v116, -v111, v114, 1.0
	v_fma_f32 v113, v116, v114, v114
	v_div_fixup_f32 v111, v113, v111, 1.0

; __device__ __forceinline__ float sigmoidf_(float x) { return 1.0f / (1.0f + __expf(-x)); }
;     __device__ __forceinline__ void operator()(const f32x4 (&acc)[2][2][4][2], const Unit& u, int wr, int wc, int fr, int fq) const {
;     ...
;                         for (int i = 0; i < 4; ++i) { float xv = acc[ai][bj][m][n][i] + bv[bj][n][i]; float r;
;                             if (type < 2) { const float sg = sigmoidf_(xv); r = -expm1f(-0.606531f * sg); }
;                             else if (type == 2) r = sigmoidf_(xv);
.LBB0_683:
	v_mul_f32_e32 v111, 0xbfb8aa3b, v112
	v_exp_f32_e32 v111, v111
	s_nop 0
	v_add_f32_e32 v111, 1.0, v111
	v_rcp_f32_e32 v113, v111
	s_nop 0
	v_fma_f32 v115, -v111, v113, 1.0
	v_fma_f32 v112, v115, v113, v113
	v_div_fixup_f32 v111, v112, v111, 1.0
	v_mul_f32_e32 v111, 0xbf1b459e, v111
	v_mul_f32_e32 v112, 0x3fb8aa3b, v111
	v_rndne_f32_e32 v112, v112
	v_fmamk_f32 v113, v112, 0xbf317218, v111
	v_fmac_f32_e32 v113, 0x3102e308, v112
	v_cvt_i32_f32_e32 v114, v112
	v_fmamk_f32 v115, v113, 0x395133b1, v171
	v_fmaak_f32 v115, v113, v115, 0x3c0887f9
	v_fmaak_f32 v115, v113, v115, 0x3d2aaa81
	v_fmaak_f32 v115, v113, v115, 0x3e2aaaab
	v_ldexp_f32 v114, 1.0, v114
	v_fma_f32 v115, v113, v115, 0.5
	v_cmp_eq_f32_e32 vcc, s90, v112
	v_mul_f32_e32 v115, v113, v115
	v_fmac_f32_e32 v113, v113, v115
	v_cndmask_b32_e32 v112, v114, v172, vcc
	v_add_f32_e32 v114, -1.0, v112
	v_fmac_f32_e32 v114, v112, v113
	v_add_f32_e32 v112, v114, v114
	v_cndmask_b32_e32 v112, v114, v112, vcc
	v_cmp_nlt_f32_e32 vcc, s91, v111
	s_nop 1
	v_cndmask_b32_e64 v112, v173, -v112, vcc
	v_cmp_ngt_f32_e32 vcc, s92, v111
	s_nop 1
	v_cndmask_b32_e32 v111, 1.0, v112, vcc
.LBB0_684:
	v_add_f32_e32 v104, v104, v28
	s_and_b64 vcc, exec, s[8:9]
	s_mov_b64 s[14:15], -1
	s_cbranch_vccnz .LBB0_688
	s_and_b64 vcc, exec, s[6:7]
	v_mov_b32_e32 v112, v104
	s_cbranch_vccnz .LBB0_687
	v_mul_f32_e32 v112, 0xbfb8aa3b, v104
	v_exp_f32_e32 v112, v112
	s_nop 0
	v_add_f32_e32 v112, 1.0, v112
	v_rcp_f32_e32 v114, v112
	s_nop 0
	v_fma_f32 v116, -v112, v114, 1.0
	v_fma_f32 v113, v116, v114, v114
	v_div_fixup_f32 v112, v113, v112, 1.0

; __device__ __forceinline__ float sigmoidf_(float x) { return 1.0f / (1.0f + __expf(-x)); }
;     __device__ __forceinline__ void operator()(const f32x4 (&acc)[2][2][4][2], const Unit& u, int wr, int wc, int fr, int fq) const {
;     ...
;                         for (int i = 0; i < 4; ++i) { float xv = acc[ai][bj][m][n][i] + bv[bj][n][i]; float r;
;                             if (type < 2) { const float sg = sigmoidf_(xv); r = -expm1f(-0.606531f * sg); }
;                             else if (type == 2) r = sigmoidf_(xv);
.LBB0_689:
	v_mul_f32_e32 v104, 0xbfb8aa3b, v104
	v_exp_f32_e32 v104, v104
	s_nop 0
	v_add_f32_e32 v104, 1.0, v104
	v_rcp_f32_e32 v113, v104
	s_nop 0
	v_fma_f32 v115, -v104, v113, 1.0
	v_fma_f32 v112, v115, v113, v113
	v_div_fixup_f32 v104, v112, v104, 1.0
	v_mul_f32_e32 v104, 0xbf1b459e, v104
	v_mul_f32_e32 v112, 0x3fb8aa3b, v104
	v_rndne_f32_e32 v112, v112
	v_fmamk_f32 v113, v112, 0xbf317218, v104
	v_fmac_f32_e32 v113, 0x3102e308, v112
	v_cvt_i32_f32_e32 v114, v112
	v_fmamk_f32 v115, v113, 0x395133b1, v171
	v_fmaak_f32 v115, v113, v115, 0x3c0887f9
	v_fmaak_f32 v115, v113, v115, 0x3d2aaa81
	v_fmaak_f32 v115, v113, v115, 0x3e2aaaab
	v_ldexp_f32 v114, 1.0, v114
	v_fma_f32 v115, v113, v115, 0.5
	v_cmp_eq_f32_e32 vcc, s90, v112
	v_mul_f32_e32 v115, v113, v115
	v_fmac_f32_e32 v113, v113, v115
	v_cndmask_b32_e32 v112, v114, v172, vcc
	v_add_f32_e32 v114, -1.0, v112
	v_fmac_f32_e32 v114, v112, v113
	v_add_f32_e32 v112, v114, v114
	v_cndmask_b32_e32 v112, v114, v112, vcc
	v_cmp_nlt_f32_e32 vcc, s91, v104
	s_nop 1
	v_cndmask_b32_e64 v112, v173, -v112, vcc
	v_cmp_ngt_f32_e32 vcc, s92, v104
	s_nop 1
	v_cndmask_b32_e32 v112, 1.0, v112, vcc
.LBB0_690:
	v_add_f32_e32 v104, v105, v29
	s_and_b64 vcc, exec, s[8:9]
	s_mov_b64 s[14:15], -1
	s_cbranch_vccnz .LBB0_694
	s_and_b64 vcc, exec, s[6:7]
	v_mov_b32_e32 v113, v104
	s_cbranch_vccnz .LBB0_693
	v_mul_f32_e32 v105, 0xbfb8aa3b, v104
	v_exp_f32_e32 v105, v105
	s_nop 0
	v_add_f32_e32 v105, 1.0, v105
	v_rcp_f32_e32 v114, v105
	s_nop 0
	v_fma_f32 v116, -v105, v114, 1.0
	v_fma_f32 v113, v116, v114, v114
	v_div_fixup_f32 v113, v113, v105, 1.0

; __device__ __forceinline__ float sigmoidf_(float x) { return 1.0f / (1.0f + __expf(-x)); }
;     __device__ __forceinline__ void operator()(const f32x4 (&acc)[2][2][4][2], const Unit& u, int wr, int wc, int fr, int fq) const {
;     ...
;                         for (int i = 0; i < 4; ++i) { float xv = acc[ai][bj][m][n][i] + bv[bj][n][i]; float r;
;                             if (type < 2) { const float sg = sigmoidf_(xv); r = -expm1f(-0.606531f * sg); }
;                             else if (type == 2) r = sigmoidf_(xv);
.LBB0_695:
	v_mul_f32_e32 v104, 0xbfb8aa3b, v104
	v_exp_f32_e32 v104, v104
	s_nop 0
	v_add_f32_e32 v104, 1.0, v104
	v_rcp_f32_e32 v113, v104
	s_nop 0
	v_fma_f32 v115, -v104, v113, 1.0
	v_fma_f32 v105, v115, v113, v113
	v_div_fixup_f32 v104, v105, v104, 1.0
	v_mul_f32_e32 v104, 0xbf1b459e, v104
	v_mul_f32_e32 v105, 0x3fb8aa3b, v104
	v_rndne_f32_e32 v105, v105
	v_fmamk_f32 v113, v105, 0xbf317218, v104
	v_fmac_f32_e32 v113, 0x3102e308, v105
	v_cvt_i32_f32_e32 v114, v105
	v_fmamk_f32 v115, v113, 0x395133b1, v171
	v_fmaak_f32 v115, v113, v115, 0x3c0887f9
	v_fmaak_f32 v115, v113, v115, 0x3d2aaa81
	v_fmaak_f32 v115, v113, v115, 0x3e2aaaab
	v_ldexp_f32 v114, 1.0, v114
	v_fma_f32 v115, v113, v115, 0.5
	v_cmp_eq_f32_e32 vcc, s90, v105
	v_mul_f32_e32 v115, v113, v115
	v_fmac_f32_e32 v113, v113, v115
	v_cndmask_b32_e32 v105, v114, v172, vcc
	v_add_f32_e32 v114, -1.0, v105
	v_fmac_f32_e32 v114, v105, v113
	v_add_f32_e32 v105, v114, v114
	v_cndmask_b32_e32 v105, v114, v105, vcc
	v_cmp_nlt_f32_e32 vcc, s91, v104
	s_nop 1
	v_cndmask_b32_e64 v105, v173, -v105, vcc
	v_cmp_ngt_f32_e32 vcc, s92, v104
	s_nop 1
	v_cndmask_b32_e32 v113, 1.0, v105, vcc
.LBB0_696:
	v_add_f32_e32 v104, v106, v30
	s_and_b64 vcc, exec, s[8:9]
	s_mov_b64 s[14:15], -1
	s_cbranch_vccnz .LBB0_700
	s_and_b64 vcc, exec, s[6:7]
	v_mov_b32_e32 v106, v104
	s_cbranch_vccnz .LBB0_699
	v_mul_f32_e32 v105, 0xbfb8aa3b, v104
	v_exp_f32_e32 v105, v105
	s_nop 0
	v_add_f32_e32 v105, 1.0, v105
	v_rcp_f32_e32 v114, v105
	s_nop 0
	v_fma_f32 v116, -v105, v114, 1.0
	v_fma_f32 v106, v116, v114, v114
	v_div_fixup_f32 v106, v106, v105, 1.0

; __device__ __forceinline__ float sigmoidf_(float x) { return 1.0f / (1.0f + __expf(-x)); }
;     __device__ __forceinline__ void operator()(const f32x4 (&acc)[2][2][4][2], const Unit& u, int wr, int wc, int fr, int fq) const {
;     ...
;                         for (int i = 0; i < 4; ++i) { float xv = acc[ai][bj][m][n][i] + bv[bj][n][i]; float r;
;                             if (type < 2) { const float sg = sigmoidf_(xv); r = -expm1f(-0.606531f * sg); }
;                             else if (type == 2) r = sigmoidf_(xv);
.LBB0_701:
	v_mul_f32_e32 v104, 0xbfb8aa3b, v104
	v_exp_f32_e32 v104, v104
	s_nop 0
	v_add_f32_e32 v104, 1.0, v104
	v_rcp_f32_e32 v106, v104
	s_nop 0
	v_fma_f32 v115, -v104, v106, 1.0
	v_fma_f32 v105, v115, v106, v106
	v_div_fixup_f32 v104, v105, v104, 1.0
	v_mul_f32_e32 v104, 0xbf1b459e, v104
	v_mul_f32_e32 v105, 0x3fb8aa3b, v104
	v_rndne_f32_e32 v105, v105
	v_fmamk_f32 v106, v105, 0xbf317218, v104
	v_fmac_f32_e32 v106, 0x3102e308, v105
	v_cvt_i32_f32_e32 v114, v105
	v_fmamk_f32 v115, v106, 0x395133b1, v171
	v_fmaak_f32 v115, v106, v115, 0x3c0887f9
	v_fmaak_f32 v115, v106, v115, 0x3d2aaa81
	v_fmaak_f32 v115, v106, v115, 0x3e2aaaab
	v_ldexp_f32 v114, 1.0, v114
	v_fma_f32 v115, v106, v115, 0.5
	v_cmp_eq_f32_e32 vcc, s90, v105
	v_mul_f32_e32 v115, v106, v115
	v_fmac_f32_e32 v106, v106, v115
	v_cndmask_b32_e32 v105, v114, v172, vcc
	v_add_f32_e32 v114, -1.0, v105
	v_fmac_f32_e32 v114, v105, v106
	v_add_f32_e32 v105, v114, v114
	v_cndmask_b32_e32 v105, v114, v105, vcc
	v_cmp_nlt_f32_e32 vcc, s91, v104
	s_nop 1
	v_cndmask_b32_e64 v105, v173, -v105, vcc
	v_cmp_ngt_f32_e32 vcc, s92, v104
	s_nop 1
	v_cndmask_b32_e32 v106, 1.0, v105, vcc
.LBB0_702:
	v_add_f32_e32 v104, v107, v31
	s_and_b64 vcc, exec, s[8:9]
	s_mov_b64 s[14:15], -1
	s_cbranch_vccnz .LBB0_706
	s_and_b64 vcc, exec, s[6:7]
	v_mov_b32_e32 v107, v104
	s_cbranch_vccnz .LBB0_705
	v_mul_f32_e32 v105, 0xbfb8aa3b, v104
	v_exp_f32_e32 v105, v105
	s_nop 0
	v_add_f32_e32 v105, 1.0, v105
	v_rcp_f32_e32 v114, v105
	s_nop 0
	v_fma_f32 v116, -v105, v114, 1.0
	v_fma_f32 v107, v116, v114, v114
	v_div_fixup_f32 v107, v107, v105, 1.0

; __device__ __forceinline__ float sigmoidf_(float x) { return 1.0f / (1.0f + __expf(-x)); }
;     __device__ __forceinline__ void operator()(const f32x4 (&acc)[2][2][4][2], const Unit& u, int wr, int wc, int fr, int fq) const {
;     ...
;             for (int m = 0; m < 4; ++m) { f16* rowp = O + (size_t)(row0 + ai * 128 + m * 16) * 4096 + col0;
; #pragma unroll
;                 for (int bj = 0; bj < 2; ++bj) { f16x8 v;
; #pragma unroll
;                     for (int n = 0; n < 2; ++n)
; #pragma unroll
;                         for (int i = 0; i < 4; ++i) { float xv = acc[ai][bj][m][n][i] + bv[bj][n][i]; float r;
;                             if (type < 2) { const float sg = sigmoidf_(xv); r = -expm1f(-0.606531f * sg); }
;                             else if (type == 2) r = sigmoidf_(xv);
;                             else r = xv;
;                             v[4 * n + i] = (f16)r; }
;                     *(f16x8*)(rowp + bj * 128) = v; } }
.LBB0_707:
	v_mul_f32_e32 v104, 0xbfb8aa3b, v104
	v_exp_f32_e32 v104, v104
	s_nop 0
	v_add_f32_e32 v104, 1.0, v104
	v_rcp_f32_e32 v107, v104
	s_nop 0
	v_fma_f32 v115, -v104, v107, 1.0
	v_fma_f32 v105, v115, v107, v107
	v_div_fixup_f32 v104, v105, v104, 1.0
	v_mul_f32_e32 v104, 0xbf1b459e, v104
	v_mul_f32_e32 v105, 0x3fb8aa3b, v104
	v_rndne_f32_e32 v105, v105
	v_fmamk_f32 v107, v105, 0xbf317218, v104
	v_fmac_f32_e32 v107, 0x3102e308, v105
	v_cvt_i32_f32_e32 v114, v105
	v_fmamk_f32 v115, v107, 0x395133b1, v171
	v_fmaak_f32 v115, v107, v115, 0x3c0887f9
	v_fmaak_f32 v115, v107, v115, 0x3d2aaa81
	v_fmaak_f32 v115, v107, v115, 0x3e2aaaab
	v_ldexp_f32 v114, 1.0, v114
	v_fma_f32 v115, v107, v115, 0.5
	v_cmp_eq_f32_e32 vcc, s90, v105
	v_mul_f32_e32 v115, v107, v115
	v_fmac_f32_e32 v107, v107, v115
	v_cndmask_b32_e32 v105, v114, v172, vcc
	v_add_f32_e32 v114, -1.0, v105
	v_fmac_f32_e32 v114, v105, v107
	v_add_f32_e32 v105, v114, v114
	v_cndmask_b32_e32 v105, v114, v105, vcc
	v_cmp_nlt_f32_e32 vcc, s91, v104
	s_nop 1
	v_cndmask_b32_e64 v105, v173, -v105, vcc
	v_cmp_ngt_f32_e32 vcc, s92, v104
	s_nop 1
	v_cndmask_b32_e32 v107, 1.0, v105, vcc
.LBB0_708:
	v_or_b32_e32 v104, 32, v138
	v_ashrrev_i32_e32 v105, 31, v104
	v_lshlrev_b64 v[104:105], 13, v[104:105]
	v_lshl_add_u64 v[104:105], s[28:29], 0, v[104:105]
	v_lshl_add_u64 v[104:105], v[136:137], 1, v[104:105]
	v_cvt_pk_f16_f32 v115, v106, v107
	v_cvt_pk_f16_f32 v114, v112, v113
	v_cvt_pk_f16_f32 v113, v110, v111
	v_cvt_pk_f16_f32 v112, v108, v109
	v_add_f32_e32 v106, v100, v20
	s_and_b64 vcc, exec, s[8:9]
	s_mov_b64 s[14:15], -1
	global_store_dwordx4 v[104:105], v[112:115], off
	s_cbranch_vccnz .LBB0_712
	s_and_b64 vcc, exec, s[6:7]
	v_mov_b32_e32 v100, v106
	s_cbranch_vccnz .LBB0_711
	v_mul_f32_e32 v100, 0xbfb8aa3b, v106
	v_exp_f32_e32 v100, v100
	s_nop 0
	v_add_f32_e32 v100, 1.0, v100
	v_rcp_f32_e32 v108, v100
	s_nop 0
	v_fma_f32 v110, -v100, v108, 1.0
	v_fma_f32 v107, v110, v108, v108
	v_div_fixup_f32 v100, v107, v100, 1.0

; __device__ __forceinline__ float sigmoidf_(float x) { return 1.0f / (1.0f + __expf(-x)); }
;     __device__ __forceinline__ void operator()(const f32x4 (&acc)[2][2][4][2], const Unit& u, int wr, int wc, int fr, int fq) const {
;     ...
;                         for (int i = 0; i < 4; ++i) { float xv = acc[ai][bj][m][n][i] + bv[bj][n][i]; float r;
;                             if (type < 2) { const float sg = sigmoidf_(xv); r = -expm1f(-0.606531f * sg); }
;                             else if (type == 2) r = sigmoidf_(xv);
.LBB0_713:
	v_mul_f32_e32 v100, 0xbfb8aa3b, v106
	v_exp_f32_e32 v100, v100
	s_nop 0
	v_add_f32_e32 v100, 1.0, v100
	v_rcp_f32_e32 v107, v100
	s_nop 0
	v_fma_f32 v109, -v100, v107, 1.0
	v_fma_f32 v106, v109, v107, v107
	v_div_fixup_f32 v100, v106, v100, 1.0
	v_mul_f32_e32 v100, 0xbf1b459e, v100
	v_mul_f32_e32 v106, 0x3fb8aa3b, v100
	v_rndne_f32_e32 v106, v106
	v_fmamk_f32 v107, v106, 0xbf317218, v100
	v_fmac_f32_e32 v107, 0x3102e308, v106
	v_cvt_i32_f32_e32 v108, v106
	v_fmamk_f32 v109, v107, 0x395133b1, v171
	v_fmaak_f32 v109, v107, v109, 0x3c0887f9
	v_fmaak_f32 v109, v107, v109, 0x3d2aaa81
	v_fmaak_f32 v109, v107, v109, 0x3e2aaaab
	v_ldexp_f32 v108, 1.0, v108
	v_fma_f32 v109, v107, v109, 0.5
	v_cmp_eq_f32_e32 vcc, s90, v106
	v_mul_f32_e32 v109, v107, v109
	v_fmac_f32_e32 v107, v107, v109
	v_cndmask_b32_e32 v106, v108, v172, vcc
	v_add_f32_e32 v108, -1.0, v106
	v_fmac_f32_e32 v108, v106, v107
	v_add_f32_e32 v106, v108, v108
	v_cndmask_b32_e32 v106, v108, v106, vcc
	v_cmp_nlt_f32_e32 vcc, s91, v100
	s_nop 1
	v_cndmask_b32_e64 v106, v173, -v106, vcc
	v_cmp_ngt_f32_e32 vcc, s92, v100
	s_nop 1
	v_cndmask_b32_e32 v100, 1.0, v106, vcc
.LBB0_714:
	v_add_f32_e32 v106, v101, v21
	s_and_b64 vcc, exec, s[8:9]
	s_mov_b64 s[14:15], -1
	s_cbranch_vccnz .LBB0_718
	s_and_b64 vcc, exec, s[6:7]
	v_mov_b32_e32 v101, v106
	s_cbranch_vccnz .LBB0_717
	v_mul_f32_e32 v101, 0xbfb8aa3b, v106
	v_exp_f32_e32 v101, v101
	s_nop 0
	v_add_f32_e32 v101, 1.0, v101
	v_rcp_f32_e32 v108, v101
	s_nop 0
	v_fma_f32 v110, -v101, v108, 1.0
	v_fma_f32 v107, v110, v108, v108
	v_div_fixup_f32 v101, v107, v101, 1.0

; __device__ __forceinline__ float sigmoidf_(float x) { return 1.0f / (1.0f + __expf(-x)); }
;     __device__ __forceinline__ void operator()(const f32x4 (&acc)[2][2][4][2], const Unit& u, int wr, int wc, int fr, int fq) const {
;     ...
;                         for (int i = 0; i < 4; ++i) { float xv = acc[ai][bj][m][n][i] + bv[bj][n][i]; float r;
;                             if (type < 2) { const float sg = sigmoidf_(xv); r = -expm1f(-0.606531f * sg); }
;                             else if (type == 2) r = sigmoidf_(xv);
.LBB0_719:
	v_mul_f32_e32 v101, 0xbfb8aa3b, v106
	v_exp_f32_e32 v101, v101
	s_nop 0
	v_add_f32_e32 v101, 1.0, v101
	v_rcp_f32_e32 v107, v101
	s_nop 0
	v_fma_f32 v109, -v101, v107, 1.0
	v_fma_f32 v106, v109, v107, v107
	v_div_fixup_f32 v101, v106, v101, 1.0
	v_mul_f32_e32 v101, 0xbf1b459e, v101
	v_mul_f32_e32 v106, 0x3fb8aa3b, v101
	v_rndne_f32_e32 v106, v106
	v_fmamk_f32 v107, v106, 0xbf317218, v101
	v_fmac_f32_e32 v107, 0x3102e308, v106
	v_cvt_i32_f32_e32 v108, v106
	v_fmamk_f32 v109, v107, 0x395133b1, v171
	v_fmaak_f32 v109, v107, v109, 0x3c0887f9
	v_fmaak_f32 v109, v107, v109, 0x3d2aaa81
	v_fmaak_f32 v109, v107, v109, 0x3e2aaaab
	v_ldexp_f32 v108, 1.0, v108
	v_fma_f32 v109, v107, v109, 0.5
	v_cmp_eq_f32_e32 vcc, s90, v106
	v_mul_f32_e32 v109, v107, v109
	v_fmac_f32_e32 v107, v107, v109
	v_cndmask_b32_e32 v106, v108, v172, vcc
	v_add_f32_e32 v108, -1.0, v106
	v_fmac_f32_e32 v108, v106, v107
	v_add_f32_e32 v106, v108, v108
	v_cndmask_b32_e32 v106, v108, v106, vcc
	v_cmp_nlt_f32_e32 vcc, s91, v101
	s_nop 1
	v_cndmask_b32_e64 v106, v173, -v106, vcc
	v_cmp_ngt_f32_e32 vcc, s92, v101
	s_nop 1
	v_cndmask_b32_e32 v101, 1.0, v106, vcc
.LBB0_720:
	v_add_f32_e32 v106, v102, v22
	s_and_b64 vcc, exec, s[8:9]
	s_mov_b64 s[14:15], -1
	s_cbranch_vccnz .LBB0_724
	s_and_b64 vcc, exec, s[6:7]
	v_mov_b32_e32 v102, v106
	s_cbranch_vccnz .LBB0_723
	v_mul_f32_e32 v102, 0xbfb8aa3b, v106
	v_exp_f32_e32 v102, v102
	s_nop 0
	v_add_f32_e32 v102, 1.0, v102
	v_rcp_f32_e32 v108, v102
	s_nop 0
	v_fma_f32 v110, -v102, v108, 1.0
	v_fma_f32 v107, v110, v108, v108
	v_div_fixup_f32 v102, v107, v102, 1.0

; __device__ __forceinline__ float sigmoidf_(float x) { return 1.0f / (1.0f + __expf(-x)); }
;     __device__ __forceinline__ void operator()(const f32x4 (&acc)[2][2][4][2], const Unit& u, int wr, int wc, int fr, int fq) const {
;     ...
;                         for (int i = 0; i < 4; ++i) { float xv = acc[ai][bj][m][n][i] + bv[bj][n][i]; float r;
;                             if (type < 2) { const float sg = sigmoidf_(xv); r = -expm1f(-0.606531f * sg); }
;                             else if (type == 2) r = sigmoidf_(xv);
.LBB0_725:
	v_mul_f32_e32 v102, 0xbfb8aa3b, v106
	v_exp_f32_e32 v102, v102
	s_nop 0
	v_add_f32_e32 v102, 1.0, v102
	v_rcp_f32_e32 v107, v102
	s_nop 0
	v_fma_f32 v109, -v102, v107, 1.0
	v_fma_f32 v106, v109, v107, v107
	v_div_fixup_f32 v102, v106, v102, 1.0
	v_mul_f32_e32 v102, 0xbf1b459e, v102
	v_mul_f32_e32 v106, 0x3fb8aa3b, v102
	v_rndne_f32_e32 v106, v106
	v_fmamk_f32 v107, v106, 0xbf317218, v102
	v_fmac_f32_e32 v107, 0x3102e308, v106
	v_cvt_i32_f32_e32 v108, v106
	v_fmamk_f32 v109, v107, 0x395133b1, v171
	v_fmaak_f32 v109, v107, v109, 0x3c0887f9
	v_fmaak_f32 v109, v107, v109, 0x3d2aaa81
	v_fmaak_f32 v109, v107, v109, 0x3e2aaaab
	v_ldexp_f32 v108, 1.0, v108
	v_fma_f32 v109, v107, v109, 0.5
	v_cmp_eq_f32_e32 vcc, s90, v106
	v_mul_f32_e32 v109, v107, v109
	v_fmac_f32_e32 v107, v107, v109
	v_cndmask_b32_e32 v106, v108, v172, vcc
	v_add_f32_e32 v108, -1.0, v106
	v_fmac_f32_e32 v108, v106, v107
	v_add_f32_e32 v106, v108, v108
	v_cndmask_b32_e32 v106, v108, v106, vcc
	v_cmp_nlt_f32_e32 vcc, s91, v102
	s_nop 1
	v_cndmask_b32_e64 v106, v173, -v106, vcc
	v_cmp_ngt_f32_e32 vcc, s92, v102
	s_nop 1
	v_cndmask_b32_e32 v102, 1.0, v106, vcc
.LBB0_726:
	v_add_f32_e32 v106, v103, v23
	s_and_b64 vcc, exec, s[8:9]
	s_mov_b64 s[14:15], -1
	s_cbranch_vccnz .LBB0_730
	s_and_b64 vcc, exec, s[6:7]
	v_mov_b32_e32 v103, v106
	s_cbranch_vccnz .LBB0_729
	v_mul_f32_e32 v103, 0xbfb8aa3b, v106
	v_exp_f32_e32 v103, v103
	s_nop 0
	v_add_f32_e32 v103, 1.0, v103
	v_rcp_f32_e32 v108, v103
	s_nop 0
	v_fma_f32 v110, -v103, v108, 1.0
	v_fma_f32 v107, v110, v108, v108
	v_div_fixup_f32 v103, v107, v103, 1.0

; __device__ __forceinline__ float sigmoidf_(float x) { return 1.0f / (1.0f + __expf(-x)); }
;     __device__ __forceinline__ void operator()(const f32x4 (&acc)[2][2][4][2], const Unit& u, int wr, int wc, int fr, int fq) const {
;     ...
;                         for (int i = 0; i < 4; ++i) { float xv = acc[ai][bj][m][n][i] + bv[bj][n][i]; float r;
;                             if (type < 2) { const float sg = sigmoidf_(xv); r = -expm1f(-0.606531f * sg); }
;                             else if (type == 2) r = sigmoidf_(xv);
.LBB0_731:
	v_mul_f32_e32 v103, 0xbfb8aa3b, v106
	v_exp_f32_e32 v103, v103
	s_nop 0
	v_add_f32_e32 v103, 1.0, v103
	v_rcp_f32_e32 v107, v103
	s_nop 0
	v_fma_f32 v109, -v103, v107, 1.0
	v_fma_f32 v106, v109, v107, v107
	v_div_fixup_f32 v103, v106, v103, 1.0
	v_mul_f32_e32 v103, 0xbf1b459e, v103
	v_mul_f32_e32 v106, 0x3fb8aa3b, v103
	v_rndne_f32_e32 v106, v106
	v_fmamk_f32 v107, v106, 0xbf317218, v103
	v_fmac_f32_e32 v107, 0x3102e308, v106
	v_cvt_i32_f32_e32 v108, v106
	v_fmamk_f32 v109, v107, 0x395133b1, v171
	v_fmaak_f32 v109, v107, v109, 0x3c0887f9
	v_fmaak_f32 v109, v107, v109, 0x3d2aaa81
	v_fmaak_f32 v109, v107, v109, 0x3e2aaaab
	v_ldexp_f32 v108, 1.0, v108
	v_fma_f32 v109, v107, v109, 0.5
	v_cmp_eq_f32_e32 vcc, s90, v106
	v_mul_f32_e32 v109, v107, v109
	v_fmac_f32_e32 v107, v107, v109
	v_cndmask_b32_e32 v106, v108, v172, vcc
	v_add_f32_e32 v108, -1.0, v106
	v_fmac_f32_e32 v108, v106, v107
	v_add_f32_e32 v106, v108, v108
	v_cndmask_b32_e32 v106, v108, v106, vcc
	v_cmp_nlt_f32_e32 vcc, s91, v103
	s_nop 1
	v_cndmask_b32_e64 v106, v173, -v106, vcc
	v_cmp_ngt_f32_e32 vcc, s92, v103
	s_nop 1
	v_cndmask_b32_e32 v103, 1.0, v106, vcc
.LBB0_732:
	v_add_f32_e32 v106, v96, v12
	s_and_b64 vcc, exec, s[8:9]
	s_mov_b64 s[14:15], -1
	s_cbranch_vccnz .LBB0_736
	s_and_b64 vcc, exec, s[6:7]
	v_mov_b32_e32 v96, v106
	s_cbranch_vccnz .LBB0_735
	v_mul_f32_e32 v96, 0xbfb8aa3b, v106
	v_exp_f32_e32 v96, v96
	s_nop 0
	v_add_f32_e32 v96, 1.0, v96
	v_rcp_f32_e32 v108, v96
	s_nop 0
	v_fma_f32 v110, -v96, v108, 1.0
	v_fma_f32 v107, v110, v108, v108
	v_div_fixup_f32 v96, v107, v96, 1.0

; __device__ __forceinline__ float sigmoidf_(float x) { return 1.0f / (1.0f + __expf(-x)); }
;     __device__ __forceinline__ void operator()(const f32x4 (&acc)[2][2][4][2], const Unit& u, int wr, int wc, int fr, int fq) const {
;     ...
;                         for (int i = 0; i < 4; ++i) { float xv = acc[ai][bj][m][n][i] + bv[bj][n][i]; float r;
;                             if (type < 2) { const float sg = sigmoidf_(xv); r = -expm1f(-0.606531f * sg); }
;                             else if (type == 2) r = sigmoidf_(xv);
.LBB0_737:
	v_mul_f32_e32 v96, 0xbfb8aa3b, v106
	v_exp_f32_e32 v96, v96
	s_nop 0
	v_add_f32_e32 v96, 1.0, v96
	v_rcp_f32_e32 v107, v96
	s_nop 0
	v_fma_f32 v109, -v96, v107, 1.0
	v_fma_f32 v106, v109, v107, v107
	v_div_fixup_f32 v96, v106, v96, 1.0
	v_mul_f32_e32 v96, 0xbf1b459e, v96
	v_mul_f32_e32 v106, 0x3fb8aa3b, v96
	v_rndne_f32_e32 v106, v106
	v_fmamk_f32 v107, v106, 0xbf317218, v96
	v_fmac_f32_e32 v107, 0x3102e308, v106
	v_cvt_i32_f32_e32 v108, v106
	v_fmamk_f32 v109, v107, 0x395133b1, v171
	v_fmaak_f32 v109, v107, v109, 0x3c0887f9
	v_fmaak_f32 v109, v107, v109, 0x3d2aaa81
	v_fmaak_f32 v109, v107, v109, 0x3e2aaaab
	v_ldexp_f32 v108, 1.0, v108
	v_fma_f32 v109, v107, v109, 0.5
	v_cmp_eq_f32_e32 vcc, s90, v106
	v_mul_f32_e32 v109, v107, v109
	v_fmac_f32_e32 v107, v107, v109
	v_cndmask_b32_e32 v106, v108, v172, vcc
	v_add_f32_e32 v108, -1.0, v106
	v_fmac_f32_e32 v108, v106, v107
	v_add_f32_e32 v106, v108, v108
	v_cndmask_b32_e32 v106, v108, v106, vcc
	v_cmp_nlt_f32_e32 vcc, s91, v96
	s_nop 1
	v_cndmask_b32_e64 v106, v173, -v106, vcc
	v_cmp_ngt_f32_e32 vcc, s92, v96
	s_nop 1
	v_cndmask_b32_e32 v96, 1.0, v106, vcc
.LBB0_738:
	v_add_f32_e32 v106, v97, v13
	s_and_b64 vcc, exec, s[8:9]
	s_mov_b64 s[14:15], -1
	s_cbranch_vccnz .LBB0_742
	s_and_b64 vcc, exec, s[6:7]
	v_mov_b32_e32 v97, v106
	s_cbranch_vccnz .LBB0_741
	v_mul_f32_e32 v97, 0xbfb8aa3b, v106
	v_exp_f32_e32 v97, v97
	s_nop 0
	v_add_f32_e32 v97, 1.0, v97
	v_rcp_f32_e32 v108, v97
	s_nop 0
	v_fma_f32 v110, -v97, v108, 1.0
	v_fma_f32 v107, v110, v108, v108
	v_div_fixup_f32 v97, v107, v97, 1.0

; __device__ __forceinline__ float sigmoidf_(float x) { return 1.0f / (1.0f + __expf(-x)); }
;     __device__ __forceinline__ void operator()(const f32x4 (&acc)[2][2][4][2], const Unit& u, int wr, int wc, int fr, int fq) const {
;     ...
;                         for (int i = 0; i < 4; ++i) { float xv = acc[ai][bj][m][n][i] + bv[bj][n][i]; float r;
;                             if (type < 2) { const float sg = sigmoidf_(xv); r = -expm1f(-0.606531f * sg); }
;                             else if (type == 2) r = sigmoidf_(xv);
.LBB0_743:
	v_mul_f32_e32 v97, 0xbfb8aa3b, v106
	v_exp_f32_e32 v97, v97
	s_nop 0
	v_add_f32_e32 v97, 1.0, v97
	v_rcp_f32_e32 v107, v97
	s_nop 0
	v_fma_f32 v109, -v97, v107, 1.0
	v_fma_f32 v106, v109, v107, v107
	v_div_fixup_f32 v97, v106, v97, 1.0
	v_mul_f32_e32 v97, 0xbf1b459e, v97
	v_mul_f32_e32 v106, 0x3fb8aa3b, v97
	v_rndne_f32_e32 v106, v106
	v_fmamk_f32 v107, v106, 0xbf317218, v97
	v_fmac_f32_e32 v107, 0x3102e308, v106
	v_cvt_i32_f32_e32 v108, v106
	v_fmamk_f32 v109, v107, 0x395133b1, v171
	v_fmaak_f32 v109, v107, v109, 0x3c0887f9
	v_fmaak_f32 v109, v107, v109, 0x3d2aaa81
	v_fmaak_f32 v109, v107, v109, 0x3e2aaaab
	v_ldexp_f32 v108, 1.0, v108
	v_fma_f32 v109, v107, v109, 0.5
	v_cmp_eq_f32_e32 vcc, s90, v106
	v_mul_f32_e32 v109, v107, v109
	v_fmac_f32_e32 v107, v107, v109
	v_cndmask_b32_e32 v106, v108, v172, vcc
	v_add_f32_e32 v108, -1.0, v106
	v_fmac_f32_e32 v108, v106, v107
	v_add_f32_e32 v106, v108, v108
	v_cndmask_b32_e32 v106, v108, v106, vcc
	v_cmp_nlt_f32_e32 vcc, s91, v97
	s_nop 1
	v_cndmask_b32_e64 v106, v173, -v106, vcc
	v_cmp_ngt_f32_e32 vcc, s92, v97
	s_nop 1
	v_cndmask_b32_e32 v97, 1.0, v106, vcc
.LBB0_744:
	v_add_f32_e32 v106, v98, v14
	s_and_b64 vcc, exec, s[8:9]
	s_mov_b64 s[14:15], -1
	s_cbranch_vccnz .LBB0_748
	s_and_b64 vcc, exec, s[6:7]
	v_mov_b32_e32 v98, v106
	s_cbranch_vccnz .LBB0_747
	v_mul_f32_e32 v98, 0xbfb8aa3b, v106
	v_exp_f32_e32 v98, v98
	s_nop 0
	v_add_f32_e32 v98, 1.0, v98
	v_rcp_f32_e32 v108, v98
	s_nop 0
	v_fma_f32 v110, -v98, v108, 1.0
	v_fma_f32 v107, v110, v108, v108
	v_div_fixup_f32 v98, v107, v98, 1.0

; __device__ __forceinline__ float sigmoidf_(float x) { return 1.0f / (1.0f + __expf(-x)); }
;     __device__ __forceinline__ void operator()(const f32x4 (&acc)[2][2][4][2], const Unit& u, int wr, int wc, int fr, int fq) const {
;     ...
;                         for (int i = 0; i < 4; ++i) { float xv = acc[ai][bj][m][n][i] + bv[bj][n][i]; float r;
;                             if (type < 2) { const float sg = sigmoidf_(xv); r = -expm1f(-0.606531f * sg); }
;                             else if (type == 2) r = sigmoidf_(xv);
.LBB0_749:
	v_mul_f32_e32 v98, 0xbfb8aa3b, v106
	v_exp_f32_e32 v98, v98
	s_nop 0
	v_add_f32_e32 v98, 1.0, v98
	v_rcp_f32_e32 v107, v98
	s_nop 0
	v_fma_f32 v109, -v98, v107, 1.0
	v_fma_f32 v106, v109, v107, v107
	v_div_fixup_f32 v98, v106, v98, 1.0
	v_mul_f32_e32 v98, 0xbf1b459e, v98
	v_mul_f32_e32 v106, 0x3fb8aa3b, v98
	v_rndne_f32_e32 v106, v106
	v_fmamk_f32 v107, v106, 0xbf317218, v98
	v_fmac_f32_e32 v107, 0x3102e308, v106
	v_cvt_i32_f32_e32 v108, v106
	v_fmamk_f32 v109, v107, 0x395133b1, v171
	v_fmaak_f32 v109, v107, v109, 0x3c0887f9
	v_fmaak_f32 v109, v107, v109, 0x3d2aaa81
	v_fmaak_f32 v109, v107, v109, 0x3e2aaaab
	v_ldexp_f32 v108, 1.0, v108
	v_fma_f32 v109, v107, v109, 0.5
	v_cmp_eq_f32_e32 vcc, s90, v106
	v_mul_f32_e32 v109, v107, v109
	v_fmac_f32_e32 v107, v107, v109
	v_cndmask_b32_e32 v106, v108, v172, vcc
	v_add_f32_e32 v108, -1.0, v106
	v_fmac_f32_e32 v108, v106, v107
	v_add_f32_e32 v106, v108, v108
	v_cndmask_b32_e32 v106, v108, v106, vcc
	v_cmp_nlt_f32_e32 vcc, s91, v98
	s_nop 1
	v_cndmask_b32_e64 v106, v173, -v106, vcc
	v_cmp_ngt_f32_e32 vcc, s92, v98
	s_nop 1
	v_cndmask_b32_e32 v98, 1.0, v106, vcc
.LBB0_750:
	v_add_f32_e32 v99, v99, v15
	s_and_b64 vcc, exec, s[8:9]
	s_mov_b64 s[14:15], -1
	s_cbranch_vccnz .LBB0_754
	s_and_b64 vcc, exec, s[6:7]
	v_mov_b32_e32 v106, v99
	s_cbranch_vccnz .LBB0_753
	v_mul_f32_e32 v106, 0xbfb8aa3b, v99
	v_exp_f32_e32 v106, v106
	s_nop 0
	v_add_f32_e32 v106, 1.0, v106
	v_rcp_f32_e32 v108, v106
	s_nop 0
	v_fma_f32 v110, -v106, v108, 1.0
	v_fma_f32 v107, v110, v108, v108
	v_div_fixup_f32 v106, v107, v106, 1.0

; __device__ __forceinline__ float sigmoidf_(float x) { return 1.0f / (1.0f + __expf(-x)); }
;     __device__ __forceinline__ void operator()(const f32x4 (&acc)[2][2][4][2], const Unit& u, int wr, int wc, int fr, int fq) const {
;     ...
;             for (int m = 0; m < 4; ++m) { f16* rowp = O + (size_t)(row0 + ai * 128 + m * 16) * 4096 + col0;
; #pragma unroll
;                 for (int bj = 0; bj < 2; ++bj) { f16x8 v;
; #pragma unroll
;                     for (int n = 0; n < 2; ++n)
; #pragma unroll
;                         for (int i = 0; i < 4; ++i) { float xv = acc[ai][bj][m][n][i] + bv[bj][n][i]; float r;
;                             if (type < 2) { const float sg = sigmoidf_(xv); r = -expm1f(-0.606531f * sg); }
;                             else if (type == 2) r = sigmoidf_(xv);
;                             else r = xv;
;                             v[4 * n + i] = (f16)r; }
;                     *(f16x8*)(rowp + bj * 128) = v; } }
.LBB0_755:
	v_mul_f32_e32 v99, 0xbfb8aa3b, v99
	v_exp_f32_e32 v99, v99
	s_nop 0
	v_add_f32_e32 v99, 1.0, v99
	v_rcp_f32_e32 v107, v99
	s_nop 0
	v_fma_f32 v109, -v99, v107, 1.0
	v_fma_f32 v106, v109, v107, v107
	v_div_fixup_f32 v99, v106, v99, 1.0
	v_mul_f32_e32 v99, 0xbf1b459e, v99
	v_mul_f32_e32 v106, 0x3fb8aa3b, v99
	v_rndne_f32_e32 v106, v106
	v_fmamk_f32 v107, v106, 0xbf317218, v99
	v_fmac_f32_e32 v107, 0x3102e308, v106
	v_cvt_i32_f32_e32 v108, v106
	v_fmamk_f32 v109, v107, 0x395133b1, v171
	v_fmaak_f32 v109, v107, v109, 0x3c0887f9
	v_fmaak_f32 v109, v107, v109, 0x3d2aaa81
	v_fmaak_f32 v109, v107, v109, 0x3e2aaaab
	v_ldexp_f32 v108, 1.0, v108
	v_fma_f32 v109, v107, v109, 0.5
	v_cmp_eq_f32_e32 vcc, s90, v106
	v_mul_f32_e32 v109, v107, v109
	v_fmac_f32_e32 v107, v107, v109
	v_cndmask_b32_e32 v106, v108, v172, vcc
	v_add_f32_e32 v108, -1.0, v106
	v_fmac_f32_e32 v108, v106, v107
	v_add_f32_e32 v106, v108, v108
	v_cndmask_b32_e32 v106, v108, v106, vcc
	v_cmp_nlt_f32_e32 vcc, s91, v99
	s_nop 1
	v_cndmask_b32_e64 v106, v173, -v106, vcc
	v_cmp_ngt_f32_e32 vcc, s92, v99
	s_nop 1
	v_cndmask_b32_e32 v106, 1.0, v106, vcc
.LBB0_756:
	v_cvt_pk_f16_f32 v99, v98, v106
	v_cvt_pk_f16_f32 v98, v96, v97
	v_cvt_pk_f16_f32 v97, v102, v103
	v_cvt_pk_f16_f32 v96, v100, v101
	global_store_dwordx4 v[104:105], v[96:99], off offset:256
	s_and_b64 vcc, exec, s[8:9]
	s_mov_b64 s[14:15], -1
	v_add_f32_e32 v96, v92, v32
	s_cbranch_vccnz .LBB0_760
	s_and_b64 vcc, exec, s[6:7]
	v_mov_b32_e32 v92, v96
	s_cbranch_vccnz .LBB0_759
	v_mul_f32_e32 v92, 0xbfb8aa3b, v96
	v_exp_f32_e32 v92, v92
	s_nop 0
	v_add_f32_e32 v92, 1.0, v92
	v_rcp_f32_e32 v98, v92
	s_nop 0
	v_fma_f32 v100, -v92, v98, 1.0
	v_fma_f32 v97, v100, v98, v98
	v_div_fixup_f32 v92, v97, v92, 1.0

; __device__ __forceinline__ float sigmoidf_(float x) { return 1.0f / (1.0f + __expf(-x)); }
;     __device__ __forceinline__ void operator()(const f32x4 (&acc)[2][2][4][2], const Unit& u, int wr, int wc, int fr, int fq) const {
;     ...
;                         for (int i = 0; i < 4; ++i) { float xv = acc[ai][bj][m][n][i] + bv[bj][n][i]; float r;
;                             if (type < 2) { const float sg = sigmoidf_(xv); r = -expm1f(-0.606531f * sg); }
;                             else if (type == 2) r = sigmoidf_(xv);
.LBB0_761:
	v_mul_f32_e32 v92, 0xbfb8aa3b, v96
	v_exp_f32_e32 v92, v92
	s_nop 0
	v_add_f32_e32 v92, 1.0, v92
	v_rcp_f32_e32 v97, v92
	s_nop 0
	v_fma_f32 v99, -v92, v97, 1.0
	v_fma_f32 v96, v99, v97, v97
	v_div_fixup_f32 v92, v96, v92, 1.0
	v_mul_f32_e32 v92, 0xbf1b459e, v92
	v_mul_f32_e32 v96, 0x3fb8aa3b, v92
	v_rndne_f32_e32 v96, v96
	v_fmamk_f32 v97, v96, 0xbf317218, v92
	v_fmac_f32_e32 v97, 0x3102e308, v96
	v_cvt_i32_f32_e32 v98, v96
	v_fmamk_f32 v99, v97, 0x395133b1, v171
	v_fmaak_f32 v99, v97, v99, 0x3c0887f9
	v_fmaak_f32 v99, v97, v99, 0x3d2aaa81
	v_fmaak_f32 v99, v97, v99, 0x3e2aaaab
	v_ldexp_f32 v98, 1.0, v98
	v_fma_f32 v99, v97, v99, 0.5
	v_cmp_eq_f32_e32 vcc, s90, v96
	v_mul_f32_e32 v99, v97, v99
	v_fmac_f32_e32 v97, v97, v99
	v_cndmask_b32_e32 v96, v98, v172, vcc
	v_add_f32_e32 v98, -1.0, v96
	v_fmac_f32_e32 v98, v96, v97
	v_add_f32_e32 v96, v98, v98
	v_cndmask_b32_e32 v96, v98, v96, vcc
	v_cmp_nlt_f32_e32 vcc, s91, v92
	s_nop 1
	v_cndmask_b32_e64 v96, v173, -v96, vcc
	v_cmp_ngt_f32_e32 vcc, s92, v92
	s_nop 1
	v_cndmask_b32_e32 v92, 1.0, v96, vcc
.LBB0_762:
	v_add_f32_e32 v96, v93, v33
	s_and_b64 vcc, exec, s[8:9]
	s_mov_b64 s[14:15], -1
	s_cbranch_vccnz .LBB0_766
	s_and_b64 vcc, exec, s[6:7]
	v_mov_b32_e32 v93, v96
	s_cbranch_vccnz .LBB0_765
	v_mul_f32_e32 v93, 0xbfb8aa3b, v96
	v_exp_f32_e32 v93, v93
	s_nop 0
	v_add_f32_e32 v93, 1.0, v93
	v_rcp_f32_e32 v98, v93
	s_nop 0
	v_fma_f32 v100, -v93, v98, 1.0
	v_fma_f32 v97, v100, v98, v98
	v_div_fixup_f32 v93, v97, v93, 1.0

; __device__ __forceinline__ float sigmoidf_(float x) { return 1.0f / (1.0f + __expf(-x)); }
;     __device__ __forceinline__ void operator()(const f32x4 (&acc)[2][2][4][2], const Unit& u, int wr, int wc, int fr, int fq) const {
;     ...
;                         for (int i = 0; i < 4; ++i) { float xv = acc[ai][bj][m][n][i] + bv[bj][n][i]; float r;
;                             if (type < 2) { const float sg = sigmoidf_(xv); r = -expm1f(-0.606531f * sg); }
;                             else if (type == 2) r = sigmoidf_(xv);
.LBB0_767:
	v_mul_f32_e32 v93, 0xbfb8aa3b, v96
	v_exp_f32_e32 v93, v93
	s_nop 0
	v_add_f32_e32 v93, 1.0, v93
	v_rcp_f32_e32 v97, v93
	s_nop 0
	v_fma_f32 v99, -v93, v97, 1.0
	v_fma_f32 v96, v99, v97, v97
	v_div_fixup_f32 v93, v96, v93, 1.0
	v_mul_f32_e32 v93, 0xbf1b459e, v93
	v_mul_f32_e32 v96, 0x3fb8aa3b, v93
	v_rndne_f32_e32 v96, v96
	v_fmamk_f32 v97, v96, 0xbf317218, v93
	v_fmac_f32_e32 v97, 0x3102e308, v96
	v_cvt_i32_f32_e32 v98, v96
	v_fmamk_f32 v99, v97, 0x395133b1, v171
	v_fmaak_f32 v99, v97, v99, 0x3c0887f9
	v_fmaak_f32 v99, v97, v99, 0x3d2aaa81
	v_fmaak_f32 v99, v97, v99, 0x3e2aaaab
	v_ldexp_f32 v98, 1.0, v98
	v_fma_f32 v99, v97, v99, 0.5
	v_cmp_eq_f32_e32 vcc, s90, v96
	v_mul_f32_e32 v99, v97, v99
	v_fmac_f32_e32 v97, v97, v99
	v_cndmask_b32_e32 v96, v98, v172, vcc
	v_add_f32_e32 v98, -1.0, v96
	v_fmac_f32_e32 v98, v96, v97
	v_add_f32_e32 v96, v98, v98
	v_cndmask_b32_e32 v96, v98, v96, vcc
	v_cmp_nlt_f32_e32 vcc, s91, v93
	s_nop 1
	v_cndmask_b32_e64 v96, v173, -v96, vcc
	v_cmp_ngt_f32_e32 vcc, s92, v93
	s_nop 1
	v_cndmask_b32_e32 v93, 1.0, v96, vcc
.LBB0_768:
	v_add_f32_e32 v96, v94, v34
	s_and_b64 vcc, exec, s[8:9]
	s_mov_b64 s[14:15], -1
	s_cbranch_vccnz .LBB0_772
	s_and_b64 vcc, exec, s[6:7]
	v_mov_b32_e32 v94, v96
	s_cbranch_vccnz .LBB0_771
	v_mul_f32_e32 v94, 0xbfb8aa3b, v96
	v_exp_f32_e32 v94, v94
	s_nop 0
	v_add_f32_e32 v94, 1.0, v94
	v_rcp_f32_e32 v98, v94
	s_nop 0
	v_fma_f32 v100, -v94, v98, 1.0
	v_fma_f32 v97, v100, v98, v98
	v_div_fixup_f32 v94, v97, v94, 1.0

; __device__ __forceinline__ float sigmoidf_(float x) { return 1.0f / (1.0f + __expf(-x)); }
;     __device__ __forceinline__ void operator()(const f32x4 (&acc)[2][2][4][2], const Unit& u, int wr, int wc, int fr, int fq) const {
;     ...
;                         for (int i = 0; i < 4; ++i) { float xv = acc[ai][bj][m][n][i] + bv[bj][n][i]; float r;
;                             if (type < 2) { const float sg = sigmoidf_(xv); r = -expm1f(-0.606531f * sg); }
;                             else if (type == 2) r = sigmoidf_(xv);
.LBB0_773:
	v_mul_f32_e32 v94, 0xbfb8aa3b, v96
	v_exp_f32_e32 v94, v94
	s_nop 0
	v_add_f32_e32 v94, 1.0, v94
	v_rcp_f32_e32 v97, v94
	s_nop 0
	v_fma_f32 v99, -v94, v97, 1.0
	v_fma_f32 v96, v99, v97, v97
	v_div_fixup_f32 v94, v96, v94, 1.0
	v_mul_f32_e32 v94, 0xbf1b459e, v94
	v_mul_f32_e32 v96, 0x3fb8aa3b, v94
	v_rndne_f32_e32 v96, v96
	v_fmamk_f32 v97, v96, 0xbf317218, v94
	v_fmac_f32_e32 v97, 0x3102e308, v96
	v_cvt_i32_f32_e32 v98, v96
	v_fmamk_f32 v99, v97, 0x395133b1, v171
	v_fmaak_f32 v99, v97, v99, 0x3c0887f9
	v_fmaak_f32 v99, v97, v99, 0x3d2aaa81
	v_fmaak_f32 v99, v97, v99, 0x3e2aaaab
	v_ldexp_f32 v98, 1.0, v98
	v_fma_f32 v99, v97, v99, 0.5
	v_cmp_eq_f32_e32 vcc, s90, v96
	v_mul_f32_e32 v99, v97, v99
	v_fmac_f32_e32 v97, v97, v99
	v_cndmask_b32_e32 v96, v98, v172, vcc
	v_add_f32_e32 v98, -1.0, v96
	v_fmac_f32_e32 v98, v96, v97
	v_add_f32_e32 v96, v98, v98
	v_cndmask_b32_e32 v96, v98, v96, vcc
	v_cmp_nlt_f32_e32 vcc, s91, v94
	s_nop 1
	v_cndmask_b32_e64 v96, v173, -v96, vcc
	v_cmp_ngt_f32_e32 vcc, s92, v94
	s_nop 1
	v_cndmask_b32_e32 v94, 1.0, v96, vcc
.LBB0_774:
	v_add_f32_e32 v96, v95, v35
	s_and_b64 vcc, exec, s[8:9]
	s_mov_b64 s[14:15], -1
	s_cbranch_vccnz .LBB0_778
	s_and_b64 vcc, exec, s[6:7]
	v_mov_b32_e32 v95, v96
	s_cbranch_vccnz .LBB0_777
	v_mul_f32_e32 v95, 0xbfb8aa3b, v96
	v_exp_f32_e32 v95, v95
	s_nop 0
	v_add_f32_e32 v95, 1.0, v95
	v_rcp_f32_e32 v98, v95
	s_nop 0
	v_fma_f32 v100, -v95, v98, 1.0
	v_fma_f32 v97, v100, v98, v98
	v_div_fixup_f32 v95, v97, v95, 1.0

; __device__ __forceinline__ float sigmoidf_(float x) { return 1.0f / (1.0f + __expf(-x)); }
;     __device__ __forceinline__ void operator()(const f32x4 (&acc)[2][2][4][2], const Unit& u, int wr, int wc, int fr, int fq) const {
;     ...
;                         for (int i = 0; i < 4; ++i) { float xv = acc[ai][bj][m][n][i] + bv[bj][n][i]; float r;
;                             if (type < 2) { const float sg = sigmoidf_(xv); r = -expm1f(-0.606531f * sg); }
;                             else if (type == 2) r = sigmoidf_(xv);
.LBB0_779:
	v_mul_f32_e32 v95, 0xbfb8aa3b, v96
	v_exp_f32_e32 v95, v95
	s_nop 0
	v_add_f32_e32 v95, 1.0, v95
	v_rcp_f32_e32 v97, v95
	s_nop 0
	v_fma_f32 v99, -v95, v97, 1.0
	v_fma_f32 v96, v99, v97, v97
	v_div_fixup_f32 v95, v96, v95, 1.0
	v_mul_f32_e32 v95, 0xbf1b459e, v95
	v_mul_f32_e32 v96, 0x3fb8aa3b, v95
	v_rndne_f32_e32 v96, v96
	v_fmamk_f32 v97, v96, 0xbf317218, v95
	v_fmac_f32_e32 v97, 0x3102e308, v96
	v_cvt_i32_f32_e32 v98, v96
	v_fmamk_f32 v99, v97, 0x395133b1, v171
	v_fmaak_f32 v99, v97, v99, 0x3c0887f9
	v_fmaak_f32 v99, v97, v99, 0x3d2aaa81
	v_fmaak_f32 v99, v97, v99, 0x3e2aaaab
	v_ldexp_f32 v98, 1.0, v98
	v_fma_f32 v99, v97, v99, 0.5
	v_cmp_eq_f32_e32 vcc, s90, v96
	v_mul_f32_e32 v99, v97, v99
	v_fmac_f32_e32 v97, v97, v99
	v_cndmask_b32_e32 v96, v98, v172, vcc
	v_add_f32_e32 v98, -1.0, v96
	v_fmac_f32_e32 v98, v96, v97
	v_add_f32_e32 v96, v98, v98
	v_cndmask_b32_e32 v96, v98, v96, vcc
	v_cmp_nlt_f32_e32 vcc, s91, v95
	s_nop 1
	v_cndmask_b32_e64 v96, v173, -v96, vcc
	v_cmp_ngt_f32_e32 vcc, s92, v95
	s_nop 1
	v_cndmask_b32_e32 v95, 1.0, v96, vcc
.LBB0_780:
	v_add_f32_e32 v88, v88, v28
	s_and_b64 vcc, exec, s[8:9]
	s_mov_b64 s[14:15], -1
	s_cbranch_vccnz .LBB0_784
	s_and_b64 vcc, exec, s[6:7]
	v_mov_b32_e32 v96, v88
	s_cbranch_vccnz .LBB0_783
	v_mul_f32_e32 v96, 0xbfb8aa3b, v88
	v_exp_f32_e32 v96, v96
	s_nop 0
	v_add_f32_e32 v96, 1.0, v96
	v_rcp_f32_e32 v98, v96
	s_nop 0
	v_fma_f32 v100, -v96, v98, 1.0
	v_fma_f32 v97, v100, v98, v98
	v_div_fixup_f32 v96, v97, v96, 1.0

; __device__ __forceinline__ float sigmoidf_(float x) { return 1.0f / (1.0f + __expf(-x)); }
;     __device__ __forceinline__ void operator()(const f32x4 (&acc)[2][2][4][2], const Unit& u, int wr, int wc, int fr, int fq) const {
;     ...
;                         for (int i = 0; i < 4; ++i) { float xv = acc[ai][bj][m][n][i] + bv[bj][n][i]; float r;
;                             if (type < 2) { const float sg = sigmoidf_(xv); r = -expm1f(-0.606531f * sg); }
;                             else if (type == 2) r = sigmoidf_(xv);
.LBB0_785:
	v_mul_f32_e32 v88, 0xbfb8aa3b, v88
	v_exp_f32_e32 v88, v88
	s_nop 0
	v_add_f32_e32 v88, 1.0, v88
	v_rcp_f32_e32 v97, v88
	s_nop 0
	v_fma_f32 v99, -v88, v97, 1.0
	v_fma_f32 v96, v99, v97, v97
	v_div_fixup_f32 v88, v96, v88, 1.0
	v_mul_f32_e32 v88, 0xbf1b459e, v88
	v_mul_f32_e32 v96, 0x3fb8aa3b, v88
	v_rndne_f32_e32 v96, v96
	v_fmamk_f32 v97, v96, 0xbf317218, v88
	v_fmac_f32_e32 v97, 0x3102e308, v96
	v_cvt_i32_f32_e32 v98, v96
	v_fmamk_f32 v99, v97, 0x395133b1, v171
	v_fmaak_f32 v99, v97, v99, 0x3c0887f9
	v_fmaak_f32 v99, v97, v99, 0x3d2aaa81
	v_fmaak_f32 v99, v97, v99, 0x3e2aaaab
	v_ldexp_f32 v98, 1.0, v98
	v_fma_f32 v99, v97, v99, 0.5
	v_cmp_eq_f32_e32 vcc, s90, v96
	v_mul_f32_e32 v99, v97, v99
	v_fmac_f32_e32 v97, v97, v99
	v_cndmask_b32_e32 v96, v98, v172, vcc
	v_add_f32_e32 v98, -1.0, v96
	v_fmac_f32_e32 v98, v96, v97
	v_add_f32_e32 v96, v98, v98
	v_cndmask_b32_e32 v96, v98, v96, vcc
	v_cmp_nlt_f32_e32 vcc, s91, v88
	s_nop 1
	v_cndmask_b32_e64 v96, v173, -v96, vcc
	v_cmp_ngt_f32_e32 vcc, s92, v88
	s_nop 1
	v_cndmask_b32_e32 v96, 1.0, v96, vcc
.LBB0_786:
	v_add_f32_e32 v88, v89, v29
	s_and_b64 vcc, exec, s[8:9]
	s_mov_b64 s[14:15], -1
	s_cbranch_vccnz .LBB0_790
	s_and_b64 vcc, exec, s[6:7]
	v_mov_b32_e32 v97, v88
	s_cbranch_vccnz .LBB0_789
	v_mul_f32_e32 v89, 0xbfb8aa3b, v88
	v_exp_f32_e32 v89, v89
	s_nop 0
	v_add_f32_e32 v89, 1.0, v89
	v_rcp_f32_e32 v98, v89
	s_nop 0
	v_fma_f32 v100, -v89, v98, 1.0
	v_fma_f32 v97, v100, v98, v98
	v_div_fixup_f32 v97, v97, v89, 1.0

; __device__ __forceinline__ float sigmoidf_(float x) { return 1.0f / (1.0f + __expf(-x)); }
;     __device__ __forceinline__ void operator()(const f32x4 (&acc)[2][2][4][2], const Unit& u, int wr, int wc, int fr, int fq) const {
;     ...
;                         for (int i = 0; i < 4; ++i) { float xv = acc[ai][bj][m][n][i] + bv[bj][n][i]; float r;
;                             if (type < 2) { const float sg = sigmoidf_(xv); r = -expm1f(-0.606531f * sg); }
;                             else if (type == 2) r = sigmoidf_(xv);
.LBB0_791:
	v_mul_f32_e32 v88, 0xbfb8aa3b, v88
	v_exp_f32_e32 v88, v88
	s_nop 0
	v_add_f32_e32 v88, 1.0, v88
	v_rcp_f32_e32 v97, v88
	s_nop 0
	v_fma_f32 v99, -v88, v97, 1.0
	v_fma_f32 v89, v99, v97, v97
	v_div_fixup_f32 v88, v89, v88, 1.0
	v_mul_f32_e32 v88, 0xbf1b459e, v88
	v_mul_f32_e32 v89, 0x3fb8aa3b, v88
	v_rndne_f32_e32 v89, v89
	v_fmamk_f32 v97, v89, 0xbf317218, v88
	v_fmac_f32_e32 v97, 0x3102e308, v89
	v_cvt_i32_f32_e32 v98, v89
	v_fmamk_f32 v99, v97, 0x395133b1, v171
	v_fmaak_f32 v99, v97, v99, 0x3c0887f9
	v_fmaak_f32 v99, v97, v99, 0x3d2aaa81
	v_fmaak_f32 v99, v97, v99, 0x3e2aaaab
	v_ldexp_f32 v98, 1.0, v98
	v_fma_f32 v99, v97, v99, 0.5
	v_cmp_eq_f32_e32 vcc, s90, v89
	v_mul_f32_e32 v99, v97, v99
	v_fmac_f32_e32 v97, v97, v99
	v_cndmask_b32_e32 v89, v98, v172, vcc
	v_add_f32_e32 v98, -1.0, v89
	v_fmac_f32_e32 v98, v89, v97
	v_add_f32_e32 v89, v98, v98
	v_cndmask_b32_e32 v89, v98, v89, vcc
	v_cmp_nlt_f32_e32 vcc, s91, v88
	s_nop 1
	v_cndmask_b32_e64 v89, v173, -v89, vcc
	v_cmp_ngt_f32_e32 vcc, s92, v88
	s_nop 1
	v_cndmask_b32_e32 v97, 1.0, v89, vcc
.LBB0_792:
	v_add_f32_e32 v88, v90, v30
	s_and_b64 vcc, exec, s[8:9]
	s_mov_b64 s[14:15], -1
	s_cbranch_vccnz .LBB0_796
	s_and_b64 vcc, exec, s[6:7]
	v_mov_b32_e32 v90, v88
	s_cbranch_vccnz .LBB0_795
	v_mul_f32_e32 v89, 0xbfb8aa3b, v88
	v_exp_f32_e32 v89, v89
	s_nop 0
	v_add_f32_e32 v89, 1.0, v89
	v_rcp_f32_e32 v98, v89
	s_nop 0
	v_fma_f32 v100, -v89, v98, 1.0
	v_fma_f32 v90, v100, v98, v98
	v_div_fixup_f32 v90, v90, v89, 1.0

; __device__ __forceinline__ float sigmoidf_(float x) { return 1.0f / (1.0f + __expf(-x)); }
;     __device__ __forceinline__ void operator()(const f32x4 (&acc)[2][2][4][2], const Unit& u, int wr, int wc, int fr, int fq) const {
;     ...
;                         for (int i = 0; i < 4; ++i) { float xv = acc[ai][bj][m][n][i] + bv[bj][n][i]; float r;
;                             if (type < 2) { const float sg = sigmoidf_(xv); r = -expm1f(-0.606531f * sg); }
;                             else if (type == 2) r = sigmoidf_(xv);
.LBB0_797:
	v_mul_f32_e32 v88, 0xbfb8aa3b, v88
	v_exp_f32_e32 v88, v88
	s_nop 0
	v_add_f32_e32 v88, 1.0, v88
	v_rcp_f32_e32 v90, v88
	s_nop 0
	v_fma_f32 v99, -v88, v90, 1.0
	v_fma_f32 v89, v99, v90, v90
	v_div_fixup_f32 v88, v89, v88, 1.0
	v_mul_f32_e32 v88, 0xbf1b459e, v88
	v_mul_f32_e32 v89, 0x3fb8aa3b, v88
	v_rndne_f32_e32 v89, v89
	v_fmamk_f32 v90, v89, 0xbf317218, v88
	v_fmac_f32_e32 v90, 0x3102e308, v89
	v_cvt_i32_f32_e32 v98, v89
	v_fmamk_f32 v99, v90, 0x395133b1, v171
	v_fmaak_f32 v99, v90, v99, 0x3c0887f9
	v_fmaak_f32 v99, v90, v99, 0x3d2aaa81
	v_fmaak_f32 v99, v90, v99, 0x3e2aaaab
	v_ldexp_f32 v98, 1.0, v98
	v_fma_f32 v99, v90, v99, 0.5
	v_cmp_eq_f32_e32 vcc, s90, v89
	v_mul_f32_e32 v99, v90, v99
	v_fmac_f32_e32 v90, v90, v99
	v_cndmask_b32_e32 v89, v98, v172, vcc
	v_add_f32_e32 v98, -1.0, v89
	v_fmac_f32_e32 v98, v89, v90
	v_add_f32_e32 v89, v98, v98
	v_cndmask_b32_e32 v89, v98, v89, vcc
	v_cmp_nlt_f32_e32 vcc, s91, v88
	s_nop 1
	v_cndmask_b32_e64 v89, v173, -v89, vcc
	v_cmp_ngt_f32_e32 vcc, s92, v88
	s_nop 1
	v_cndmask_b32_e32 v90, 1.0, v89, vcc
.LBB0_798:
	v_add_f32_e32 v88, v91, v31
	s_and_b64 vcc, exec, s[8:9]
	s_mov_b64 s[14:15], -1
	s_cbranch_vccnz .LBB0_802
	s_and_b64 vcc, exec, s[6:7]
	v_mov_b32_e32 v91, v88
	s_cbranch_vccnz .LBB0_801
	v_mul_f32_e32 v89, 0xbfb8aa3b, v88
	v_exp_f32_e32 v89, v89
	s_nop 0
	v_add_f32_e32 v89, 1.0, v89
	v_rcp_f32_e32 v98, v89
	s_nop 0
	v_fma_f32 v100, -v89, v98, 1.0
	v_fma_f32 v91, v100, v98, v98
	v_div_fixup_f32 v91, v91, v89, 1.0

; __device__ __forceinline__ float sigmoidf_(float x) { return 1.0f / (1.0f + __expf(-x)); }
;     __device__ __forceinline__ void operator()(const f32x4 (&acc)[2][2][4][2], const Unit& u, int wr, int wc, int fr, int fq) const {
;     ...
;                         for (int i = 0; i < 4; ++i) { float xv = acc[ai][bj][m][n][i] + bv[bj][n][i]; float r;
;                             if (type < 2) { const float sg = sigmoidf_(xv); r = -expm1f(-0.606531f * sg); }
;                             else if (type == 2) r = sigmoidf_(xv);
;                             else r = xv;
;                             v[4 * n + i] = (f16)r; }
;                     *(f16x8*)(rowp + bj * 128) = v; } }
.LBB0_803:
	v_mul_f32_e32 v88, 0xbfb8aa3b, v88
	v_exp_f32_e32 v88, v88
	s_nop 0
	v_add_f32_e32 v88, 1.0, v88
	v_rcp_f32_e32 v91, v88
	s_nop 0
	v_fma_f32 v99, -v88, v91, 1.0
	v_fma_f32 v89, v99, v91, v91
	v_div_fixup_f32 v88, v89, v88, 1.0
	v_mul_f32_e32 v88, 0xbf1b459e, v88
	v_mul_f32_e32 v89, 0x3fb8aa3b, v88
	v_rndne_f32_e32 v89, v89
	v_fmamk_f32 v91, v89, 0xbf317218, v88
	v_fmac_f32_e32 v91, 0x3102e308, v89
	v_cvt_i32_f32_e32 v98, v89
	v_fmamk_f32 v99, v91, 0x395133b1, v171
	v_fmaak_f32 v99, v91, v99, 0x3c0887f9
	v_fmaak_f32 v99, v91, v99, 0x3d2aaa81
	v_fmaak_f32 v99, v91, v99, 0x3e2aaaab
	v_ldexp_f32 v98, 1.0, v98
	v_fma_f32 v99, v91, v99, 0.5
	v_cmp_eq_f32_e32 vcc, s90, v89
	v_mul_f32_e32 v99, v91, v99
	v_fmac_f32_e32 v91, v91, v99
	v_cndmask_b32_e32 v89, v98, v172, vcc
	v_add_f32_e32 v98, -1.0, v89
	v_fmac_f32_e32 v98, v89, v91
	v_add_f32_e32 v89, v98, v98
	v_cndmask_b32_e32 v89, v98, v89, vcc
	v_cmp_nlt_f32_e32 vcc, s91, v88
	s_nop 1
	v_cndmask_b32_e64 v89, v173, -v89, vcc
	v_cmp_ngt_f32_e32 vcc, s92, v88
	s_nop 1
	v_cndmask_b32_e32 v91, 1.0, v89, vcc
.LBB0_804:
	v_or_b32_e32 v88, 48, v138
	v_ashrrev_i32_e32 v89, 31, v88
	v_lshlrev_b64 v[88:89], 13, v[88:89]
	v_lshl_add_u64 v[88:89], s[28:29], 0, v[88:89]
	v_lshl_add_u64 v[88:89], v[136:137], 1, v[88:89]
	v_cvt_pk_f16_f32 v99, v90, v91
	v_cvt_pk_f16_f32 v98, v96, v97
	v_cvt_pk_f16_f32 v97, v94, v95
	v_cvt_pk_f16_f32 v96, v92, v93
	v_add_f32_e32 v90, v84, v20
	s_and_b64 vcc, exec, s[8:9]
	s_mov_b64 s[14:15], -1
	global_store_dwordx4 v[88:89], v[96:99], off
	s_cbranch_vccnz .LBB0_808
	s_and_b64 vcc, exec, s[6:7]
	v_mov_b32_e32 v84, v90
	s_cbranch_vccnz .LBB0_807
	v_mul_f32_e32 v84, 0xbfb8aa3b, v90
	v_exp_f32_e32 v84, v84
	s_nop 0
	v_add_f32_e32 v84, 1.0, v84
	v_rcp_f32_e32 v92, v84
	s_nop 0
	v_fma_f32 v94, -v84, v92, 1.0
	v_fma_f32 v91, v94, v92, v92
	v_div_fixup_f32 v84, v91, v84, 1.0

; __device__ __forceinline__ float sigmoidf_(float x) { return 1.0f / (1.0f + __expf(-x)); }
;     __device__ __forceinline__ void operator()(const f32x4 (&acc)[2][2][4][2], const Unit& u, int wr, int wc, int fr, int fq) const {
;     ...
;                         for (int i = 0; i < 4; ++i) { float xv = acc[ai][bj][m][n][i] + bv[bj][n][i]; float r;
;                             if (type < 2) { const float sg = sigmoidf_(xv); r = -expm1f(-0.606531f * sg); }
;                             else if (type == 2) r = sigmoidf_(xv);
.LBB0_809:
	v_mul_f32_e32 v84, 0xbfb8aa3b, v90
	v_exp_f32_e32 v84, v84
	s_nop 0
	v_add_f32_e32 v84, 1.0, v84
	v_rcp_f32_e32 v91, v84
	s_nop 0
	v_fma_f32 v93, -v84, v91, 1.0
	v_fma_f32 v90, v93, v91, v91
	v_div_fixup_f32 v84, v90, v84, 1.0
	v_mul_f32_e32 v84, 0xbf1b459e, v84
	v_mul_f32_e32 v90, 0x3fb8aa3b, v84
	v_rndne_f32_e32 v90, v90
	v_fmamk_f32 v91, v90, 0xbf317218, v84
	v_fmac_f32_e32 v91, 0x3102e308, v90
	v_cvt_i32_f32_e32 v92, v90
	v_fmamk_f32 v93, v91, 0x395133b1, v171
	v_fmaak_f32 v93, v91, v93, 0x3c0887f9
	v_fmaak_f32 v93, v91, v93, 0x3d2aaa81
	v_fmaak_f32 v93, v91, v93, 0x3e2aaaab
	v_ldexp_f32 v92, 1.0, v92
	v_fma_f32 v93, v91, v93, 0.5
	v_cmp_eq_f32_e32 vcc, s90, v90
	v_mul_f32_e32 v93, v91, v93
	v_fmac_f32_e32 v91, v91, v93
	v_cndmask_b32_e32 v90, v92, v172, vcc
	v_add_f32_e32 v92, -1.0, v90
	v_fmac_f32_e32 v92, v90, v91
	v_add_f32_e32 v90, v92, v92
	v_cndmask_b32_e32 v90, v92, v90, vcc
	v_cmp_nlt_f32_e32 vcc, s91, v84
	s_nop 1
	v_cndmask_b32_e64 v90, v173, -v90, vcc
	v_cmp_ngt_f32_e32 vcc, s92, v84
	s_nop 1
	v_cndmask_b32_e32 v84, 1.0, v90, vcc
.LBB0_810:
	v_add_f32_e32 v90, v85, v21
	s_and_b64 vcc, exec, s[8:9]
	s_mov_b64 s[14:15], -1
	s_cbranch_vccnz .LBB0_814
	s_and_b64 vcc, exec, s[6:7]
	v_mov_b32_e32 v85, v90
	s_cbranch_vccnz .LBB0_813
	v_mul_f32_e32 v85, 0xbfb8aa3b, v90
	v_exp_f32_e32 v85, v85
	s_nop 0
	v_add_f32_e32 v85, 1.0, v85
	v_rcp_f32_e32 v92, v85
	s_nop 0
	v_fma_f32 v94, -v85, v92, 1.0
	v_fma_f32 v91, v94, v92, v92
	v_div_fixup_f32 v85, v91, v85, 1.0

; __device__ __forceinline__ float sigmoidf_(float x) { return 1.0f / (1.0f + __expf(-x)); }
;     __device__ __forceinline__ void operator()(const f32x4 (&acc)[2][2][4][2], const Unit& u, int wr, int wc, int fr, int fq) const {
;     ...
;                         for (int i = 0; i < 4; ++i) { float xv = acc[ai][bj][m][n][i] + bv[bj][n][i]; float r;
;                             if (type < 2) { const float sg = sigmoidf_(xv); r = -expm1f(-0.606531f * sg); }
;                             else if (type == 2) r = sigmoidf_(xv);
.LBB0_815:
	v_mul_f32_e32 v85, 0xbfb8aa3b, v90
	v_exp_f32_e32 v85, v85
	s_nop 0
	v_add_f32_e32 v85, 1.0, v85
	v_rcp_f32_e32 v91, v85
	s_nop 0
	v_fma_f32 v93, -v85, v91, 1.0
	v_fma_f32 v90, v93, v91, v91
	v_div_fixup_f32 v85, v90, v85, 1.0
	v_mul_f32_e32 v85, 0xbf1b459e, v85
	v_mul_f32_e32 v90, 0x3fb8aa3b, v85
	v_rndne_f32_e32 v90, v90
	v_fmamk_f32 v91, v90, 0xbf317218, v85
	v_fmac_f32_e32 v91, 0x3102e308, v90
	v_cvt_i32_f32_e32 v92, v90
	v_fmamk_f32 v93, v91, 0x395133b1, v171
	v_fmaak_f32 v93, v91, v93, 0x3c0887f9
	v_fmaak_f32 v93, v91, v93, 0x3d2aaa81
	v_fmaak_f32 v93, v91, v93, 0x3e2aaaab
	v_ldexp_f32 v92, 1.0, v92
	v_fma_f32 v93, v91, v93, 0.5
	v_cmp_eq_f32_e32 vcc, s90, v90
	v_mul_f32_e32 v93, v91, v93
	v_fmac_f32_e32 v91, v91, v93
	v_cndmask_b32_e32 v90, v92, v172, vcc
	v_add_f32_e32 v92, -1.0, v90
	v_fmac_f32_e32 v92, v90, v91
	v_add_f32_e32 v90, v92, v92
	v_cndmask_b32_e32 v90, v92, v90, vcc
	v_cmp_nlt_f32_e32 vcc, s91, v85
	s_nop 1
	v_cndmask_b32_e64 v90, v173, -v90, vcc
	v_cmp_ngt_f32_e32 vcc, s92, v85
	s_nop 1
	v_cndmask_b32_e32 v85, 1.0, v90, vcc
.LBB0_816:
	v_add_f32_e32 v90, v86, v22
	s_and_b64 vcc, exec, s[8:9]
	s_mov_b64 s[14:15], -1
	s_cbranch_vccnz .LBB0_820
	s_and_b64 vcc, exec, s[6:7]
	v_mov_b32_e32 v86, v90
	s_cbranch_vccnz .LBB0_819
	v_mul_f32_e32 v86, 0xbfb8aa3b, v90
	v_exp_f32_e32 v86, v86
	s_nop 0
	v_add_f32_e32 v86, 1.0, v86
	v_rcp_f32_e32 v92, v86
	s_nop 0
	v_fma_f32 v94, -v86, v92, 1.0
	v_fma_f32 v91, v94, v92, v92
	v_div_fixup_f32 v86, v91, v86, 1.0

; __device__ __forceinline__ float sigmoidf_(float x) { return 1.0f / (1.0f + __expf(-x)); }
;     __device__ __forceinline__ void operator()(const f32x4 (&acc)[2][2][4][2], const Unit& u, int wr, int wc, int fr, int fq) const {
;     ...
;                         for (int i = 0; i < 4; ++i) { float xv = acc[ai][bj][m][n][i] + bv[bj][n][i]; float r;
;                             if (type < 2) { const float sg = sigmoidf_(xv); r = -expm1f(-0.606531f * sg); }
;                             else if (type == 2) r = sigmoidf_(xv);
.LBB0_821:
	v_mul_f32_e32 v86, 0xbfb8aa3b, v90
	v_exp_f32_e32 v86, v86
	s_nop 0
	v_add_f32_e32 v86, 1.0, v86
	v_rcp_f32_e32 v91, v86
	s_nop 0
	v_fma_f32 v93, -v86, v91, 1.0
	v_fma_f32 v90, v93, v91, v91
	v_div_fixup_f32 v86, v90, v86, 1.0
	v_mul_f32_e32 v86, 0xbf1b459e, v86
	v_mul_f32_e32 v90, 0x3fb8aa3b, v86
	v_rndne_f32_e32 v90, v90
	v_fmamk_f32 v91, v90, 0xbf317218, v86
	v_fmac_f32_e32 v91, 0x3102e308, v90
	v_cvt_i32_f32_e32 v92, v90
	v_fmamk_f32 v93, v91, 0x395133b1, v171
	v_fmaak_f32 v93, v91, v93, 0x3c0887f9
	v_fmaak_f32 v93, v91, v93, 0x3d2aaa81
	v_fmaak_f32 v93, v91, v93, 0x3e2aaaab
	v_ldexp_f32 v92, 1.0, v92
	v_fma_f32 v93, v91, v93, 0.5
	v_cmp_eq_f32_e32 vcc, s90, v90
	v_mul_f32_e32 v93, v91, v93
	v_fmac_f32_e32 v91, v91, v93
	v_cndmask_b32_e32 v90, v92, v172, vcc
	v_add_f32_e32 v92, -1.0, v90
	v_fmac_f32_e32 v92, v90, v91
	v_add_f32_e32 v90, v92, v92
	v_cndmask_b32_e32 v90, v92, v90, vcc
	v_cmp_nlt_f32_e32 vcc, s91, v86
	s_nop 1
	v_cndmask_b32_e64 v90, v173, -v90, vcc
	v_cmp_ngt_f32_e32 vcc, s92, v86
	s_nop 1
	v_cndmask_b32_e32 v86, 1.0, v90, vcc
.LBB0_822:
	v_add_f32_e32 v90, v87, v23
	s_and_b64 vcc, exec, s[8:9]
	s_mov_b64 s[14:15], -1
	s_cbranch_vccnz .LBB0_826
	s_and_b64 vcc, exec, s[6:7]
	v_mov_b32_e32 v87, v90
	s_cbranch_vccnz .LBB0_825
	v_mul_f32_e32 v87, 0xbfb8aa3b, v90
	v_exp_f32_e32 v87, v87
	s_nop 0
	v_add_f32_e32 v87, 1.0, v87
	v_rcp_f32_e32 v92, v87
	s_nop 0
	v_fma_f32 v94, -v87, v92, 1.0
	v_fma_f32 v91, v94, v92, v92
	v_div_fixup_f32 v87, v91, v87, 1.0

; __device__ __forceinline__ float sigmoidf_(float x) { return 1.0f / (1.0f + __expf(-x)); }
;     __device__ __forceinline__ void operator()(const f32x4 (&acc)[2][2][4][2], const Unit& u, int wr, int wc, int fr, int fq) const {
;     ...
;                         for (int i = 0; i < 4; ++i) { float xv = acc[ai][bj][m][n][i] + bv[bj][n][i]; float r;
;                             if (type < 2) { const float sg = sigmoidf_(xv); r = -expm1f(-0.606531f * sg); }
;                             else if (type == 2) r = sigmoidf_(xv);
.LBB0_827:
	v_mul_f32_e32 v87, 0xbfb8aa3b, v90
	v_exp_f32_e32 v87, v87
	s_nop 0
	v_add_f32_e32 v87, 1.0, v87
	v_rcp_f32_e32 v91, v87
	s_nop 0
	v_fma_f32 v93, -v87, v91, 1.0
	v_fma_f32 v90, v93, v91, v91
	v_div_fixup_f32 v87, v90, v87, 1.0
	v_mul_f32_e32 v87, 0xbf1b459e, v87
	v_mul_f32_e32 v90, 0x3fb8aa3b, v87
	v_rndne_f32_e32 v90, v90
	v_fmamk_f32 v91, v90, 0xbf317218, v87
	v_fmac_f32_e32 v91, 0x3102e308, v90
	v_cvt_i32_f32_e32 v92, v90
	v_fmamk_f32 v93, v91, 0x395133b1, v171
	v_fmaak_f32 v93, v91, v93, 0x3c0887f9
	v_fmaak_f32 v93, v91, v93, 0x3d2aaa81
	v_fmaak_f32 v93, v91, v93, 0x3e2aaaab
	v_ldexp_f32 v92, 1.0, v92
	v_fma_f32 v93, v91, v93, 0.5
	v_cmp_eq_f32_e32 vcc, s90, v90
	v_mul_f32_e32 v93, v91, v93
	v_fmac_f32_e32 v91, v91, v93
	v_cndmask_b32_e32 v90, v92, v172, vcc
	v_add_f32_e32 v92, -1.0, v90
	v_fmac_f32_e32 v92, v90, v91
	v_add_f32_e32 v90, v92, v92
	v_cndmask_b32_e32 v90, v92, v90, vcc
	v_cmp_nlt_f32_e32 vcc, s91, v87
	s_nop 1
	v_cndmask_b32_e64 v90, v173, -v90, vcc
	v_cmp_ngt_f32_e32 vcc, s92, v87
	s_nop 1
	v_cndmask_b32_e32 v87, 1.0, v90, vcc
.LBB0_828:
	v_add_f32_e32 v90, v80, v12
	s_and_b64 vcc, exec, s[8:9]
	s_mov_b64 s[14:15], -1
	s_cbranch_vccnz .LBB0_832
	s_and_b64 vcc, exec, s[6:7]
	v_mov_b32_e32 v80, v90
	s_cbranch_vccnz .LBB0_831
	v_mul_f32_e32 v80, 0xbfb8aa3b, v90
	v_exp_f32_e32 v80, v80
	s_nop 0
	v_add_f32_e32 v80, 1.0, v80
	v_rcp_f32_e32 v92, v80
	s_nop 0
	v_fma_f32 v94, -v80, v92, 1.0
	v_fma_f32 v91, v94, v92, v92
	v_div_fixup_f32 v80, v91, v80, 1.0

; __device__ __forceinline__ float sigmoidf_(float x) { return 1.0f / (1.0f + __expf(-x)); }
;     __device__ __forceinline__ void operator()(const f32x4 (&acc)[2][2][4][2], const Unit& u, int wr, int wc, int fr, int fq) const {
;     ...
;                         for (int i = 0; i < 4; ++i) { float xv = acc[ai][bj][m][n][i] + bv[bj][n][i]; float r;
;                             if (type < 2) { const float sg = sigmoidf_(xv); r = -expm1f(-0.606531f * sg); }
;                             else if (type == 2) r = sigmoidf_(xv);
.LBB0_833:
	v_mul_f32_e32 v80, 0xbfb8aa3b, v90
	v_exp_f32_e32 v80, v80
	s_nop 0
	v_add_f32_e32 v80, 1.0, v80
	v_rcp_f32_e32 v91, v80
	s_nop 0
	v_fma_f32 v93, -v80, v91, 1.0
	v_fma_f32 v90, v93, v91, v91
	v_div_fixup_f32 v80, v90, v80, 1.0
	v_mul_f32_e32 v80, 0xbf1b459e, v80
	v_mul_f32_e32 v90, 0x3fb8aa3b, v80
	v_rndne_f32_e32 v90, v90
	v_fmamk_f32 v91, v90, 0xbf317218, v80
	v_fmac_f32_e32 v91, 0x3102e308, v90
	v_cvt_i32_f32_e32 v92, v90
	v_fmamk_f32 v93, v91, 0x395133b1, v171
	v_fmaak_f32 v93, v91, v93, 0x3c0887f9
	v_fmaak_f32 v93, v91, v93, 0x3d2aaa81
	v_fmaak_f32 v93, v91, v93, 0x3e2aaaab
	v_ldexp_f32 v92, 1.0, v92
	v_fma_f32 v93, v91, v93, 0.5
	v_cmp_eq_f32_e32 vcc, s90, v90
	v_mul_f32_e32 v93, v91, v93
	v_fmac_f32_e32 v91, v91, v93
	v_cndmask_b32_e32 v90, v92, v172, vcc
	v_add_f32_e32 v92, -1.0, v90
	v_fmac_f32_e32 v92, v90, v91
	v_add_f32_e32 v90, v92, v92
	v_cndmask_b32_e32 v90, v92, v90, vcc
	v_cmp_nlt_f32_e32 vcc, s91, v80
	s_nop 1
	v_cndmask_b32_e64 v90, v173, -v90, vcc
	v_cmp_ngt_f32_e32 vcc, s92, v80
	s_nop 1
	v_cndmask_b32_e32 v80, 1.0, v90, vcc
.LBB0_834:
	v_add_f32_e32 v90, v81, v13
	s_and_b64 vcc, exec, s[8:9]
	s_mov_b64 s[14:15], -1
	s_cbranch_vccnz .LBB0_838
	s_and_b64 vcc, exec, s[6:7]
	v_mov_b32_e32 v81, v90
	s_cbranch_vccnz .LBB0_837
	v_mul_f32_e32 v81, 0xbfb8aa3b, v90
	v_exp_f32_e32 v81, v81
	s_nop 0
	v_add_f32_e32 v81, 1.0, v81
	v_rcp_f32_e32 v92, v81
	s_nop 0
	v_fma_f32 v94, -v81, v92, 1.0
	v_fma_f32 v91, v94, v92, v92
	v_div_fixup_f32 v81, v91, v81, 1.0

; __device__ __forceinline__ float sigmoidf_(float x) { return 1.0f / (1.0f + __expf(-x)); }
;     __device__ __forceinline__ void operator()(const f32x4 (&acc)[2][2][4][2], const Unit& u, int wr, int wc, int fr, int fq) const {
;     ...
;                         for (int i = 0; i < 4; ++i) { float xv = acc[ai][bj][m][n][i] + bv[bj][n][i]; float r;
;                             if (type < 2) { const float sg = sigmoidf_(xv); r = -expm1f(-0.606531f * sg); }
;                             else if (type == 2) r = sigmoidf_(xv);
.LBB0_839:
	v_mul_f32_e32 v81, 0xbfb8aa3b, v90
	v_exp_f32_e32 v81, v81
	s_nop 0
	v_add_f32_e32 v81, 1.0, v81
	v_rcp_f32_e32 v91, v81
	s_nop 0
	v_fma_f32 v93, -v81, v91, 1.0
	v_fma_f32 v90, v93, v91, v91
	v_div_fixup_f32 v81, v90, v81, 1.0
	v_mul_f32_e32 v81, 0xbf1b459e, v81
	v_mul_f32_e32 v90, 0x3fb8aa3b, v81
	v_rndne_f32_e32 v90, v90
	v_fmamk_f32 v91, v90, 0xbf317218, v81
	v_fmac_f32_e32 v91, 0x3102e308, v90
	v_cvt_i32_f32_e32 v92, v90
	v_fmamk_f32 v93, v91, 0x395133b1, v171
	v_fmaak_f32 v93, v91, v93, 0x3c0887f9
	v_fmaak_f32 v93, v91, v93, 0x3d2aaa81
	v_fmaak_f32 v93, v91, v93, 0x3e2aaaab
	v_ldexp_f32 v92, 1.0, v92
	v_fma_f32 v93, v91, v93, 0.5
	v_cmp_eq_f32_e32 vcc, s90, v90
	v_mul_f32_e32 v93, v91, v93
	v_fmac_f32_e32 v91, v91, v93
	v_cndmask_b32_e32 v90, v92, v172, vcc
	v_add_f32_e32 v92, -1.0, v90
	v_fmac_f32_e32 v92, v90, v91
	v_add_f32_e32 v90, v92, v92
	v_cndmask_b32_e32 v90, v92, v90, vcc
	v_cmp_nlt_f32_e32 vcc, s91, v81
	s_nop 1
	v_cndmask_b32_e64 v90, v173, -v90, vcc
	v_cmp_ngt_f32_e32 vcc, s92, v81
	s_nop 1
	v_cndmask_b32_e32 v81, 1.0, v90, vcc
.LBB0_840:
	v_add_f32_e32 v90, v82, v14
	s_and_b64 vcc, exec, s[8:9]
	s_mov_b64 s[14:15], -1
	s_cbranch_vccnz .LBB0_844
	s_and_b64 vcc, exec, s[6:7]
	v_mov_b32_e32 v82, v90
	s_cbranch_vccnz .LBB0_843
	v_mul_f32_e32 v82, 0xbfb8aa3b, v90
	v_exp_f32_e32 v82, v82
	s_nop 0
	v_add_f32_e32 v82, 1.0, v82
	v_rcp_f32_e32 v92, v82
	s_nop 0
	v_fma_f32 v94, -v82, v92, 1.0
	v_fma_f32 v91, v94, v92, v92
	v_div_fixup_f32 v82, v91, v82, 1.0

; __device__ __forceinline__ float sigmoidf_(float x) { return 1.0f / (1.0f + __expf(-x)); }
;     __device__ __forceinline__ void operator()(const f32x4 (&acc)[2][2][4][2], const Unit& u, int wr, int wc, int fr, int fq) const {
;     ...
;                         for (int i = 0; i < 4; ++i) { float xv = acc[ai][bj][m][n][i] + bv[bj][n][i]; float r;
;                             if (type < 2) { const float sg = sigmoidf_(xv); r = -expm1f(-0.606531f * sg); }
;                             else if (type == 2) r = sigmoidf_(xv);
.LBB0_845:
	v_mul_f32_e32 v82, 0xbfb8aa3b, v90
	v_exp_f32_e32 v82, v82
	s_nop 0
	v_add_f32_e32 v82, 1.0, v82
	v_rcp_f32_e32 v91, v82
	s_nop 0
	v_fma_f32 v93, -v82, v91, 1.0
	v_fma_f32 v90, v93, v91, v91
	v_div_fixup_f32 v82, v90, v82, 1.0
	v_mul_f32_e32 v82, 0xbf1b459e, v82
	v_mul_f32_e32 v90, 0x3fb8aa3b, v82
	v_rndne_f32_e32 v90, v90
	v_fmamk_f32 v91, v90, 0xbf317218, v82
	v_fmac_f32_e32 v91, 0x3102e308, v90
	v_cvt_i32_f32_e32 v92, v90
	v_fmamk_f32 v93, v91, 0x395133b1, v171
	v_fmaak_f32 v93, v91, v93, 0x3c0887f9
	v_fmaak_f32 v93, v91, v93, 0x3d2aaa81
	v_fmaak_f32 v93, v91, v93, 0x3e2aaaab
	v_ldexp_f32 v92, 1.0, v92
	v_fma_f32 v93, v91, v93, 0.5
	v_cmp_eq_f32_e32 vcc, s90, v90
	v_mul_f32_e32 v93, v91, v93
	v_fmac_f32_e32 v91, v91, v93
	v_cndmask_b32_e32 v90, v92, v172, vcc
	v_add_f32_e32 v92, -1.0, v90
	v_fmac_f32_e32 v92, v90, v91
	v_add_f32_e32 v90, v92, v92
	v_cndmask_b32_e32 v90, v92, v90, vcc
	v_cmp_nlt_f32_e32 vcc, s91, v82
	s_nop 1
	v_cndmask_b32_e64 v90, v173, -v90, vcc
	v_cmp_ngt_f32_e32 vcc, s92, v82
	s_nop 1
	v_cndmask_b32_e32 v82, 1.0, v90, vcc
.LBB0_846:
	v_add_f32_e32 v83, v83, v15
	s_and_b64 vcc, exec, s[8:9]
	s_mov_b64 s[14:15], -1
	s_cbranch_vccnz .LBB0_850
	s_and_b64 vcc, exec, s[6:7]
	v_mov_b32_e32 v90, v83
	s_cbranch_vccnz .LBB0_849
	v_mul_f32_e32 v90, 0xbfb8aa3b, v83
	v_exp_f32_e32 v90, v90
	s_nop 0
	v_add_f32_e32 v90, 1.0, v90
	v_rcp_f32_e32 v92, v90
	s_nop 0
	v_fma_f32 v94, -v90, v92, 1.0
	v_fma_f32 v91, v94, v92, v92
	v_div_fixup_f32 v90, v91, v90, 1.0

; __device__ __forceinline__ float sigmoidf_(float x) { return 1.0f / (1.0f + __expf(-x)); }
;     __device__ __forceinline__ void operator()(const f32x4 (&acc)[2][2][4][2], const Unit& u, int wr, int wc, int fr, int fq) const {
;     ...
;                         for (int i = 0; i < 4; ++i) { float xv = acc[ai][bj][m][n][i] + bv[bj][n][i]; float r;
;                             if (type < 2) { const float sg = sigmoidf_(xv); r = -expm1f(-0.606531f * sg); }
;                             else if (type == 2) r = sigmoidf_(xv);
;                             else r = xv;
;                             v[4 * n + i] = (f16)r; }
;                     *(f16x8*)(rowp + bj * 128) = v; } }
.LBB0_851:
	v_mul_f32_e32 v83, 0xbfb8aa3b, v83
	v_exp_f32_e32 v83, v83
	s_nop 0
	v_add_f32_e32 v83, 1.0, v83
	v_rcp_f32_e32 v91, v83
	s_nop 0
	v_fma_f32 v93, -v83, v91, 1.0
	v_fma_f32 v90, v93, v91, v91
	v_div_fixup_f32 v83, v90, v83, 1.0
	v_mul_f32_e32 v83, 0xbf1b459e, v83
	v_mul_f32_e32 v90, 0x3fb8aa3b, v83
	v_rndne_f32_e32 v90, v90
	v_fmamk_f32 v91, v90, 0xbf317218, v83
	v_fmac_f32_e32 v91, 0x3102e308, v90
	v_cvt_i32_f32_e32 v92, v90
	v_fmamk_f32 v93, v91, 0x395133b1, v171
	v_fmaak_f32 v93, v91, v93, 0x3c0887f9
	v_fmaak_f32 v93, v91, v93, 0x3d2aaa81
	v_fmaak_f32 v93, v91, v93, 0x3e2aaaab
	v_ldexp_f32 v92, 1.0, v92
	v_fma_f32 v93, v91, v93, 0.5
	v_cmp_eq_f32_e32 vcc, s90, v90
	v_mul_f32_e32 v93, v91, v93
	v_fmac_f32_e32 v91, v91, v93
	v_cndmask_b32_e32 v90, v92, v172, vcc
	v_add_f32_e32 v92, -1.0, v90
	v_fmac_f32_e32 v92, v90, v91
	v_add_f32_e32 v90, v92, v92
	v_cndmask_b32_e32 v90, v92, v90, vcc
	v_cmp_nlt_f32_e32 vcc, s91, v83
	s_nop 1
	v_cndmask_b32_e64 v90, v173, -v90, vcc
	v_cmp_ngt_f32_e32 vcc, s92, v83
	s_nop 1
	v_cndmask_b32_e32 v90, 1.0, v90, vcc
.LBB0_852:
	v_cvt_pk_f16_f32 v83, v82, v90
	v_cvt_pk_f16_f32 v82, v80, v81
	v_cvt_pk_f16_f32 v81, v86, v87
	v_cvt_pk_f16_f32 v80, v84, v85
	global_store_dwordx4 v[88:89], v[80:83], off offset:256
	s_and_b64 vcc, exec, s[8:9]
	s_mov_b64 s[14:15], -1
	v_add_f32_e32 v80, v76, v32
	s_cbranch_vccnz .LBB0_856
	s_and_b64 vcc, exec, s[6:7]
	v_mov_b32_e32 v76, v80
	s_cbranch_vccnz .LBB0_855
	v_mul_f32_e32 v76, 0xbfb8aa3b, v80
	v_exp_f32_e32 v76, v76
	s_nop 0
	v_add_f32_e32 v76, 1.0, v76
	v_rcp_f32_e32 v82, v76
	s_nop 0
	v_fma_f32 v84, -v76, v82, 1.0
	v_fma_f32 v81, v84, v82, v82
	v_div_fixup_f32 v76, v81, v76, 1.0

; __device__ __forceinline__ float sigmoidf_(float x) { return 1.0f / (1.0f + __expf(-x)); }
;     __device__ __forceinline__ void operator()(const f32x4 (&acc)[2][2][4][2], const Unit& u, int wr, int wc, int fr, int fq) const {
;     ...
;                         for (int i = 0; i < 4; ++i) { float xv = acc[ai][bj][m][n][i] + bv[bj][n][i]; float r;
;                             if (type < 2) { const float sg = sigmoidf_(xv); r = -expm1f(-0.606531f * sg); }
;                             else if (type == 2) r = sigmoidf_(xv);
.LBB0_857:
	v_mul_f32_e32 v76, 0xbfb8aa3b, v80
	v_exp_f32_e32 v76, v76
	s_nop 0
	v_add_f32_e32 v76, 1.0, v76
	v_rcp_f32_e32 v81, v76
	s_nop 0
	v_fma_f32 v83, -v76, v81, 1.0
	v_fma_f32 v80, v83, v81, v81
	v_div_fixup_f32 v76, v80, v76, 1.0
	v_mul_f32_e32 v76, 0xbf1b459e, v76
	v_mul_f32_e32 v80, 0x3fb8aa3b, v76
	v_rndne_f32_e32 v80, v80
	v_fmamk_f32 v81, v80, 0xbf317218, v76
	v_fmac_f32_e32 v81, 0x3102e308, v80
	v_cvt_i32_f32_e32 v82, v80
	v_fmamk_f32 v83, v81, 0x395133b1, v171
	v_fmaak_f32 v83, v81, v83, 0x3c0887f9
	v_fmaak_f32 v83, v81, v83, 0x3d2aaa81
	v_fmaak_f32 v83, v81, v83, 0x3e2aaaab
	v_ldexp_f32 v82, 1.0, v82
	v_fma_f32 v83, v81, v83, 0.5
	v_cmp_eq_f32_e32 vcc, s90, v80
	v_mul_f32_e32 v83, v81, v83
	v_fmac_f32_e32 v81, v81, v83
	v_cndmask_b32_e32 v80, v82, v172, vcc
	v_add_f32_e32 v82, -1.0, v80
	v_fmac_f32_e32 v82, v80, v81
	v_add_f32_e32 v80, v82, v82
	v_cndmask_b32_e32 v80, v82, v80, vcc
	v_cmp_nlt_f32_e32 vcc, s91, v76
	s_nop 1
	v_cndmask_b32_e64 v80, v173, -v80, vcc
	v_cmp_ngt_f32_e32 vcc, s92, v76
	s_nop 1
	v_cndmask_b32_e32 v76, 1.0, v80, vcc
.LBB0_858:
	v_add_f32_e32 v80, v77, v33
	s_and_b64 vcc, exec, s[8:9]
	s_mov_b64 s[14:15], -1
	s_cbranch_vccnz .LBB0_862
	s_and_b64 vcc, exec, s[6:7]
	v_mov_b32_e32 v77, v80
	s_cbranch_vccnz .LBB0_861
	v_mul_f32_e32 v77, 0xbfb8aa3b, v80
	v_exp_f32_e32 v77, v77
	s_nop 0
	v_add_f32_e32 v77, 1.0, v77
	v_rcp_f32_e32 v82, v77
	s_nop 0
	v_fma_f32 v84, -v77, v82, 1.0
	v_fma_f32 v81, v84, v82, v82
	v_div_fixup_f32 v77, v81, v77, 1.0

; __device__ __forceinline__ float sigmoidf_(float x) { return 1.0f / (1.0f + __expf(-x)); }
;     __device__ __forceinline__ void operator()(const f32x4 (&acc)[2][2][4][2], const Unit& u, int wr, int wc, int fr, int fq) const {
;     ...
;                         for (int i = 0; i < 4; ++i) { float xv = acc[ai][bj][m][n][i] + bv[bj][n][i]; float r;
;                             if (type < 2) { const float sg = sigmoidf_(xv); r = -expm1f(-0.606531f * sg); }
;                             else if (type == 2) r = sigmoidf_(xv);
.LBB0_863:
	v_mul_f32_e32 v77, 0xbfb8aa3b, v80
	v_exp_f32_e32 v77, v77
	s_nop 0
	v_add_f32_e32 v77, 1.0, v77
	v_rcp_f32_e32 v81, v77
	s_nop 0
	v_fma_f32 v83, -v77, v81, 1.0
	v_fma_f32 v80, v83, v81, v81
	v_div_fixup_f32 v77, v80, v77, 1.0
	v_mul_f32_e32 v77, 0xbf1b459e, v77
	v_mul_f32_e32 v80, 0x3fb8aa3b, v77
	v_rndne_f32_e32 v80, v80
	v_fmamk_f32 v81, v80, 0xbf317218, v77
	v_fmac_f32_e32 v81, 0x3102e308, v80
	v_cvt_i32_f32_e32 v82, v80
	v_fmamk_f32 v83, v81, 0x395133b1, v171
	v_fmaak_f32 v83, v81, v83, 0x3c0887f9
	v_fmaak_f32 v83, v81, v83, 0x3d2aaa81
	v_fmaak_f32 v83, v81, v83, 0x3e2aaaab
	v_ldexp_f32 v82, 1.0, v82
	v_fma_f32 v83, v81, v83, 0.5
	v_cmp_eq_f32_e32 vcc, s90, v80
	v_mul_f32_e32 v83, v81, v83
	v_fmac_f32_e32 v81, v81, v83
	v_cndmask_b32_e32 v80, v82, v172, vcc
	v_add_f32_e32 v82, -1.0, v80
	v_fmac_f32_e32 v82, v80, v81
	v_add_f32_e32 v80, v82, v82
	v_cndmask_b32_e32 v80, v82, v80, vcc
	v_cmp_nlt_f32_e32 vcc, s91, v77
	s_nop 1
	v_cndmask_b32_e64 v80, v173, -v80, vcc
	v_cmp_ngt_f32_e32 vcc, s92, v77
	s_nop 1
	v_cndmask_b32_e32 v77, 1.0, v80, vcc
.LBB0_864:
	v_add_f32_e32 v80, v78, v34
	s_and_b64 vcc, exec, s[8:9]
	s_mov_b64 s[14:15], -1
	s_cbranch_vccnz .LBB0_868
	s_and_b64 vcc, exec, s[6:7]
	v_mov_b32_e32 v78, v80
	s_cbranch_vccnz .LBB0_867
	v_mul_f32_e32 v78, 0xbfb8aa3b, v80
	v_exp_f32_e32 v78, v78
	s_nop 0
	v_add_f32_e32 v78, 1.0, v78
	v_rcp_f32_e32 v82, v78
	s_nop 0
	v_fma_f32 v84, -v78, v82, 1.0
	v_fma_f32 v81, v84, v82, v82
	v_div_fixup_f32 v78, v81, v78, 1.0

; __device__ __forceinline__ float sigmoidf_(float x) { return 1.0f / (1.0f + __expf(-x)); }
;     __device__ __forceinline__ void operator()(const f32x4 (&acc)[2][2][4][2], const Unit& u, int wr, int wc, int fr, int fq) const {
;     ...
;                         for (int i = 0; i < 4; ++i) { float xv = acc[ai][bj][m][n][i] + bv[bj][n][i]; float r;
;                             if (type < 2) { const float sg = sigmoidf_(xv); r = -expm1f(-0.606531f * sg); }
;                             else if (type == 2) r = sigmoidf_(xv);
.LBB0_869:
	v_mul_f32_e32 v78, 0xbfb8aa3b, v80
	v_exp_f32_e32 v78, v78
	s_nop 0
	v_add_f32_e32 v78, 1.0, v78
	v_rcp_f32_e32 v81, v78
	s_nop 0
	v_fma_f32 v83, -v78, v81, 1.0
	v_fma_f32 v80, v83, v81, v81
	v_div_fixup_f32 v78, v80, v78, 1.0
	v_mul_f32_e32 v78, 0xbf1b459e, v78
	v_mul_f32_e32 v80, 0x3fb8aa3b, v78
	v_rndne_f32_e32 v80, v80
	v_fmamk_f32 v81, v80, 0xbf317218, v78
	v_fmac_f32_e32 v81, 0x3102e308, v80
	v_cvt_i32_f32_e32 v82, v80
	v_fmamk_f32 v83, v81, 0x395133b1, v171
	v_fmaak_f32 v83, v81, v83, 0x3c0887f9
	v_fmaak_f32 v83, v81, v83, 0x3d2aaa81
	v_fmaak_f32 v83, v81, v83, 0x3e2aaaab
	v_ldexp_f32 v82, 1.0, v82
	v_fma_f32 v83, v81, v83, 0.5
	v_cmp_eq_f32_e32 vcc, s90, v80
	v_mul_f32_e32 v83, v81, v83
	v_fmac_f32_e32 v81, v81, v83
	v_cndmask_b32_e32 v80, v82, v172, vcc
	v_add_f32_e32 v82, -1.0, v80
	v_fmac_f32_e32 v82, v80, v81
	v_add_f32_e32 v80, v82, v82
	v_cndmask_b32_e32 v80, v82, v80, vcc
	v_cmp_nlt_f32_e32 vcc, s91, v78
	s_nop 1
	v_cndmask_b32_e64 v80, v173, -v80, vcc
	v_cmp_ngt_f32_e32 vcc, s92, v78
	s_nop 1
	v_cndmask_b32_e32 v78, 1.0, v80, vcc
.LBB0_870:
	v_add_f32_e32 v80, v79, v35
	s_and_b64 vcc, exec, s[8:9]
	s_mov_b64 s[14:15], -1
	s_cbranch_vccnz .LBB0_874
	s_and_b64 vcc, exec, s[6:7]
	v_mov_b32_e32 v79, v80
	s_cbranch_vccnz .LBB0_873
	v_mul_f32_e32 v79, 0xbfb8aa3b, v80
	v_exp_f32_e32 v79, v79
	s_nop 0
	v_add_f32_e32 v79, 1.0, v79
	v_rcp_f32_e32 v82, v79
	s_nop 0
	v_fma_f32 v84, -v79, v82, 1.0
	v_fma_f32 v81, v84, v82, v82
	v_div_fixup_f32 v79, v81, v79, 1.0

; __device__ __forceinline__ float sigmoidf_(float x) { return 1.0f / (1.0f + __expf(-x)); }
;     __device__ __forceinline__ void operator()(const f32x4 (&acc)[2][2][4][2], const Unit& u, int wr, int wc, int fr, int fq) const {
;     ...
;                         for (int i = 0; i < 4; ++i) { float xv = acc[ai][bj][m][n][i] + bv[bj][n][i]; float r;
;                             if (type < 2) { const float sg = sigmoidf_(xv); r = -expm1f(-0.606531f * sg); }
;                             else if (type == 2) r = sigmoidf_(xv);
.LBB0_875:
	v_mul_f32_e32 v79, 0xbfb8aa3b, v80
	v_exp_f32_e32 v79, v79
	s_nop 0
	v_add_f32_e32 v79, 1.0, v79
	v_rcp_f32_e32 v81, v79
	s_nop 0
	v_fma_f32 v83, -v79, v81, 1.0
	v_fma_f32 v80, v83, v81, v81
	v_div_fixup_f32 v79, v80, v79, 1.0
	v_mul_f32_e32 v79, 0xbf1b459e, v79
	v_mul_f32_e32 v80, 0x3fb8aa3b, v79
	v_rndne_f32_e32 v80, v80
	v_fmamk_f32 v81, v80, 0xbf317218, v79
	v_fmac_f32_e32 v81, 0x3102e308, v80
	v_cvt_i32_f32_e32 v82, v80
	v_fmamk_f32 v83, v81, 0x395133b1, v171
	v_fmaak_f32 v83, v81, v83, 0x3c0887f9
	v_fmaak_f32 v83, v81, v83, 0x3d2aaa81
	v_fmaak_f32 v83, v81, v83, 0x3e2aaaab
	v_ldexp_f32 v82, 1.0, v82
	v_fma_f32 v83, v81, v83, 0.5
	v_cmp_eq_f32_e32 vcc, s90, v80
	v_mul_f32_e32 v83, v81, v83
	v_fmac_f32_e32 v81, v81, v83
	v_cndmask_b32_e32 v80, v82, v172, vcc
	v_add_f32_e32 v82, -1.0, v80
	v_fmac_f32_e32 v82, v80, v81
	v_add_f32_e32 v80, v82, v82
	v_cndmask_b32_e32 v80, v82, v80, vcc
	v_cmp_nlt_f32_e32 vcc, s91, v79
	s_nop 1
	v_cndmask_b32_e64 v80, v173, -v80, vcc
	v_cmp_ngt_f32_e32 vcc, s92, v79
	s_nop 1
	v_cndmask_b32_e32 v79, 1.0, v80, vcc
.LBB0_876:
	v_add_f32_e32 v72, v72, v28
	s_and_b64 vcc, exec, s[8:9]
	s_mov_b64 s[14:15], -1
	s_cbranch_vccnz .LBB0_880
	s_and_b64 vcc, exec, s[6:7]
	v_mov_b32_e32 v80, v72
	s_cbranch_vccnz .LBB0_879
	v_mul_f32_e32 v80, 0xbfb8aa3b, v72
	v_exp_f32_e32 v80, v80
	s_nop 0
	v_add_f32_e32 v80, 1.0, v80
	v_rcp_f32_e32 v82, v80
	s_nop 0
	v_fma_f32 v84, -v80, v82, 1.0
	v_fma_f32 v81, v84, v82, v82
	v_div_fixup_f32 v80, v81, v80, 1.0

; __device__ __forceinline__ float sigmoidf_(float x) { return 1.0f / (1.0f + __expf(-x)); }
;     __device__ __forceinline__ void operator()(const f32x4 (&acc)[2][2][4][2], const Unit& u, int wr, int wc, int fr, int fq) const {
;     ...
;                         for (int i = 0; i < 4; ++i) { float xv = acc[ai][bj][m][n][i] + bv[bj][n][i]; float r;
;                             if (type < 2) { const float sg = sigmoidf_(xv); r = -expm1f(-0.606531f * sg); }
;                             else if (type == 2) r = sigmoidf_(xv);
.LBB0_881:
	v_mul_f32_e32 v72, 0xbfb8aa3b, v72
	v_exp_f32_e32 v72, v72
	s_nop 0
	v_add_f32_e32 v72, 1.0, v72
	v_rcp_f32_e32 v81, v72
	s_nop 0
	v_fma_f32 v83, -v72, v81, 1.0
	v_fma_f32 v80, v83, v81, v81
	v_div_fixup_f32 v72, v80, v72, 1.0
	v_mul_f32_e32 v72, 0xbf1b459e, v72
	v_mul_f32_e32 v80, 0x3fb8aa3b, v72
	v_rndne_f32_e32 v80, v80
	v_fmamk_f32 v81, v80, 0xbf317218, v72
	v_fmac_f32_e32 v81, 0x3102e308, v80
	v_cvt_i32_f32_e32 v82, v80
	v_fmamk_f32 v83, v81, 0x395133b1, v171
	v_fmaak_f32 v83, v81, v83, 0x3c0887f9
	v_fmaak_f32 v83, v81, v83, 0x3d2aaa81
	v_fmaak_f32 v83, v81, v83, 0x3e2aaaab
	v_ldexp_f32 v82, 1.0, v82
	v_fma_f32 v83, v81, v83, 0.5
	v_cmp_eq_f32_e32 vcc, s90, v80
	v_mul_f32_e32 v83, v81, v83
	v_fmac_f32_e32 v81, v81, v83
	v_cndmask_b32_e32 v80, v82, v172, vcc
	v_add_f32_e32 v82, -1.0, v80
	v_fmac_f32_e32 v82, v80, v81
	v_add_f32_e32 v80, v82, v82
	v_cndmask_b32_e32 v80, v82, v80, vcc
	v_cmp_nlt_f32_e32 vcc, s91, v72
	s_nop 1
	v_cndmask_b32_e64 v80, v173, -v80, vcc
	v_cmp_ngt_f32_e32 vcc, s92, v72
	s_nop 1
	v_cndmask_b32_e32 v80, 1.0, v80, vcc
.LBB0_882:
	v_add_f32_e32 v72, v73, v29
	s_and_b64 vcc, exec, s[8:9]
	s_mov_b64 s[14:15], -1
	s_cbranch_vccnz .LBB0_886
	s_and_b64 vcc, exec, s[6:7]
	v_mov_b32_e32 v81, v72
	s_cbranch_vccnz .LBB0_885
	v_mul_f32_e32 v73, 0xbfb8aa3b, v72
	v_exp_f32_e32 v73, v73
	s_nop 0
	v_add_f32_e32 v73, 1.0, v73
	v_rcp_f32_e32 v82, v73
	s_nop 0
	v_fma_f32 v84, -v73, v82, 1.0
	v_fma_f32 v81, v84, v82, v82
	v_div_fixup_f32 v81, v81, v73, 1.0

; __device__ __forceinline__ float sigmoidf_(float x) { return 1.0f / (1.0f + __expf(-x)); }
;     __device__ __forceinline__ void operator()(const f32x4 (&acc)[2][2][4][2], const Unit& u, int wr, int wc, int fr, int fq) const {
;     ...
;                         for (int i = 0; i < 4; ++i) { float xv = acc[ai][bj][m][n][i] + bv[bj][n][i]; float r;
;                             if (type < 2) { const float sg = sigmoidf_(xv); r = -expm1f(-0.606531f * sg); }
;                             else if (type == 2) r = sigmoidf_(xv);
.LBB0_887:
	v_mul_f32_e32 v72, 0xbfb8aa3b, v72
	v_exp_f32_e32 v72, v72
	s_nop 0
	v_add_f32_e32 v72, 1.0, v72
	v_rcp_f32_e32 v81, v72
	s_nop 0
	v_fma_f32 v83, -v72, v81, 1.0
	v_fma_f32 v73, v83, v81, v81
	v_div_fixup_f32 v72, v73, v72, 1.0
	v_mul_f32_e32 v72, 0xbf1b459e, v72
	v_mul_f32_e32 v73, 0x3fb8aa3b, v72
	v_rndne_f32_e32 v73, v73
	v_fmamk_f32 v81, v73, 0xbf317218, v72
	v_fmac_f32_e32 v81, 0x3102e308, v73
	v_cvt_i32_f32_e32 v82, v73
	v_fmamk_f32 v83, v81, 0x395133b1, v171
	v_fmaak_f32 v83, v81, v83, 0x3c0887f9
	v_fmaak_f32 v83, v81, v83, 0x3d2aaa81
	v_fmaak_f32 v83, v81, v83, 0x3e2aaaab
	v_ldexp_f32 v82, 1.0, v82
	v_fma_f32 v83, v81, v83, 0.5
	v_cmp_eq_f32_e32 vcc, s90, v73
	v_mul_f32_e32 v83, v81, v83
	v_fmac_f32_e32 v81, v81, v83
	v_cndmask_b32_e32 v73, v82, v172, vcc
	v_add_f32_e32 v82, -1.0, v73
	v_fmac_f32_e32 v82, v73, v81
	v_add_f32_e32 v73, v82, v82
	v_cndmask_b32_e32 v73, v82, v73, vcc
	v_cmp_nlt_f32_e32 vcc, s91, v72
	s_nop 1
	v_cndmask_b32_e64 v73, v173, -v73, vcc
	v_cmp_ngt_f32_e32 vcc, s92, v72
	s_nop 1
	v_cndmask_b32_e32 v81, 1.0, v73, vcc
.LBB0_888:
	v_add_f32_e32 v72, v74, v30
	s_and_b64 vcc, exec, s[8:9]
	s_mov_b64 s[14:15], -1
	s_cbranch_vccnz .LBB0_892
	s_and_b64 vcc, exec, s[6:7]
	v_mov_b32_e32 v74, v72
	s_cbranch_vccnz .LBB0_891
	v_mul_f32_e32 v73, 0xbfb8aa3b, v72
	v_exp_f32_e32 v73, v73
	s_nop 0
	v_add_f32_e32 v73, 1.0, v73
	v_rcp_f32_e32 v82, v73
	s_nop 0
	v_fma_f32 v84, -v73, v82, 1.0
	v_fma_f32 v74, v84, v82, v82
	v_div_fixup_f32 v74, v74, v73, 1.0

; __device__ __forceinline__ float sigmoidf_(float x) { return 1.0f / (1.0f + __expf(-x)); }
;     __device__ __forceinline__ void operator()(const f32x4 (&acc)[2][2][4][2], const Unit& u, int wr, int wc, int fr, int fq) const {
;     ...
;                         for (int i = 0; i < 4; ++i) { float xv = acc[ai][bj][m][n][i] + bv[bj][n][i]; float r;
;                             if (type < 2) { const float sg = sigmoidf_(xv); r = -expm1f(-0.606531f * sg); }
;                             else if (type == 2) r = sigmoidf_(xv);
.LBB0_893:
	v_mul_f32_e32 v72, 0xbfb8aa3b, v72
	v_exp_f32_e32 v72, v72
	s_nop 0
	v_add_f32_e32 v72, 1.0, v72
	v_rcp_f32_e32 v74, v72
	s_nop 0
	v_fma_f32 v83, -v72, v74, 1.0
	v_fma_f32 v73, v83, v74, v74
	v_div_fixup_f32 v72, v73, v72, 1.0
	v_mul_f32_e32 v72, 0xbf1b459e, v72
	v_mul_f32_e32 v73, 0x3fb8aa3b, v72
	v_rndne_f32_e32 v73, v73
	v_fmamk_f32 v74, v73, 0xbf317218, v72
	v_fmac_f32_e32 v74, 0x3102e308, v73
	v_cvt_i32_f32_e32 v82, v73
	v_fmamk_f32 v83, v74, 0x395133b1, v171
	v_fmaak_f32 v83, v74, v83, 0x3c0887f9
	v_fmaak_f32 v83, v74, v83, 0x3d2aaa81
	v_fmaak_f32 v83, v74, v83, 0x3e2aaaab
	v_ldexp_f32 v82, 1.0, v82
	v_fma_f32 v83, v74, v83, 0.5
	v_cmp_eq_f32_e32 vcc, s90, v73
	v_mul_f32_e32 v83, v74, v83
	v_fmac_f32_e32 v74, v74, v83
	v_cndmask_b32_e32 v73, v82, v172, vcc
	v_add_f32_e32 v82, -1.0, v73
	v_fmac_f32_e32 v82, v73, v74
	v_add_f32_e32 v73, v82, v82
	v_cndmask_b32_e32 v73, v82, v73, vcc
	v_cmp_nlt_f32_e32 vcc, s91, v72
	s_nop 1
	v_cndmask_b32_e64 v73, v173, -v73, vcc
	v_cmp_ngt_f32_e32 vcc, s92, v72
	s_nop 1
	v_cndmask_b32_e32 v74, 1.0, v73, vcc
.LBB0_894:
	v_add_f32_e32 v72, v75, v31
	s_and_b64 vcc, exec, s[8:9]
	s_mov_b64 s[14:15], -1
	s_cbranch_vccnz .LBB0_898
	s_and_b64 vcc, exec, s[6:7]
	v_mov_b32_e32 v75, v72
	s_cbranch_vccnz .LBB0_897
	v_mul_f32_e32 v73, 0xbfb8aa3b, v72
	v_exp_f32_e32 v73, v73
	s_nop 0
	v_add_f32_e32 v73, 1.0, v73
	v_rcp_f32_e32 v82, v73
	s_nop 0
	v_fma_f32 v84, -v73, v82, 1.0
	v_fma_f32 v75, v84, v82, v82
	v_div_fixup_f32 v75, v75, v73, 1.0

; __device__ __forceinline__ float sigmoidf_(float x) { return 1.0f / (1.0f + __expf(-x)); }
;     __device__ __forceinline__ void operator()(const f32x4 (&acc)[2][2][4][2], const Unit& u, int wr, int wc, int fr, int fq) const {
;     ...
;                         for (int i = 0; i < 4; ++i) { float xv = acc[ai][bj][m][n][i] + bv[bj][n][i]; float r;
;                             if (type < 2) { const float sg = sigmoidf_(xv); r = -expm1f(-0.606531f * sg); }
;                             else if (type == 2) r = sigmoidf_(xv);
;                             else r = xv;
;                             v[4 * n + i] = (f16)r; }
;                     *(f16x8*)(rowp + bj * 128) = v; } }
.LBB0_899:
	v_mul_f32_e32 v72, 0xbfb8aa3b, v72
	v_exp_f32_e32 v72, v72
	s_nop 0
	v_add_f32_e32 v72, 1.0, v72
	v_rcp_f32_e32 v75, v72
	s_nop 0
	v_fma_f32 v83, -v72, v75, 1.0
	v_fma_f32 v73, v83, v75, v75
	v_div_fixup_f32 v72, v73, v72, 1.0
	v_mul_f32_e32 v72, 0xbf1b459e, v72
	v_mul_f32_e32 v73, 0x3fb8aa3b, v72
	v_rndne_f32_e32 v73, v73
	v_fmamk_f32 v75, v73, 0xbf317218, v72
	v_fmac_f32_e32 v75, 0x3102e308, v73
	v_cvt_i32_f32_e32 v82, v73
	v_fmamk_f32 v83, v75, 0x395133b1, v171
	v_fmaak_f32 v83, v75, v83, 0x3c0887f9
	v_fmaak_f32 v83, v75, v83, 0x3d2aaa81
	v_fmaak_f32 v83, v75, v83, 0x3e2aaaab
	v_ldexp_f32 v82, 1.0, v82
	v_fma_f32 v83, v75, v83, 0.5
	v_cmp_eq_f32_e32 vcc, s90, v73
	v_mul_f32_e32 v83, v75, v83
	v_fmac_f32_e32 v75, v75, v83
	v_cndmask_b32_e32 v73, v82, v172, vcc
	v_add_f32_e32 v82, -1.0, v73
	v_fmac_f32_e32 v82, v73, v75
	v_add_f32_e32 v73, v82, v82
	v_cndmask_b32_e32 v73, v82, v73, vcc
	v_cmp_nlt_f32_e32 vcc, s91, v72
	s_nop 1
	v_cndmask_b32_e64 v73, v173, -v73, vcc
	v_cmp_ngt_f32_e32 vcc, s92, v72
	s_nop 1
	v_cndmask_b32_e32 v75, 1.0, v73, vcc
.LBB0_900:
	v_lshlrev_b64 v[72:73], 13, v[138:139]
	v_lshl_add_u64 v[72:73], s[28:29], 0, v[72:73]
	v_lshl_add_u64 v[72:73], v[136:137], 1, v[72:73]
	v_cvt_pk_f16_f32 v83, v74, v75
	v_add_co_u32_e32 v74, vcc, 0x100000, v72
	v_cvt_pk_f16_f32 v82, v80, v81
	v_cvt_pk_f16_f32 v81, v78, v79
	v_cvt_pk_f16_f32 v80, v76, v77
	v_addc_co_u32_e32 v75, vcc, 0, v73, vcc
	global_store_dwordx4 v[74:75], v[80:83], off
	v_add_f32_e32 v74, v68, v20
	s_and_b64 vcc, exec, s[8:9]
	s_mov_b64 s[14:15], -1
	s_cbranch_vccnz .LBB0_904
	s_and_b64 vcc, exec, s[6:7]
	v_mov_b32_e32 v68, v74
	s_cbranch_vccnz .LBB0_903
	v_mul_f32_e32 v68, 0xbfb8aa3b, v74
	v_exp_f32_e32 v68, v68
	s_nop 0
	v_add_f32_e32 v68, 1.0, v68
	v_rcp_f32_e32 v76, v68
	s_nop 0
	v_fma_f32 v78, -v68, v76, 1.0
	v_fma_f32 v75, v78, v76, v76
	v_div_fixup_f32 v68, v75, v68, 1.0

; __device__ __forceinline__ float sigmoidf_(float x) { return 1.0f / (1.0f + __expf(-x)); }
;     __device__ __forceinline__ void operator()(const f32x4 (&acc)[2][2][4][2], const Unit& u, int wr, int wc, int fr, int fq) const {
;     ...
;                         for (int i = 0; i < 4; ++i) { float xv = acc[ai][bj][m][n][i] + bv[bj][n][i]; float r;
;                             if (type < 2) { const float sg = sigmoidf_(xv); r = -expm1f(-0.606531f * sg); }
;                             else if (type == 2) r = sigmoidf_(xv);
.LBB0_905:
	v_mul_f32_e32 v68, 0xbfb8aa3b, v74
	v_exp_f32_e32 v68, v68
	s_nop 0
	v_add_f32_e32 v68, 1.0, v68
	v_rcp_f32_e32 v75, v68
	s_nop 0
	v_fma_f32 v77, -v68, v75, 1.0
	v_fma_f32 v74, v77, v75, v75
	v_div_fixup_f32 v68, v74, v68, 1.0
	v_mul_f32_e32 v68, 0xbf1b459e, v68
	v_mul_f32_e32 v74, 0x3fb8aa3b, v68
	v_rndne_f32_e32 v74, v74
	v_fmamk_f32 v75, v74, 0xbf317218, v68
	v_fmac_f32_e32 v75, 0x3102e308, v74
	v_cvt_i32_f32_e32 v76, v74
	v_fmamk_f32 v77, v75, 0x395133b1, v171
	v_fmaak_f32 v77, v75, v77, 0x3c0887f9
	v_fmaak_f32 v77, v75, v77, 0x3d2aaa81
	v_fmaak_f32 v77, v75, v77, 0x3e2aaaab
	v_ldexp_f32 v76, 1.0, v76
	v_fma_f32 v77, v75, v77, 0.5
	v_cmp_eq_f32_e32 vcc, s90, v74
	v_mul_f32_e32 v77, v75, v77
	v_fmac_f32_e32 v75, v75, v77
	v_cndmask_b32_e32 v74, v76, v172, vcc
	v_add_f32_e32 v76, -1.0, v74
	v_fmac_f32_e32 v76, v74, v75
	v_add_f32_e32 v74, v76, v76
	v_cndmask_b32_e32 v74, v76, v74, vcc
	v_cmp_nlt_f32_e32 vcc, s91, v68
	s_nop 1
	v_cndmask_b32_e64 v74, v173, -v74, vcc
	v_cmp_ngt_f32_e32 vcc, s92, v68
	s_nop 1
	v_cndmask_b32_e32 v68, 1.0, v74, vcc
.LBB0_906:
	v_add_f32_e32 v74, v69, v21
	s_and_b64 vcc, exec, s[8:9]
	s_mov_b64 s[14:15], -1
	s_cbranch_vccnz .LBB0_910
	s_and_b64 vcc, exec, s[6:7]
	v_mov_b32_e32 v69, v74
	s_cbranch_vccnz .LBB0_909
	v_mul_f32_e32 v69, 0xbfb8aa3b, v74
	v_exp_f32_e32 v69, v69
	s_nop 0
	v_add_f32_e32 v69, 1.0, v69
	v_rcp_f32_e32 v76, v69
	s_nop 0
	v_fma_f32 v78, -v69, v76, 1.0
	v_fma_f32 v75, v78, v76, v76
	v_div_fixup_f32 v69, v75, v69, 1.0

; __device__ __forceinline__ float sigmoidf_(float x) { return 1.0f / (1.0f + __expf(-x)); }
;     __device__ __forceinline__ void operator()(const f32x4 (&acc)[2][2][4][2], const Unit& u, int wr, int wc, int fr, int fq) const {
;     ...
;                         for (int i = 0; i < 4; ++i) { float xv = acc[ai][bj][m][n][i] + bv[bj][n][i]; float r;
;                             if (type < 2) { const float sg = sigmoidf_(xv); r = -expm1f(-0.606531f * sg); }
;                             else if (type == 2) r = sigmoidf_(xv);
.LBB0_911:
	v_mul_f32_e32 v69, 0xbfb8aa3b, v74
	v_exp_f32_e32 v69, v69
	s_nop 0
	v_add_f32_e32 v69, 1.0, v69
	v_rcp_f32_e32 v75, v69
	s_nop 0
	v_fma_f32 v77, -v69, v75, 1.0
	v_fma_f32 v74, v77, v75, v75
	v_div_fixup_f32 v69, v74, v69, 1.0
	v_mul_f32_e32 v69, 0xbf1b459e, v69
	v_mul_f32_e32 v74, 0x3fb8aa3b, v69
	v_rndne_f32_e32 v74, v74
	v_fmamk_f32 v75, v74, 0xbf317218, v69
	v_fmac_f32_e32 v75, 0x3102e308, v74
	v_cvt_i32_f32_e32 v76, v74
	v_fmamk_f32 v77, v75, 0x395133b1, v171
	v_fmaak_f32 v77, v75, v77, 0x3c0887f9
	v_fmaak_f32 v77, v75, v77, 0x3d2aaa81
	v_fmaak_f32 v77, v75, v77, 0x3e2aaaab
	v_ldexp_f32 v76, 1.0, v76
	v_fma_f32 v77, v75, v77, 0.5
	v_cmp_eq_f32_e32 vcc, s90, v74
	v_mul_f32_e32 v77, v75, v77
	v_fmac_f32_e32 v75, v75, v77
	v_cndmask_b32_e32 v74, v76, v172, vcc
	v_add_f32_e32 v76, -1.0, v74
	v_fmac_f32_e32 v76, v74, v75
	v_add_f32_e32 v74, v76, v76
	v_cndmask_b32_e32 v74, v76, v74, vcc
	v_cmp_nlt_f32_e32 vcc, s91, v69
	s_nop 1
	v_cndmask_b32_e64 v74, v173, -v74, vcc
	v_cmp_ngt_f32_e32 vcc, s92, v69
	s_nop 1
	v_cndmask_b32_e32 v69, 1.0, v74, vcc
.LBB0_912:
	v_add_f32_e32 v74, v70, v22
	s_and_b64 vcc, exec, s[8:9]
	s_mov_b64 s[14:15], -1
	s_cbranch_vccnz .LBB0_916
	s_and_b64 vcc, exec, s[6:7]
	v_mov_b32_e32 v70, v74
	s_cbranch_vccnz .LBB0_915
	v_mul_f32_e32 v70, 0xbfb8aa3b, v74
	v_exp_f32_e32 v70, v70
	s_nop 0
	v_add_f32_e32 v70, 1.0, v70
	v_rcp_f32_e32 v76, v70
	s_nop 0
	v_fma_f32 v78, -v70, v76, 1.0
	v_fma_f32 v75, v78, v76, v76
	v_div_fixup_f32 v70, v75, v70, 1.0

; __device__ __forceinline__ float sigmoidf_(float x) { return 1.0f / (1.0f + __expf(-x)); }
;     __device__ __forceinline__ void operator()(const f32x4 (&acc)[2][2][4][2], const Unit& u, int wr, int wc, int fr, int fq) const {
;     ...
;                         for (int i = 0; i < 4; ++i) { float xv = acc[ai][bj][m][n][i] + bv[bj][n][i]; float r;
;                             if (type < 2) { const float sg = sigmoidf_(xv); r = -expm1f(-0.606531f * sg); }
;                             else if (type == 2) r = sigmoidf_(xv);
.LBB0_917:
	v_mul_f32_e32 v70, 0xbfb8aa3b, v74
	v_exp_f32_e32 v70, v70
	s_nop 0
	v_add_f32_e32 v70, 1.0, v70
	v_rcp_f32_e32 v75, v70
	s_nop 0
	v_fma_f32 v77, -v70, v75, 1.0
	v_fma_f32 v74, v77, v75, v75
	v_div_fixup_f32 v70, v74, v70, 1.0
	v_mul_f32_e32 v70, 0xbf1b459e, v70
	v_mul_f32_e32 v74, 0x3fb8aa3b, v70
	v_rndne_f32_e32 v74, v74
	v_fmamk_f32 v75, v74, 0xbf317218, v70
	v_fmac_f32_e32 v75, 0x3102e308, v74
	v_cvt_i32_f32_e32 v76, v74
	v_fmamk_f32 v77, v75, 0x395133b1, v171
	v_fmaak_f32 v77, v75, v77, 0x3c0887f9
	v_fmaak_f32 v77, v75, v77, 0x3d2aaa81
	v_fmaak_f32 v77, v75, v77, 0x3e2aaaab
	v_ldexp_f32 v76, 1.0, v76
	v_fma_f32 v77, v75, v77, 0.5
	v_cmp_eq_f32_e32 vcc, s90, v74
	v_mul_f32_e32 v77, v75, v77
	v_fmac_f32_e32 v75, v75, v77
	v_cndmask_b32_e32 v74, v76, v172, vcc
	v_add_f32_e32 v76, -1.0, v74
	v_fmac_f32_e32 v76, v74, v75
	v_add_f32_e32 v74, v76, v76
	v_cndmask_b32_e32 v74, v76, v74, vcc
	v_cmp_nlt_f32_e32 vcc, s91, v70
	s_nop 1
	v_cndmask_b32_e64 v74, v173, -v74, vcc
	v_cmp_ngt_f32_e32 vcc, s92, v70
	s_nop 1
	v_cndmask_b32_e32 v70, 1.0, v74, vcc
.LBB0_918:
	v_add_f32_e32 v74, v71, v23
	s_and_b64 vcc, exec, s[8:9]
	s_mov_b64 s[14:15], -1
	s_cbranch_vccnz .LBB0_922
	s_and_b64 vcc, exec, s[6:7]
	v_mov_b32_e32 v71, v74
	s_cbranch_vccnz .LBB0_921
	v_mul_f32_e32 v71, 0xbfb8aa3b, v74
	v_exp_f32_e32 v71, v71
	s_nop 0
	v_add_f32_e32 v71, 1.0, v71
	v_rcp_f32_e32 v76, v71
	s_nop 0
	v_fma_f32 v78, -v71, v76, 1.0
	v_fma_f32 v75, v78, v76, v76
	v_div_fixup_f32 v71, v75, v71, 1.0

; __device__ __forceinline__ float sigmoidf_(float x) { return 1.0f / (1.0f + __expf(-x)); }
;     __device__ __forceinline__ void operator()(const f32x4 (&acc)[2][2][4][2], const Unit& u, int wr, int wc, int fr, int fq) const {
;     ...
;                         for (int i = 0; i < 4; ++i) { float xv = acc[ai][bj][m][n][i] + bv[bj][n][i]; float r;
;                             if (type < 2) { const float sg = sigmoidf_(xv); r = -expm1f(-0.606531f * sg); }
;                             else if (type == 2) r = sigmoidf_(xv);
.LBB0_923:
	v_mul_f32_e32 v71, 0xbfb8aa3b, v74
	v_exp_f32_e32 v71, v71
	s_nop 0
	v_add_f32_e32 v71, 1.0, v71
	v_rcp_f32_e32 v75, v71
	s_nop 0
	v_fma_f32 v77, -v71, v75, 1.0
	v_fma_f32 v74, v77, v75, v75
	v_div_fixup_f32 v71, v74, v71, 1.0
	v_mul_f32_e32 v71, 0xbf1b459e, v71
	v_mul_f32_e32 v74, 0x3fb8aa3b, v71
	v_rndne_f32_e32 v74, v74
	v_fmamk_f32 v75, v74, 0xbf317218, v71
	v_fmac_f32_e32 v75, 0x3102e308, v74
	v_cvt_i32_f32_e32 v76, v74
	v_fmamk_f32 v77, v75, 0x395133b1, v171
	v_fmaak_f32 v77, v75, v77, 0x3c0887f9
	v_fmaak_f32 v77, v75, v77, 0x3d2aaa81
	v_fmaak_f32 v77, v75, v77, 0x3e2aaaab
	v_ldexp_f32 v76, 1.0, v76
	v_fma_f32 v77, v75, v77, 0.5
	v_cmp_eq_f32_e32 vcc, s90, v74
	v_mul_f32_e32 v77, v75, v77
	v_fmac_f32_e32 v75, v75, v77
	v_cndmask_b32_e32 v74, v76, v172, vcc
	v_add_f32_e32 v76, -1.0, v74
	v_fmac_f32_e32 v76, v74, v75
	v_add_f32_e32 v74, v76, v76
	v_cndmask_b32_e32 v74, v76, v74, vcc
	v_cmp_nlt_f32_e32 vcc, s91, v71
	s_nop 1
	v_cndmask_b32_e64 v74, v173, -v74, vcc
	v_cmp_ngt_f32_e32 vcc, s92, v71
	s_nop 1
	v_cndmask_b32_e32 v71, 1.0, v74, vcc
.LBB0_924:
	v_add_f32_e32 v74, v64, v12
	s_and_b64 vcc, exec, s[8:9]
	s_mov_b64 s[14:15], -1
	s_cbranch_vccnz .LBB0_928
	s_and_b64 vcc, exec, s[6:7]
	v_mov_b32_e32 v64, v74
	s_cbranch_vccnz .LBB0_927
	v_mul_f32_e32 v64, 0xbfb8aa3b, v74
	v_exp_f32_e32 v64, v64
	s_nop 0
	v_add_f32_e32 v64, 1.0, v64
	v_rcp_f32_e32 v76, v64
	s_nop 0
	v_fma_f32 v78, -v64, v76, 1.0
	v_fma_f32 v75, v78, v76, v76
	v_div_fixup_f32 v64, v75, v64, 1.0

; __device__ __forceinline__ float sigmoidf_(float x) { return 1.0f / (1.0f + __expf(-x)); }
;     __device__ __forceinline__ void operator()(const f32x4 (&acc)[2][2][4][2], const Unit& u, int wr, int wc, int fr, int fq) const {
;     ...
;                         for (int i = 0; i < 4; ++i) { float xv = acc[ai][bj][m][n][i] + bv[bj][n][i]; float r;
;                             if (type < 2) { const float sg = sigmoidf_(xv); r = -expm1f(-0.606531f * sg); }
;                             else if (type == 2) r = sigmoidf_(xv);
.LBB0_929:
	v_mul_f32_e32 v64, 0xbfb8aa3b, v74
	v_exp_f32_e32 v64, v64
	s_nop 0
	v_add_f32_e32 v64, 1.0, v64
	v_rcp_f32_e32 v75, v64
	s_nop 0
	v_fma_f32 v77, -v64, v75, 1.0
	v_fma_f32 v74, v77, v75, v75
	v_div_fixup_f32 v64, v74, v64, 1.0
	v_mul_f32_e32 v64, 0xbf1b459e, v64
	v_mul_f32_e32 v74, 0x3fb8aa3b, v64
	v_rndne_f32_e32 v74, v74
	v_fmamk_f32 v75, v74, 0xbf317218, v64
	v_fmac_f32_e32 v75, 0x3102e308, v74
	v_cvt_i32_f32_e32 v76, v74
	v_fmamk_f32 v77, v75, 0x395133b1, v171
	v_fmaak_f32 v77, v75, v77, 0x3c0887f9
	v_fmaak_f32 v77, v75, v77, 0x3d2aaa81
	v_fmaak_f32 v77, v75, v77, 0x3e2aaaab
	v_ldexp_f32 v76, 1.0, v76
	v_fma_f32 v77, v75, v77, 0.5
	v_cmp_eq_f32_e32 vcc, s90, v74
	v_mul_f32_e32 v77, v75, v77
	v_fmac_f32_e32 v75, v75, v77
	v_cndmask_b32_e32 v74, v76, v172, vcc
	v_add_f32_e32 v76, -1.0, v74
	v_fmac_f32_e32 v76, v74, v75
	v_add_f32_e32 v74, v76, v76
	v_cndmask_b32_e32 v74, v76, v74, vcc
	v_cmp_nlt_f32_e32 vcc, s91, v64
	s_nop 1
	v_cndmask_b32_e64 v74, v173, -v74, vcc
	v_cmp_ngt_f32_e32 vcc, s92, v64
	s_nop 1
	v_cndmask_b32_e32 v64, 1.0, v74, vcc
.LBB0_930:
	v_add_f32_e32 v74, v65, v13
	s_and_b64 vcc, exec, s[8:9]
	s_mov_b64 s[14:15], -1
	s_cbranch_vccnz .LBB0_934
	s_and_b64 vcc, exec, s[6:7]
	v_mov_b32_e32 v65, v74
	s_cbranch_vccnz .LBB0_933
	v_mul_f32_e32 v65, 0xbfb8aa3b, v74
	v_exp_f32_e32 v65, v65
	s_nop 0
	v_add_f32_e32 v65, 1.0, v65
	v_rcp_f32_e32 v76, v65
	s_nop 0
	v_fma_f32 v78, -v65, v76, 1.0
	v_fma_f32 v75, v78, v76, v76
	v_div_fixup_f32 v65, v75, v65, 1.0

; __device__ __forceinline__ float sigmoidf_(float x) { return 1.0f / (1.0f + __expf(-x)); }
;     __device__ __forceinline__ void operator()(const f32x4 (&acc)[2][2][4][2], const Unit& u, int wr, int wc, int fr, int fq) const {
;     ...
;                         for (int i = 0; i < 4; ++i) { float xv = acc[ai][bj][m][n][i] + bv[bj][n][i]; float r;
;                             if (type < 2) { const float sg = sigmoidf_(xv); r = -expm1f(-0.606531f * sg); }
;                             else if (type == 2) r = sigmoidf_(xv);
.LBB0_935:
	v_mul_f32_e32 v65, 0xbfb8aa3b, v74
	v_exp_f32_e32 v65, v65
	s_nop 0
	v_add_f32_e32 v65, 1.0, v65
	v_rcp_f32_e32 v75, v65
	s_nop 0
	v_fma_f32 v77, -v65, v75, 1.0
	v_fma_f32 v74, v77, v75, v75
	v_div_fixup_f32 v65, v74, v65, 1.0
	v_mul_f32_e32 v65, 0xbf1b459e, v65
	v_mul_f32_e32 v74, 0x3fb8aa3b, v65
	v_rndne_f32_e32 v74, v74
	v_fmamk_f32 v75, v74, 0xbf317218, v65
	v_fmac_f32_e32 v75, 0x3102e308, v74
	v_cvt_i32_f32_e32 v76, v74
	v_fmamk_f32 v77, v75, 0x395133b1, v171
	v_fmaak_f32 v77, v75, v77, 0x3c0887f9
	v_fmaak_f32 v77, v75, v77, 0x3d2aaa81
	v_fmaak_f32 v77, v75, v77, 0x3e2aaaab
	v_ldexp_f32 v76, 1.0, v76
	v_fma_f32 v77, v75, v77, 0.5
	v_cmp_eq_f32_e32 vcc, s90, v74
	v_mul_f32_e32 v77, v75, v77
	v_fmac_f32_e32 v75, v75, v77
	v_cndmask_b32_e32 v74, v76, v172, vcc
	v_add_f32_e32 v76, -1.0, v74
	v_fmac_f32_e32 v76, v74, v75
	v_add_f32_e32 v74, v76, v76
	v_cndmask_b32_e32 v74, v76, v74, vcc
	v_cmp_nlt_f32_e32 vcc, s91, v65
	s_nop 1
	v_cndmask_b32_e64 v74, v173, -v74, vcc
	v_cmp_ngt_f32_e32 vcc, s92, v65
	s_nop 1
	v_cndmask_b32_e32 v65, 1.0, v74, vcc
.LBB0_936:
	v_add_f32_e32 v74, v66, v14
	s_and_b64 vcc, exec, s[8:9]
	s_mov_b64 s[14:15], -1
	s_cbranch_vccnz .LBB0_940
	s_and_b64 vcc, exec, s[6:7]
	v_mov_b32_e32 v66, v74
	s_cbranch_vccnz .LBB0_939
	v_mul_f32_e32 v66, 0xbfb8aa3b, v74
	v_exp_f32_e32 v66, v66
	s_nop 0
	v_add_f32_e32 v66, 1.0, v66
	v_rcp_f32_e32 v76, v66
	s_nop 0
	v_fma_f32 v78, -v66, v76, 1.0
	v_fma_f32 v75, v78, v76, v76
	v_div_fixup_f32 v66, v75, v66, 1.0

; __device__ __forceinline__ float sigmoidf_(float x) { return 1.0f / (1.0f + __expf(-x)); }
;     __device__ __forceinline__ void operator()(const f32x4 (&acc)[2][2][4][2], const Unit& u, int wr, int wc, int fr, int fq) const {
;     ...
;                         for (int i = 0; i < 4; ++i) { float xv = acc[ai][bj][m][n][i] + bv[bj][n][i]; float r;
;                             if (type < 2) { const float sg = sigmoidf_(xv); r = -expm1f(-0.606531f * sg); }
;                             else if (type == 2) r = sigmoidf_(xv);
.LBB0_941:
	v_mul_f32_e32 v66, 0xbfb8aa3b, v74
	v_exp_f32_e32 v66, v66
	s_nop 0
	v_add_f32_e32 v66, 1.0, v66
	v_rcp_f32_e32 v75, v66
	s_nop 0
	v_fma_f32 v77, -v66, v75, 1.0
	v_fma_f32 v74, v77, v75, v75
	v_div_fixup_f32 v66, v74, v66, 1.0
	v_mul_f32_e32 v66, 0xbf1b459e, v66
	v_mul_f32_e32 v74, 0x3fb8aa3b, v66
	v_rndne_f32_e32 v74, v74
	v_fmamk_f32 v75, v74, 0xbf317218, v66
	v_fmac_f32_e32 v75, 0x3102e308, v74
	v_cvt_i32_f32_e32 v76, v74
	v_fmamk_f32 v77, v75, 0x395133b1, v171
	v_fmaak_f32 v77, v75, v77, 0x3c0887f9
	v_fmaak_f32 v77, v75, v77, 0x3d2aaa81
	v_fmaak_f32 v77, v75, v77, 0x3e2aaaab
	v_ldexp_f32 v76, 1.0, v76
	v_fma_f32 v77, v75, v77, 0.5
	v_cmp_eq_f32_e32 vcc, s90, v74
	v_mul_f32_e32 v77, v75, v77
	v_fmac_f32_e32 v75, v75, v77
	v_cndmask_b32_e32 v74, v76, v172, vcc
	v_add_f32_e32 v76, -1.0, v74
	v_fmac_f32_e32 v76, v74, v75
	v_add_f32_e32 v74, v76, v76
	v_cndmask_b32_e32 v74, v76, v74, vcc
	v_cmp_nlt_f32_e32 vcc, s91, v66
	s_nop 1
	v_cndmask_b32_e64 v74, v173, -v74, vcc
	v_cmp_ngt_f32_e32 vcc, s92, v66
	s_nop 1
	v_cndmask_b32_e32 v66, 1.0, v74, vcc
.LBB0_942:
	v_add_f32_e32 v67, v67, v15
	s_and_b64 vcc, exec, s[8:9]
	s_mov_b64 s[14:15], -1
	s_cbranch_vccnz .LBB0_946
	s_and_b64 vcc, exec, s[6:7]
	v_mov_b32_e32 v74, v67
	s_cbranch_vccnz .LBB0_945
	v_mul_f32_e32 v74, 0xbfb8aa3b, v67
	v_exp_f32_e32 v74, v74
	s_nop 0
	v_add_f32_e32 v74, 1.0, v74
	v_rcp_f32_e32 v76, v74
	s_nop 0
	v_fma_f32 v78, -v74, v76, 1.0
	v_fma_f32 v75, v78, v76, v76
	v_div_fixup_f32 v74, v75, v74, 1.0

; __device__ __forceinline__ float sigmoidf_(float x) { return 1.0f / (1.0f + __expf(-x)); }
;     __device__ __forceinline__ void operator()(const f32x4 (&acc)[2][2][4][2], const Unit& u, int wr, int wc, int fr, int fq) const {
;     ...
;                         for (int i = 0; i < 4; ++i) { float xv = acc[ai][bj][m][n][i] + bv[bj][n][i]; float r;
;                             if (type < 2) { const float sg = sigmoidf_(xv); r = -expm1f(-0.606531f * sg); }
;                             else if (type == 2) r = sigmoidf_(xv);
;                             else r = xv;
;                             v[4 * n + i] = (f16)r; }
;                     *(f16x8*)(rowp + bj * 128) = v; } }
.LBB0_947:
	v_mul_f32_e32 v67, 0xbfb8aa3b, v67
	v_exp_f32_e32 v67, v67
	s_nop 0
	v_add_f32_e32 v67, 1.0, v67
	v_rcp_f32_e32 v75, v67
	s_nop 0
	v_fma_f32 v77, -v67, v75, 1.0
	v_fma_f32 v74, v77, v75, v75
	v_div_fixup_f32 v67, v74, v67, 1.0
	v_mul_f32_e32 v67, 0xbf1b459e, v67
	v_mul_f32_e32 v74, 0x3fb8aa3b, v67
	v_rndne_f32_e32 v74, v74
	v_fmamk_f32 v75, v74, 0xbf317218, v67
	v_fmac_f32_e32 v75, 0x3102e308, v74
	v_cvt_i32_f32_e32 v76, v74
	v_fmamk_f32 v77, v75, 0x395133b1, v171
	v_fmaak_f32 v77, v75, v77, 0x3c0887f9
	v_fmaak_f32 v77, v75, v77, 0x3d2aaa81
	v_fmaak_f32 v77, v75, v77, 0x3e2aaaab
	v_ldexp_f32 v76, 1.0, v76
	v_fma_f32 v77, v75, v77, 0.5
	v_cmp_eq_f32_e32 vcc, s90, v74
	v_mul_f32_e32 v77, v75, v77
	v_fmac_f32_e32 v75, v75, v77
	v_cndmask_b32_e32 v74, v76, v172, vcc
	v_add_f32_e32 v76, -1.0, v74
	v_fmac_f32_e32 v76, v74, v75
	v_add_f32_e32 v74, v76, v76
	v_cndmask_b32_e32 v74, v76, v74, vcc
	v_cmp_nlt_f32_e32 vcc, s91, v67
	s_nop 1
	v_cndmask_b32_e64 v74, v173, -v74, vcc
	v_cmp_ngt_f32_e32 vcc, s92, v67
	s_nop 1
	v_cndmask_b32_e32 v74, 1.0, v74, vcc
.LBB0_948:
	s_mov_b64 s[2:3], 0x100000
	v_lshl_add_u64 v[72:73], v[72:73], 0, s[2:3]
	v_cvt_pk_f16_f32 v67, v66, v74
	v_cvt_pk_f16_f32 v66, v64, v65
	v_cvt_pk_f16_f32 v65, v70, v71
	v_cvt_pk_f16_f32 v64, v68, v69
	global_store_dwordx4 v[72:73], v[64:67], off offset:256
	s_and_b64 vcc, exec, s[8:9]
	s_mov_b64 s[14:15], -1
	v_add_f32_e32 v64, v60, v32
	s_cbranch_vccnz .LBB0_952
	s_and_b64 vcc, exec, s[6:7]
	v_mov_b32_e32 v60, v64
	s_cbranch_vccnz .LBB0_951
	v_mul_f32_e32 v60, 0xbfb8aa3b, v64
	v_exp_f32_e32 v60, v60
	s_nop 0
	v_add_f32_e32 v60, 1.0, v60
	v_rcp_f32_e32 v66, v60
	s_nop 0
	v_fma_f32 v68, -v60, v66, 1.0
	v_fma_f32 v65, v68, v66, v66
	v_div_fixup_f32 v60, v65, v60, 1.0

; __device__ __forceinline__ float sigmoidf_(float x) { return 1.0f / (1.0f + __expf(-x)); }
;     __device__ __forceinline__ void operator()(const f32x4 (&acc)[2][2][4][2], const Unit& u, int wr, int wc, int fr, int fq) const {
;     ...
;                         for (int i = 0; i < 4; ++i) { float xv = acc[ai][bj][m][n][i] + bv[bj][n][i]; float r;
;                             if (type < 2) { const float sg = sigmoidf_(xv); r = -expm1f(-0.606531f * sg); }
;                             else if (type == 2) r = sigmoidf_(xv);
.LBB0_953:
	v_mul_f32_e32 v60, 0xbfb8aa3b, v64
	v_exp_f32_e32 v60, v60
	s_nop 0
	v_add_f32_e32 v60, 1.0, v60
	v_rcp_f32_e32 v65, v60
	s_nop 0
	v_fma_f32 v67, -v60, v65, 1.0
	v_fma_f32 v64, v67, v65, v65
	v_div_fixup_f32 v60, v64, v60, 1.0
	v_mul_f32_e32 v60, 0xbf1b459e, v60
	v_mul_f32_e32 v64, 0x3fb8aa3b, v60
	v_rndne_f32_e32 v64, v64
	v_fmamk_f32 v65, v64, 0xbf317218, v60
	v_fmac_f32_e32 v65, 0x3102e308, v64
	v_cvt_i32_f32_e32 v66, v64
	v_fmamk_f32 v67, v65, 0x395133b1, v171
	v_fmaak_f32 v67, v65, v67, 0x3c0887f9
	v_fmaak_f32 v67, v65, v67, 0x3d2aaa81
	v_fmaak_f32 v67, v65, v67, 0x3e2aaaab
	v_ldexp_f32 v66, 1.0, v66
	v_fma_f32 v67, v65, v67, 0.5
	v_cmp_eq_f32_e32 vcc, s90, v64
	v_mul_f32_e32 v67, v65, v67
	v_fmac_f32_e32 v65, v65, v67
	v_cndmask_b32_e32 v64, v66, v172, vcc
	v_add_f32_e32 v66, -1.0, v64
	v_fmac_f32_e32 v66, v64, v65
	v_add_f32_e32 v64, v66, v66
	v_cndmask_b32_e32 v64, v66, v64, vcc
	v_cmp_nlt_f32_e32 vcc, s91, v60
	s_nop 1
	v_cndmask_b32_e64 v64, v173, -v64, vcc
	v_cmp_ngt_f32_e32 vcc, s92, v60
	s_nop 1
	v_cndmask_b32_e32 v60, 1.0, v64, vcc
.LBB0_954:
	v_add_f32_e32 v64, v61, v33
	s_and_b64 vcc, exec, s[8:9]
	s_mov_b64 s[14:15], -1
	s_cbranch_vccnz .LBB0_958
	s_and_b64 vcc, exec, s[6:7]
	v_mov_b32_e32 v61, v64
	s_cbranch_vccnz .LBB0_957
	v_mul_f32_e32 v61, 0xbfb8aa3b, v64
	v_exp_f32_e32 v61, v61
	s_nop 0
	v_add_f32_e32 v61, 1.0, v61
	v_rcp_f32_e32 v66, v61
	s_nop 0
	v_fma_f32 v68, -v61, v66, 1.0
	v_fma_f32 v65, v68, v66, v66
	v_div_fixup_f32 v61, v65, v61, 1.0

; __device__ __forceinline__ float sigmoidf_(float x) { return 1.0f / (1.0f + __expf(-x)); }
;     __device__ __forceinline__ void operator()(const f32x4 (&acc)[2][2][4][2], const Unit& u, int wr, int wc, int fr, int fq) const {
;     ...
;                         for (int i = 0; i < 4; ++i) { float xv = acc[ai][bj][m][n][i] + bv[bj][n][i]; float r;
;                             if (type < 2) { const float sg = sigmoidf_(xv); r = -expm1f(-0.606531f * sg); }
;                             else if (type == 2) r = sigmoidf_(xv);
.LBB0_959:
	v_mul_f32_e32 v61, 0xbfb8aa3b, v64
	v_exp_f32_e32 v61, v61
	s_nop 0
	v_add_f32_e32 v61, 1.0, v61
	v_rcp_f32_e32 v65, v61
	s_nop 0
	v_fma_f32 v67, -v61, v65, 1.0
	v_fma_f32 v64, v67, v65, v65
	v_div_fixup_f32 v61, v64, v61, 1.0
	v_mul_f32_e32 v61, 0xbf1b459e, v61
	v_mul_f32_e32 v64, 0x3fb8aa3b, v61
	v_rndne_f32_e32 v64, v64
	v_fmamk_f32 v65, v64, 0xbf317218, v61
	v_fmac_f32_e32 v65, 0x3102e308, v64
	v_cvt_i32_f32_e32 v66, v64
	v_fmamk_f32 v67, v65, 0x395133b1, v171
	v_fmaak_f32 v67, v65, v67, 0x3c0887f9
	v_fmaak_f32 v67, v65, v67, 0x3d2aaa81
	v_fmaak_f32 v67, v65, v67, 0x3e2aaaab
	v_ldexp_f32 v66, 1.0, v66
	v_fma_f32 v67, v65, v67, 0.5
	v_cmp_eq_f32_e32 vcc, s90, v64
	v_mul_f32_e32 v67, v65, v67
	v_fmac_f32_e32 v65, v65, v67
	v_cndmask_b32_e32 v64, v66, v172, vcc
	v_add_f32_e32 v66, -1.0, v64
	v_fmac_f32_e32 v66, v64, v65
	v_add_f32_e32 v64, v66, v66
	v_cndmask_b32_e32 v64, v66, v64, vcc
	v_cmp_nlt_f32_e32 vcc, s91, v61
	s_nop 1
	v_cndmask_b32_e64 v64, v173, -v64, vcc
	v_cmp_ngt_f32_e32 vcc, s92, v61
	s_nop 1
	v_cndmask_b32_e32 v61, 1.0, v64, vcc
.LBB0_960:
	v_add_f32_e32 v64, v62, v34
	s_and_b64 vcc, exec, s[8:9]
	s_mov_b64 s[14:15], -1
	s_cbranch_vccnz .LBB0_964
	s_and_b64 vcc, exec, s[6:7]
	v_mov_b32_e32 v62, v64
	s_cbranch_vccnz .LBB0_963
	v_mul_f32_e32 v62, 0xbfb8aa3b, v64
	v_exp_f32_e32 v62, v62
	s_nop 0
	v_add_f32_e32 v62, 1.0, v62
	v_rcp_f32_e32 v66, v62
	s_nop 0
	v_fma_f32 v68, -v62, v66, 1.0
	v_fma_f32 v65, v68, v66, v66
	v_div_fixup_f32 v62, v65, v62, 1.0

; __device__ __forceinline__ float sigmoidf_(float x) { return 1.0f / (1.0f + __expf(-x)); }
;     __device__ __forceinline__ void operator()(const f32x4 (&acc)[2][2][4][2], const Unit& u, int wr, int wc, int fr, int fq) const {
;     ...
;                         for (int i = 0; i < 4; ++i) { float xv = acc[ai][bj][m][n][i] + bv[bj][n][i]; float r;
;                             if (type < 2) { const float sg = sigmoidf_(xv); r = -expm1f(-0.606531f * sg); }
;                             else if (type == 2) r = sigmoidf_(xv);
.LBB0_965:
	v_mul_f32_e32 v62, 0xbfb8aa3b, v64
	v_exp_f32_e32 v62, v62
	s_nop 0
	v_add_f32_e32 v62, 1.0, v62
	v_rcp_f32_e32 v65, v62
	s_nop 0
	v_fma_f32 v67, -v62, v65, 1.0
	v_fma_f32 v64, v67, v65, v65
	v_div_fixup_f32 v62, v64, v62, 1.0
	v_mul_f32_e32 v62, 0xbf1b459e, v62
	v_mul_f32_e32 v64, 0x3fb8aa3b, v62
	v_rndne_f32_e32 v64, v64
	v_fmamk_f32 v65, v64, 0xbf317218, v62
	v_fmac_f32_e32 v65, 0x3102e308, v64
	v_cvt_i32_f32_e32 v66, v64
	v_fmamk_f32 v67, v65, 0x395133b1, v171
	v_fmaak_f32 v67, v65, v67, 0x3c0887f9
	v_fmaak_f32 v67, v65, v67, 0x3d2aaa81
	v_fmaak_f32 v67, v65, v67, 0x3e2aaaab
	v_ldexp_f32 v66, 1.0, v66
	v_fma_f32 v67, v65, v67, 0.5
	v_cmp_eq_f32_e32 vcc, s90, v64
	v_mul_f32_e32 v67, v65, v67
	v_fmac_f32_e32 v65, v65, v67
	v_cndmask_b32_e32 v64, v66, v172, vcc
	v_add_f32_e32 v66, -1.0, v64
	v_fmac_f32_e32 v66, v64, v65
	v_add_f32_e32 v64, v66, v66
	v_cndmask_b32_e32 v64, v66, v64, vcc
	v_cmp_nlt_f32_e32 vcc, s91, v62
	s_nop 1
	v_cndmask_b32_e64 v64, v173, -v64, vcc
	v_cmp_ngt_f32_e32 vcc, s92, v62
	s_nop 1
	v_cndmask_b32_e32 v62, 1.0, v64, vcc
.LBB0_966:
	v_add_f32_e32 v64, v63, v35
	s_and_b64 vcc, exec, s[8:9]
	s_mov_b64 s[14:15], -1
	s_cbranch_vccnz .LBB0_970
	s_and_b64 vcc, exec, s[6:7]
	v_mov_b32_e32 v63, v64
	s_cbranch_vccnz .LBB0_969
	v_mul_f32_e32 v63, 0xbfb8aa3b, v64
	v_exp_f32_e32 v63, v63
	s_nop 0
	v_add_f32_e32 v63, 1.0, v63
	v_rcp_f32_e32 v66, v63
	s_nop 0
	v_fma_f32 v68, -v63, v66, 1.0
	v_fma_f32 v65, v68, v66, v66
	v_div_fixup_f32 v63, v65, v63, 1.0

; __device__ __forceinline__ float sigmoidf_(float x) { return 1.0f / (1.0f + __expf(-x)); }
;     __device__ __forceinline__ void operator()(const f32x4 (&acc)[2][2][4][2], const Unit& u, int wr, int wc, int fr, int fq) const {
;     ...
;                         for (int i = 0; i < 4; ++i) { float xv = acc[ai][bj][m][n][i] + bv[bj][n][i]; float r;
;                             if (type < 2) { const float sg = sigmoidf_(xv); r = -expm1f(-0.606531f * sg); }
;                             else if (type == 2) r = sigmoidf_(xv);
.LBB0_971:
	v_mul_f32_e32 v63, 0xbfb8aa3b, v64
	v_exp_f32_e32 v63, v63
	s_nop 0
	v_add_f32_e32 v63, 1.0, v63
	v_rcp_f32_e32 v65, v63
	s_nop 0
	v_fma_f32 v67, -v63, v65, 1.0
	v_fma_f32 v64, v67, v65, v65
	v_div_fixup_f32 v63, v64, v63, 1.0
	v_mul_f32_e32 v63, 0xbf1b459e, v63
	v_mul_f32_e32 v64, 0x3fb8aa3b, v63
	v_rndne_f32_e32 v64, v64
	v_fmamk_f32 v65, v64, 0xbf317218, v63
	v_fmac_f32_e32 v65, 0x3102e308, v64
	v_cvt_i32_f32_e32 v66, v64
	v_fmamk_f32 v67, v65, 0x395133b1, v171
	v_fmaak_f32 v67, v65, v67, 0x3c0887f9
	v_fmaak_f32 v67, v65, v67, 0x3d2aaa81
	v_fmaak_f32 v67, v65, v67, 0x3e2aaaab
	v_ldexp_f32 v66, 1.0, v66
	v_fma_f32 v67, v65, v67, 0.5
	v_cmp_eq_f32_e32 vcc, s90, v64
	v_mul_f32_e32 v67, v65, v67
	v_fmac_f32_e32 v65, v65, v67
	v_cndmask_b32_e32 v64, v66, v172, vcc
	v_add_f32_e32 v66, -1.0, v64
	v_fmac_f32_e32 v66, v64, v65
	v_add_f32_e32 v64, v66, v66
	v_cndmask_b32_e32 v64, v66, v64, vcc
	v_cmp_nlt_f32_e32 vcc, s91, v63
	s_nop 1
	v_cndmask_b32_e64 v64, v173, -v64, vcc
	v_cmp_ngt_f32_e32 vcc, s92, v63
	s_nop 1
	v_cndmask_b32_e32 v63, 1.0, v64, vcc
.LBB0_972:
	v_add_f32_e32 v56, v56, v28
	s_and_b64 vcc, exec, s[8:9]
	s_mov_b64 s[14:15], -1
	s_cbranch_vccnz .LBB0_976
	s_and_b64 vcc, exec, s[6:7]
	v_mov_b32_e32 v64, v56
	s_cbranch_vccnz .LBB0_975
	v_mul_f32_e32 v64, 0xbfb8aa3b, v56
	v_exp_f32_e32 v64, v64
	s_nop 0
	v_add_f32_e32 v64, 1.0, v64
	v_rcp_f32_e32 v66, v64
	s_nop 0
	v_fma_f32 v68, -v64, v66, 1.0
	v_fma_f32 v65, v68, v66, v66
	v_div_fixup_f32 v64, v65, v64, 1.0

; __device__ __forceinline__ float sigmoidf_(float x) { return 1.0f / (1.0f + __expf(-x)); }
;     __device__ __forceinline__ void operator()(const f32x4 (&acc)[2][2][4][2], const Unit& u, int wr, int wc, int fr, int fq) const {
;     ...
;                         for (int i = 0; i < 4; ++i) { float xv = acc[ai][bj][m][n][i] + bv[bj][n][i]; float r;
;                             if (type < 2) { const float sg = sigmoidf_(xv); r = -expm1f(-0.606531f * sg); }
;                             else if (type == 2) r = sigmoidf_(xv);
.LBB0_977:
	v_mul_f32_e32 v56, 0xbfb8aa3b, v56
	v_exp_f32_e32 v56, v56
	s_nop 0
	v_add_f32_e32 v56, 1.0, v56
	v_rcp_f32_e32 v65, v56
	s_nop 0
	v_fma_f32 v67, -v56, v65, 1.0
	v_fma_f32 v64, v67, v65, v65
	v_div_fixup_f32 v56, v64, v56, 1.0
	v_mul_f32_e32 v56, 0xbf1b459e, v56
	v_mul_f32_e32 v64, 0x3fb8aa3b, v56
	v_rndne_f32_e32 v64, v64
	v_fmamk_f32 v65, v64, 0xbf317218, v56
	v_fmac_f32_e32 v65, 0x3102e308, v64
	v_cvt_i32_f32_e32 v66, v64
	v_fmamk_f32 v67, v65, 0x395133b1, v171
	v_fmaak_f32 v67, v65, v67, 0x3c0887f9
	v_fmaak_f32 v67, v65, v67, 0x3d2aaa81
	v_fmaak_f32 v67, v65, v67, 0x3e2aaaab
	v_ldexp_f32 v66, 1.0, v66
	v_fma_f32 v67, v65, v67, 0.5
	v_cmp_eq_f32_e32 vcc, s90, v64
	v_mul_f32_e32 v67, v65, v67
	v_fmac_f32_e32 v65, v65, v67
	v_cndmask_b32_e32 v64, v66, v172, vcc
	v_add_f32_e32 v66, -1.0, v64
	v_fmac_f32_e32 v66, v64, v65
	v_add_f32_e32 v64, v66, v66
	v_cndmask_b32_e32 v64, v66, v64, vcc
	v_cmp_nlt_f32_e32 vcc, s91, v56
	s_nop 1
	v_cndmask_b32_e64 v64, v173, -v64, vcc
	v_cmp_ngt_f32_e32 vcc, s92, v56
	s_nop 1
	v_cndmask_b32_e32 v64, 1.0, v64, vcc
.LBB0_978:
	v_add_f32_e32 v56, v57, v29
	s_and_b64 vcc, exec, s[8:9]
	s_mov_b64 s[14:15], -1
	s_cbranch_vccnz .LBB0_982
	s_and_b64 vcc, exec, s[6:7]
	v_mov_b32_e32 v65, v56
	s_cbranch_vccnz .LBB0_981
	v_mul_f32_e32 v57, 0xbfb8aa3b, v56
	v_exp_f32_e32 v57, v57
	s_nop 0
	v_add_f32_e32 v57, 1.0, v57
	v_rcp_f32_e32 v66, v57
	s_nop 0
	v_fma_f32 v68, -v57, v66, 1.0
	v_fma_f32 v65, v68, v66, v66
	v_div_fixup_f32 v65, v65, v57, 1.0

; __device__ __forceinline__ float sigmoidf_(float x) { return 1.0f / (1.0f + __expf(-x)); }
;     __device__ __forceinline__ void operator()(const f32x4 (&acc)[2][2][4][2], const Unit& u, int wr, int wc, int fr, int fq) const {
;     ...
;                         for (int i = 0; i < 4; ++i) { float xv = acc[ai][bj][m][n][i] + bv[bj][n][i]; float r;
;                             if (type < 2) { const float sg = sigmoidf_(xv); r = -expm1f(-0.606531f * sg); }
;                             else if (type == 2) r = sigmoidf_(xv);
.LBB0_983:
	v_mul_f32_e32 v56, 0xbfb8aa3b, v56
	v_exp_f32_e32 v56, v56
	s_nop 0
	v_add_f32_e32 v56, 1.0, v56
	v_rcp_f32_e32 v65, v56
	s_nop 0
	v_fma_f32 v67, -v56, v65, 1.0
	v_fma_f32 v57, v67, v65, v65
	v_div_fixup_f32 v56, v57, v56, 1.0
	v_mul_f32_e32 v56, 0xbf1b459e, v56
	v_mul_f32_e32 v57, 0x3fb8aa3b, v56
	v_rndne_f32_e32 v57, v57
	v_fmamk_f32 v65, v57, 0xbf317218, v56
	v_fmac_f32_e32 v65, 0x3102e308, v57
	v_cvt_i32_f32_e32 v66, v57
	v_fmamk_f32 v67, v65, 0x395133b1, v171
	v_fmaak_f32 v67, v65, v67, 0x3c0887f9
	v_fmaak_f32 v67, v65, v67, 0x3d2aaa81
	v_fmaak_f32 v67, v65, v67, 0x3e2aaaab
	v_ldexp_f32 v66, 1.0, v66
	v_fma_f32 v67, v65, v67, 0.5
	v_cmp_eq_f32_e32 vcc, s90, v57
	v_mul_f32_e32 v67, v65, v67
	v_fmac_f32_e32 v65, v65, v67
	v_cndmask_b32_e32 v57, v66, v172, vcc
	v_add_f32_e32 v66, -1.0, v57
	v_fmac_f32_e32 v66, v57, v65
	v_add_f32_e32 v57, v66, v66
	v_cndmask_b32_e32 v57, v66, v57, vcc
	v_cmp_nlt_f32_e32 vcc, s91, v56
	s_nop 1
	v_cndmask_b32_e64 v57, v173, -v57, vcc
	v_cmp_ngt_f32_e32 vcc, s92, v56
	s_nop 1
	v_cndmask_b32_e32 v65, 1.0, v57, vcc
.LBB0_984:
	v_add_f32_e32 v56, v58, v30
	s_and_b64 vcc, exec, s[8:9]
	s_mov_b64 s[14:15], -1
	s_cbranch_vccnz .LBB0_988
	s_and_b64 vcc, exec, s[6:7]
	v_mov_b32_e32 v58, v56
	s_cbranch_vccnz .LBB0_987
	v_mul_f32_e32 v57, 0xbfb8aa3b, v56
	v_exp_f32_e32 v57, v57
	s_nop 0
	v_add_f32_e32 v57, 1.0, v57
	v_rcp_f32_e32 v66, v57
	s_nop 0
	v_fma_f32 v68, -v57, v66, 1.0
	v_fma_f32 v58, v68, v66, v66
	v_div_fixup_f32 v58, v58, v57, 1.0

; __device__ __forceinline__ float sigmoidf_(float x) { return 1.0f / (1.0f + __expf(-x)); }
;     __device__ __forceinline__ void operator()(const f32x4 (&acc)[2][2][4][2], const Unit& u, int wr, int wc, int fr, int fq) const {
;     ...
;                         for (int i = 0; i < 4; ++i) { float xv = acc[ai][bj][m][n][i] + bv[bj][n][i]; float r;
;                             if (type < 2) { const float sg = sigmoidf_(xv); r = -expm1f(-0.606531f * sg); }
;                             else if (type == 2) r = sigmoidf_(xv);
.LBB0_989:
	v_mul_f32_e32 v56, 0xbfb8aa3b, v56
	v_exp_f32_e32 v56, v56
	s_nop 0
	v_add_f32_e32 v56, 1.0, v56
	v_rcp_f32_e32 v58, v56
	s_nop 0
	v_fma_f32 v67, -v56, v58, 1.0
	v_fma_f32 v57, v67, v58, v58
	v_div_fixup_f32 v56, v57, v56, 1.0
	v_mul_f32_e32 v56, 0xbf1b459e, v56
	v_mul_f32_e32 v57, 0x3fb8aa3b, v56
	v_rndne_f32_e32 v57, v57
	v_fmamk_f32 v58, v57, 0xbf317218, v56
	v_fmac_f32_e32 v58, 0x3102e308, v57
	v_cvt_i32_f32_e32 v66, v57
	v_fmamk_f32 v67, v58, 0x395133b1, v171
	v_fmaak_f32 v67, v58, v67, 0x3c0887f9
	v_fmaak_f32 v67, v58, v67, 0x3d2aaa81
	v_fmaak_f32 v67, v58, v67, 0x3e2aaaab
	v_ldexp_f32 v66, 1.0, v66
	v_fma_f32 v67, v58, v67, 0.5
	v_cmp_eq_f32_e32 vcc, s90, v57
	v_mul_f32_e32 v67, v58, v67
	v_fmac_f32_e32 v58, v58, v67
	v_cndmask_b32_e32 v57, v66, v172, vcc
	v_add_f32_e32 v66, -1.0, v57
	v_fmac_f32_e32 v66, v57, v58
	v_add_f32_e32 v57, v66, v66
	v_cndmask_b32_e32 v57, v66, v57, vcc
	v_cmp_nlt_f32_e32 vcc, s91, v56
	s_nop 1
	v_cndmask_b32_e64 v57, v173, -v57, vcc
	v_cmp_ngt_f32_e32 vcc, s92, v56
	s_nop 1
	v_cndmask_b32_e32 v58, 1.0, v57, vcc
.LBB0_990:
	v_add_f32_e32 v56, v59, v31
	s_and_b64 vcc, exec, s[8:9]
	s_mov_b64 s[14:15], -1
	s_cbranch_vccnz .LBB0_994
	s_and_b64 vcc, exec, s[6:7]
	v_mov_b32_e32 v59, v56
	s_cbranch_vccnz .LBB0_993
	v_mul_f32_e32 v57, 0xbfb8aa3b, v56
	v_exp_f32_e32 v57, v57
	s_nop 0
	v_add_f32_e32 v57, 1.0, v57
	v_rcp_f32_e32 v66, v57
	s_nop 0
	v_fma_f32 v68, -v57, v66, 1.0
	v_fma_f32 v59, v68, v66, v66
	v_div_fixup_f32 v59, v59, v57, 1.0

; __device__ __forceinline__ float sigmoidf_(float x) { return 1.0f / (1.0f + __expf(-x)); }
;     __device__ __forceinline__ void operator()(const f32x4 (&acc)[2][2][4][2], const Unit& u, int wr, int wc, int fr, int fq) const {
;     ...
;                         for (int i = 0; i < 4; ++i) { float xv = acc[ai][bj][m][n][i] + bv[bj][n][i]; float r;
;                             if (type < 2) { const float sg = sigmoidf_(xv); r = -expm1f(-0.606531f * sg); }
;                             else if (type == 2) r = sigmoidf_(xv);
;                             else r = xv;
;                             v[4 * n + i] = (f16)r; }
;                     *(f16x8*)(rowp + bj * 128) = v; } }
.LBB0_995:
	v_mul_f32_e32 v56, 0xbfb8aa3b, v56
	v_exp_f32_e32 v56, v56
	s_nop 0
	v_add_f32_e32 v56, 1.0, v56
	v_rcp_f32_e32 v59, v56
	s_nop 0
	v_fma_f32 v67, -v56, v59, 1.0
	v_fma_f32 v57, v67, v59, v59
	v_div_fixup_f32 v56, v57, v56, 1.0
	v_mul_f32_e32 v56, 0xbf1b459e, v56
	v_mul_f32_e32 v57, 0x3fb8aa3b, v56
	v_rndne_f32_e32 v57, v57
	v_fmamk_f32 v59, v57, 0xbf317218, v56
	v_fmac_f32_e32 v59, 0x3102e308, v57
	v_cvt_i32_f32_e32 v66, v57
	v_fmamk_f32 v67, v59, 0x395133b1, v171
	v_fmaak_f32 v67, v59, v67, 0x3c0887f9
	v_fmaak_f32 v67, v59, v67, 0x3d2aaa81
	v_fmaak_f32 v67, v59, v67, 0x3e2aaaab
	v_ldexp_f32 v66, 1.0, v66
	v_fma_f32 v67, v59, v67, 0.5
	v_cmp_eq_f32_e32 vcc, s90, v57
	v_mul_f32_e32 v67, v59, v67
	v_fmac_f32_e32 v59, v59, v67
	v_cndmask_b32_e32 v57, v66, v172, vcc
	v_add_f32_e32 v66, -1.0, v57
	v_fmac_f32_e32 v66, v57, v59
	v_add_f32_e32 v57, v66, v66
	v_cndmask_b32_e32 v57, v66, v57, vcc
	v_cmp_nlt_f32_e32 vcc, s91, v56
	s_nop 1
	v_cndmask_b32_e64 v57, v173, -v57, vcc
	v_cmp_ngt_f32_e32 vcc, s92, v56
	s_nop 1
	v_cndmask_b32_e32 v59, 1.0, v57, vcc
.LBB0_996:
	v_lshlrev_b64 v[56:57], 13, v[138:139]
	v_lshl_add_u64 v[56:57], s[28:29], 0, v[56:57]
	v_lshl_add_u64 v[56:57], v[136:137], 1, v[56:57]
	v_cvt_pk_f16_f32 v67, v58, v59
	v_add_co_u32_e32 v58, vcc, 0x120000, v56
	v_cvt_pk_f16_f32 v66, v64, v65
	v_cvt_pk_f16_f32 v65, v62, v63
	v_cvt_pk_f16_f32 v64, v60, v61
	v_addc_co_u32_e32 v59, vcc, 0, v57, vcc
	global_store_dwordx4 v[58:59], v[64:67], off
	v_add_f32_e32 v58, v52, v20
	s_and_b64 vcc, exec, s[8:9]
	s_mov_b64 s[14:15], -1
	s_cbranch_vccnz .LBB0_1000
	s_and_b64 vcc, exec, s[6:7]
	v_mov_b32_e32 v52, v58
	s_cbranch_vccnz .LBB0_999
	v_mul_f32_e32 v52, 0xbfb8aa3b, v58
	v_exp_f32_e32 v52, v52
	s_nop 0
	v_add_f32_e32 v52, 1.0, v52
	v_rcp_f32_e32 v60, v52
	s_nop 0
	v_fma_f32 v62, -v52, v60, 1.0
	v_fma_f32 v59, v62, v60, v60
	v_div_fixup_f32 v52, v59, v52, 1.0

; __device__ __forceinline__ float sigmoidf_(float x) { return 1.0f / (1.0f + __expf(-x)); }
;     __device__ __forceinline__ void operator()(const f32x4 (&acc)[2][2][4][2], const Unit& u, int wr, int wc, int fr, int fq) const {
;     ...
;                         for (int i = 0; i < 4; ++i) { float xv = acc[ai][bj][m][n][i] + bv[bj][n][i]; float r;
;                             if (type < 2) { const float sg = sigmoidf_(xv); r = -expm1f(-0.606531f * sg); }
;                             else if (type == 2) r = sigmoidf_(xv);
.LBB0_1001:
	v_mul_f32_e32 v52, 0xbfb8aa3b, v58
	v_exp_f32_e32 v52, v52
	s_nop 0
	v_add_f32_e32 v52, 1.0, v52
	v_rcp_f32_e32 v59, v52
	s_nop 0
	v_fma_f32 v61, -v52, v59, 1.0
	v_fma_f32 v58, v61, v59, v59
	v_div_fixup_f32 v52, v58, v52, 1.0
	v_mul_f32_e32 v52, 0xbf1b459e, v52
	v_mul_f32_e32 v58, 0x3fb8aa3b, v52
	v_rndne_f32_e32 v58, v58
	v_fmamk_f32 v59, v58, 0xbf317218, v52
	v_fmac_f32_e32 v59, 0x3102e308, v58
	v_cvt_i32_f32_e32 v60, v58
	v_fmamk_f32 v61, v59, 0x395133b1, v171
	v_fmaak_f32 v61, v59, v61, 0x3c0887f9
	v_fmaak_f32 v61, v59, v61, 0x3d2aaa81
	v_fmaak_f32 v61, v59, v61, 0x3e2aaaab
	v_ldexp_f32 v60, 1.0, v60
	v_fma_f32 v61, v59, v61, 0.5
	v_cmp_eq_f32_e32 vcc, s90, v58
	v_mul_f32_e32 v61, v59, v61
	v_fmac_f32_e32 v59, v59, v61
	v_cndmask_b32_e32 v58, v60, v172, vcc
	v_add_f32_e32 v60, -1.0, v58
	v_fmac_f32_e32 v60, v58, v59
	v_add_f32_e32 v58, v60, v60
	v_cndmask_b32_e32 v58, v60, v58, vcc
	v_cmp_nlt_f32_e32 vcc, s91, v52
	s_nop 1
	v_cndmask_b32_e64 v58, v173, -v58, vcc
	v_cmp_ngt_f32_e32 vcc, s92, v52
	s_nop 1
	v_cndmask_b32_e32 v52, 1.0, v58, vcc
.LBB0_1002:
	v_add_f32_e32 v58, v53, v21
	s_and_b64 vcc, exec, s[8:9]
	s_mov_b64 s[14:15], -1
	s_cbranch_vccnz .LBB0_1006
	s_and_b64 vcc, exec, s[6:7]
	v_mov_b32_e32 v53, v58
	s_cbranch_vccnz .LBB0_1005
	v_mul_f32_e32 v53, 0xbfb8aa3b, v58
	v_exp_f32_e32 v53, v53
	s_nop 0
	v_add_f32_e32 v53, 1.0, v53
	v_rcp_f32_e32 v60, v53
	s_nop 0
	v_fma_f32 v62, -v53, v60, 1.0
	v_fma_f32 v59, v62, v60, v60
	v_div_fixup_f32 v53, v59, v53, 1.0

; __device__ __forceinline__ float sigmoidf_(float x) { return 1.0f / (1.0f + __expf(-x)); }
;     __device__ __forceinline__ void operator()(const f32x4 (&acc)[2][2][4][2], const Unit& u, int wr, int wc, int fr, int fq) const {
;     ...
;                         for (int i = 0; i < 4; ++i) { float xv = acc[ai][bj][m][n][i] + bv[bj][n][i]; float r;
;                             if (type < 2) { const float sg = sigmoidf_(xv); r = -expm1f(-0.606531f * sg); }
;                             else if (type == 2) r = sigmoidf_(xv);
.LBB0_1007:
	v_mul_f32_e32 v53, 0xbfb8aa3b, v58
	v_exp_f32_e32 v53, v53
	s_nop 0
	v_add_f32_e32 v53, 1.0, v53
	v_rcp_f32_e32 v59, v53
	s_nop 0
	v_fma_f32 v61, -v53, v59, 1.0
	v_fma_f32 v58, v61, v59, v59
	v_div_fixup_f32 v53, v58, v53, 1.0
	v_mul_f32_e32 v53, 0xbf1b459e, v53
	v_mul_f32_e32 v58, 0x3fb8aa3b, v53
	v_rndne_f32_e32 v58, v58
	v_fmamk_f32 v59, v58, 0xbf317218, v53
	v_fmac_f32_e32 v59, 0x3102e308, v58
	v_cvt_i32_f32_e32 v60, v58
	v_fmamk_f32 v61, v59, 0x395133b1, v171
	v_fmaak_f32 v61, v59, v61, 0x3c0887f9
	v_fmaak_f32 v61, v59, v61, 0x3d2aaa81
	v_fmaak_f32 v61, v59, v61, 0x3e2aaaab
	v_ldexp_f32 v60, 1.0, v60
	v_fma_f32 v61, v59, v61, 0.5
	v_cmp_eq_f32_e32 vcc, s90, v58
	v_mul_f32_e32 v61, v59, v61
	v_fmac_f32_e32 v59, v59, v61
	v_cndmask_b32_e32 v58, v60, v172, vcc
	v_add_f32_e32 v60, -1.0, v58
	v_fmac_f32_e32 v60, v58, v59
	v_add_f32_e32 v58, v60, v60
	v_cndmask_b32_e32 v58, v60, v58, vcc
	v_cmp_nlt_f32_e32 vcc, s91, v53
	s_nop 1
	v_cndmask_b32_e64 v58, v173, -v58, vcc
	v_cmp_ngt_f32_e32 vcc, s92, v53
	s_nop 1
	v_cndmask_b32_e32 v53, 1.0, v58, vcc
.LBB0_1008:
	v_add_f32_e32 v58, v54, v22
	s_and_b64 vcc, exec, s[8:9]
	s_mov_b64 s[14:15], -1
	s_cbranch_vccnz .LBB0_1012
	s_and_b64 vcc, exec, s[6:7]
	v_mov_b32_e32 v54, v58
	s_cbranch_vccnz .LBB0_1011
	v_mul_f32_e32 v54, 0xbfb8aa3b, v58
	v_exp_f32_e32 v54, v54
	s_nop 0
	v_add_f32_e32 v54, 1.0, v54
	v_rcp_f32_e32 v60, v54
	s_nop 0
	v_fma_f32 v62, -v54, v60, 1.0
	v_fma_f32 v59, v62, v60, v60
	v_div_fixup_f32 v54, v59, v54, 1.0

; __device__ __forceinline__ float sigmoidf_(float x) { return 1.0f / (1.0f + __expf(-x)); }
;     __device__ __forceinline__ void operator()(const f32x4 (&acc)[2][2][4][2], const Unit& u, int wr, int wc, int fr, int fq) const {
;     ...
;                         for (int i = 0; i < 4; ++i) { float xv = acc[ai][bj][m][n][i] + bv[bj][n][i]; float r;
;                             if (type < 2) { const float sg = sigmoidf_(xv); r = -expm1f(-0.606531f * sg); }
;                             else if (type == 2) r = sigmoidf_(xv);
.LBB0_1013:
	v_mul_f32_e32 v54, 0xbfb8aa3b, v58
	v_exp_f32_e32 v54, v54
	s_nop 0
	v_add_f32_e32 v54, 1.0, v54
	v_rcp_f32_e32 v59, v54
	s_nop 0
	v_fma_f32 v61, -v54, v59, 1.0
	v_fma_f32 v58, v61, v59, v59
	v_div_fixup_f32 v54, v58, v54, 1.0
	v_mul_f32_e32 v54, 0xbf1b459e, v54
	v_mul_f32_e32 v58, 0x3fb8aa3b, v54
	v_rndne_f32_e32 v58, v58
	v_fmamk_f32 v59, v58, 0xbf317218, v54
	v_fmac_f32_e32 v59, 0x3102e308, v58
	v_cvt_i32_f32_e32 v60, v58
	v_fmamk_f32 v61, v59, 0x395133b1, v171
	v_fmaak_f32 v61, v59, v61, 0x3c0887f9
	v_fmaak_f32 v61, v59, v61, 0x3d2aaa81
	v_fmaak_f32 v61, v59, v61, 0x3e2aaaab
	v_ldexp_f32 v60, 1.0, v60
	v_fma_f32 v61, v59, v61, 0.5
	v_cmp_eq_f32_e32 vcc, s90, v58
	v_mul_f32_e32 v61, v59, v61
	v_fmac_f32_e32 v59, v59, v61
	v_cndmask_b32_e32 v58, v60, v172, vcc
	v_add_f32_e32 v60, -1.0, v58
	v_fmac_f32_e32 v60, v58, v59
	v_add_f32_e32 v58, v60, v60
	v_cndmask_b32_e32 v58, v60, v58, vcc
	v_cmp_nlt_f32_e32 vcc, s91, v54
	s_nop 1
	v_cndmask_b32_e64 v58, v173, -v58, vcc
	v_cmp_ngt_f32_e32 vcc, s92, v54
	s_nop 1
	v_cndmask_b32_e32 v54, 1.0, v58, vcc
.LBB0_1014:
	v_add_f32_e32 v58, v55, v23
	s_and_b64 vcc, exec, s[8:9]
	s_mov_b64 s[14:15], -1
	s_cbranch_vccnz .LBB0_1018
	s_and_b64 vcc, exec, s[6:7]
	v_mov_b32_e32 v55, v58
	s_cbranch_vccnz .LBB0_1017
	v_mul_f32_e32 v55, 0xbfb8aa3b, v58
	v_exp_f32_e32 v55, v55
	s_nop 0
	v_add_f32_e32 v55, 1.0, v55
	v_rcp_f32_e32 v60, v55
	s_nop 0
	v_fma_f32 v62, -v55, v60, 1.0
	v_fma_f32 v59, v62, v60, v60
	v_div_fixup_f32 v55, v59, v55, 1.0

; __device__ __forceinline__ float sigmoidf_(float x) { return 1.0f / (1.0f + __expf(-x)); }
;     __device__ __forceinline__ void operator()(const f32x4 (&acc)[2][2][4][2], const Unit& u, int wr, int wc, int fr, int fq) const {
;     ...
;                         for (int i = 0; i < 4; ++i) { float xv = acc[ai][bj][m][n][i] + bv[bj][n][i]; float r;
;                             if (type < 2) { const float sg = sigmoidf_(xv); r = -expm1f(-0.606531f * sg); }
;                             else if (type == 2) r = sigmoidf_(xv);
.LBB0_1019:
	v_mul_f32_e32 v55, 0xbfb8aa3b, v58
	v_exp_f32_e32 v55, v55
	s_nop 0
	v_add_f32_e32 v55, 1.0, v55
	v_rcp_f32_e32 v59, v55
	s_nop 0
	v_fma_f32 v61, -v55, v59, 1.0
	v_fma_f32 v58, v61, v59, v59
	v_div_fixup_f32 v55, v58, v55, 1.0
	v_mul_f32_e32 v55, 0xbf1b459e, v55
	v_mul_f32_e32 v58, 0x3fb8aa3b, v55
	v_rndne_f32_e32 v58, v58
	v_fmamk_f32 v59, v58, 0xbf317218, v55
	v_fmac_f32_e32 v59, 0x3102e308, v58
	v_cvt_i32_f32_e32 v60, v58
	v_fmamk_f32 v61, v59, 0x395133b1, v171
	v_fmaak_f32 v61, v59, v61, 0x3c0887f9
	v_fmaak_f32 v61, v59, v61, 0x3d2aaa81
	v_fmaak_f32 v61, v59, v61, 0x3e2aaaab
	v_ldexp_f32 v60, 1.0, v60
	v_fma_f32 v61, v59, v61, 0.5
	v_cmp_eq_f32_e32 vcc, s90, v58
	v_mul_f32_e32 v61, v59, v61
	v_fmac_f32_e32 v59, v59, v61
	v_cndmask_b32_e32 v58, v60, v172, vcc
	v_add_f32_e32 v60, -1.0, v58
	v_fmac_f32_e32 v60, v58, v59
	v_add_f32_e32 v58, v60, v60
	v_cndmask_b32_e32 v58, v60, v58, vcc
	v_cmp_nlt_f32_e32 vcc, s91, v55
	s_nop 1
	v_cndmask_b32_e64 v58, v173, -v58, vcc
	v_cmp_ngt_f32_e32 vcc, s92, v55
	s_nop 1
	v_cndmask_b32_e32 v55, 1.0, v58, vcc
.LBB0_1020:
	v_add_f32_e32 v58, v48, v12
	s_and_b64 vcc, exec, s[8:9]
	s_mov_b64 s[14:15], -1
	s_cbranch_vccnz .LBB0_1024
	s_and_b64 vcc, exec, s[6:7]
	v_mov_b32_e32 v48, v58
	s_cbranch_vccnz .LBB0_1023
	v_mul_f32_e32 v48, 0xbfb8aa3b, v58
	v_exp_f32_e32 v48, v48
	s_nop 0
	v_add_f32_e32 v48, 1.0, v48
	v_rcp_f32_e32 v60, v48
	s_nop 0
	v_fma_f32 v62, -v48, v60, 1.0
	v_fma_f32 v59, v62, v60, v60
	v_div_fixup_f32 v48, v59, v48, 1.0

; __device__ __forceinline__ float sigmoidf_(float x) { return 1.0f / (1.0f + __expf(-x)); }
;     __device__ __forceinline__ void operator()(const f32x4 (&acc)[2][2][4][2], const Unit& u, int wr, int wc, int fr, int fq) const {
;     ...
;                         for (int i = 0; i < 4; ++i) { float xv = acc[ai][bj][m][n][i] + bv[bj][n][i]; float r;
;                             if (type < 2) { const float sg = sigmoidf_(xv); r = -expm1f(-0.606531f * sg); }
;                             else if (type == 2) r = sigmoidf_(xv);
.LBB0_1025:
	v_mul_f32_e32 v48, 0xbfb8aa3b, v58
	v_exp_f32_e32 v48, v48
	s_nop 0
	v_add_f32_e32 v48, 1.0, v48
	v_rcp_f32_e32 v59, v48
	s_nop 0
	v_fma_f32 v61, -v48, v59, 1.0
	v_fma_f32 v58, v61, v59, v59
	v_div_fixup_f32 v48, v58, v48, 1.0
	v_mul_f32_e32 v48, 0xbf1b459e, v48
	v_mul_f32_e32 v58, 0x3fb8aa3b, v48
	v_rndne_f32_e32 v58, v58
	v_fmamk_f32 v59, v58, 0xbf317218, v48
	v_fmac_f32_e32 v59, 0x3102e308, v58
	v_cvt_i32_f32_e32 v60, v58
	v_fmamk_f32 v61, v59, 0x395133b1, v171
	v_fmaak_f32 v61, v59, v61, 0x3c0887f9
	v_fmaak_f32 v61, v59, v61, 0x3d2aaa81
	v_fmaak_f32 v61, v59, v61, 0x3e2aaaab
	v_ldexp_f32 v60, 1.0, v60
	v_fma_f32 v61, v59, v61, 0.5
	v_cmp_eq_f32_e32 vcc, s90, v58
	v_mul_f32_e32 v61, v59, v61
	v_fmac_f32_e32 v59, v59, v61
	v_cndmask_b32_e32 v58, v60, v172, vcc
	v_add_f32_e32 v60, -1.0, v58
	v_fmac_f32_e32 v60, v58, v59
	v_add_f32_e32 v58, v60, v60
	v_cndmask_b32_e32 v58, v60, v58, vcc
	v_cmp_nlt_f32_e32 vcc, s91, v48
	s_nop 1
	v_cndmask_b32_e64 v58, v173, -v58, vcc
	v_cmp_ngt_f32_e32 vcc, s92, v48
	s_nop 1
	v_cndmask_b32_e32 v48, 1.0, v58, vcc
.LBB0_1026:
	v_add_f32_e32 v58, v49, v13
	s_and_b64 vcc, exec, s[8:9]
	s_mov_b64 s[14:15], -1
	s_cbranch_vccnz .LBB0_1030
	s_and_b64 vcc, exec, s[6:7]
	v_mov_b32_e32 v49, v58
	s_cbranch_vccnz .LBB0_1029
	v_mul_f32_e32 v49, 0xbfb8aa3b, v58
	v_exp_f32_e32 v49, v49
	s_nop 0
	v_add_f32_e32 v49, 1.0, v49
	v_rcp_f32_e32 v60, v49
	s_nop 0
	v_fma_f32 v62, -v49, v60, 1.0
	v_fma_f32 v59, v62, v60, v60
	v_div_fixup_f32 v49, v59, v49, 1.0

; __device__ __forceinline__ float sigmoidf_(float x) { return 1.0f / (1.0f + __expf(-x)); }
;     __device__ __forceinline__ void operator()(const f32x4 (&acc)[2][2][4][2], const Unit& u, int wr, int wc, int fr, int fq) const {
;     ...
;                         for (int i = 0; i < 4; ++i) { float xv = acc[ai][bj][m][n][i] + bv[bj][n][i]; float r;
;                             if (type < 2) { const float sg = sigmoidf_(xv); r = -expm1f(-0.606531f * sg); }
;                             else if (type == 2) r = sigmoidf_(xv);
.LBB0_1031:
	v_mul_f32_e32 v49, 0xbfb8aa3b, v58
	v_exp_f32_e32 v49, v49
	s_nop 0
	v_add_f32_e32 v49, 1.0, v49
	v_rcp_f32_e32 v59, v49
	s_nop 0
	v_fma_f32 v61, -v49, v59, 1.0
	v_fma_f32 v58, v61, v59, v59
	v_div_fixup_f32 v49, v58, v49, 1.0
	v_mul_f32_e32 v49, 0xbf1b459e, v49
	v_mul_f32_e32 v58, 0x3fb8aa3b, v49
	v_rndne_f32_e32 v58, v58
	v_fmamk_f32 v59, v58, 0xbf317218, v49
	v_fmac_f32_e32 v59, 0x3102e308, v58
	v_cvt_i32_f32_e32 v60, v58
	v_fmamk_f32 v61, v59, 0x395133b1, v171
	v_fmaak_f32 v61, v59, v61, 0x3c0887f9
	v_fmaak_f32 v61, v59, v61, 0x3d2aaa81
	v_fmaak_f32 v61, v59, v61, 0x3e2aaaab
	v_ldexp_f32 v60, 1.0, v60
	v_fma_f32 v61, v59, v61, 0.5
	v_cmp_eq_f32_e32 vcc, s90, v58
	v_mul_f32_e32 v61, v59, v61
	v_fmac_f32_e32 v59, v59, v61
	v_cndmask_b32_e32 v58, v60, v172, vcc
	v_add_f32_e32 v60, -1.0, v58
	v_fmac_f32_e32 v60, v58, v59
	v_add_f32_e32 v58, v60, v60
	v_cndmask_b32_e32 v58, v60, v58, vcc
	v_cmp_nlt_f32_e32 vcc, s91, v49
	s_nop 1
	v_cndmask_b32_e64 v58, v173, -v58, vcc
	v_cmp_ngt_f32_e32 vcc, s92, v49
	s_nop 1
	v_cndmask_b32_e32 v49, 1.0, v58, vcc
.LBB0_1032:
	v_add_f32_e32 v58, v50, v14
	s_and_b64 vcc, exec, s[8:9]
	s_mov_b64 s[14:15], -1
	s_cbranch_vccnz .LBB0_1036
	s_and_b64 vcc, exec, s[6:7]
	v_mov_b32_e32 v50, v58
	s_cbranch_vccnz .LBB0_1035
	v_mul_f32_e32 v50, 0xbfb8aa3b, v58
	v_exp_f32_e32 v50, v50
	s_nop 0
	v_add_f32_e32 v50, 1.0, v50
	v_rcp_f32_e32 v60, v50
	s_nop 0
	v_fma_f32 v62, -v50, v60, 1.0
	v_fma_f32 v59, v62, v60, v60
	v_div_fixup_f32 v50, v59, v50, 1.0

; __device__ __forceinline__ float sigmoidf_(float x) { return 1.0f / (1.0f + __expf(-x)); }
;     __device__ __forceinline__ void operator()(const f32x4 (&acc)[2][2][4][2], const Unit& u, int wr, int wc, int fr, int fq) const {
;     ...
;                         for (int i = 0; i < 4; ++i) { float xv = acc[ai][bj][m][n][i] + bv[bj][n][i]; float r;
;                             if (type < 2) { const float sg = sigmoidf_(xv); r = -expm1f(-0.606531f * sg); }
;                             else if (type == 2) r = sigmoidf_(xv);
.LBB0_1037:
	v_mul_f32_e32 v50, 0xbfb8aa3b, v58
	v_exp_f32_e32 v50, v50
	s_nop 0
	v_add_f32_e32 v50, 1.0, v50
	v_rcp_f32_e32 v59, v50
	s_nop 0
	v_fma_f32 v61, -v50, v59, 1.0
	v_fma_f32 v58, v61, v59, v59
	v_div_fixup_f32 v50, v58, v50, 1.0
	v_mul_f32_e32 v50, 0xbf1b459e, v50
	v_mul_f32_e32 v58, 0x3fb8aa3b, v50
	v_rndne_f32_e32 v58, v58
	v_fmamk_f32 v59, v58, 0xbf317218, v50
	v_fmac_f32_e32 v59, 0x3102e308, v58
	v_cvt_i32_f32_e32 v60, v58
	v_fmamk_f32 v61, v59, 0x395133b1, v171
	v_fmaak_f32 v61, v59, v61, 0x3c0887f9
	v_fmaak_f32 v61, v59, v61, 0x3d2aaa81
	v_fmaak_f32 v61, v59, v61, 0x3e2aaaab
	v_ldexp_f32 v60, 1.0, v60
	v_fma_f32 v61, v59, v61, 0.5
	v_cmp_eq_f32_e32 vcc, s90, v58
	v_mul_f32_e32 v61, v59, v61
	v_fmac_f32_e32 v59, v59, v61
	v_cndmask_b32_e32 v58, v60, v172, vcc
	v_add_f32_e32 v60, -1.0, v58
	v_fmac_f32_e32 v60, v58, v59
	v_add_f32_e32 v58, v60, v60
	v_cndmask_b32_e32 v58, v60, v58, vcc
	v_cmp_nlt_f32_e32 vcc, s91, v50
	s_nop 1
	v_cndmask_b32_e64 v58, v173, -v58, vcc
	v_cmp_ngt_f32_e32 vcc, s92, v50
	s_nop 1
	v_cndmask_b32_e32 v50, 1.0, v58, vcc
.LBB0_1038:
	v_add_f32_e32 v51, v51, v15
	s_and_b64 vcc, exec, s[8:9]
	s_mov_b64 s[14:15], -1
	s_cbranch_vccnz .LBB0_1042
	s_and_b64 vcc, exec, s[6:7]
	v_mov_b32_e32 v58, v51
	s_cbranch_vccnz .LBB0_1041
	v_mul_f32_e32 v58, 0xbfb8aa3b, v51
	v_exp_f32_e32 v58, v58
	s_nop 0
	v_add_f32_e32 v58, 1.0, v58
	v_rcp_f32_e32 v60, v58
	s_nop 0
	v_fma_f32 v62, -v58, v60, 1.0
	v_fma_f32 v59, v62, v60, v60
	v_div_fixup_f32 v58, v59, v58, 1.0

; __device__ __forceinline__ float sigmoidf_(float x) { return 1.0f / (1.0f + __expf(-x)); }
;     __device__ __forceinline__ void operator()(const f32x4 (&acc)[2][2][4][2], const Unit& u, int wr, int wc, int fr, int fq) const {
;     ...
;                         for (int i = 0; i < 4; ++i) { float xv = acc[ai][bj][m][n][i] + bv[bj][n][i]; float r;
;                             if (type < 2) { const float sg = sigmoidf_(xv); r = -expm1f(-0.606531f * sg); }
;                             else if (type == 2) r = sigmoidf_(xv);
;                             else r = xv;
;                             v[4 * n + i] = (f16)r; }
;                     *(f16x8*)(rowp + bj * 128) = v; } }
.LBB0_1043:
	v_mul_f32_e32 v51, 0xbfb8aa3b, v51
	v_exp_f32_e32 v51, v51
	s_nop 0
	v_add_f32_e32 v51, 1.0, v51
	v_rcp_f32_e32 v59, v51
	s_nop 0
	v_fma_f32 v61, -v51, v59, 1.0
	v_fma_f32 v58, v61, v59, v59
	v_div_fixup_f32 v51, v58, v51, 1.0
	v_mul_f32_e32 v51, 0xbf1b459e, v51
	v_mul_f32_e32 v58, 0x3fb8aa3b, v51
	v_rndne_f32_e32 v58, v58
	v_fmamk_f32 v59, v58, 0xbf317218, v51
	v_fmac_f32_e32 v59, 0x3102e308, v58
	v_cvt_i32_f32_e32 v60, v58
	v_fmamk_f32 v61, v59, 0x395133b1, v171
	v_fmaak_f32 v61, v59, v61, 0x3c0887f9
	v_fmaak_f32 v61, v59, v61, 0x3d2aaa81
	v_fmaak_f32 v61, v59, v61, 0x3e2aaaab
	v_ldexp_f32 v60, 1.0, v60
	v_fma_f32 v61, v59, v61, 0.5
	v_cmp_eq_f32_e32 vcc, s90, v58
	v_mul_f32_e32 v61, v59, v61
	v_fmac_f32_e32 v59, v59, v61
	v_cndmask_b32_e32 v58, v60, v172, vcc
	v_add_f32_e32 v60, -1.0, v58
	v_fmac_f32_e32 v60, v58, v59
	v_add_f32_e32 v58, v60, v60
	v_cndmask_b32_e32 v58, v60, v58, vcc
	v_cmp_nlt_f32_e32 vcc, s91, v51
	s_nop 1
	v_cndmask_b32_e64 v58, v173, -v58, vcc
	v_cmp_ngt_f32_e32 vcc, s92, v51
	s_nop 1
	v_cndmask_b32_e32 v58, 1.0, v58, vcc
.LBB0_1044:
	s_mov_b64 s[2:3], 0x120000
	v_lshl_add_u64 v[56:57], v[56:57], 0, s[2:3]
	v_cvt_pk_f16_f32 v51, v50, v58
	v_cvt_pk_f16_f32 v50, v48, v49
	v_cvt_pk_f16_f32 v49, v54, v55
	v_cvt_pk_f16_f32 v48, v52, v53
	global_store_dwordx4 v[56:57], v[48:51], off offset:256
	s_and_b64 vcc, exec, s[8:9]
	s_mov_b64 s[14:15], -1
	v_add_f32_e32 v48, v44, v32
	s_cbranch_vccnz .LBB0_1048
	s_and_b64 vcc, exec, s[6:7]
	v_mov_b32_e32 v44, v48
	s_cbranch_vccnz .LBB0_1047
	v_mul_f32_e32 v44, 0xbfb8aa3b, v48
	v_exp_f32_e32 v44, v44
	s_nop 0
	v_add_f32_e32 v44, 1.0, v44
	v_rcp_f32_e32 v50, v44
	s_nop 0
	v_fma_f32 v52, -v44, v50, 1.0
	v_fma_f32 v49, v52, v50, v50
	v_div_fixup_f32 v44, v49, v44, 1.0

; __device__ __forceinline__ float sigmoidf_(float x) { return 1.0f / (1.0f + __expf(-x)); }
;     __device__ __forceinline__ void operator()(const f32x4 (&acc)[2][2][4][2], const Unit& u, int wr, int wc, int fr, int fq) const {
;     ...
;                         for (int i = 0; i < 4; ++i) { float xv = acc[ai][bj][m][n][i] + bv[bj][n][i]; float r;
;                             if (type < 2) { const float sg = sigmoidf_(xv); r = -expm1f(-0.606531f * sg); }
;                             else if (type == 2) r = sigmoidf_(xv);
.LBB0_1049:
	v_mul_f32_e32 v44, 0xbfb8aa3b, v48
	v_exp_f32_e32 v44, v44
	s_nop 0
	v_add_f32_e32 v44, 1.0, v44
	v_rcp_f32_e32 v49, v44
	s_nop 0
	v_fma_f32 v51, -v44, v49, 1.0
	v_fma_f32 v48, v51, v49, v49
	v_div_fixup_f32 v44, v48, v44, 1.0
	v_mul_f32_e32 v44, 0xbf1b459e, v44
	v_mul_f32_e32 v48, 0x3fb8aa3b, v44
	v_rndne_f32_e32 v48, v48
	v_fmamk_f32 v49, v48, 0xbf317218, v44
	v_fmac_f32_e32 v49, 0x3102e308, v48
	v_cvt_i32_f32_e32 v50, v48
	v_fmamk_f32 v51, v49, 0x395133b1, v171
	v_fmaak_f32 v51, v49, v51, 0x3c0887f9
	v_fmaak_f32 v51, v49, v51, 0x3d2aaa81
	v_fmaak_f32 v51, v49, v51, 0x3e2aaaab
	v_ldexp_f32 v50, 1.0, v50
	v_fma_f32 v51, v49, v51, 0.5
	v_cmp_eq_f32_e32 vcc, s90, v48
	v_mul_f32_e32 v51, v49, v51
	v_fmac_f32_e32 v49, v49, v51
	v_cndmask_b32_e32 v48, v50, v172, vcc
	v_add_f32_e32 v50, -1.0, v48
	v_fmac_f32_e32 v50, v48, v49
	v_add_f32_e32 v48, v50, v50
	v_cndmask_b32_e32 v48, v50, v48, vcc
	v_cmp_nlt_f32_e32 vcc, s91, v44
	s_nop 1
	v_cndmask_b32_e64 v48, v173, -v48, vcc
	v_cmp_ngt_f32_e32 vcc, s92, v44
	s_nop 1
	v_cndmask_b32_e32 v44, 1.0, v48, vcc
.LBB0_1050:
	v_add_f32_e32 v48, v45, v33
	s_and_b64 vcc, exec, s[8:9]
	s_mov_b64 s[14:15], -1
	s_cbranch_vccnz .LBB0_1054
	s_and_b64 vcc, exec, s[6:7]
	v_mov_b32_e32 v45, v48
	s_cbranch_vccnz .LBB0_1053
	v_mul_f32_e32 v45, 0xbfb8aa3b, v48
	v_exp_f32_e32 v45, v45
	s_nop 0
	v_add_f32_e32 v45, 1.0, v45
	v_rcp_f32_e32 v50, v45
	s_nop 0
	v_fma_f32 v52, -v45, v50, 1.0
	v_fma_f32 v49, v52, v50, v50
	v_div_fixup_f32 v45, v49, v45, 1.0

; __device__ __forceinline__ float sigmoidf_(float x) { return 1.0f / (1.0f + __expf(-x)); }
;     __device__ __forceinline__ void operator()(const f32x4 (&acc)[2][2][4][2], const Unit& u, int wr, int wc, int fr, int fq) const {
;     ...
;                         for (int i = 0; i < 4; ++i) { float xv = acc[ai][bj][m][n][i] + bv[bj][n][i]; float r;
;                             if (type < 2) { const float sg = sigmoidf_(xv); r = -expm1f(-0.606531f * sg); }
;                             else if (type == 2) r = sigmoidf_(xv);
.LBB0_1055:
	v_mul_f32_e32 v45, 0xbfb8aa3b, v48
	v_exp_f32_e32 v45, v45
	s_nop 0
	v_add_f32_e32 v45, 1.0, v45
	v_rcp_f32_e32 v49, v45
	s_nop 0
	v_fma_f32 v51, -v45, v49, 1.0
	v_fma_f32 v48, v51, v49, v49
	v_div_fixup_f32 v45, v48, v45, 1.0
	v_mul_f32_e32 v45, 0xbf1b459e, v45
	v_mul_f32_e32 v48, 0x3fb8aa3b, v45
	v_rndne_f32_e32 v48, v48
	v_fmamk_f32 v49, v48, 0xbf317218, v45
	v_fmac_f32_e32 v49, 0x3102e308, v48
	v_cvt_i32_f32_e32 v50, v48
	v_fmamk_f32 v51, v49, 0x395133b1, v171
	v_fmaak_f32 v51, v49, v51, 0x3c0887f9
	v_fmaak_f32 v51, v49, v51, 0x3d2aaa81
	v_fmaak_f32 v51, v49, v51, 0x3e2aaaab
	v_ldexp_f32 v50, 1.0, v50
	v_fma_f32 v51, v49, v51, 0.5
	v_cmp_eq_f32_e32 vcc, s90, v48
	v_mul_f32_e32 v51, v49, v51
	v_fmac_f32_e32 v49, v49, v51
	v_cndmask_b32_e32 v48, v50, v172, vcc
	v_add_f32_e32 v50, -1.0, v48
	v_fmac_f32_e32 v50, v48, v49
	v_add_f32_e32 v48, v50, v50
	v_cndmask_b32_e32 v48, v50, v48, vcc
	v_cmp_nlt_f32_e32 vcc, s91, v45
	s_nop 1
	v_cndmask_b32_e64 v48, v173, -v48, vcc
	v_cmp_ngt_f32_e32 vcc, s92, v45
	s_nop 1
	v_cndmask_b32_e32 v45, 1.0, v48, vcc
.LBB0_1056:
	v_add_f32_e32 v48, v46, v34
	s_and_b64 vcc, exec, s[8:9]
	s_mov_b64 s[14:15], -1
	s_cbranch_vccnz .LBB0_1060
	s_and_b64 vcc, exec, s[6:7]
	v_mov_b32_e32 v46, v48
	s_cbranch_vccnz .LBB0_1059
	v_mul_f32_e32 v46, 0xbfb8aa3b, v48
	v_exp_f32_e32 v46, v46
	s_nop 0
	v_add_f32_e32 v46, 1.0, v46
	v_rcp_f32_e32 v50, v46
	s_nop 0
	v_fma_f32 v52, -v46, v50, 1.0
	v_fma_f32 v49, v52, v50, v50
	v_div_fixup_f32 v46, v49, v46, 1.0

; __device__ __forceinline__ float sigmoidf_(float x) { return 1.0f / (1.0f + __expf(-x)); }
;     __device__ __forceinline__ void operator()(const f32x4 (&acc)[2][2][4][2], const Unit& u, int wr, int wc, int fr, int fq) const {
;     ...
;                         for (int i = 0; i < 4; ++i) { float xv = acc[ai][bj][m][n][i] + bv[bj][n][i]; float r;
;                             if (type < 2) { const float sg = sigmoidf_(xv); r = -expm1f(-0.606531f * sg); }
;                             else if (type == 2) r = sigmoidf_(xv);
.LBB0_1061:
	v_mul_f32_e32 v46, 0xbfb8aa3b, v48
	v_exp_f32_e32 v46, v46
	s_nop 0
	v_add_f32_e32 v46, 1.0, v46
	v_rcp_f32_e32 v49, v46
	s_nop 0
	v_fma_f32 v51, -v46, v49, 1.0
	v_fma_f32 v48, v51, v49, v49
	v_div_fixup_f32 v46, v48, v46, 1.0
	v_mul_f32_e32 v46, 0xbf1b459e, v46
	v_mul_f32_e32 v48, 0x3fb8aa3b, v46
	v_rndne_f32_e32 v48, v48
	v_fmamk_f32 v49, v48, 0xbf317218, v46
	v_fmac_f32_e32 v49, 0x3102e308, v48
	v_cvt_i32_f32_e32 v50, v48
	v_fmamk_f32 v51, v49, 0x395133b1, v171
	v_fmaak_f32 v51, v49, v51, 0x3c0887f9
	v_fmaak_f32 v51, v49, v51, 0x3d2aaa81
	v_fmaak_f32 v51, v49, v51, 0x3e2aaaab
	v_ldexp_f32 v50, 1.0, v50
	v_fma_f32 v51, v49, v51, 0.5
	v_cmp_eq_f32_e32 vcc, s90, v48
	v_mul_f32_e32 v51, v49, v51
	v_fmac_f32_e32 v49, v49, v51
	v_cndmask_b32_e32 v48, v50, v172, vcc
	v_add_f32_e32 v50, -1.0, v48
	v_fmac_f32_e32 v50, v48, v49
	v_add_f32_e32 v48, v50, v50
	v_cndmask_b32_e32 v48, v50, v48, vcc
	v_cmp_nlt_f32_e32 vcc, s91, v46
	s_nop 1
	v_cndmask_b32_e64 v48, v173, -v48, vcc
	v_cmp_ngt_f32_e32 vcc, s92, v46
	s_nop 1
	v_cndmask_b32_e32 v46, 1.0, v48, vcc
.LBB0_1062:
	v_add_f32_e32 v48, v47, v35
	s_and_b64 vcc, exec, s[8:9]
	s_mov_b64 s[14:15], -1
	s_cbranch_vccnz .LBB0_1066
	s_and_b64 vcc, exec, s[6:7]
	v_mov_b32_e32 v47, v48
	s_cbranch_vccnz .LBB0_1065
	v_mul_f32_e32 v47, 0xbfb8aa3b, v48
	v_exp_f32_e32 v47, v47
	s_nop 0
	v_add_f32_e32 v47, 1.0, v47
	v_rcp_f32_e32 v50, v47
	s_nop 0
	v_fma_f32 v52, -v47, v50, 1.0
	v_fma_f32 v49, v52, v50, v50
	v_div_fixup_f32 v47, v49, v47, 1.0

; __device__ __forceinline__ float sigmoidf_(float x) { return 1.0f / (1.0f + __expf(-x)); }
;     __device__ __forceinline__ void operator()(const f32x4 (&acc)[2][2][4][2], const Unit& u, int wr, int wc, int fr, int fq) const {
;     ...
;                         for (int i = 0; i < 4; ++i) { float xv = acc[ai][bj][m][n][i] + bv[bj][n][i]; float r;
;                             if (type < 2) { const float sg = sigmoidf_(xv); r = -expm1f(-0.606531f * sg); }
;                             else if (type == 2) r = sigmoidf_(xv);
.LBB0_1067:
	v_mul_f32_e32 v47, 0xbfb8aa3b, v48
	v_exp_f32_e32 v47, v47
	s_nop 0
	v_add_f32_e32 v47, 1.0, v47
	v_rcp_f32_e32 v49, v47
	s_nop 0
	v_fma_f32 v51, -v47, v49, 1.0
	v_fma_f32 v48, v51, v49, v49
	v_div_fixup_f32 v47, v48, v47, 1.0
	v_mul_f32_e32 v47, 0xbf1b459e, v47
	v_mul_f32_e32 v48, 0x3fb8aa3b, v47
	v_rndne_f32_e32 v48, v48
	v_fmamk_f32 v49, v48, 0xbf317218, v47
	v_fmac_f32_e32 v49, 0x3102e308, v48
	v_cvt_i32_f32_e32 v50, v48
	v_fmamk_f32 v51, v49, 0x395133b1, v171
	v_fmaak_f32 v51, v49, v51, 0x3c0887f9
	v_fmaak_f32 v51, v49, v51, 0x3d2aaa81
	v_fmaak_f32 v51, v49, v51, 0x3e2aaaab
	v_ldexp_f32 v50, 1.0, v50
	v_fma_f32 v51, v49, v51, 0.5
	v_cmp_eq_f32_e32 vcc, s90, v48
	v_mul_f32_e32 v51, v49, v51
	v_fmac_f32_e32 v49, v49, v51
	v_cndmask_b32_e32 v48, v50, v172, vcc
	v_add_f32_e32 v50, -1.0, v48
	v_fmac_f32_e32 v50, v48, v49
	v_add_f32_e32 v48, v50, v50
	v_cndmask_b32_e32 v48, v50, v48, vcc
	v_cmp_nlt_f32_e32 vcc, s91, v47
	s_nop 1
	v_cndmask_b32_e64 v48, v173, -v48, vcc
	v_cmp_ngt_f32_e32 vcc, s92, v47
	s_nop 1
	v_cndmask_b32_e32 v47, 1.0, v48, vcc
.LBB0_1068:
	v_add_f32_e32 v40, v40, v28
	s_and_b64 vcc, exec, s[8:9]
	s_mov_b64 s[14:15], -1
	s_cbranch_vccnz .LBB0_1072
	s_and_b64 vcc, exec, s[6:7]
	v_mov_b32_e32 v48, v40
	s_cbranch_vccnz .LBB0_1071
	v_mul_f32_e32 v48, 0xbfb8aa3b, v40
	v_exp_f32_e32 v48, v48
	s_nop 0
	v_add_f32_e32 v48, 1.0, v48
	v_rcp_f32_e32 v50, v48
	s_nop 0
	v_fma_f32 v52, -v48, v50, 1.0
	v_fma_f32 v49, v52, v50, v50
	v_div_fixup_f32 v48, v49, v48, 1.0

; __device__ __forceinline__ float sigmoidf_(float x) { return 1.0f / (1.0f + __expf(-x)); }
;     __device__ __forceinline__ void operator()(const f32x4 (&acc)[2][2][4][2], const Unit& u, int wr, int wc, int fr, int fq) const {
;     ...
;                         for (int i = 0; i < 4; ++i) { float xv = acc[ai][bj][m][n][i] + bv[bj][n][i]; float r;
;                             if (type < 2) { const float sg = sigmoidf_(xv); r = -expm1f(-0.606531f * sg); }
;                             else if (type == 2) r = sigmoidf_(xv);
.LBB0_1073:
	v_mul_f32_e32 v40, 0xbfb8aa3b, v40
	v_exp_f32_e32 v40, v40
	s_nop 0
	v_add_f32_e32 v40, 1.0, v40
	v_rcp_f32_e32 v49, v40
	s_nop 0
	v_fma_f32 v51, -v40, v49, 1.0
	v_fma_f32 v48, v51, v49, v49
	v_div_fixup_f32 v40, v48, v40, 1.0
	v_mul_f32_e32 v40, 0xbf1b459e, v40
	v_mul_f32_e32 v48, 0x3fb8aa3b, v40
	v_rndne_f32_e32 v48, v48
	v_fmamk_f32 v49, v48, 0xbf317218, v40
	v_fmac_f32_e32 v49, 0x3102e308, v48
	v_cvt_i32_f32_e32 v50, v48
	v_fmamk_f32 v51, v49, 0x395133b1, v171
	v_fmaak_f32 v51, v49, v51, 0x3c0887f9
	v_fmaak_f32 v51, v49, v51, 0x3d2aaa81
	v_fmaak_f32 v51, v49, v51, 0x3e2aaaab
	v_ldexp_f32 v50, 1.0, v50
	v_fma_f32 v51, v49, v51, 0.5
	v_cmp_eq_f32_e32 vcc, s90, v48
	v_mul_f32_e32 v51, v49, v51
	v_fmac_f32_e32 v49, v49, v51
	v_cndmask_b32_e32 v48, v50, v172, vcc
	v_add_f32_e32 v50, -1.0, v48
	v_fmac_f32_e32 v50, v48, v49
	v_add_f32_e32 v48, v50, v50
	v_cndmask_b32_e32 v48, v50, v48, vcc
	v_cmp_nlt_f32_e32 vcc, s91, v40
	s_nop 1
	v_cndmask_b32_e64 v48, v173, -v48, vcc
	v_cmp_ngt_f32_e32 vcc, s92, v40
	s_nop 1
	v_cndmask_b32_e32 v48, 1.0, v48, vcc
.LBB0_1074:
	v_add_f32_e32 v40, v41, v29
	s_and_b64 vcc, exec, s[8:9]
	s_mov_b64 s[14:15], -1
	s_cbranch_vccnz .LBB0_1078
	s_and_b64 vcc, exec, s[6:7]
	v_mov_b32_e32 v49, v40
	s_cbranch_vccnz .LBB0_1077
	v_mul_f32_e32 v41, 0xbfb8aa3b, v40
	v_exp_f32_e32 v41, v41
	s_nop 0
	v_add_f32_e32 v41, 1.0, v41
	v_rcp_f32_e32 v50, v41
	s_nop 0
	v_fma_f32 v52, -v41, v50, 1.0
	v_fma_f32 v49, v52, v50, v50
	v_div_fixup_f32 v49, v49, v41, 1.0

; __device__ __forceinline__ float sigmoidf_(float x) { return 1.0f / (1.0f + __expf(-x)); }
;     __device__ __forceinline__ void operator()(const f32x4 (&acc)[2][2][4][2], const Unit& u, int wr, int wc, int fr, int fq) const {
;     ...
;                         for (int i = 0; i < 4; ++i) { float xv = acc[ai][bj][m][n][i] + bv[bj][n][i]; float r;
;                             if (type < 2) { const float sg = sigmoidf_(xv); r = -expm1f(-0.606531f * sg); }
;                             else if (type == 2) r = sigmoidf_(xv);
.LBB0_1079:
	v_mul_f32_e32 v40, 0xbfb8aa3b, v40
	v_exp_f32_e32 v40, v40
	s_nop 0
	v_add_f32_e32 v40, 1.0, v40
	v_rcp_f32_e32 v49, v40
	s_nop 0
	v_fma_f32 v51, -v40, v49, 1.0
	v_fma_f32 v41, v51, v49, v49
	v_div_fixup_f32 v40, v41, v40, 1.0
	v_mul_f32_e32 v40, 0xbf1b459e, v40
	v_mul_f32_e32 v41, 0x3fb8aa3b, v40
	v_rndne_f32_e32 v41, v41
	v_fmamk_f32 v49, v41, 0xbf317218, v40
	v_fmac_f32_e32 v49, 0x3102e308, v41
	v_cvt_i32_f32_e32 v50, v41
	v_fmamk_f32 v51, v49, 0x395133b1, v171
	v_fmaak_f32 v51, v49, v51, 0x3c0887f9
	v_fmaak_f32 v51, v49, v51, 0x3d2aaa81
	v_fmaak_f32 v51, v49, v51, 0x3e2aaaab
	v_ldexp_f32 v50, 1.0, v50
	v_fma_f32 v51, v49, v51, 0.5
	v_cmp_eq_f32_e32 vcc, s90, v41
	v_mul_f32_e32 v51, v49, v51
	v_fmac_f32_e32 v49, v49, v51
	v_cndmask_b32_e32 v41, v50, v172, vcc
	v_add_f32_e32 v50, -1.0, v41
	v_fmac_f32_e32 v50, v41, v49
	v_add_f32_e32 v41, v50, v50
	v_cndmask_b32_e32 v41, v50, v41, vcc
	v_cmp_nlt_f32_e32 vcc, s91, v40
	s_nop 1
	v_cndmask_b32_e64 v41, v173, -v41, vcc
	v_cmp_ngt_f32_e32 vcc, s92, v40
	s_nop 1
	v_cndmask_b32_e32 v49, 1.0, v41, vcc
.LBB0_1080:
	v_add_f32_e32 v40, v42, v30
	s_and_b64 vcc, exec, s[8:9]
	s_mov_b64 s[14:15], -1
	s_cbranch_vccnz .LBB0_1084
	s_and_b64 vcc, exec, s[6:7]
	v_mov_b32_e32 v42, v40
	s_cbranch_vccnz .LBB0_1083
	v_mul_f32_e32 v41, 0xbfb8aa3b, v40
	v_exp_f32_e32 v41, v41
	s_nop 0
	v_add_f32_e32 v41, 1.0, v41
	v_rcp_f32_e32 v50, v41
	s_nop 0
	v_fma_f32 v52, -v41, v50, 1.0
	v_fma_f32 v42, v52, v50, v50
	v_div_fixup_f32 v42, v42, v41, 1.0

; __device__ __forceinline__ float sigmoidf_(float x) { return 1.0f / (1.0f + __expf(-x)); }
;     __device__ __forceinline__ void operator()(const f32x4 (&acc)[2][2][4][2], const Unit& u, int wr, int wc, int fr, int fq) const {
;     ...
;                         for (int i = 0; i < 4; ++i) { float xv = acc[ai][bj][m][n][i] + bv[bj][n][i]; float r;
;                             if (type < 2) { const float sg = sigmoidf_(xv); r = -expm1f(-0.606531f * sg); }
;                             else if (type == 2) r = sigmoidf_(xv);
.LBB0_1085:
	v_mul_f32_e32 v40, 0xbfb8aa3b, v40
	v_exp_f32_e32 v40, v40
	s_nop 0
	v_add_f32_e32 v40, 1.0, v40
	v_rcp_f32_e32 v42, v40
	s_nop 0
	v_fma_f32 v51, -v40, v42, 1.0
	v_fma_f32 v41, v51, v42, v42
	v_div_fixup_f32 v40, v41, v40, 1.0
	v_mul_f32_e32 v40, 0xbf1b459e, v40
	v_mul_f32_e32 v41, 0x3fb8aa3b, v40
	v_rndne_f32_e32 v41, v41
	v_fmamk_f32 v42, v41, 0xbf317218, v40
	v_fmac_f32_e32 v42, 0x3102e308, v41
	v_cvt_i32_f32_e32 v50, v41
	v_fmamk_f32 v51, v42, 0x395133b1, v171
	v_fmaak_f32 v51, v42, v51, 0x3c0887f9
	v_fmaak_f32 v51, v42, v51, 0x3d2aaa81
	v_fmaak_f32 v51, v42, v51, 0x3e2aaaab
	v_ldexp_f32 v50, 1.0, v50
	v_fma_f32 v51, v42, v51, 0.5
	v_cmp_eq_f32_e32 vcc, s90, v41
	v_mul_f32_e32 v51, v42, v51
	v_fmac_f32_e32 v42, v42, v51
	v_cndmask_b32_e32 v41, v50, v172, vcc
	v_add_f32_e32 v50, -1.0, v41
	v_fmac_f32_e32 v50, v41, v42
	v_add_f32_e32 v41, v50, v50
	v_cndmask_b32_e32 v41, v50, v41, vcc
	v_cmp_nlt_f32_e32 vcc, s91, v40
	s_nop 1
	v_cndmask_b32_e64 v41, v173, -v41, vcc
	v_cmp_ngt_f32_e32 vcc, s92, v40
	s_nop 1
	v_cndmask_b32_e32 v42, 1.0, v41, vcc
.LBB0_1086:
	v_add_f32_e32 v40, v43, v31
	s_and_b64 vcc, exec, s[8:9]
	s_mov_b64 s[14:15], -1
	s_cbranch_vccnz .LBB0_1090
	s_and_b64 vcc, exec, s[6:7]
	v_mov_b32_e32 v43, v40
	s_cbranch_vccnz .LBB0_1089
	v_mul_f32_e32 v41, 0xbfb8aa3b, v40
	v_exp_f32_e32 v41, v41
	s_nop 0
	v_add_f32_e32 v41, 1.0, v41
	v_rcp_f32_e32 v50, v41
	s_nop 0
	v_fma_f32 v52, -v41, v50, 1.0
	v_fma_f32 v43, v52, v50, v50
	v_div_fixup_f32 v43, v43, v41, 1.0

; __device__ __forceinline__ float sigmoidf_(float x) { return 1.0f / (1.0f + __expf(-x)); }
;     __device__ __forceinline__ void operator()(const f32x4 (&acc)[2][2][4][2], const Unit& u, int wr, int wc, int fr, int fq) const {
;     ...
;                         for (int i = 0; i < 4; ++i) { float xv = acc[ai][bj][m][n][i] + bv[bj][n][i]; float r;
;                             if (type < 2) { const float sg = sigmoidf_(xv); r = -expm1f(-0.606531f * sg); }
;                             else if (type == 2) r = sigmoidf_(xv);
;                             else r = xv;
;                             v[4 * n + i] = (f16)r; }
;                     *(f16x8*)(rowp + bj * 128) = v; } }
.LBB0_1091:
	v_mul_f32_e32 v40, 0xbfb8aa3b, v40
	v_exp_f32_e32 v40, v40
	s_nop 0
	v_add_f32_e32 v40, 1.0, v40
	v_rcp_f32_e32 v43, v40
	s_nop 0
	v_fma_f32 v51, -v40, v43, 1.0
	v_fma_f32 v41, v51, v43, v43
	v_div_fixup_f32 v40, v41, v40, 1.0
	v_mul_f32_e32 v40, 0xbf1b459e, v40
	v_mul_f32_e32 v41, 0x3fb8aa3b, v40
	v_rndne_f32_e32 v41, v41
	v_fmamk_f32 v43, v41, 0xbf317218, v40
	v_fmac_f32_e32 v43, 0x3102e308, v41
	v_cvt_i32_f32_e32 v50, v41
	v_fmamk_f32 v51, v43, 0x395133b1, v171
	v_fmaak_f32 v51, v43, v51, 0x3c0887f9
	v_fmaak_f32 v51, v43, v51, 0x3d2aaa81
	v_fmaak_f32 v51, v43, v51, 0x3e2aaaab
	v_ldexp_f32 v50, 1.0, v50
	v_fma_f32 v51, v43, v51, 0.5
	v_cmp_eq_f32_e32 vcc, s90, v41
	v_mul_f32_e32 v51, v43, v51
	v_fmac_f32_e32 v43, v43, v51
	v_cndmask_b32_e32 v41, v50, v172, vcc
	v_add_f32_e32 v50, -1.0, v41
	v_fmac_f32_e32 v50, v41, v43
	v_add_f32_e32 v41, v50, v50
	v_cndmask_b32_e32 v41, v50, v41, vcc
	v_cmp_nlt_f32_e32 vcc, s91, v40
	s_nop 1
	v_cndmask_b32_e64 v41, v173, -v41, vcc
	v_cmp_ngt_f32_e32 vcc, s92, v40
	s_nop 1
	v_cndmask_b32_e32 v43, 1.0, v41, vcc
.LBB0_1092:
	v_lshlrev_b64 v[40:41], 13, v[138:139]
	v_lshl_add_u64 v[40:41], s[28:29], 0, v[40:41]
	v_lshl_add_u64 v[40:41], v[136:137], 1, v[40:41]
	v_cvt_pk_f16_f32 v51, v42, v43
	v_add_co_u32_e32 v42, vcc, 0x140000, v40
	v_cvt_pk_f16_f32 v50, v48, v49
	v_cvt_pk_f16_f32 v49, v46, v47
	v_cvt_pk_f16_f32 v48, v44, v45
	v_addc_co_u32_e32 v43, vcc, 0, v41, vcc
	global_store_dwordx4 v[42:43], v[48:51], off
	v_add_f32_e32 v42, v36, v20
	s_and_b64 vcc, exec, s[8:9]
	s_mov_b64 s[14:15], -1
	s_cbranch_vccnz .LBB0_1096
	s_and_b64 vcc, exec, s[6:7]
	v_mov_b32_e32 v36, v42
	s_cbranch_vccnz .LBB0_1095
	v_mul_f32_e32 v36, 0xbfb8aa3b, v42
	v_exp_f32_e32 v36, v36
	s_nop 0
	v_add_f32_e32 v36, 1.0, v36
	v_rcp_f32_e32 v44, v36
	s_nop 0
	v_fma_f32 v46, -v36, v44, 1.0
	v_fma_f32 v43, v46, v44, v44
	v_div_fixup_f32 v36, v43, v36, 1.0

; __device__ __forceinline__ float sigmoidf_(float x) { return 1.0f / (1.0f + __expf(-x)); }
;     __device__ __forceinline__ void operator()(const f32x4 (&acc)[2][2][4][2], const Unit& u, int wr, int wc, int fr, int fq) const {
;     ...
;                         for (int i = 0; i < 4; ++i) { float xv = acc[ai][bj][m][n][i] + bv[bj][n][i]; float r;
;                             if (type < 2) { const float sg = sigmoidf_(xv); r = -expm1f(-0.606531f * sg); }
;                             else if (type == 2) r = sigmoidf_(xv);
.LBB0_1097:
	v_mul_f32_e32 v36, 0xbfb8aa3b, v42
	v_exp_f32_e32 v36, v36
	s_nop 0
	v_add_f32_e32 v36, 1.0, v36
	v_rcp_f32_e32 v43, v36
	s_nop 0
	v_fma_f32 v45, -v36, v43, 1.0
	v_fma_f32 v42, v45, v43, v43
	v_div_fixup_f32 v36, v42, v36, 1.0
	v_mul_f32_e32 v36, 0xbf1b459e, v36
	v_mul_f32_e32 v42, 0x3fb8aa3b, v36
	v_rndne_f32_e32 v42, v42
	v_fmamk_f32 v43, v42, 0xbf317218, v36
	v_fmac_f32_e32 v43, 0x3102e308, v42
	v_cvt_i32_f32_e32 v44, v42
	v_fmamk_f32 v45, v43, 0x395133b1, v171
	v_fmaak_f32 v45, v43, v45, 0x3c0887f9
	v_fmaak_f32 v45, v43, v45, 0x3d2aaa81
	v_fmaak_f32 v45, v43, v45, 0x3e2aaaab
	v_ldexp_f32 v44, 1.0, v44
	v_fma_f32 v45, v43, v45, 0.5
	v_cmp_eq_f32_e32 vcc, s90, v42
	v_mul_f32_e32 v45, v43, v45
	v_fmac_f32_e32 v43, v43, v45
	v_cndmask_b32_e32 v42, v44, v172, vcc
	v_add_f32_e32 v44, -1.0, v42
	v_fmac_f32_e32 v44, v42, v43
	v_add_f32_e32 v42, v44, v44
	v_cndmask_b32_e32 v42, v44, v42, vcc
	v_cmp_nlt_f32_e32 vcc, s91, v36
	s_nop 1
	v_cndmask_b32_e64 v42, v173, -v42, vcc
	v_cmp_ngt_f32_e32 vcc, s92, v36
	s_nop 1
	v_cndmask_b32_e32 v36, 1.0, v42, vcc
.LBB0_1098:
	v_add_f32_e32 v42, v37, v21
	s_and_b64 vcc, exec, s[8:9]
	s_mov_b64 s[14:15], -1
	s_cbranch_vccnz .LBB0_1102
	s_and_b64 vcc, exec, s[6:7]
	v_mov_b32_e32 v37, v42
	s_cbranch_vccnz .LBB0_1101
	v_mul_f32_e32 v37, 0xbfb8aa3b, v42
	v_exp_f32_e32 v37, v37
	s_nop 0
	v_add_f32_e32 v37, 1.0, v37
	v_rcp_f32_e32 v44, v37
	s_nop 0
	v_fma_f32 v46, -v37, v44, 1.0
	v_fma_f32 v43, v46, v44, v44
	v_div_fixup_f32 v37, v43, v37, 1.0

; __device__ __forceinline__ float sigmoidf_(float x) { return 1.0f / (1.0f + __expf(-x)); }
;     __device__ __forceinline__ void operator()(const f32x4 (&acc)[2][2][4][2], const Unit& u, int wr, int wc, int fr, int fq) const {
;     ...
;                 for (int bj = 0; bj < 2; ++bj) { f16x8 v;
; #pragma unroll
;                     for (int n = 0; n < 2; ++n)
; #pragma unroll
;                         for (int i = 0; i < 4; ++i) { float xv = acc[ai][bj][m][n][i] + bv[bj][n][i]; float r;
;                             if (type < 2) { const float sg = sigmoidf_(xv); r = -expm1f(-0.606531f * sg); }
;                             else if (type == 2) r = sigmoidf_(xv);
;                             else r = xv;
;                             v[4 * n + i] = (f16)r; }
;                     *(f16x8*)(rowp + bj * 128) = v; } }
.LBB0_1103:
	v_mul_f32_e32 v37, 0xbfb8aa3b, v42
	v_exp_f32_e32 v37, v37
	s_nop 0
	v_add_f32_e32 v37, 1.0, v37
	v_rcp_f32_e32 v43, v37
	s_nop 0
	v_fma_f32 v45, -v37, v43, 1.0
	v_fma_f32 v42, v45, v43, v43
	v_div_fixup_f32 v37, v42, v37, 1.0
	v_mul_f32_e32 v37, 0xbf1b459e, v37
	v_mul_f32_e32 v42, 0x3fb8aa3b, v37
	v_rndne_f32_e32 v42, v42
	v_fmamk_f32 v43, v42, 0xbf317218, v37
	v_fmac_f32_e32 v43, 0x3102e308, v42
	v_cvt_i32_f32_e32 v44, v42
	v_fmamk_f32 v45, v43, 0x395133b1, v171
	v_fmaak_f32 v45, v43, v45, 0x3c0887f9
	v_fmaak_f32 v45, v43, v45, 0x3d2aaa81
	v_fmaak_f32 v45, v43, v45, 0x3e2aaaab
	v_ldexp_f32 v44, 1.0, v44
	v_fma_f32 v45, v43, v45, 0.5
	v_cmp_eq_f32_e32 vcc, s90, v42
	v_mul_f32_e32 v45, v43, v45
	v_fmac_f32_e32 v43, v43, v45
	v_cndmask_b32_e32 v42, v44, v172, vcc
	v_add_f32_e32 v44, -1.0, v42
	v_fmac_f32_e32 v44, v42, v43
	v_add_f32_e32 v42, v44, v44
	v_cndmask_b32_e32 v42, v44, v42, vcc
	v_cmp_nlt_f32_e32 vcc, s91, v37
	s_nop 1
	v_cndmask_b32_e64 v42, v173, -v42, vcc
	v_cmp_ngt_f32_e32 vcc, s92, v37
	s_nop 1
	v_cndmask_b32_e32 v37, 1.0, v42, vcc
.LBB0_1104:
	v_add_f32_e32 v42, v38, v22
	s_and_b64 vcc, exec, s[8:9]
	s_mov_b64 s[14:15], -1
	s_cbranch_vccnz .LBB0_1108
	s_and_b64 vcc, exec, s[6:7]
	v_mov_b32_e32 v38, v42
	s_cbranch_vccnz .LBB0_1107
	v_mul_f32_e32 v38, 0xbfb8aa3b, v42
	v_exp_f32_e32 v38, v38
	s_nop 0
	v_add_f32_e32 v38, 1.0, v38
	v_rcp_f32_e32 v44, v38
	s_nop 0
	v_fma_f32 v46, -v38, v44, 1.0
	v_fma_f32 v43, v46, v44, v44
	v_div_fixup_f32 v38, v43, v38, 1.0

; __device__ __forceinline__ float sigmoidf_(float x) { return 1.0f / (1.0f + __expf(-x)); }
;     __device__ __forceinline__ void operator()(const f32x4 (&acc)[2][2][4][2], const Unit& u, int wr, int wc, int fr, int fq) const {
;     ...
;                 for (int bj = 0; bj < 2; ++bj) { f16x8 v;
; #pragma unroll
;                     for (int n = 0; n < 2; ++n)
; #pragma unroll
;                         for (int i = 0; i < 4; ++i) { float xv = acc[ai][bj][m][n][i] + bv[bj][n][i]; float r;
;                             if (type < 2) { const float sg = sigmoidf_(xv); r = -expm1f(-0.606531f * sg); }
;                             else if (type == 2) r = sigmoidf_(xv);
;                             else r = xv;
;                             v[4 * n + i] = (f16)r; }
;                     *(f16x8*)(rowp + bj * 128) = v; } }
.LBB0_1109:
	v_mul_f32_e32 v38, 0xbfb8aa3b, v42
	v_exp_f32_e32 v38, v38
	s_nop 0
	v_add_f32_e32 v38, 1.0, v38
	v_rcp_f32_e32 v43, v38
	s_nop 0
	v_fma_f32 v45, -v38, v43, 1.0
	v_fma_f32 v42, v45, v43, v43
	v_div_fixup_f32 v38, v42, v38, 1.0
	v_mul_f32_e32 v38, 0xbf1b459e, v38
	v_mul_f32_e32 v42, 0x3fb8aa3b, v38
	v_rndne_f32_e32 v42, v42
	v_fmamk_f32 v43, v42, 0xbf317218, v38
	v_fmac_f32_e32 v43, 0x3102e308, v42
	v_cvt_i32_f32_e32 v44, v42
	v_fmamk_f32 v45, v43, 0x395133b1, v171
	v_fmaak_f32 v45, v43, v45, 0x3c0887f9
	v_fmaak_f32 v45, v43, v45, 0x3d2aaa81
	v_fmaak_f32 v45, v43, v45, 0x3e2aaaab
	v_ldexp_f32 v44, 1.0, v44
	v_fma_f32 v45, v43, v45, 0.5
	v_cmp_eq_f32_e32 vcc, s90, v42
	v_mul_f32_e32 v45, v43, v45
	v_fmac_f32_e32 v43, v43, v45
	v_cndmask_b32_e32 v42, v44, v172, vcc
	v_add_f32_e32 v44, -1.0, v42
	v_fmac_f32_e32 v44, v42, v43
	v_add_f32_e32 v42, v44, v44
	v_cndmask_b32_e32 v42, v44, v42, vcc
	v_cmp_nlt_f32_e32 vcc, s91, v38
	s_nop 1
	v_cndmask_b32_e64 v42, v173, -v42, vcc
	v_cmp_ngt_f32_e32 vcc, s92, v38
	s_nop 1
	v_cndmask_b32_e32 v38, 1.0, v42, vcc
.LBB0_1110:
	v_add_f32_e32 v42, v39, v23
	s_and_b64 vcc, exec, s[8:9]
	s_mov_b64 s[14:15], -1
	s_cbranch_vccnz .LBB0_1114
	s_and_b64 vcc, exec, s[6:7]
	v_mov_b32_e32 v39, v42
	s_cbranch_vccnz .LBB0_1113
	v_mul_f32_e32 v39, 0xbfb8aa3b, v42
	v_exp_f32_e32 v39, v39
	s_nop 0
	v_add_f32_e32 v39, 1.0, v39
	v_rcp_f32_e32 v44, v39
	s_nop 0
	v_fma_f32 v46, -v39, v44, 1.0
	v_fma_f32 v43, v46, v44, v44
	v_div_fixup_f32 v39, v43, v39, 1.0

; __device__ __forceinline__ float sigmoidf_(float x) { return 1.0f / (1.0f + __expf(-x)); }
;     __device__ __forceinline__ void operator()(const f32x4 (&acc)[2][2][4][2], const Unit& u, int wr, int wc, int fr, int fq) const {
;     ...
;                 for (int bj = 0; bj < 2; ++bj) { f16x8 v;
; #pragma unroll
;                     for (int n = 0; n < 2; ++n)
; #pragma unroll
;                         for (int i = 0; i < 4; ++i) { float xv = acc[ai][bj][m][n][i] + bv[bj][n][i]; float r;
;                             if (type < 2) { const float sg = sigmoidf_(xv); r = -expm1f(-0.606531f * sg); }
;                             else if (type == 2) r = sigmoidf_(xv);
;                             else r = xv;
;                             v[4 * n + i] = (f16)r; }
;                     *(f16x8*)(rowp + bj * 128) = v; } }
.LBB0_1115:
	v_mul_f32_e32 v39, 0xbfb8aa3b, v42
	v_exp_f32_e32 v39, v39
	s_nop 0
	v_add_f32_e32 v39, 1.0, v39
	v_rcp_f32_e32 v43, v39
	s_nop 0
	v_fma_f32 v45, -v39, v43, 1.0
	v_fma_f32 v42, v45, v43, v43
	v_div_fixup_f32 v39, v42, v39, 1.0
	v_mul_f32_e32 v39, 0xbf1b459e, v39
	v_mul_f32_e32 v42, 0x3fb8aa3b, v39
	v_rndne_f32_e32 v42, v42
	v_fmamk_f32 v43, v42, 0xbf317218, v39
	v_fmac_f32_e32 v43, 0x3102e308, v42
	v_cvt_i32_f32_e32 v44, v42
	v_fmamk_f32 v45, v43, 0x395133b1, v171
	v_fmaak_f32 v45, v43, v45, 0x3c0887f9
	v_fmaak_f32 v45, v43, v45, 0x3d2aaa81
	v_fmaak_f32 v45, v43, v45, 0x3e2aaaab
	v_ldexp_f32 v44, 1.0, v44
	v_fma_f32 v45, v43, v45, 0.5
	v_cmp_eq_f32_e32 vcc, s90, v42
	v_mul_f32_e32 v45, v43, v45
	v_fmac_f32_e32 v43, v43, v45
	v_cndmask_b32_e32 v42, v44, v172, vcc
	v_add_f32_e32 v44, -1.0, v42
	v_fmac_f32_e32 v44, v42, v43
	v_add_f32_e32 v42, v44, v44
	v_cndmask_b32_e32 v42, v44, v42, vcc
	v_cmp_nlt_f32_e32 vcc, s91, v39
	s_nop 1
	v_cndmask_b32_e64 v42, v173, -v42, vcc
	v_cmp_ngt_f32_e32 vcc, s92, v39
	s_nop 1
	v_cndmask_b32_e32 v39, 1.0, v42, vcc
.LBB0_1116:
	v_add_f32_e32 v42, v24, v12
	s_and_b64 vcc, exec, s[8:9]
	s_mov_b64 s[14:15], -1
	s_cbranch_vccnz .LBB0_1120
	s_and_b64 vcc, exec, s[6:7]
	v_mov_b32_e32 v24, v42
	s_cbranch_vccnz .LBB0_1119
	v_mul_f32_e32 v24, 0xbfb8aa3b, v42
	v_exp_f32_e32 v24, v24
	s_nop 0
	v_add_f32_e32 v24, 1.0, v24
	v_rcp_f32_e32 v44, v24
	s_nop 0
	v_fma_f32 v46, -v24, v44, 1.0
	v_fma_f32 v43, v46, v44, v44
	v_div_fixup_f32 v24, v43, v24, 1.0

; __device__ __forceinline__ float sigmoidf_(float x) { return 1.0f / (1.0f + __expf(-x)); }
;     __device__ __forceinline__ void operator()(const f32x4 (&acc)[2][2][4][2], const Unit& u, int wr, int wc, int fr, int fq) const {
;     ...
;                 for (int bj = 0; bj < 2; ++bj) { f16x8 v;
; #pragma unroll
;                     for (int n = 0; n < 2; ++n)
; #pragma unroll
;                         for (int i = 0; i < 4; ++i) { float xv = acc[ai][bj][m][n][i] + bv[bj][n][i]; float r;
;                             if (type < 2) { const float sg = sigmoidf_(xv); r = -expm1f(-0.606531f * sg); }
;                             else if (type == 2) r = sigmoidf_(xv);
;                             else r = xv;
;                             v[4 * n + i] = (f16)r; }
;                     *(f16x8*)(rowp + bj * 128) = v; } }
.LBB0_1121:
	v_mul_f32_e32 v24, 0xbfb8aa3b, v42
	v_exp_f32_e32 v24, v24
	s_nop 0
	v_add_f32_e32 v24, 1.0, v24
	v_rcp_f32_e32 v43, v24
	s_nop 0
	v_fma_f32 v45, -v24, v43, 1.0
	v_fma_f32 v42, v45, v43, v43
	v_div_fixup_f32 v24, v42, v24, 1.0
	v_mul_f32_e32 v24, 0xbf1b459e, v24
	v_mul_f32_e32 v42, 0x3fb8aa3b, v24
	v_rndne_f32_e32 v42, v42
	v_fmamk_f32 v43, v42, 0xbf317218, v24
	v_fmac_f32_e32 v43, 0x3102e308, v42
	v_cvt_i32_f32_e32 v44, v42
	v_fmamk_f32 v45, v43, 0x395133b1, v171
	v_fmaak_f32 v45, v43, v45, 0x3c0887f9
	v_fmaak_f32 v45, v43, v45, 0x3d2aaa81
	v_fmaak_f32 v45, v43, v45, 0x3e2aaaab
	v_ldexp_f32 v44, 1.0, v44
	v_fma_f32 v45, v43, v45, 0.5
	v_cmp_eq_f32_e32 vcc, s90, v42
	v_mul_f32_e32 v45, v43, v45
	v_fmac_f32_e32 v43, v43, v45
	v_cndmask_b32_e32 v42, v44, v172, vcc
	v_add_f32_e32 v44, -1.0, v42
	v_fmac_f32_e32 v44, v42, v43
	v_add_f32_e32 v42, v44, v44
	v_cndmask_b32_e32 v42, v44, v42, vcc
	v_cmp_nlt_f32_e32 vcc, s91, v24
	s_nop 1
	v_cndmask_b32_e64 v42, v173, -v42, vcc
	v_cmp_ngt_f32_e32 vcc, s92, v24
	s_nop 1
	v_cndmask_b32_e32 v24, 1.0, v42, vcc
.LBB0_1122:
	v_add_f32_e32 v42, v25, v13
	s_and_b64 vcc, exec, s[8:9]
	s_mov_b64 s[14:15], -1
	s_cbranch_vccnz .LBB0_1126
	s_and_b64 vcc, exec, s[6:7]
	v_mov_b32_e32 v25, v42
	s_cbranch_vccnz .LBB0_1125
	v_mul_f32_e32 v25, 0xbfb8aa3b, v42
	v_exp_f32_e32 v25, v25
	s_nop 0
	v_add_f32_e32 v25, 1.0, v25
	v_rcp_f32_e32 v44, v25
	s_nop 0
	v_fma_f32 v46, -v25, v44, 1.0
	v_fma_f32 v43, v46, v44, v44
	v_div_fixup_f32 v25, v43, v25, 1.0

; __device__ __forceinline__ float sigmoidf_(float x) { return 1.0f / (1.0f + __expf(-x)); }
;     __device__ __forceinline__ void operator()(const f32x4 (&acc)[2][2][4][2], const Unit& u, int wr, int wc, int fr, int fq) const {
;     ...
;                 for (int bj = 0; bj < 2; ++bj) { f16x8 v;
; #pragma unroll
;                     for (int n = 0; n < 2; ++n)
; #pragma unroll
;                         for (int i = 0; i < 4; ++i) { float xv = acc[ai][bj][m][n][i] + bv[bj][n][i]; float r;
;                             if (type < 2) { const float sg = sigmoidf_(xv); r = -expm1f(-0.606531f * sg); }
;                             else if (type == 2) r = sigmoidf_(xv);
;                             else r = xv;
;                             v[4 * n + i] = (f16)r; }
;                     *(f16x8*)(rowp + bj * 128) = v; } }
.LBB0_1127:
	v_mul_f32_e32 v25, 0xbfb8aa3b, v42
	v_exp_f32_e32 v25, v25
	s_nop 0
	v_add_f32_e32 v25, 1.0, v25
	v_rcp_f32_e32 v43, v25
	s_nop 0
	v_fma_f32 v45, -v25, v43, 1.0
	v_fma_f32 v42, v45, v43, v43
	v_div_fixup_f32 v25, v42, v25, 1.0
	v_mul_f32_e32 v25, 0xbf1b459e, v25
	v_mul_f32_e32 v42, 0x3fb8aa3b, v25
	v_rndne_f32_e32 v42, v42
	v_fmamk_f32 v43, v42, 0xbf317218, v25
	v_fmac_f32_e32 v43, 0x3102e308, v42
	v_cvt_i32_f32_e32 v44, v42
	v_fmamk_f32 v45, v43, 0x395133b1, v171
	v_fmaak_f32 v45, v43, v45, 0x3c0887f9
	v_fmaak_f32 v45, v43, v45, 0x3d2aaa81
	v_fmaak_f32 v45, v43, v45, 0x3e2aaaab
	v_ldexp_f32 v44, 1.0, v44
	v_fma_f32 v45, v43, v45, 0.5
	v_cmp_eq_f32_e32 vcc, s90, v42
	v_mul_f32_e32 v45, v43, v45
	v_fmac_f32_e32 v43, v43, v45
	v_cndmask_b32_e32 v42, v44, v172, vcc
	v_add_f32_e32 v44, -1.0, v42
	v_fmac_f32_e32 v44, v42, v43
	v_add_f32_e32 v42, v44, v44
	v_cndmask_b32_e32 v42, v44, v42, vcc
	v_cmp_nlt_f32_e32 vcc, s91, v25
	s_nop 1
	v_cndmask_b32_e64 v42, v173, -v42, vcc
	v_cmp_ngt_f32_e32 vcc, s92, v25
	s_nop 1
	v_cndmask_b32_e32 v25, 1.0, v42, vcc
.LBB0_1128:
	v_add_f32_e32 v42, v26, v14
	s_and_b64 vcc, exec, s[8:9]
	s_mov_b64 s[14:15], -1
	s_cbranch_vccnz .LBB0_1132
	s_and_b64 vcc, exec, s[6:7]
	v_mov_b32_e32 v26, v42
	s_cbranch_vccnz .LBB0_1131
	v_mul_f32_e32 v26, 0xbfb8aa3b, v42
	v_exp_f32_e32 v26, v26
	s_nop 0
	v_add_f32_e32 v26, 1.0, v26
	v_rcp_f32_e32 v44, v26
	s_nop 0
	v_fma_f32 v46, -v26, v44, 1.0
	v_fma_f32 v43, v46, v44, v44
	v_div_fixup_f32 v26, v43, v26, 1.0

; __device__ __forceinline__ float sigmoidf_(float x) { return 1.0f / (1.0f + __expf(-x)); }
;     __device__ __forceinline__ void operator()(const f32x4 (&acc)[2][2][4][2], const Unit& u, int wr, int wc, int fr, int fq) const {
;     ...
;                 for (int bj = 0; bj < 2; ++bj) { f16x8 v;
; #pragma unroll
;                     for (int n = 0; n < 2; ++n)
; #pragma unroll
;                         for (int i = 0; i < 4; ++i) { float xv = acc[ai][bj][m][n][i] + bv[bj][n][i]; float r;
;                             if (type < 2) { const float sg = sigmoidf_(xv); r = -expm1f(-0.606531f * sg); }
;                             else if (type == 2) r = sigmoidf_(xv);
;                             else r = xv;
;                             v[4 * n + i] = (f16)r; }
;                     *(f16x8*)(rowp + bj * 128) = v; } }
.LBB0_1133:
	v_mul_f32_e32 v26, 0xbfb8aa3b, v42
	v_exp_f32_e32 v26, v26
	s_nop 0
	v_add_f32_e32 v26, 1.0, v26
	v_rcp_f32_e32 v43, v26
	s_nop 0
	v_fma_f32 v45, -v26, v43, 1.0
	v_fma_f32 v42, v45, v43, v43
	v_div_fixup_f32 v26, v42, v26, 1.0
	v_mul_f32_e32 v26, 0xbf1b459e, v26
	v_mul_f32_e32 v42, 0x3fb8aa3b, v26
	v_rndne_f32_e32 v42, v42
	v_fmamk_f32 v43, v42, 0xbf317218, v26
	v_fmac_f32_e32 v43, 0x3102e308, v42
	v_cvt_i32_f32_e32 v44, v42
	v_fmamk_f32 v45, v43, 0x395133b1, v171
	v_fmaak_f32 v45, v43, v45, 0x3c0887f9
	v_fmaak_f32 v45, v43, v45, 0x3d2aaa81
	v_fmaak_f32 v45, v43, v45, 0x3e2aaaab
	v_ldexp_f32 v44, 1.0, v44
	v_fma_f32 v45, v43, v45, 0.5
	v_cmp_eq_f32_e32 vcc, s90, v42
	v_mul_f32_e32 v45, v43, v45
	v_fmac_f32_e32 v43, v43, v45
	v_cndmask_b32_e32 v42, v44, v172, vcc
	v_add_f32_e32 v44, -1.0, v42
	v_fmac_f32_e32 v44, v42, v43
	v_add_f32_e32 v42, v44, v44
	v_cndmask_b32_e32 v42, v44, v42, vcc
	v_cmp_nlt_f32_e32 vcc, s91, v26
	s_nop 1
	v_cndmask_b32_e64 v42, v173, -v42, vcc
	v_cmp_ngt_f32_e32 vcc, s92, v26
	s_nop 1
	v_cndmask_b32_e32 v26, 1.0, v42, vcc
.LBB0_1134:
	v_add_f32_e32 v27, v27, v15
	s_and_b64 vcc, exec, s[8:9]
	s_mov_b64 s[14:15], -1
	s_cbranch_vccnz .LBB0_1138
	s_and_b64 vcc, exec, s[6:7]
	v_mov_b32_e32 v42, v27
	s_cbranch_vccnz .LBB0_1137
	v_mul_f32_e32 v42, 0xbfb8aa3b, v27
	v_exp_f32_e32 v42, v42
	s_nop 0
	v_add_f32_e32 v42, 1.0, v42
	v_rcp_f32_e32 v44, v42
	s_nop 0
	v_fma_f32 v46, -v42, v44, 1.0
	v_fma_f32 v43, v46, v44, v44
	v_div_fixup_f32 v42, v43, v42, 1.0

; __device__ __forceinline__ float sigmoidf_(float x) { return 1.0f / (1.0f + __expf(-x)); }
;     __device__ __forceinline__ void operator()(const f32x4 (&acc)[2][2][4][2], const Unit& u, int wr, int wc, int fr, int fq) const {
;     ...
;                 for (int bj = 0; bj < 2; ++bj) { f16x8 v;
; #pragma unroll
;                     for (int n = 0; n < 2; ++n)
; #pragma unroll
;                         for (int i = 0; i < 4; ++i) { float xv = acc[ai][bj][m][n][i] + bv[bj][n][i]; float r;
;                             if (type < 2) { const float sg = sigmoidf_(xv); r = -expm1f(-0.606531f * sg); }
;                             else if (type == 2) r = sigmoidf_(xv);
;                             else r = xv;
;                             v[4 * n + i] = (f16)r; }
;                     *(f16x8*)(rowp + bj * 128) = v; } }
.LBB0_1139:
	v_mul_f32_e32 v27, 0xbfb8aa3b, v27
	v_exp_f32_e32 v27, v27
	s_nop 0
	v_add_f32_e32 v27, 1.0, v27
	v_rcp_f32_e32 v43, v27
	s_nop 0
	v_fma_f32 v45, -v27, v43, 1.0
	v_fma_f32 v42, v45, v43, v43
	v_div_fixup_f32 v27, v42, v27, 1.0
	v_mul_f32_e32 v27, 0xbf1b459e, v27
	v_mul_f32_e32 v42, 0x3fb8aa3b, v27
	v_rndne_f32_e32 v42, v42
	v_fmamk_f32 v43, v42, 0xbf317218, v27
	v_fmac_f32_e32 v43, 0x3102e308, v42
	v_cvt_i32_f32_e32 v44, v42
	v_fmamk_f32 v45, v43, 0x395133b1, v171
	v_fmaak_f32 v45, v43, v45, 0x3c0887f9
	v_fmaak_f32 v45, v43, v45, 0x3d2aaa81
	v_fmaak_f32 v45, v43, v45, 0x3e2aaaab
	v_ldexp_f32 v44, 1.0, v44
	v_fma_f32 v45, v43, v45, 0.5
	v_cmp_eq_f32_e32 vcc, s90, v42
	v_mul_f32_e32 v45, v43, v45
	v_fmac_f32_e32 v43, v43, v45
	v_cndmask_b32_e32 v42, v44, v172, vcc
	v_add_f32_e32 v44, -1.0, v42
	v_fmac_f32_e32 v44, v42, v43
	v_add_f32_e32 v42, v44, v44
	v_cndmask_b32_e32 v42, v44, v42, vcc
	v_cmp_nlt_f32_e32 vcc, s91, v27
	s_nop 1
	v_cndmask_b32_e64 v42, v173, -v42, vcc
	v_cmp_ngt_f32_e32 vcc, s92, v27
	s_nop 1
	v_cndmask_b32_e32 v42, 1.0, v42, vcc
.LBB0_1140:
	s_mov_b64 s[2:3], 0x140000
	v_lshl_add_u64 v[40:41], v[40:41], 0, s[2:3]
	v_cvt_pk_f16_f32 v27, v26, v42
	v_cvt_pk_f16_f32 v26, v24, v25
	v_cvt_pk_f16_f32 v25, v38, v39
	v_cvt_pk_f16_f32 v24, v36, v37
	global_store_dwordx4 v[40:41], v[24:27], off offset:256
	s_and_b64 vcc, exec, s[8:9]
	s_mov_b64 s[14:15], -1
	v_add_f32_e32 v24, v16, v32
	s_cbranch_vccnz .LBB0_1144
	s_and_b64 vcc, exec, s[6:7]
	v_mov_b32_e32 v16, v24
	s_cbranch_vccnz .LBB0_1143
	v_mul_f32_e32 v16, 0xbfb8aa3b, v24
	v_exp_f32_e32 v16, v16
	s_nop 0
	v_add_f32_e32 v16, 1.0, v16
	v_rcp_f32_e32 v26, v16
	s_nop 0
	v_fma_f32 v32, -v16, v26, 1.0
	v_fma_f32 v25, v32, v26, v26
	v_div_fixup_f32 v16, v25, v16, 1.0

; __device__ __forceinline__ float sigmoidf_(float x) { return 1.0f / (1.0f + __expf(-x)); }
;     __device__ __forceinline__ void operator()(const f32x4 (&acc)[2][2][4][2], const Unit& u, int wr, int wc, int fr, int fq) const {
;     ...
;                 for (int bj = 0; bj < 2; ++bj) { f16x8 v;
; #pragma unroll
;                     for (int n = 0; n < 2; ++n)
; #pragma unroll
;                         for (int i = 0; i < 4; ++i) { float xv = acc[ai][bj][m][n][i] + bv[bj][n][i]; float r;
;                             if (type < 2) { const float sg = sigmoidf_(xv); r = -expm1f(-0.606531f * sg); }
;                             else if (type == 2) r = sigmoidf_(xv);
;                             else r = xv;
;                             v[4 * n + i] = (f16)r; }
;                     *(f16x8*)(rowp + bj * 128) = v; } }
.LBB0_1145:
	v_mul_f32_e32 v16, 0xbfb8aa3b, v24
	v_exp_f32_e32 v16, v16
	s_nop 0
	v_add_f32_e32 v16, 1.0, v16
	v_rcp_f32_e32 v25, v16
	s_nop 0
	v_fma_f32 v27, -v16, v25, 1.0
	v_fma_f32 v24, v27, v25, v25
	v_div_fixup_f32 v16, v24, v16, 1.0
	v_mul_f32_e32 v16, 0xbf1b459e, v16
	v_mul_f32_e32 v24, 0x3fb8aa3b, v16
	v_rndne_f32_e32 v24, v24
	v_fmamk_f32 v25, v24, 0xbf317218, v16
	v_fmac_f32_e32 v25, 0x3102e308, v24
	v_cvt_i32_f32_e32 v26, v24
	v_fmamk_f32 v27, v25, 0x395133b1, v171
	v_fmaak_f32 v27, v25, v27, 0x3c0887f9
	v_fmaak_f32 v27, v25, v27, 0x3d2aaa81
	v_fmaak_f32 v27, v25, v27, 0x3e2aaaab
	v_ldexp_f32 v26, 1.0, v26
	v_fma_f32 v27, v25, v27, 0.5
	v_cmp_eq_f32_e32 vcc, s90, v24
	v_mul_f32_e32 v27, v25, v27
	v_fmac_f32_e32 v25, v25, v27
	v_cndmask_b32_e32 v24, v26, v172, vcc
	v_add_f32_e32 v26, -1.0, v24
	v_fmac_f32_e32 v26, v24, v25
	v_add_f32_e32 v24, v26, v26
	v_cndmask_b32_e32 v24, v26, v24, vcc
	v_cmp_nlt_f32_e32 vcc, s91, v16
	s_nop 1
	v_cndmask_b32_e64 v24, v173, -v24, vcc
	v_cmp_ngt_f32_e32 vcc, s92, v16
	s_nop 1
	v_cndmask_b32_e32 v16, 1.0, v24, vcc
.LBB0_1146:
	v_add_f32_e32 v24, v17, v33
	s_and_b64 vcc, exec, s[8:9]
	s_mov_b64 s[14:15], -1
	s_cbranch_vccnz .LBB0_1150
	s_and_b64 vcc, exec, s[6:7]
	v_mov_b32_e32 v17, v24
	s_cbranch_vccnz .LBB0_1149
	v_mul_f32_e32 v17, 0xbfb8aa3b, v24
	v_exp_f32_e32 v17, v17
	s_nop 0
	v_add_f32_e32 v17, 1.0, v17
	v_rcp_f32_e32 v26, v17
	s_nop 0
	v_fma_f32 v32, -v17, v26, 1.0
	v_fma_f32 v25, v32, v26, v26
	v_div_fixup_f32 v17, v25, v17, 1.0

; __device__ __forceinline__ float sigmoidf_(float x) { return 1.0f / (1.0f + __expf(-x)); }
;     __device__ __forceinline__ void operator()(const f32x4 (&acc)[2][2][4][2], const Unit& u, int wr, int wc, int fr, int fq) const {
;     ...
;                 for (int bj = 0; bj < 2; ++bj) { f16x8 v;
; #pragma unroll
;                     for (int n = 0; n < 2; ++n)
; #pragma unroll
;                         for (int i = 0; i < 4; ++i) { float xv = acc[ai][bj][m][n][i] + bv[bj][n][i]; float r;
;                             if (type < 2) { const float sg = sigmoidf_(xv); r = -expm1f(-0.606531f * sg); }
;                             else if (type == 2) r = sigmoidf_(xv);
;                             else r = xv;
;                             v[4 * n + i] = (f16)r; }
;                     *(f16x8*)(rowp + bj * 128) = v; } }
.LBB0_1151:
	v_mul_f32_e32 v17, 0xbfb8aa3b, v24
	v_exp_f32_e32 v17, v17
	s_nop 0
	v_add_f32_e32 v17, 1.0, v17
	v_rcp_f32_e32 v25, v17
	s_nop 0
	v_fma_f32 v27, -v17, v25, 1.0
	v_fma_f32 v24, v27, v25, v25
	v_div_fixup_f32 v17, v24, v17, 1.0
	v_mul_f32_e32 v17, 0xbf1b459e, v17
	v_mul_f32_e32 v24, 0x3fb8aa3b, v17
	v_rndne_f32_e32 v24, v24
	v_fmamk_f32 v25, v24, 0xbf317218, v17
	v_fmac_f32_e32 v25, 0x3102e308, v24
	v_cvt_i32_f32_e32 v26, v24
	v_fmamk_f32 v27, v25, 0x395133b1, v171
	v_fmaak_f32 v27, v25, v27, 0x3c0887f9
	v_fmaak_f32 v27, v25, v27, 0x3d2aaa81
	v_fmaak_f32 v27, v25, v27, 0x3e2aaaab
	v_ldexp_f32 v26, 1.0, v26
	v_fma_f32 v27, v25, v27, 0.5
	v_cmp_eq_f32_e32 vcc, s90, v24
	v_mul_f32_e32 v27, v25, v27
	v_fmac_f32_e32 v25, v25, v27
	v_cndmask_b32_e32 v24, v26, v172, vcc
	v_add_f32_e32 v26, -1.0, v24
	v_fmac_f32_e32 v26, v24, v25
	v_add_f32_e32 v24, v26, v26
	v_cndmask_b32_e32 v24, v26, v24, vcc
	v_cmp_nlt_f32_e32 vcc, s91, v17
	s_nop 1
	v_cndmask_b32_e64 v24, v173, -v24, vcc
	v_cmp_ngt_f32_e32 vcc, s92, v17
	s_nop 1
	v_cndmask_b32_e32 v17, 1.0, v24, vcc
.LBB0_1152:
	v_add_f32_e32 v24, v18, v34
	s_and_b64 vcc, exec, s[8:9]
	s_mov_b64 s[14:15], -1
	s_cbranch_vccnz .LBB0_1156
	s_and_b64 vcc, exec, s[6:7]
	v_mov_b32_e32 v18, v24
	s_cbranch_vccnz .LBB0_1155
	v_mul_f32_e32 v18, 0xbfb8aa3b, v24
	v_exp_f32_e32 v18, v18
	s_nop 0
	v_add_f32_e32 v18, 1.0, v18
	v_rcp_f32_e32 v26, v18
	s_nop 0
	v_fma_f32 v32, -v18, v26, 1.0
	v_fma_f32 v25, v32, v26, v26
	v_div_fixup_f32 v18, v25, v18, 1.0

; __device__ __forceinline__ float sigmoidf_(float x) { return 1.0f / (1.0f + __expf(-x)); }
;     __device__ __forceinline__ void operator()(const f32x4 (&acc)[2][2][4][2], const Unit& u, int wr, int wc, int fr, int fq) const {
;     ...
;                 for (int bj = 0; bj < 2; ++bj) { f16x8 v;
; #pragma unroll
;                     for (int n = 0; n < 2; ++n)
; #pragma unroll
;                         for (int i = 0; i < 4; ++i) { float xv = acc[ai][bj][m][n][i] + bv[bj][n][i]; float r;
;                             if (type < 2) { const float sg = sigmoidf_(xv); r = -expm1f(-0.606531f * sg); }
;                             else if (type == 2) r = sigmoidf_(xv);
;                             else r = xv;
;                             v[4 * n + i] = (f16)r; }
;                     *(f16x8*)(rowp + bj * 128) = v; } }
.LBB0_1157:
	v_mul_f32_e32 v18, 0xbfb8aa3b, v24
	v_exp_f32_e32 v18, v18
	s_nop 0
	v_add_f32_e32 v18, 1.0, v18
	v_rcp_f32_e32 v25, v18
	s_nop 0
	v_fma_f32 v27, -v18, v25, 1.0
	v_fma_f32 v24, v27, v25, v25
	v_div_fixup_f32 v18, v24, v18, 1.0
	v_mul_f32_e32 v18, 0xbf1b459e, v18
	v_mul_f32_e32 v24, 0x3fb8aa3b, v18
	v_rndne_f32_e32 v24, v24
	v_fmamk_f32 v25, v24, 0xbf317218, v18
	v_fmac_f32_e32 v25, 0x3102e308, v24
	v_cvt_i32_f32_e32 v26, v24
	v_fmamk_f32 v27, v25, 0x395133b1, v171
	v_fmaak_f32 v27, v25, v27, 0x3c0887f9
	v_fmaak_f32 v27, v25, v27, 0x3d2aaa81
	v_fmaak_f32 v27, v25, v27, 0x3e2aaaab
	v_ldexp_f32 v26, 1.0, v26
	v_fma_f32 v27, v25, v27, 0.5
	v_cmp_eq_f32_e32 vcc, s90, v24
	v_mul_f32_e32 v27, v25, v27
	v_fmac_f32_e32 v25, v25, v27
	v_cndmask_b32_e32 v24, v26, v172, vcc
	v_add_f32_e32 v26, -1.0, v24
	v_fmac_f32_e32 v26, v24, v25
	v_add_f32_e32 v24, v26, v26
	v_cndmask_b32_e32 v24, v26, v24, vcc
	v_cmp_nlt_f32_e32 vcc, s91, v18
	s_nop 1
	v_cndmask_b32_e64 v24, v173, -v24, vcc
	v_cmp_ngt_f32_e32 vcc, s92, v18
	s_nop 1
	v_cndmask_b32_e32 v18, 1.0, v24, vcc
.LBB0_1158:
	v_add_f32_e32 v24, v19, v35
	s_and_b64 vcc, exec, s[8:9]
	s_mov_b64 s[14:15], -1
	s_cbranch_vccnz .LBB0_1162
	s_and_b64 vcc, exec, s[6:7]
	v_mov_b32_e32 v19, v24
	s_cbranch_vccnz .LBB0_1161
	v_mul_f32_e32 v19, 0xbfb8aa3b, v24
	v_exp_f32_e32 v19, v19
	s_nop 0
	v_add_f32_e32 v19, 1.0, v19
	v_rcp_f32_e32 v26, v19
	s_nop 0
	v_fma_f32 v32, -v19, v26, 1.0
	v_fma_f32 v25, v32, v26, v26
	v_div_fixup_f32 v19, v25, v19, 1.0

; __device__ __forceinline__ float sigmoidf_(float x) { return 1.0f / (1.0f + __expf(-x)); }
;     __device__ __forceinline__ void operator()(const f32x4 (&acc)[2][2][4][2], const Unit& u, int wr, int wc, int fr, int fq) const {
;     ...
;                 for (int bj = 0; bj < 2; ++bj) { f16x8 v;
; #pragma unroll
;                     for (int n = 0; n < 2; ++n)
; #pragma unroll
;                         for (int i = 0; i < 4; ++i) { float xv = acc[ai][bj][m][n][i] + bv[bj][n][i]; float r;
;                             if (type < 2) { const float sg = sigmoidf_(xv); r = -expm1f(-0.606531f * sg); }
;                             else if (type == 2) r = sigmoidf_(xv);
;                             else r = xv;
;                             v[4 * n + i] = (f16)r; }
;                     *(f16x8*)(rowp + bj * 128) = v; } }
.LBB0_1163:
	v_mul_f32_e32 v19, 0xbfb8aa3b, v24
	v_exp_f32_e32 v19, v19
	s_nop 0
	v_add_f32_e32 v19, 1.0, v19
	v_rcp_f32_e32 v25, v19
	s_nop 0
	v_fma_f32 v27, -v19, v25, 1.0
	v_fma_f32 v24, v27, v25, v25
	v_div_fixup_f32 v19, v24, v19, 1.0
	v_mul_f32_e32 v19, 0xbf1b459e, v19
	v_mul_f32_e32 v24, 0x3fb8aa3b, v19
	v_rndne_f32_e32 v24, v24
	v_fmamk_f32 v25, v24, 0xbf317218, v19
	v_fmac_f32_e32 v25, 0x3102e308, v24
	v_cvt_i32_f32_e32 v26, v24
	v_fmamk_f32 v27, v25, 0x395133b1, v171
	v_fmaak_f32 v27, v25, v27, 0x3c0887f9
	v_fmaak_f32 v27, v25, v27, 0x3d2aaa81
	v_fmaak_f32 v27, v25, v27, 0x3e2aaaab
	v_ldexp_f32 v26, 1.0, v26
	v_fma_f32 v27, v25, v27, 0.5
	v_cmp_eq_f32_e32 vcc, s90, v24
	v_mul_f32_e32 v27, v25, v27
	v_fmac_f32_e32 v25, v25, v27
	v_cndmask_b32_e32 v24, v26, v172, vcc
	v_add_f32_e32 v26, -1.0, v24
	v_fmac_f32_e32 v26, v24, v25
	v_add_f32_e32 v24, v26, v26
	v_cndmask_b32_e32 v24, v26, v24, vcc
	v_cmp_nlt_f32_e32 vcc, s91, v19
	s_nop 1
	v_cndmask_b32_e64 v24, v173, -v24, vcc
	v_cmp_ngt_f32_e32 vcc, s92, v19
	s_nop 1
	v_cndmask_b32_e32 v19, 1.0, v24, vcc
.LBB0_1164:
	v_add_f32_e32 v8, v8, v28
	s_and_b64 vcc, exec, s[8:9]
	s_mov_b64 s[14:15], -1
	s_cbranch_vccnz .LBB0_1168
	s_and_b64 vcc, exec, s[6:7]
	v_mov_b32_e32 v24, v8
	s_cbranch_vccnz .LBB0_1167
	v_mul_f32_e32 v24, 0xbfb8aa3b, v8
	v_exp_f32_e32 v24, v24
	s_nop 0
	v_add_f32_e32 v24, 1.0, v24
	v_rcp_f32_e32 v26, v24
	s_nop 0
	v_fma_f32 v28, -v24, v26, 1.0
	v_fma_f32 v25, v28, v26, v26
	v_div_fixup_f32 v24, v25, v24, 1.0

; __device__ __forceinline__ float sigmoidf_(float x) { return 1.0f / (1.0f + __expf(-x)); }
;     __device__ __forceinline__ void operator()(const f32x4 (&acc)[2][2][4][2], const Unit& u, int wr, int wc, int fr, int fq) const {
;     ...
;                 for (int bj = 0; bj < 2; ++bj) { f16x8 v;
; #pragma unroll
;                     for (int n = 0; n < 2; ++n)
; #pragma unroll
;                         for (int i = 0; i < 4; ++i) { float xv = acc[ai][bj][m][n][i] + bv[bj][n][i]; float r;
;                             if (type < 2) { const float sg = sigmoidf_(xv); r = -expm1f(-0.606531f * sg); }
;                             else if (type == 2) r = sigmoidf_(xv);
;                             else r = xv;
;                             v[4 * n + i] = (f16)r; }
;                     *(f16x8*)(rowp + bj * 128) = v; } }
.LBB0_1169:
	v_mul_f32_e32 v8, 0xbfb8aa3b, v8
	v_exp_f32_e32 v8, v8
	s_nop 0
	v_add_f32_e32 v8, 1.0, v8
	v_rcp_f32_e32 v25, v8
	s_nop 0
	v_fma_f32 v27, -v8, v25, 1.0
	v_fma_f32 v24, v27, v25, v25
	v_div_fixup_f32 v8, v24, v8, 1.0
	v_mul_f32_e32 v8, 0xbf1b459e, v8
	v_mul_f32_e32 v24, 0x3fb8aa3b, v8
	v_rndne_f32_e32 v24, v24
	v_fmamk_f32 v25, v24, 0xbf317218, v8
	v_fmac_f32_e32 v25, 0x3102e308, v24
	v_cvt_i32_f32_e32 v26, v24
	v_fmamk_f32 v27, v25, 0x395133b1, v171
	v_fmaak_f32 v27, v25, v27, 0x3c0887f9
	v_fmaak_f32 v27, v25, v27, 0x3d2aaa81
	v_fmaak_f32 v27, v25, v27, 0x3e2aaaab
	v_ldexp_f32 v26, 1.0, v26
	v_fma_f32 v27, v25, v27, 0.5
	v_cmp_eq_f32_e32 vcc, s90, v24
	v_mul_f32_e32 v27, v25, v27
	v_fmac_f32_e32 v25, v25, v27
	v_cndmask_b32_e32 v24, v26, v172, vcc
	v_add_f32_e32 v26, -1.0, v24
	v_fmac_f32_e32 v26, v24, v25
	v_add_f32_e32 v24, v26, v26
	v_cndmask_b32_e32 v24, v26, v24, vcc
	v_cmp_nlt_f32_e32 vcc, s91, v8
	s_nop 1
	v_cndmask_b32_e64 v24, v173, -v24, vcc
	v_cmp_ngt_f32_e32 vcc, s92, v8
	s_nop 1
	v_cndmask_b32_e32 v24, 1.0, v24, vcc
.LBB0_1170:
	v_add_f32_e32 v8, v9, v29
	s_and_b64 vcc, exec, s[8:9]
	s_mov_b64 s[14:15], -1
	s_cbranch_vccnz .LBB0_1174
	s_and_b64 vcc, exec, s[6:7]
	v_mov_b32_e32 v25, v8
	s_cbranch_vccnz .LBB0_1173
	v_mul_f32_e32 v9, 0xbfb8aa3b, v8
	v_exp_f32_e32 v9, v9
	s_nop 0
	v_add_f32_e32 v9, 1.0, v9
	v_rcp_f32_e32 v26, v9
	s_nop 0
	v_fma_f32 v28, -v9, v26, 1.0
	v_fma_f32 v25, v28, v26, v26
	v_div_fixup_f32 v25, v25, v9, 1.0

; __device__ __forceinline__ float sigmoidf_(float x) { return 1.0f / (1.0f + __expf(-x)); }
;     __device__ __forceinline__ void operator()(const f32x4 (&acc)[2][2][4][2], const Unit& u, int wr, int wc, int fr, int fq) const {
;     ...
;                 for (int bj = 0; bj < 2; ++bj) { f16x8 v;
; #pragma unroll
;                     for (int n = 0; n < 2; ++n)
; #pragma unroll
;                         for (int i = 0; i < 4; ++i) { float xv = acc[ai][bj][m][n][i] + bv[bj][n][i]; float r;
;                             if (type < 2) { const float sg = sigmoidf_(xv); r = -expm1f(-0.606531f * sg); }
;                             else if (type == 2) r = sigmoidf_(xv);
;                             else r = xv;
;                             v[4 * n + i] = (f16)r; }
;                     *(f16x8*)(rowp + bj * 128) = v; } }
.LBB0_1175:
	v_mul_f32_e32 v8, 0xbfb8aa3b, v8
	v_exp_f32_e32 v8, v8
	s_nop 0
	v_add_f32_e32 v8, 1.0, v8
	v_rcp_f32_e32 v25, v8
	s_nop 0
	v_fma_f32 v27, -v8, v25, 1.0
	v_fma_f32 v9, v27, v25, v25
	v_div_fixup_f32 v8, v9, v8, 1.0
	v_mul_f32_e32 v8, 0xbf1b459e, v8
	v_mul_f32_e32 v9, 0x3fb8aa3b, v8
	v_rndne_f32_e32 v9, v9
	v_fmamk_f32 v25, v9, 0xbf317218, v8
	v_fmac_f32_e32 v25, 0x3102e308, v9
	v_cvt_i32_f32_e32 v26, v9
	v_fmamk_f32 v27, v25, 0x395133b1, v171
	v_fmaak_f32 v27, v25, v27, 0x3c0887f9
	v_fmaak_f32 v27, v25, v27, 0x3d2aaa81
	v_fmaak_f32 v27, v25, v27, 0x3e2aaaab
	v_ldexp_f32 v26, 1.0, v26
	v_fma_f32 v27, v25, v27, 0.5
	v_cmp_eq_f32_e32 vcc, s90, v9
	v_mul_f32_e32 v27, v25, v27
	v_fmac_f32_e32 v25, v25, v27
	v_cndmask_b32_e32 v9, v26, v172, vcc
	v_add_f32_e32 v26, -1.0, v9
	v_fmac_f32_e32 v26, v9, v25
	v_add_f32_e32 v9, v26, v26
	v_cndmask_b32_e32 v9, v26, v9, vcc
	v_cmp_nlt_f32_e32 vcc, s91, v8
	s_nop 1
	v_cndmask_b32_e64 v9, v173, -v9, vcc
	v_cmp_ngt_f32_e32 vcc, s92, v8
	s_nop 1
	v_cndmask_b32_e32 v25, 1.0, v9, vcc
.LBB0_1176:
	v_add_f32_e32 v8, v10, v30
	s_and_b64 vcc, exec, s[8:9]
	s_mov_b64 s[14:15], -1
	s_cbranch_vccnz .LBB0_1180
	s_and_b64 vcc, exec, s[6:7]
	v_mov_b32_e32 v10, v8
	s_cbranch_vccnz .LBB0_1179
	v_mul_f32_e32 v9, 0xbfb8aa3b, v8
	v_exp_f32_e32 v9, v9
	s_nop 0
	v_add_f32_e32 v9, 1.0, v9
	v_rcp_f32_e32 v26, v9
	s_nop 0
	v_fma_f32 v28, -v9, v26, 1.0
	v_fma_f32 v10, v28, v26, v26
	v_div_fixup_f32 v10, v10, v9, 1.0

; __device__ __forceinline__ float sigmoidf_(float x) { return 1.0f / (1.0f + __expf(-x)); }
;     __device__ __forceinline__ void operator()(const f32x4 (&acc)[2][2][4][2], const Unit& u, int wr, int wc, int fr, int fq) const {
;     ...
;                 for (int bj = 0; bj < 2; ++bj) { f16x8 v;
; #pragma unroll
;                     for (int n = 0; n < 2; ++n)
; #pragma unroll
;                         for (int i = 0; i < 4; ++i) { float xv = acc[ai][bj][m][n][i] + bv[bj][n][i]; float r;
;                             if (type < 2) { const float sg = sigmoidf_(xv); r = -expm1f(-0.606531f * sg); }
;                             else if (type == 2) r = sigmoidf_(xv);
;                             else r = xv;
;                             v[4 * n + i] = (f16)r; }
;                     *(f16x8*)(rowp + bj * 128) = v; } }
.LBB0_1181:
	v_mul_f32_e32 v8, 0xbfb8aa3b, v8
	v_exp_f32_e32 v8, v8
	s_nop 0
	v_add_f32_e32 v8, 1.0, v8
	v_rcp_f32_e32 v10, v8
	s_nop 0
	v_fma_f32 v27, -v8, v10, 1.0
	v_fma_f32 v9, v27, v10, v10
	v_div_fixup_f32 v8, v9, v8, 1.0
	v_mul_f32_e32 v8, 0xbf1b459e, v8
	v_mul_f32_e32 v9, 0x3fb8aa3b, v8
	v_rndne_f32_e32 v9, v9
	v_fmamk_f32 v10, v9, 0xbf317218, v8
	v_fmac_f32_e32 v10, 0x3102e308, v9
	v_cvt_i32_f32_e32 v26, v9
	v_fmamk_f32 v27, v10, 0x395133b1, v171
	v_fmaak_f32 v27, v10, v27, 0x3c0887f9
	v_fmaak_f32 v27, v10, v27, 0x3d2aaa81
	v_fmaak_f32 v27, v10, v27, 0x3e2aaaab
	v_ldexp_f32 v26, 1.0, v26
	v_fma_f32 v27, v10, v27, 0.5
	v_cmp_eq_f32_e32 vcc, s90, v9
	v_mul_f32_e32 v27, v10, v27
	v_fmac_f32_e32 v10, v10, v27
	v_cndmask_b32_e32 v9, v26, v172, vcc
	v_add_f32_e32 v26, -1.0, v9
	v_fmac_f32_e32 v26, v9, v10
	v_add_f32_e32 v9, v26, v26
	v_cndmask_b32_e32 v9, v26, v9, vcc
	v_cmp_nlt_f32_e32 vcc, s91, v8
	s_nop 1
	v_cndmask_b32_e64 v9, v173, -v9, vcc
	v_cmp_ngt_f32_e32 vcc, s92, v8
	s_nop 1
	v_cndmask_b32_e32 v10, 1.0, v9, vcc
.LBB0_1182:
	v_add_f32_e32 v8, v11, v31
	s_and_b64 vcc, exec, s[8:9]
	s_mov_b64 s[14:15], -1
	s_cbranch_vccnz .LBB0_1186
	s_and_b64 vcc, exec, s[6:7]
	v_mov_b32_e32 v11, v8
	s_cbranch_vccnz .LBB0_1185
	v_mul_f32_e32 v9, 0xbfb8aa3b, v8
	v_exp_f32_e32 v9, v9
	s_nop 0
	v_add_f32_e32 v9, 1.0, v9
	v_rcp_f32_e32 v26, v9
	s_nop 0
	v_fma_f32 v28, -v9, v26, 1.0
	v_fma_f32 v11, v28, v26, v26
	v_div_fixup_f32 v11, v11, v9, 1.0

; __device__ __forceinline__ float sigmoidf_(float x) { return 1.0f / (1.0f + __expf(-x)); }
;     __device__ __forceinline__ void operator()(const f32x4 (&acc)[2][2][4][2], const Unit& u, int wr, int wc, int fr, int fq) const {
;     ...
;                 for (int bj = 0; bj < 2; ++bj) { f16x8 v;
; #pragma unroll
;                     for (int n = 0; n < 2; ++n)
; #pragma unroll
;                         for (int i = 0; i < 4; ++i) { float xv = acc[ai][bj][m][n][i] + bv[bj][n][i]; float r;
;                             if (type < 2) { const float sg = sigmoidf_(xv); r = -expm1f(-0.606531f * sg); }
;                             else if (type == 2) r = sigmoidf_(xv);
;                             else r = xv;
;                             v[4 * n + i] = (f16)r; }
;                     *(f16x8*)(rowp + bj * 128) = v; } }
.LBB0_1187:
	v_mul_f32_e32 v8, 0xbfb8aa3b, v8
	v_exp_f32_e32 v8, v8
	s_nop 0
	v_add_f32_e32 v8, 1.0, v8
	v_rcp_f32_e32 v11, v8
	s_nop 0
	v_fma_f32 v27, -v8, v11, 1.0
	v_fma_f32 v9, v27, v11, v11
	v_div_fixup_f32 v8, v9, v8, 1.0
	v_mul_f32_e32 v8, 0xbf1b459e, v8
	v_mul_f32_e32 v9, 0x3fb8aa3b, v8
	v_rndne_f32_e32 v9, v9
	v_fmamk_f32 v11, v9, 0xbf317218, v8
	v_fmac_f32_e32 v11, 0x3102e308, v9
	v_cvt_i32_f32_e32 v26, v9
	v_fmamk_f32 v27, v11, 0x395133b1, v171
	v_fmaak_f32 v27, v11, v27, 0x3c0887f9
	v_fmaak_f32 v27, v11, v27, 0x3d2aaa81
	v_fmaak_f32 v27, v11, v27, 0x3e2aaaab
	v_ldexp_f32 v26, 1.0, v26
	v_fma_f32 v27, v11, v27, 0.5
	v_cmp_eq_f32_e32 vcc, s90, v9
	v_mul_f32_e32 v27, v11, v27
	v_fmac_f32_e32 v11, v11, v27
	v_cndmask_b32_e32 v9, v26, v172, vcc
	v_add_f32_e32 v26, -1.0, v9
	v_fmac_f32_e32 v26, v9, v11
	v_add_f32_e32 v9, v26, v26
	v_cndmask_b32_e32 v9, v26, v9, vcc
	v_cmp_nlt_f32_e32 vcc, s91, v8
	s_nop 1
	v_cndmask_b32_e64 v9, v173, -v9, vcc
	v_cmp_ngt_f32_e32 vcc, s92, v8
	s_nop 1
	v_cndmask_b32_e32 v11, 1.0, v9, vcc
.LBB0_1188:
	v_lshlrev_b64 v[8:9], 13, v[138:139]
	v_lshl_add_u64 v[8:9], s[28:29], 0, v[8:9]
	v_lshl_add_u64 v[8:9], v[136:137], 1, v[8:9]
	v_cvt_pk_f16_f32 v27, v10, v11
	v_add_co_u32_e32 v10, vcc, 0x160000, v8
	v_cvt_pk_f16_f32 v26, v24, v25
	v_cvt_pk_f16_f32 v25, v18, v19
	v_cvt_pk_f16_f32 v24, v16, v17
	v_addc_co_u32_e32 v11, vcc, 0, v9, vcc
	global_store_dwordx4 v[10:11], v[24:27], off
	v_add_f32_e32 v10, v4, v20
	s_and_b64 vcc, exec, s[8:9]
	s_mov_b64 s[14:15], -1
	s_cbranch_vccnz .LBB0_1192
	s_and_b64 vcc, exec, s[6:7]
	v_mov_b32_e32 v4, v10
	s_cbranch_vccnz .LBB0_1191
	v_mul_f32_e32 v4, 0xbfb8aa3b, v10
	v_exp_f32_e32 v4, v4
	s_nop 0
	v_add_f32_e32 v4, 1.0, v4
	v_rcp_f32_e32 v16, v4
	s_nop 0
	v_fma_f32 v18, -v4, v16, 1.0
	v_fma_f32 v11, v18, v16, v16
	v_div_fixup_f32 v4, v11, v4, 1.0

; __device__ __forceinline__ float sigmoidf_(float x) { return 1.0f / (1.0f + __expf(-x)); }
;     __device__ __forceinline__ void operator()(const f32x4 (&acc)[2][2][4][2], const Unit& u, int wr, int wc, int fr, int fq) const {
;     ...
;                 for (int bj = 0; bj < 2; ++bj) { f16x8 v;
; #pragma unroll
;                     for (int n = 0; n < 2; ++n)
; #pragma unroll
;                         for (int i = 0; i < 4; ++i) { float xv = acc[ai][bj][m][n][i] + bv[bj][n][i]; float r;
;                             if (type < 2) { const float sg = sigmoidf_(xv); r = -expm1f(-0.606531f * sg); }
;                             else if (type == 2) r = sigmoidf_(xv);
;                             else r = xv;
;                             v[4 * n + i] = (f16)r; }
;                     *(f16x8*)(rowp + bj * 128) = v; } }
.LBB0_1193:
	v_mul_f32_e32 v4, 0xbfb8aa3b, v10
	v_exp_f32_e32 v4, v4
	s_nop 0
	v_add_f32_e32 v4, 1.0, v4
	v_rcp_f32_e32 v11, v4
	s_nop 0
	v_fma_f32 v17, -v4, v11, 1.0
	v_fma_f32 v10, v17, v11, v11
	v_div_fixup_f32 v4, v10, v4, 1.0
	v_mul_f32_e32 v4, 0xbf1b459e, v4
	v_mul_f32_e32 v10, 0x3fb8aa3b, v4
	v_rndne_f32_e32 v10, v10
	v_fmamk_f32 v11, v10, 0xbf317218, v4
	v_fmac_f32_e32 v11, 0x3102e308, v10
	v_cvt_i32_f32_e32 v16, v10
	v_fmamk_f32 v17, v11, 0x395133b1, v171
	v_fmaak_f32 v17, v11, v17, 0x3c0887f9
	v_fmaak_f32 v17, v11, v17, 0x3d2aaa81
	v_fmaak_f32 v17, v11, v17, 0x3e2aaaab
	v_ldexp_f32 v16, 1.0, v16
	v_fma_f32 v17, v11, v17, 0.5
	v_cmp_eq_f32_e32 vcc, s90, v10
	v_mul_f32_e32 v17, v11, v17
	v_fmac_f32_e32 v11, v11, v17
	v_cndmask_b32_e32 v10, v16, v172, vcc
	v_add_f32_e32 v16, -1.0, v10
	v_fmac_f32_e32 v16, v10, v11
	v_add_f32_e32 v10, v16, v16
	v_cndmask_b32_e32 v10, v16, v10, vcc
	v_cmp_nlt_f32_e32 vcc, s91, v4
	s_nop 1
	v_cndmask_b32_e64 v10, v173, -v10, vcc
	v_cmp_ngt_f32_e32 vcc, s92, v4
	s_nop 1
	v_cndmask_b32_e32 v4, 1.0, v10, vcc
.LBB0_1194:
	v_add_f32_e32 v10, v5, v21
	s_and_b64 vcc, exec, s[8:9]
	s_mov_b64 s[14:15], -1
	s_cbranch_vccnz .LBB0_1198
	s_and_b64 vcc, exec, s[6:7]
	v_mov_b32_e32 v5, v10
	s_cbranch_vccnz .LBB0_1197
	v_mul_f32_e32 v5, 0xbfb8aa3b, v10
	v_exp_f32_e32 v5, v5
	s_nop 0
	v_add_f32_e32 v5, 1.0, v5
	v_rcp_f32_e32 v16, v5
	s_nop 0
	v_fma_f32 v18, -v5, v16, 1.0
	v_fma_f32 v11, v18, v16, v16
	v_div_fixup_f32 v5, v11, v5, 1.0

; __device__ __forceinline__ float sigmoidf_(float x) { return 1.0f / (1.0f + __expf(-x)); }
;     __device__ __forceinline__ void operator()(const f32x4 (&acc)[2][2][4][2], const Unit& u, int wr, int wc, int fr, int fq) const {
;     ...
;                 for (int bj = 0; bj < 2; ++bj) { f16x8 v;
; #pragma unroll
;                     for (int n = 0; n < 2; ++n)
; #pragma unroll
;                         for (int i = 0; i < 4; ++i) { float xv = acc[ai][bj][m][n][i] + bv[bj][n][i]; float r;
;                             if (type < 2) { const float sg = sigmoidf_(xv); r = -expm1f(-0.606531f * sg); }
;                             else if (type == 2) r = sigmoidf_(xv);
;                             else r = xv;
;                             v[4 * n + i] = (f16)r; }
;                     *(f16x8*)(rowp + bj * 128) = v; } }
.LBB0_1199:
	v_mul_f32_e32 v5, 0xbfb8aa3b, v10
	v_exp_f32_e32 v5, v5
	s_nop 0
	v_add_f32_e32 v5, 1.0, v5
	v_rcp_f32_e32 v11, v5
	s_nop 0
	v_fma_f32 v17, -v5, v11, 1.0
	v_fma_f32 v10, v17, v11, v11
	v_div_fixup_f32 v5, v10, v5, 1.0
	v_mul_f32_e32 v5, 0xbf1b459e, v5
	v_mul_f32_e32 v10, 0x3fb8aa3b, v5
	v_rndne_f32_e32 v10, v10
	v_fmamk_f32 v11, v10, 0xbf317218, v5
	v_fmac_f32_e32 v11, 0x3102e308, v10
	v_cvt_i32_f32_e32 v16, v10
	v_fmamk_f32 v17, v11, 0x395133b1, v171
	v_fmaak_f32 v17, v11, v17, 0x3c0887f9
	v_fmaak_f32 v17, v11, v17, 0x3d2aaa81
	v_fmaak_f32 v17, v11, v17, 0x3e2aaaab
	v_ldexp_f32 v16, 1.0, v16
	v_fma_f32 v17, v11, v17, 0.5
	v_cmp_eq_f32_e32 vcc, s90, v10
	v_mul_f32_e32 v17, v11, v17
	v_fmac_f32_e32 v11, v11, v17
	v_cndmask_b32_e32 v10, v16, v172, vcc
	v_add_f32_e32 v16, -1.0, v10
	v_fmac_f32_e32 v16, v10, v11
	v_add_f32_e32 v10, v16, v16
	v_cndmask_b32_e32 v10, v16, v10, vcc
	v_cmp_nlt_f32_e32 vcc, s91, v5
	s_nop 1
	v_cndmask_b32_e64 v10, v173, -v10, vcc
	v_cmp_ngt_f32_e32 vcc, s92, v5
	s_nop 1
	v_cndmask_b32_e32 v5, 1.0, v10, vcc
.LBB0_1200:
	v_add_f32_e32 v10, v6, v22
	s_and_b64 vcc, exec, s[8:9]
	s_mov_b64 s[14:15], -1
	s_cbranch_vccnz .LBB0_1204
	s_and_b64 vcc, exec, s[6:7]
	v_mov_b32_e32 v6, v10
	s_cbranch_vccnz .LBB0_1203
	v_mul_f32_e32 v6, 0xbfb8aa3b, v10
	v_exp_f32_e32 v6, v6
	s_nop 0
	v_add_f32_e32 v6, 1.0, v6
	v_rcp_f32_e32 v16, v6
	s_nop 0
	v_fma_f32 v18, -v6, v16, 1.0
	v_fma_f32 v11, v18, v16, v16
	v_div_fixup_f32 v6, v11, v6, 1.0

; __device__ __forceinline__ float sigmoidf_(float x) { return 1.0f / (1.0f + __expf(-x)); }
;     __device__ __forceinline__ void operator()(const f32x4 (&acc)[2][2][4][2], const Unit& u, int wr, int wc, int fr, int fq) const {
;     ...
;                 for (int bj = 0; bj < 2; ++bj) { f16x8 v;
; #pragma unroll
;                     for (int n = 0; n < 2; ++n)
; #pragma unroll
;                         for (int i = 0; i < 4; ++i) { float xv = acc[ai][bj][m][n][i] + bv[bj][n][i]; float r;
;                             if (type < 2) { const float sg = sigmoidf_(xv); r = -expm1f(-0.606531f * sg); }
;                             else if (type == 2) r = sigmoidf_(xv);
;                             else r = xv;
;                             v[4 * n + i] = (f16)r; }
;                     *(f16x8*)(rowp + bj * 128) = v; } }
.LBB0_1205:
	v_mul_f32_e32 v6, 0xbfb8aa3b, v10
	v_exp_f32_e32 v6, v6
	s_nop 0
	v_add_f32_e32 v6, 1.0, v6
	v_rcp_f32_e32 v11, v6
	s_nop 0
	v_fma_f32 v17, -v6, v11, 1.0
	v_fma_f32 v10, v17, v11, v11
	v_div_fixup_f32 v6, v10, v6, 1.0
	v_mul_f32_e32 v6, 0xbf1b459e, v6
	v_mul_f32_e32 v10, 0x3fb8aa3b, v6
	v_rndne_f32_e32 v10, v10
	v_fmamk_f32 v11, v10, 0xbf317218, v6
	v_fmac_f32_e32 v11, 0x3102e308, v10
	v_cvt_i32_f32_e32 v16, v10
	v_fmamk_f32 v17, v11, 0x395133b1, v171
	v_fmaak_f32 v17, v11, v17, 0x3c0887f9
	v_fmaak_f32 v17, v11, v17, 0x3d2aaa81
	v_fmaak_f32 v17, v11, v17, 0x3e2aaaab
	v_ldexp_f32 v16, 1.0, v16
	v_fma_f32 v17, v11, v17, 0.5
	v_cmp_eq_f32_e32 vcc, s90, v10
	v_mul_f32_e32 v17, v11, v17
	v_fmac_f32_e32 v11, v11, v17
	v_cndmask_b32_e32 v10, v16, v172, vcc
	v_add_f32_e32 v16, -1.0, v10
	v_fmac_f32_e32 v16, v10, v11
	v_add_f32_e32 v10, v16, v16
	v_cndmask_b32_e32 v10, v16, v10, vcc
	v_cmp_nlt_f32_e32 vcc, s91, v6
	s_nop 1
	v_cndmask_b32_e64 v10, v173, -v10, vcc
	v_cmp_ngt_f32_e32 vcc, s92, v6
	s_nop 1
	v_cndmask_b32_e32 v6, 1.0, v10, vcc
.LBB0_1206:
	v_add_f32_e32 v10, v7, v23
	s_and_b64 vcc, exec, s[8:9]
	s_mov_b64 s[14:15], -1
	s_cbranch_vccnz .LBB0_1210
	s_and_b64 vcc, exec, s[6:7]
	v_mov_b32_e32 v7, v10
	s_cbranch_vccnz .LBB0_1209
	v_mul_f32_e32 v7, 0xbfb8aa3b, v10
	v_exp_f32_e32 v7, v7
	s_nop 0
	v_add_f32_e32 v7, 1.0, v7
	v_rcp_f32_e32 v16, v7
	s_nop 0
	v_fma_f32 v18, -v7, v16, 1.0
	v_fma_f32 v11, v18, v16, v16
	v_div_fixup_f32 v7, v11, v7, 1.0

; __device__ __forceinline__ float sigmoidf_(float x) { return 1.0f / (1.0f + __expf(-x)); }
;     __device__ __forceinline__ void operator()(const f32x4 (&acc)[2][2][4][2], const Unit& u, int wr, int wc, int fr, int fq) const {
;     ...
;                 for (int bj = 0; bj < 2; ++bj) { f16x8 v;
; #pragma unroll
;                     for (int n = 0; n < 2; ++n)
; #pragma unroll
;                         for (int i = 0; i < 4; ++i) { float xv = acc[ai][bj][m][n][i] + bv[bj][n][i]; float r;
;                             if (type < 2) { const float sg = sigmoidf_(xv); r = -expm1f(-0.606531f * sg); }
;                             else if (type == 2) r = sigmoidf_(xv);
;                             else r = xv;
;                             v[4 * n + i] = (f16)r; }
;                     *(f16x8*)(rowp + bj * 128) = v; } }
.LBB0_1211:
	v_mul_f32_e32 v7, 0xbfb8aa3b, v10
	v_exp_f32_e32 v7, v7
	s_nop 0
	v_add_f32_e32 v7, 1.0, v7
	v_rcp_f32_e32 v11, v7
	s_nop 0
	v_fma_f32 v17, -v7, v11, 1.0
	v_fma_f32 v10, v17, v11, v11
	v_div_fixup_f32 v7, v10, v7, 1.0
	v_mul_f32_e32 v7, 0xbf1b459e, v7
	v_mul_f32_e32 v10, 0x3fb8aa3b, v7
	v_rndne_f32_e32 v10, v10
	v_fmamk_f32 v11, v10, 0xbf317218, v7
	v_fmac_f32_e32 v11, 0x3102e308, v10
	v_cvt_i32_f32_e32 v16, v10
	v_fmamk_f32 v17, v11, 0x395133b1, v171
	v_fmaak_f32 v17, v11, v17, 0x3c0887f9
	v_fmaak_f32 v17, v11, v17, 0x3d2aaa81
	v_fmaak_f32 v17, v11, v17, 0x3e2aaaab
	v_ldexp_f32 v16, 1.0, v16
	v_fma_f32 v17, v11, v17, 0.5
	v_cmp_eq_f32_e32 vcc, s90, v10
	v_mul_f32_e32 v17, v11, v17
	v_fmac_f32_e32 v11, v11, v17
	v_cndmask_b32_e32 v10, v16, v172, vcc
	v_add_f32_e32 v16, -1.0, v10
	v_fmac_f32_e32 v16, v10, v11
	v_add_f32_e32 v10, v16, v16
	v_cndmask_b32_e32 v10, v16, v10, vcc
	v_cmp_nlt_f32_e32 vcc, s91, v7
	s_nop 1
	v_cndmask_b32_e64 v10, v173, -v10, vcc
	v_cmp_ngt_f32_e32 vcc, s92, v7
	s_nop 1
	v_cndmask_b32_e32 v7, 1.0, v10, vcc
.LBB0_1212:
	v_add_f32_e32 v10, v0, v12
	s_and_b64 vcc, exec, s[8:9]
	s_mov_b64 s[14:15], -1
	s_cbranch_vccnz .LBB0_1216
	s_and_b64 vcc, exec, s[6:7]
	v_mov_b32_e32 v0, v10
	s_cbranch_vccnz .LBB0_1215
	v_mul_f32_e32 v0, 0xbfb8aa3b, v10
	v_exp_f32_e32 v0, v0
	s_nop 0
	v_add_f32_e32 v0, 1.0, v0
	v_rcp_f32_e32 v12, v0
	s_nop 0
	v_fma_f32 v17, -v0, v12, 1.0
	v_fma_f32 v11, v17, v12, v12
	v_div_fixup_f32 v0, v11, v0, 1.0

; __device__ __forceinline__ float sigmoidf_(float x) { return 1.0f / (1.0f + __expf(-x)); }
;     __device__ __forceinline__ void operator()(const f32x4 (&acc)[2][2][4][2], const Unit& u, int wr, int wc, int fr, int fq) const {
;     ...
;                 for (int bj = 0; bj < 2; ++bj) { f16x8 v;
; #pragma unroll
;                     for (int n = 0; n < 2; ++n)
; #pragma unroll
;                         for (int i = 0; i < 4; ++i) { float xv = acc[ai][bj][m][n][i] + bv[bj][n][i]; float r;
;                             if (type < 2) { const float sg = sigmoidf_(xv); r = -expm1f(-0.606531f * sg); }
;                             else if (type == 2) r = sigmoidf_(xv);
;                             else r = xv;
;                             v[4 * n + i] = (f16)r; }
;                     *(f16x8*)(rowp + bj * 128) = v; } }
.LBB0_1217:
	v_mul_f32_e32 v0, 0xbfb8aa3b, v10
	v_exp_f32_e32 v0, v0
	s_nop 0
	v_add_f32_e32 v0, 1.0, v0
	v_rcp_f32_e32 v11, v0
	s_nop 0
	v_fma_f32 v16, -v0, v11, 1.0
	v_fma_f32 v10, v16, v11, v11
	v_div_fixup_f32 v0, v10, v0, 1.0
	v_mul_f32_e32 v0, 0xbf1b459e, v0
	v_mul_f32_e32 v10, 0x3fb8aa3b, v0
	v_rndne_f32_e32 v10, v10
	v_fmamk_f32 v11, v10, 0xbf317218, v0
	v_fmac_f32_e32 v11, 0x3102e308, v10
	v_cvt_i32_f32_e32 v12, v10
	v_fmamk_f32 v16, v11, 0x395133b1, v171
	v_fmaak_f32 v16, v11, v16, 0x3c0887f9
	v_fmaak_f32 v16, v11, v16, 0x3d2aaa81
	v_fmaak_f32 v16, v11, v16, 0x3e2aaaab
	v_ldexp_f32 v12, 1.0, v12
	v_fma_f32 v16, v11, v16, 0.5
	v_cmp_eq_f32_e32 vcc, s90, v10
	v_mul_f32_e32 v16, v11, v16
	v_fmac_f32_e32 v11, v11, v16
	v_cndmask_b32_e32 v10, v12, v172, vcc
	v_add_f32_e32 v12, -1.0, v10
	v_fmac_f32_e32 v12, v10, v11
	v_add_f32_e32 v10, v12, v12
	v_cndmask_b32_e32 v10, v12, v10, vcc
	v_cmp_nlt_f32_e32 vcc, s91, v0
	s_nop 1
	v_cndmask_b32_e64 v10, v173, -v10, vcc
	v_cmp_ngt_f32_e32 vcc, s92, v0
	s_nop 1
	v_cndmask_b32_e32 v0, 1.0, v10, vcc
.LBB0_1218:
	v_add_f32_e32 v10, v1, v13
	s_and_b64 vcc, exec, s[8:9]
	s_mov_b64 s[14:15], -1
	s_cbranch_vccnz .LBB0_1222
	s_and_b64 vcc, exec, s[6:7]
	v_mov_b32_e32 v1, v10
	s_cbranch_vccnz .LBB0_1221
	v_mul_f32_e32 v1, 0xbfb8aa3b, v10
	v_exp_f32_e32 v1, v1
	s_nop 0
	v_add_f32_e32 v1, 1.0, v1
	v_rcp_f32_e32 v12, v1
	s_nop 0
	v_fma_f32 v16, -v1, v12, 1.0
	v_fma_f32 v11, v16, v12, v12
	v_div_fixup_f32 v1, v11, v1, 1.0

; __device__ __forceinline__ float sigmoidf_(float x) { return 1.0f / (1.0f + __expf(-x)); }
;     __device__ __forceinline__ void operator()(const f32x4 (&acc)[2][2][4][2], const Unit& u, int wr, int wc, int fr, int fq) const {
;     ...
;                 for (int bj = 0; bj < 2; ++bj) { f16x8 v;
; #pragma unroll
;                     for (int n = 0; n < 2; ++n)
; #pragma unroll
;                         for (int i = 0; i < 4; ++i) { float xv = acc[ai][bj][m][n][i] + bv[bj][n][i]; float r;
;                             if (type < 2) { const float sg = sigmoidf_(xv); r = -expm1f(-0.606531f * sg); }
;                             else if (type == 2) r = sigmoidf_(xv);
;                             else r = xv;
;                             v[4 * n + i] = (f16)r; }
;                     *(f16x8*)(rowp + bj * 128) = v; } }
.LBB0_1223:
	v_mul_f32_e32 v1, 0xbfb8aa3b, v10
	v_exp_f32_e32 v1, v1
	s_nop 0
	v_add_f32_e32 v1, 1.0, v1
	v_rcp_f32_e32 v11, v1
	s_nop 0
	v_fma_f32 v13, -v1, v11, 1.0
	v_fma_f32 v10, v13, v11, v11
	v_div_fixup_f32 v1, v10, v1, 1.0
	v_mul_f32_e32 v1, 0xbf1b459e, v1
	v_mul_f32_e32 v10, 0x3fb8aa3b, v1
	v_rndne_f32_e32 v10, v10
	v_fmamk_f32 v11, v10, 0xbf317218, v1
	v_fmac_f32_e32 v11, 0x3102e308, v10
	v_cvt_i32_f32_e32 v12, v10
	v_fmamk_f32 v13, v11, 0x395133b1, v171
	v_fmaak_f32 v13, v11, v13, 0x3c0887f9
	v_fmaak_f32 v13, v11, v13, 0x3d2aaa81
	v_fmaak_f32 v13, v11, v13, 0x3e2aaaab
	v_ldexp_f32 v12, 1.0, v12
	v_fma_f32 v13, v11, v13, 0.5
	v_cmp_eq_f32_e32 vcc, s90, v10
	v_mul_f32_e32 v13, v11, v13
	v_fmac_f32_e32 v11, v11, v13
	v_cndmask_b32_e32 v10, v12, v172, vcc
	v_add_f32_e32 v12, -1.0, v10
	v_fmac_f32_e32 v12, v10, v11
	v_add_f32_e32 v10, v12, v12
	v_cndmask_b32_e32 v10, v12, v10, vcc
	v_cmp_nlt_f32_e32 vcc, s91, v1
	s_nop 1
	v_cndmask_b32_e64 v10, v173, -v10, vcc
	v_cmp_ngt_f32_e32 vcc, s92, v1
	s_nop 1
	v_cndmask_b32_e32 v1, 1.0, v10, vcc
.LBB0_1224:
	v_add_f32_e32 v10, v2, v14
	s_and_b64 vcc, exec, s[8:9]
	s_mov_b64 s[14:15], -1
	s_cbranch_vccnz .LBB0_1228
	s_and_b64 vcc, exec, s[6:7]
	v_mov_b32_e32 v2, v10
	s_cbranch_vccnz .LBB0_1227
	v_mul_f32_e32 v2, 0xbfb8aa3b, v10
	v_exp_f32_e32 v2, v2
	s_nop 0
	v_add_f32_e32 v2, 1.0, v2
	v_rcp_f32_e32 v12, v2
	s_nop 0
	v_fma_f32 v14, -v2, v12, 1.0
	v_fma_f32 v11, v14, v12, v12
	v_div_fixup_f32 v2, v11, v2, 1.0

; __device__ __forceinline__ float sigmoidf_(float x) { return 1.0f / (1.0f + __expf(-x)); }
;     __device__ __forceinline__ void operator()(const f32x4 (&acc)[2][2][4][2], const Unit& u, int wr, int wc, int fr, int fq) const {
;     ...
;                 for (int bj = 0; bj < 2; ++bj) { f16x8 v;
; #pragma unroll
;                     for (int n = 0; n < 2; ++n)
; #pragma unroll
;                         for (int i = 0; i < 4; ++i) { float xv = acc[ai][bj][m][n][i] + bv[bj][n][i]; float r;
;                             if (type < 2) { const float sg = sigmoidf_(xv); r = -expm1f(-0.606531f * sg); }
;                             else if (type == 2) r = sigmoidf_(xv);
;                             else r = xv;
;                             v[4 * n + i] = (f16)r; }
;                     *(f16x8*)(rowp + bj * 128) = v; } }
.LBB0_1229:
	v_mul_f32_e32 v2, 0xbfb8aa3b, v10
	v_exp_f32_e32 v2, v2
	s_nop 0
	v_add_f32_e32 v2, 1.0, v2
	v_rcp_f32_e32 v11, v2
	s_nop 0
	v_fma_f32 v13, -v2, v11, 1.0
	v_fma_f32 v10, v13, v11, v11
	v_div_fixup_f32 v2, v10, v2, 1.0
	v_mul_f32_e32 v2, 0xbf1b459e, v2
	v_mul_f32_e32 v10, 0x3fb8aa3b, v2
	v_rndne_f32_e32 v10, v10
	v_fmamk_f32 v11, v10, 0xbf317218, v2
	v_fmac_f32_e32 v11, 0x3102e308, v10
	v_cvt_i32_f32_e32 v12, v10
	v_fmamk_f32 v13, v11, 0x395133b1, v171
	v_fmaak_f32 v13, v11, v13, 0x3c0887f9
	v_fmaak_f32 v13, v11, v13, 0x3d2aaa81
	v_fmaak_f32 v13, v11, v13, 0x3e2aaaab
	v_ldexp_f32 v12, 1.0, v12
	v_fma_f32 v13, v11, v13, 0.5
	v_cmp_eq_f32_e32 vcc, s90, v10
	v_mul_f32_e32 v13, v11, v13
	v_fmac_f32_e32 v11, v11, v13
	v_cndmask_b32_e32 v10, v12, v172, vcc
	v_add_f32_e32 v12, -1.0, v10
	v_fmac_f32_e32 v12, v10, v11
	v_add_f32_e32 v10, v12, v12
	v_cndmask_b32_e32 v10, v12, v10, vcc
	v_cmp_nlt_f32_e32 vcc, s91, v2
	s_nop 1
	v_cndmask_b32_e64 v10, v173, -v10, vcc
	v_cmp_ngt_f32_e32 vcc, s92, v2
	s_nop 1
	v_cndmask_b32_e32 v2, 1.0, v10, vcc
.LBB0_1230:
	v_add_f32_e32 v3, v3, v15
	s_and_b64 vcc, exec, s[8:9]
	s_mov_b64 s[8:9], -1
	s_cbranch_vccnz .LBB0_1234
	s_and_b64 vcc, exec, s[6:7]
	v_mov_b32_e32 v10, v3
	s_cbranch_vccnz .LBB0_1233
	v_mul_f32_e32 v10, 0xbfb8aa3b, v3
	v_exp_f32_e32 v10, v10
	s_nop 0
	v_add_f32_e32 v10, 1.0, v10
	v_rcp_f32_e32 v12, v10
	s_nop 0
	v_fma_f32 v14, -v10, v12, 1.0
	v_fma_f32 v11, v14, v12, v12
	v_div_fixup_f32 v10, v11, v10, 1.0

; __device__ __forceinline__ float sigmoidf_(float x) { return 1.0f / (1.0f + __expf(-x)); }
;     __device__ __forceinline__ void operator()(const f32x4 (&acc)[2][2][4][2], const Unit& u, int wr, int wc, int fr, int fq) const {
;     ...
;                 for (int bj = 0; bj < 2; ++bj) { f16x8 v;
; #pragma unroll
;                     for (int n = 0; n < 2; ++n)
; #pragma unroll
;                         for (int i = 0; i < 4; ++i) { float xv = acc[ai][bj][m][n][i] + bv[bj][n][i]; float r;
;                             if (type < 2) { const float sg = sigmoidf_(xv); r = -expm1f(-0.606531f * sg); }
;                             else if (type == 2) r = sigmoidf_(xv);
;                             else r = xv;
;                             v[4 * n + i] = (f16)r; }
;                     *(f16x8*)(rowp + bj * 128) = v; } }
.LBB0_1235:
	v_mul_f32_e32 v3, 0xbfb8aa3b, v3
	v_exp_f32_e32 v3, v3
	s_nop 0
	v_add_f32_e32 v3, 1.0, v3
	v_rcp_f32_e32 v11, v3
	s_nop 0
	v_fma_f32 v13, -v3, v11, 1.0
	v_fma_f32 v10, v13, v11, v11
	v_div_fixup_f32 v3, v10, v3, 1.0
	v_mul_f32_e32 v3, 0xbf1b459e, v3
	v_mul_f32_e32 v10, 0x3fb8aa3b, v3
	v_rndne_f32_e32 v10, v10
	v_fmamk_f32 v11, v10, 0xbf317218, v3
	v_fmac_f32_e32 v11, 0x3102e308, v10
	v_cvt_i32_f32_e32 v12, v10
	v_fmamk_f32 v13, v11, 0x395133b1, v171
	v_fmaak_f32 v13, v11, v13, 0x3c0887f9
	v_fmaak_f32 v13, v11, v13, 0x3d2aaa81
	v_fmaak_f32 v13, v11, v13, 0x3e2aaaab
	v_ldexp_f32 v12, 1.0, v12
	v_fma_f32 v13, v11, v13, 0.5
	v_cmp_eq_f32_e32 vcc, s90, v10
	v_mul_f32_e32 v13, v11, v13
	v_fmac_f32_e32 v11, v11, v13
	v_cndmask_b32_e32 v10, v12, v172, vcc
	v_add_f32_e32 v12, -1.0, v10
	v_fmac_f32_e32 v12, v10, v11
	v_add_f32_e32 v10, v12, v12
	v_cndmask_b32_e32 v10, v12, v10, vcc
	v_cmp_nlt_f32_e32 vcc, s91, v3
	s_nop 1
	v_cndmask_b32_e64 v10, v173, -v10, vcc
	v_cmp_ngt_f32_e32 vcc, s92, v3
	s_nop 1
	v_cndmask_b32_e32 v10, 1.0, v10, vcc
	s_branch .LBB0_443

; #define PG8_STAGE(bufoff, gbase, voff) do { _Pragma("unroll") for (int _i = 0; _i < 2; ++_i) \
;         __builtin_amdgcn_global_load_lds((const unsigned*)((const char*)(gbase) + (voff)[_i]), (LAS unsigned*)(lds + (bufoff) + ldsw + _i * 8192), 16, 0, 0); } while (0)
; #define PG8_LDA(dst, b, h) do { _Pragma("unroll") for (int m = 0; m < 4; ++m) _Pragma("unroll") for (int k = 0; k < 2; ++k) dst[m][k] = *(const LAS bf16x8*)(lds + PG8_SA(b, h) + aoff + m * 2048 + k * 1024); } while (0)
; #define PG8_LDB(dst, b, h) do { _Pragma("unroll") for (int n = 0; n < 2; ++n) _Pragma("unroll") for (int k = 0; k < 2; ++k) dst[n][k] = *(const LAS bf16x8*)(lds + PG8_SB(b, h) + boff + n * 2048 + k * 1024); } while (0)
; #define PG8_MMA(ai, bj, At, Bt) do { __builtin_amdgcn_s_setprio(1); _Pragma("unroll") for (int m = 0; m < 4; ++m) _Pragma("unroll") for (int n = 0; n < 2; ++n) _Pragma("unroll") for (int k = 0; k < 2; ++k) \
;         acc[ai][bj][m][n] = __builtin_amdgcn_mfma_f32_16x16x32_bf16(Bt[n][k], At[m][k], acc[ai][bj][m][n], 0, 0, 0); __builtin_amdgcn_s_setprio(0); } while (0)
; #define PG8_WAIT_V(n) asm volatile("s_waitcnt vmcnt(" #n ")" ::: "memory")
; #define PG8_WAIT_L(n) asm volatile("s_waitcnt lgkmcnt(" #n ")" ::: "memory")
; #define PG8_BAR __builtin_amdgcn_s_barrier()
; #define PG8_SCHED __builtin_amdgcn_sched_barrier(0)
; template <class Epi>
; __device__ __forceinline__ void gemm_phase(LAS unsigned char* lds, const Gemm g, const StaticOrder& S, const Epi& E) {
;     ...
;             PG8_LDB(B0, 0, 0); PG8_SCHED; PG8_LDA(At, 0, 0); PG8_STAGE(PG8_SA(1, 1), a1 + hstep, voffA);
;             PG8_WAIT_L(8); PG8_BAR; PG8_WAIT_L(0); PG8_MMA(0, 0, At, B0); PG8_BAR; PG8_SCHED;
;             PG8_LDB(B1, 0, 1); PG8_STAGE(PG8_SB(0, 0), b2, voffB);
;             PG8_BAR; PG8_WAIT_L(0); PG8_MMA(0, 1, At, B1); PG8_BAR;
;             PG8_LDA(At, 0, 1); PG8_STAGE(PG8_SA(0, 0), a2, voffA);
;             PG8_BAR; PG8_WAIT_L(0); PG8_MMA(1, 0, At, B0); PG8_BAR; PG8_SCHED;
;             PG8_STAGE(PG8_SB(0, 1), b2 + hstep, voffB);
;             PG8_WAIT_V(6); PG8_BAR; PG8_MMA(1, 1, At, B1); PG8_BAR;
.LBB0_1769:
	ds_read_b128 v[154:157], v147
	ds_read_b128 v[158:161], v147 offset:1024
	ds_read_b128 v[162:165], v147 offset:2048
	ds_read_b128 v[166:169], v147 offset:3072
	s_add_u32 s30, s26, 0xfff80080
	s_addc_u32 s31, s27, -1
	s_cmp_eq_u32 s59, 28
	s_cselect_b32 s35, s13, s31
	s_cselect_b32 s34, s55, s30
	s_cselect_b32 s31, s7, s58
	s_cselect_b32 s30, s56, s57
	v_lshl_add_u64 v[150:151], s[26:27], 0, v[136:137]
	s_add_i32 m0, s21, 0xc000
	ds_read_b128 v[172:175], v148
	ds_read_b128 v[176:179], v148 offset:1024
	ds_read_b128 v[180:183], v148 offset:2048
	ds_read_b128 v[184:187], v148 offset:3072
	ds_read_b128 v[188:191], v148 offset:4096
	ds_read_b128 v[192:195], v148 offset:5120
	ds_read_b128 v[196:199], v148 offset:6144
	ds_read_b128 v[200:203], v148 offset:7168
	global_load_lds_dwordx4 v[150:151], off
	v_lshl_add_u64 v[150:151], s[26:27], 0, v[138:139]
	s_add_i32 m0, s21, 0xe000
	s_nop 0
	global_load_lds_dwordx4 v[150:151], off
	s_waitcnt lgkmcnt(8)
	s_barrier
	s_waitcnt lgkmcnt(0)
	s_setprio 1
	s_waitcnt lgkmcnt(0)
	v_mfma_f32_16x16x32_bf16 v[124:127], v[154:157], v[172:175], v[124:127]
	v_mfma_f32_16x16x32_bf16 v[116:119], v[162:165], v[172:175], v[116:119]
	v_mfma_f32_16x16x32_bf16 v[108:111], v[154:157], v[180:183], v[108:111]
	v_mfma_f32_16x16x32_bf16 v[100:103], v[162:165], v[180:183], v[100:103]
	v_mfma_f32_16x16x32_bf16 v[92:95], v[154:157], v[188:191], v[92:95]
	v_mfma_f32_16x16x32_bf16 v[84:87], v[162:165], v[188:191], v[84:87]
	v_mfma_f32_16x16x32_bf16 v[76:79], v[154:157], v[196:199], v[76:79]
	v_mfma_f32_16x16x32_bf16 v[68:71], v[162:165], v[196:199], v[68:71]
	v_mfma_f32_16x16x32_bf16 v[124:127], v[158:161], v[176:179], v[124:127]
	v_mfma_f32_16x16x32_bf16 v[116:119], v[166:169], v[176:179], v[116:119]
	v_mfma_f32_16x16x32_bf16 v[108:111], v[158:161], v[184:187], v[108:111]
	v_mfma_f32_16x16x32_bf16 v[100:103], v[166:169], v[184:187], v[100:103]
	v_mfma_f32_16x16x32_bf16 v[92:95], v[158:161], v[192:195], v[92:95]
	v_mfma_f32_16x16x32_bf16 v[84:87], v[166:169], v[192:195], v[84:87]
	v_mfma_f32_16x16x32_bf16 v[76:79], v[158:161], v[200:203], v[76:79]
	v_mfma_f32_16x16x32_bf16 v[68:71], v[166:169], v[200:203], v[68:71]
	s_setprio 0
	s_barrier
	s_add_i32 s60, s51, s37
	v_lshl_add_u64 v[150:151], s[30:31], 0, v[132:133]
	s_mov_b32 m0, s60
	ds_read_b128 v[204:207], v149
	ds_read_b128 v[208:211], v149 offset:1024
	ds_read_b128 v[212:215], v149 offset:2048
	ds_read_b128 v[216:219], v149 offset:3072
	global_load_lds_dwordx4 v[150:151], off
	v_lshl_add_u64 v[220:221], s[30:31], 0, v[128:129]
	s_add_i32 m0, s60, 0x2000
	s_nop 0
	global_load_lds_dwordx4 v[220:221], off
	s_barrier
	s_waitcnt lgkmcnt(0)
	s_setprio 1
	s_waitcnt lgkmcnt(0)
	v_mfma_f32_16x16x32_bf16 v[120:123], v[204:207], v[172:175], v[120:123]
	v_mfma_f32_16x16x32_bf16 v[112:115], v[212:215], v[172:175], v[112:115]
	v_mfma_f32_16x16x32_bf16 v[104:107], v[204:207], v[180:183], v[104:107]
	v_mfma_f32_16x16x32_bf16 v[96:99], v[212:215], v[180:183], v[96:99]
	v_mfma_f32_16x16x32_bf16 v[88:91], v[204:207], v[188:191], v[88:91]
	v_mfma_f32_16x16x32_bf16 v[80:83], v[212:215], v[188:191], v[80:83]
	v_mfma_f32_16x16x32_bf16 v[72:75], v[204:207], v[196:199], v[72:75]
	v_mfma_f32_16x16x32_bf16 v[64:67], v[212:215], v[196:199], v[64:67]
	v_mfma_f32_16x16x32_bf16 v[120:123], v[208:211], v[176:179], v[120:123]
	v_mfma_f32_16x16x32_bf16 v[112:115], v[216:219], v[176:179], v[112:115]
	v_mfma_f32_16x16x32_bf16 v[104:107], v[208:211], v[184:187], v[104:107]
	v_mfma_f32_16x16x32_bf16 v[96:99], v[216:219], v[184:187], v[96:99]
	v_mfma_f32_16x16x32_bf16 v[88:91], v[208:211], v[192:195], v[88:91]
	v_mfma_f32_16x16x32_bf16 v[80:83], v[216:219], v[192:195], v[80:83]
	v_mfma_f32_16x16x32_bf16 v[72:75], v[208:211], v[200:203], v[72:75]
	v_mfma_f32_16x16x32_bf16 v[64:67], v[216:219], v[200:203], v[64:67]
	s_setprio 0
	s_mov_b32 m0, s21
	v_lshl_add_u64 v[222:223], s[34:35], 0, v[134:135]
	s_barrier
	ds_read_b128 v[172:175], v148 offset:16384
	ds_read_b128 v[176:179], v148 offset:17408
	ds_read_b128 v[180:183], v148 offset:18432
	ds_read_b128 v[184:187], v148 offset:19456
	ds_read_b128 v[188:191], v148 offset:20480
	ds_read_b128 v[192:195], v148 offset:21504
	ds_read_b128 v[196:199], v148 offset:22528
	ds_read_b128 v[200:203], v148 offset:23552
	global_load_lds_dwordx4 v[222:223], off
	v_lshl_add_u64 v[224:225], s[34:35], 0, v[130:131]
	s_mov_b32 m0, s40
	s_nop 0
	global_load_lds_dwordx4 v[224:225], off
	s_barrier
	s_waitcnt lgkmcnt(0)
	s_setprio 1
	s_waitcnt lgkmcnt(0)
	v_mfma_f32_16x16x32_bf16 v[60:63], v[154:157], v[172:175], v[60:63]
	v_mfma_f32_16x16x32_bf16 v[52:55], v[162:165], v[172:175], v[52:55]
	v_mfma_f32_16x16x32_bf16 v[44:47], v[154:157], v[180:183], v[44:47]
	v_mfma_f32_16x16x32_bf16 v[36:39], v[162:165], v[180:183], v[36:39]
	v_mfma_f32_16x16x32_bf16 v[28:31], v[154:157], v[188:191], v[28:31]
	v_mfma_f32_16x16x32_bf16 v[20:23], v[162:165], v[188:191], v[20:23]
	v_mfma_f32_16x16x32_bf16 v[12:15], v[154:157], v[196:199], v[12:15]
	v_mfma_f32_16x16x32_bf16 v[4:7], v[162:165], v[196:199], v[4:7]
	v_mfma_f32_16x16x32_bf16 v[60:63], v[158:161], v[176:179], v[60:63]
	v_mfma_f32_16x16x32_bf16 v[52:55], v[166:169], v[176:179], v[52:55]
	v_mfma_f32_16x16x32_bf16 v[44:47], v[158:161], v[184:187], v[44:47]
	v_mfma_f32_16x16x32_bf16 v[36:39], v[166:169], v[184:187], v[36:39]
	v_mfma_f32_16x16x32_bf16 v[28:31], v[158:161], v[192:195], v[28:31]
	v_mfma_f32_16x16x32_bf16 v[20:23], v[166:169], v[192:195], v[20:23]
	v_mfma_f32_16x16x32_bf16 v[12:15], v[158:161], v[200:203], v[12:15]
	v_mfma_f32_16x16x32_bf16 v[4:7], v[166:169], v[200:203], v[4:7]
	s_setprio 0
	s_barrier
; #define PG8_STAGE(bufoff, gbase, voff) do { _Pragma("unroll") for (int _i = 0; _i < 2; ++_i) \
;         __builtin_amdgcn_global_load_lds((const unsigned*)((const char*)(gbase) + (voff)[_i]), (LAS unsigned*)(lds + (bufoff) + ldsw + _i * 8192), 16, 0, 0); } while (0)
; #define PG8_LDA(dst, b, h) do { _Pragma("unroll") for (int m = 0; m < 4; ++m) _Pragma("unroll") for (int k = 0; k < 2; ++k) dst[m][k] = *(const LAS bf16x8*)(lds + PG8_SA(b, h) + aoff + m * 2048 + k * 1024); } while (0)
; #define PG8_LDB(dst, b, h) do { _Pragma("unroll") for (int n = 0; n < 2; ++n) _Pragma("unroll") for (int k = 0; k < 2; ++k) dst[n][k] = *(const LAS bf16x8*)(lds + PG8_SB(b, h) + boff + n * 2048 + k * 1024); } while (0)
; #define PG8_MMA(ai, bj, At, Bt) do { __builtin_amdgcn_s_setprio(1); _Pragma("unroll") for (int m = 0; m < 4; ++m) _Pragma("unroll") for (int n = 0; n < 2; ++n) _Pragma("unroll") for (int k = 0; k < 2; ++k) \
;         acc[ai][bj][m][n] = __builtin_amdgcn_mfma_f32_16x16x32_bf16(Bt[n][k], At[m][k], acc[ai][bj][m][n], 0, 0, 0); __builtin_amdgcn_s_setprio(0); } while (0)
; #define PG8_WAIT_V(n) asm volatile("s_waitcnt vmcnt(" #n ")" ::: "memory")
; #define PG8_WAIT_L(n) asm volatile("s_waitcnt lgkmcnt(" #n ")" ::: "memory")
; #define PG8_BAR __builtin_amdgcn_s_barrier()
; #define PG8_SCHED __builtin_amdgcn_sched_barrier(0)
; template <class Epi>
; __device__ __forceinline__ void gemm_phase(LAS unsigned char* lds, const Gemm g, const StaticOrder& S, const Epi& E) {
;     ...
;             PG8_WAIT_V(6); PG8_BAR; PG8_MMA(1, 1, At, B1); PG8_BAR;
;             PG8_LDB(B0, 1, 0); PG8_SCHED; PG8_LDA(At, 1, 0); PG8_STAGE(PG8_SA(0, 1), a2 + hstep, voffA);
;             PG8_WAIT_L(8); PG8_BAR; PG8_WAIT_L(0); PG8_MMA(0, 0, At, B0); PG8_BAR; PG8_SCHED;
;             PG8_LDB(B1, 1, 1); PG8_STAGE(PG8_SB(1, 0), b3, voffB);
;             PG8_BAR; PG8_WAIT_L(0); PG8_MMA(0, 1, At, B1); PG8_BAR;
;             PG8_LDA(At, 1, 1); PG8_STAGE(PG8_SA(1, 0), a3, voffA);
;             PG8_BAR; PG8_WAIT_L(0); PG8_MMA(1, 0, At, B0); PG8_BAR; PG8_SCHED;
	s_add_u32 s60, s30, 0x80000
	s_addc_u32 s61, s31, 0
	s_add_i32 s62, s52, s37
	v_lshl_add_u64 v[154:155], s[60:61], 0, v[132:133]
	s_mov_b32 m0, s62
	s_nop 0
	global_load_lds_dwordx4 v[154:155], off
	v_lshl_add_u64 v[154:155], s[60:61], 0, v[128:129]
	s_add_i32 m0, s62, 0x2000
	s_nop 0
	global_load_lds_dwordx4 v[154:155], off
	s_waitcnt vmcnt(6)
	s_barrier
	s_setprio 1
	v_mfma_f32_16x16x32_bf16 v[56:59], v[204:207], v[172:175], v[56:59]
	v_mfma_f32_16x16x32_bf16 v[48:51], v[212:215], v[172:175], v[48:51]
	v_mfma_f32_16x16x32_bf16 v[40:43], v[204:207], v[180:183], v[40:43]
	v_mfma_f32_16x16x32_bf16 v[32:35], v[212:215], v[180:183], v[32:35]
	v_mfma_f32_16x16x32_bf16 v[24:27], v[204:207], v[188:191], v[24:27]
	v_mfma_f32_16x16x32_bf16 v[16:19], v[212:215], v[188:191], v[16:19]
	v_mfma_f32_16x16x32_bf16 v[8:11], v[204:207], v[196:199], v[8:11]
	v_mfma_f32_16x16x32_bf16 v[0:3], v[212:215], v[196:199], v[0:3]
	v_mfma_f32_16x16x32_bf16 v[56:59], v[208:211], v[176:179], v[56:59]
	v_mfma_f32_16x16x32_bf16 v[48:51], v[216:219], v[176:179], v[48:51]
	v_mfma_f32_16x16x32_bf16 v[40:43], v[208:211], v[184:187], v[40:43]
	v_mfma_f32_16x16x32_bf16 v[32:35], v[216:219], v[184:187], v[32:35]
	v_mfma_f32_16x16x32_bf16 v[24:27], v[208:211], v[192:195], v[24:27]
	v_mfma_f32_16x16x32_bf16 v[16:19], v[216:219], v[192:195], v[16:19]
	v_mfma_f32_16x16x32_bf16 v[8:11], v[208:211], v[200:203], v[8:11]
	v_mfma_f32_16x16x32_bf16 v[0:3], v[216:219], v[200:203], v[0:3]
	s_setprio 0
	s_add_i32 s60, 0, 0x18000
	v_add_u32_e32 v153, s60, v145
	s_barrier
	ds_read_b128 v[154:157], v153
	ds_read_b128 v[158:161], v153 offset:1024
	ds_read_b128 v[162:165], v153 offset:2048
	ds_read_b128 v[166:169], v153 offset:3072
	s_add_u32 s34, s34, 0x80000
	s_addc_u32 s35, s35, 0
	s_mov_b32 m0, s41
	v_lshl_add_u64 v[204:205], s[34:35], 0, v[134:135]
	ds_read_b128 v[172:175], v148 offset:32768
	ds_read_b128 v[176:179], v148 offset:33792
	ds_read_b128 v[180:183], v148 offset:34816
	ds_read_b128 v[184:187], v148 offset:35840
	ds_read_b128 v[188:191], v148 offset:36864
	ds_read_b128 v[192:195], v148 offset:37888
	ds_read_b128 v[196:199], v148 offset:38912
	ds_read_b128 v[200:203], v148 offset:39936
	global_load_lds_dwordx4 v[204:205], off
	v_lshl_add_u64 v[204:205], s[34:35], 0, v[130:131]
	s_mov_b32 m0, s42
	s_nop 0
	global_load_lds_dwordx4 v[204:205], off
	s_waitcnt lgkmcnt(8)
	s_barrier
	s_waitcnt lgkmcnt(0)
	s_setprio 1
	s_waitcnt lgkmcnt(0)
	v_mfma_f32_16x16x32_bf16 v[124:127], v[154:157], v[172:175], v[124:127]
	v_mfma_f32_16x16x32_bf16 v[116:119], v[162:165], v[172:175], v[116:119]
	v_mfma_f32_16x16x32_bf16 v[108:111], v[154:157], v[180:183], v[108:111]
	v_mfma_f32_16x16x32_bf16 v[100:103], v[162:165], v[180:183], v[100:103]
	v_mfma_f32_16x16x32_bf16 v[92:95], v[154:157], v[188:191], v[92:95]
	v_mfma_f32_16x16x32_bf16 v[84:87], v[162:165], v[188:191], v[84:87]
	v_mfma_f32_16x16x32_bf16 v[76:79], v[154:157], v[196:199], v[76:79]
	v_mfma_f32_16x16x32_bf16 v[68:71], v[162:165], v[196:199], v[68:71]
	v_mfma_f32_16x16x32_bf16 v[124:127], v[158:161], v[176:179], v[124:127]
	v_mfma_f32_16x16x32_bf16 v[116:119], v[166:169], v[176:179], v[116:119]
	v_mfma_f32_16x16x32_bf16 v[108:111], v[158:161], v[184:187], v[108:111]
	v_mfma_f32_16x16x32_bf16 v[100:103], v[166:169], v[184:187], v[100:103]
	v_mfma_f32_16x16x32_bf16 v[92:95], v[158:161], v[192:195], v[92:95]
	v_mfma_f32_16x16x32_bf16 v[84:87], v[166:169], v[192:195], v[84:87]
	v_mfma_f32_16x16x32_bf16 v[76:79], v[158:161], v[200:203], v[76:79]
	v_mfma_f32_16x16x32_bf16 v[68:71], v[166:169], v[200:203], v[68:71]
	s_setprio 0
	s_barrier
	s_add_i32 s34, 0, 0x1c000
	s_add_i32 s35, s60, s37
	v_add_u32_e32 v153, s34, v145
	v_lshl_add_u64 v[150:151], v[150:151], 0, s[0:1]
	s_mov_b32 m0, s35
	ds_read_b128 v[204:207], v153
	ds_read_b128 v[208:211], v153 offset:1024
	ds_read_b128 v[212:215], v153 offset:2048
	ds_read_b128 v[216:219], v153 offset:3072
	global_load_lds_dwordx4 v[150:151], off
	v_lshl_add_u64 v[150:151], v[220:221], 0, s[0:1]
	s_add_i32 m0, s35, 0x2000
	s_nop 0
	global_load_lds_dwordx4 v[150:151], off
	s_barrier
	s_waitcnt lgkmcnt(0)
	s_setprio 1
	s_waitcnt lgkmcnt(0)
	v_mfma_f32_16x16x32_bf16 v[120:123], v[204:207], v[172:175], v[120:123]
	v_mfma_f32_16x16x32_bf16 v[112:115], v[212:215], v[172:175], v[112:115]
	v_mfma_f32_16x16x32_bf16 v[104:107], v[204:207], v[180:183], v[104:107]
	v_mfma_f32_16x16x32_bf16 v[96:99], v[212:215], v[180:183], v[96:99]
	v_mfma_f32_16x16x32_bf16 v[88:91], v[204:207], v[188:191], v[88:91]
	v_mfma_f32_16x16x32_bf16 v[80:83], v[212:215], v[188:191], v[80:83]
	v_mfma_f32_16x16x32_bf16 v[72:75], v[204:207], v[196:199], v[72:75]
	v_mfma_f32_16x16x32_bf16 v[64:67], v[212:215], v[196:199], v[64:67]
	v_mfma_f32_16x16x32_bf16 v[120:123], v[208:211], v[176:179], v[120:123]
	v_mfma_f32_16x16x32_bf16 v[112:115], v[216:219], v[176:179], v[112:115]
	v_mfma_f32_16x16x32_bf16 v[104:107], v[208:211], v[184:187], v[104:107]
	v_mfma_f32_16x16x32_bf16 v[96:99], v[216:219], v[184:187], v[96:99]
	v_mfma_f32_16x16x32_bf16 v[88:91], v[208:211], v[192:195], v[88:91]
	v_mfma_f32_16x16x32_bf16 v[80:83], v[216:219], v[192:195], v[80:83]
	v_mfma_f32_16x16x32_bf16 v[72:75], v[208:211], v[200:203], v[72:75]
	v_mfma_f32_16x16x32_bf16 v[64:67], v[216:219], v[200:203], v[64:67]
	s_setprio 0
	s_mov_b32 m0, s48
	v_lshl_add_u64 v[150:151], v[222:223], 0, s[0:1]
	s_barrier
	ds_read_b128 v[172:175], v148 offset:49152
	ds_read_b128 v[176:179], v148 offset:50176
	ds_read_b128 v[180:183], v148 offset:51200
	ds_read_b128 v[184:187], v148 offset:52224
	ds_read_b128 v[188:191], v148 offset:53248
	ds_read_b128 v[192:195], v148 offset:54272
	ds_read_b128 v[196:199], v148 offset:55296
	ds_read_b128 v[200:203], v148 offset:56320
	global_load_lds_dwordx4 v[150:151], off
	v_lshl_add_u64 v[150:151], v[224:225], 0, s[0:1]
	s_mov_b32 m0, s49
	s_nop 0
	global_load_lds_dwordx4 v[150:151], off
	s_barrier
; __device__ __forceinline__ unsigned cvt_pk_bf16(float lo, float hi) { unsigned r; asm volatile("v_cvt_pk_bf16_f32 %0, %1, %2" : "=v"(r) : "v"(lo), "v"(hi)); return r; }
; __device__ __forceinline__ float sigmoidf_(float x) { return 1.0f / (1.0f + __expf(-x)); }
; #define PG8_STAGE(bufoff, gbase, voff) do { _Pragma("unroll") for (int _i = 0; _i < 2; ++_i) \
;         __builtin_amdgcn_global_load_lds((const unsigned*)((const char*)(gbase) + (voff)[_i]), (LAS unsigned*)(lds + (bufoff) + ldsw + _i * 8192), 16, 0, 0); } while (0)
; #define PG8_MMA(ai, bj, At, Bt) do { __builtin_amdgcn_s_setprio(1); _Pragma("unroll") for (int m = 0; m < 4; ++m) _Pragma("unroll") for (int n = 0; n < 2; ++n) _Pragma("unroll") for (int k = 0; k < 2; ++k) \
;         acc[ai][bj][m][n] = __builtin_amdgcn_mfma_f32_16x16x32_bf16(Bt[n][k], At[m][k], acc[ai][bj][m][n], 0, 0, 0); __builtin_amdgcn_s_setprio(0); } while (0)
; #define PG8_WAIT_V(n) asm volatile("s_waitcnt vmcnt(" #n ")" ::: "memory")
; #define PG8_WAIT_L(n) asm volatile("s_waitcnt lgkmcnt(" #n ")" ::: "memory")
; #define PG8_BAR __builtin_amdgcn_s_barrier()
; #define PG8_SCHED __builtin_amdgcn_sched_barrier(0)
; template <class Epi>
; __device__ __forceinline__ void gemm_phase(LAS unsigned char* lds, const Gemm g, const StaticOrder& S, const Epi& E) {
;     ...
;             PG8_BAR; PG8_WAIT_L(0); PG8_MMA(1, 0, At, B0); PG8_BAR; PG8_SCHED;
;             PG8_STAGE(PG8_SB(1, 1), b3 + hstep, voffB);
;             PG8_WAIT_V(6); PG8_BAR; PG8_MMA(1, 1, At, B1); PG8_BAR;
;         }
;     __device__ __forceinline__ void operator()(const f32x4 (&acc)[2][2][4][2], const Unit& u, int wr, int wc, int fr, int fq) const {
;     ...
;             for (int m = 0; m < 4; ++m) { float hv[8];
; #pragma unroll
;                 for (int n = 0; n < 2; ++n)
; #pragma unroll
;                     for (int i = 0; i < 4; ++i) { const float gt = acc[ai][0][m][n][i], up = acc[ai][1][m][n][i]; hv[4 * n + i] = gt * sigmoidf_(gt) * up; }
;                 u32x4 o; o[0] = cvt_pk_bf16(hv[0], hv[1]); o[1] = cvt_pk_bf16(hv[2], hv[3]); o[2] = cvt_pk_bf16(hv[4], hv[5]); o[3] = cvt_pk_bf16(hv[6], hv[7]);
;                 *(u32x4*)(O + (size_t)(row0 + ai * 128 + m * 16) * 5632 + col0) = o; }
	s_waitcnt lgkmcnt(0)
	s_setprio 1
	s_waitcnt lgkmcnt(0)
	v_mfma_f32_16x16x32_bf16 v[60:63], v[154:157], v[172:175], v[60:63]
	v_mfma_f32_16x16x32_bf16 v[52:55], v[162:165], v[172:175], v[52:55]
	v_mfma_f32_16x16x32_bf16 v[44:47], v[154:157], v[180:183], v[44:47]
	v_mfma_f32_16x16x32_bf16 v[36:39], v[162:165], v[180:183], v[36:39]
	v_mfma_f32_16x16x32_bf16 v[28:31], v[154:157], v[188:191], v[28:31]
	v_mfma_f32_16x16x32_bf16 v[20:23], v[162:165], v[188:191], v[20:23]
	v_mfma_f32_16x16x32_bf16 v[12:15], v[154:157], v[196:199], v[12:15]
	v_mfma_f32_16x16x32_bf16 v[4:7], v[162:165], v[196:199], v[4:7]
	v_mfma_f32_16x16x32_bf16 v[60:63], v[158:161], v[176:179], v[60:63]
	v_mfma_f32_16x16x32_bf16 v[52:55], v[166:169], v[176:179], v[52:55]
	v_mfma_f32_16x16x32_bf16 v[44:47], v[158:161], v[184:187], v[44:47]
	v_mfma_f32_16x16x32_bf16 v[36:39], v[166:169], v[184:187], v[36:39]
	v_mfma_f32_16x16x32_bf16 v[28:31], v[158:161], v[192:195], v[28:31]
	v_mfma_f32_16x16x32_bf16 v[20:23], v[166:169], v[192:195], v[20:23]
	v_mfma_f32_16x16x32_bf16 v[12:15], v[158:161], v[200:203], v[12:15]
	v_mfma_f32_16x16x32_bf16 v[4:7], v[166:169], v[200:203], v[4:7]
	s_setprio 0
	s_barrier
	s_add_u32 s30, s30, 0x80080
	s_addc_u32 s31, s31, 0
	s_add_i32 s34, s34, s37
	v_lshl_add_u64 v[150:151], s[30:31], 0, v[132:133]
	s_mov_b32 m0, s34
	s_nop 0
	global_load_lds_dwordx4 v[150:151], off
	v_lshl_add_u64 v[150:151], s[30:31], 0, v[128:129]
	s_add_i32 m0, s34, 0x2000
	s_nop 0
	global_load_lds_dwordx4 v[150:151], off
	s_waitcnt vmcnt(6)
	s_barrier
	s_setprio 1
	v_mfma_f32_16x16x32_bf16 v[56:59], v[204:207], v[172:175], v[56:59]
	v_mfma_f32_16x16x32_bf16 v[48:51], v[212:215], v[172:175], v[48:51]
	v_mfma_f32_16x16x32_bf16 v[40:43], v[204:207], v[180:183], v[40:43]
	v_mfma_f32_16x16x32_bf16 v[32:35], v[212:215], v[180:183], v[32:35]
	v_mfma_f32_16x16x32_bf16 v[24:27], v[204:207], v[188:191], v[24:27]
	v_mfma_f32_16x16x32_bf16 v[16:19], v[212:215], v[188:191], v[16:19]
	v_mfma_f32_16x16x32_bf16 v[8:11], v[204:207], v[196:199], v[8:11]
	v_mfma_f32_16x16x32_bf16 v[0:3], v[212:215], v[196:199], v[0:3]
	v_mfma_f32_16x16x32_bf16 v[56:59], v[208:211], v[176:179], v[56:59]
	v_mfma_f32_16x16x32_bf16 v[48:51], v[216:219], v[176:179], v[48:51]
	v_mfma_f32_16x16x32_bf16 v[40:43], v[208:211], v[184:187], v[40:43]
	v_mfma_f32_16x16x32_bf16 v[32:35], v[216:219], v[184:187], v[32:35]
	v_mfma_f32_16x16x32_bf16 v[24:27], v[208:211], v[192:195], v[24:27]
	v_mfma_f32_16x16x32_bf16 v[16:19], v[216:219], v[192:195], v[16:19]
	v_mfma_f32_16x16x32_bf16 v[8:11], v[208:211], v[200:203], v[8:11]
	v_mfma_f32_16x16x32_bf16 v[0:3], v[216:219], v[200:203], v[0:3]
	s_setprio 0
	s_add_i32 s59, s59, 2
	s_add_u32 s26, s26, 0x100
	s_addc_u32 s27, s27, 0
	s_add_u32 s57, s57, 0x100
	s_addc_u32 s58, s58, 0
	s_cmp_gt_u32 s59, 29
	s_barrier
	s_cbranch_scc0 .LBB0_1769
	v_mul_f32_e32 v150, 0xbfb8aa3b, v124
	v_exp_f32_e32 v151, v150
	v_lshl_or_b32 v154, s54, 7, v146
	v_lshl_add_u32 v150, s20, 8, v144
	v_ashrrev_i32_e32 v155, 31, v154
	v_add_f32_e32 v151, 1.0, v151
	v_rcp_f32_e32 v156, v151
	s_mov_b32 s54, s6
	v_mul_f32_e32 v159, 0xbfb8aa3b, v125
	v_exp_f32_e32 v159, v159
	v_fma_f32 v158, -v151, v156, 1.0
	v_fma_f32 v153, v158, v156, v156
	v_div_fixup_f32 v151, v153, v151, 1.0
	v_add_f32_e32 v156, 1.0, v159
	v_rcp_f32_e32 v158, v156
	v_mul_f32_e32 v124, v124, v151
	v_mul_f32_e32 v120, v124, v120
	s_mov_b32 s20, s12
	v_mul_f32_e32 v153, 0xbfb8aa3b, v126
	v_exp_f32_e32 v153, v153
	v_fma_f32 v151, -v156, v158, 1.0
	v_fma_f32 v124, v151, v158, v158
	v_div_fixup_f32 v124, v124, v156, 1.0
	v_add_f32_e32 v151, 1.0, v153
	v_rcp_f32_e32 v157, v151
	v_mul_f32_e32 v124, v125, v124
	v_mul_f32_e32 v121, v124, v121
	s_mov_b64 s[30:31], s[16:17]
	v_mul_f32_e32 v156, 0xbfb8aa3b, v127
	v_exp_f32_e32 v156, v156
	v_fma_f32 v125, -v151, v157, 1.0
	v_fma_f32 v124, v125, v157, v157
	v_div_fixup_f32 v124, v124, v151, 1.0
	v_add_f32_e32 v125, 1.0, v156
	v_rcp_f32_e32 v156, v125
	v_mul_f32_e32 v124, v126, v124
	v_mul_f32_e32 v122, v124, v122
	v_mul_f32_e32 v151, 0xbfb8aa3b, v116
	v_exp_f32_e32 v151, v151
	v_fma_f32 v126, -v125, v156, 1.0
	v_fma_f32 v124, v126, v156, v156
	v_div_fixup_f32 v124, v124, v125, 1.0
	v_add_f32_e32 v126, 1.0, v151
	v_rcp_f32_e32 v153, v126
	v_mul_f32_e32 v124, v127, v124
	v_mul_f32_e32 v123, v124, v123
	v_mul_f32_e32 v127, 0xbfb8aa3b, v117
	v_exp_f32_e32 v127, v127
	v_fma_f32 v125, -v126, v153, 1.0
	v_fma_f32 v124, v125, v153, v153
	v_div_fixup_f32 v124, v124, v126, 1.0
	v_add_f32_e32 v125, 1.0, v127
	v_rcp_f32_e32 v151, v125
	v_mul_f32_e32 v116, v116, v124
	v_mul_f32_e32 v112, v116, v112
	v_mul_f32_e32 v126, 0xbfb8aa3b, v118
	v_exp_f32_e32 v126, v126
	v_fma_f32 v124, -v125, v151, 1.0
	v_fma_f32 v116, v124, v151, v151
	v_div_fixup_f32 v116, v116, v125, 1.0
	v_add_f32_e32 v124, 1.0, v126
	v_rcp_f32_e32 v127, v124
	v_mul_f32_e32 v116, v117, v116
	v_mul_f32_e32 v113, v116, v113
	v_mul_f32_e32 v125, 0xbfb8aa3b, v119
	v_exp_f32_e32 v125, v125
	v_fma_f32 v117, -v124, v127, 1.0
	v_fma_f32 v116, v117, v127, v127
	v_div_fixup_f32 v116, v116, v124, 1.0
	v_add_f32_e32 v117, 1.0, v125
	v_rcp_f32_e32 v126, v117
	v_mul_f32_e32 v116, v118, v116
	v_mul_f32_e32 v114, v116, v114
	v_fma_f32 v118, -v117, v126, 1.0
	v_fma_f32 v116, v118, v126, v126
	v_div_fixup_f32 v116, v116, v117, 1.0
	v_mul_f32_e32 v116, v119, v116
	v_mul_f32_e32 v115, v116, v115
	v_cvt_pk_bf16_f32 v116, v120, v121
	v_cvt_pk_bf16_f32 v117, v122, v123
	v_cvt_pk_bf16_f32 v118, v112, v113
	v_mul_f32_e32 v112, 0xbfb8aa3b, v108
	v_cvt_pk_bf16_f32 v119, v114, v115
	v_exp_f32_e32 v114, v112
	v_mov_b64_e32 v[112:113], s[96:97]
	v_mad_i64_i32 v[120:121], s[26:27], v150, s53, v[112:113]
; __device__ __forceinline__ unsigned cvt_pk_bf16(float lo, float hi) { unsigned r; asm volatile("v_cvt_pk_bf16_f32 %0, %1, %2" : "=v"(r) : "v"(lo), "v"(hi)); return r; }
; __device__ __forceinline__ float sigmoidf_(float x) { return 1.0f / (1.0f + __expf(-x)); }
;     __device__ __forceinline__ void operator()(const f32x4 (&acc)[2][2][4][2], const Unit& u, int wr, int wc, int fr, int fq) const {
;     ...
;             for (int m = 0; m < 4; ++m) { float hv[8];
; #pragma unroll
;                 for (int n = 0; n < 2; ++n)
; #pragma unroll
;                     for (int i = 0; i < 4; ++i) { const float gt = acc[ai][0][m][n][i], up = acc[ai][1][m][n][i]; hv[4 * n + i] = gt * sigmoidf_(gt) * up; }
;                 u32x4 o; o[0] = cvt_pk_bf16(hv[0], hv[1]); o[1] = cvt_pk_bf16(hv[2], hv[3]); o[2] = cvt_pk_bf16(hv[4], hv[5]); o[3] = cvt_pk_bf16(hv[6], hv[7]);
;                 *(u32x4*)(O + (size_t)(row0 + ai * 128 + m * 16) * 5632 + col0) = o; }
	v_add_f32_e32 v122, 1.0, v114
	v_rcp_f32_e32 v124, v122
	v_lshlrev_b64 v[114:115], 1, v[154:155]
	v_lshl_add_u64 v[120:121], v[120:121], 0, v[114:115]
	global_store_dwordx4 v[120:121], v[116:119], off
	s_nop 1
	v_mul_f32_e32 v118, 0xbfb8aa3b, v109
	v_exp_f32_e32 v118, v118
	v_fma_f32 v117, -v122, v124, 1.0
	v_fma_f32 v116, v117, v124, v124
	v_div_fixup_f32 v116, v116, v122, 1.0
	v_add_f32_e32 v117, 1.0, v118
	v_rcp_f32_e32 v119, v117
	v_mul_f32_e32 v108, v108, v116
	v_mul_f32_e32 v104, v108, v104
	v_mul_f32_e32 v120, 0xbfb8aa3b, v110
	v_exp_f32_e32 v120, v120
	v_fma_f32 v116, -v117, v119, 1.0
	v_fma_f32 v108, v116, v119, v119
	v_div_fixup_f32 v108, v108, v117, 1.0
	v_add_f32_e32 v116, 1.0, v120
	v_rcp_f32_e32 v119, v116
	v_mul_f32_e32 v108, v109, v108
	v_mul_f32_e32 v105, v108, v105
	v_mul_f32_e32 v117, 0xbfb8aa3b, v111
	v_exp_f32_e32 v117, v117
	v_fma_f32 v109, -v116, v119, 1.0
	v_fma_f32 v108, v109, v119, v119
	v_div_fixup_f32 v108, v108, v116, 1.0
	v_add_f32_e32 v109, 1.0, v117
	v_rcp_f32_e32 v118, v109
	v_mul_f32_e32 v108, v110, v108
	v_mul_f32_e32 v106, v108, v106
	v_mul_f32_e32 v116, 0xbfb8aa3b, v100
	v_exp_f32_e32 v116, v116
	v_fma_f32 v110, -v109, v118, 1.0
	v_fma_f32 v108, v110, v118, v118
	v_div_fixup_f32 v108, v108, v109, 1.0
	v_add_f32_e32 v110, 1.0, v116
	v_rcp_f32_e32 v117, v110
	v_mul_f32_e32 v108, v111, v108
	v_mul_f32_e32 v107, v108, v107
	v_mul_f32_e32 v111, 0xbfb8aa3b, v101
	v_exp_f32_e32 v111, v111
	v_fma_f32 v109, -v110, v117, 1.0
	v_fma_f32 v108, v109, v117, v117
	v_div_fixup_f32 v108, v108, v110, 1.0
	v_add_f32_e32 v109, 1.0, v111
	v_rcp_f32_e32 v116, v109
	v_mul_f32_e32 v100, v100, v108
	v_mul_f32_e32 v100, v100, v96
	v_mul_f32_e32 v110, 0xbfb8aa3b, v102
	v_exp_f32_e32 v110, v110
	v_fma_f32 v108, -v109, v116, 1.0
	v_fma_f32 v96, v108, v116, v116
	v_div_fixup_f32 v96, v96, v109, 1.0
	v_add_f32_e32 v108, 1.0, v110
	v_rcp_f32_e32 v111, v108
	v_mul_f32_e32 v96, v101, v96
	v_mul_f32_e32 v101, v96, v97
	v_mul_f32_e32 v109, 0xbfb8aa3b, v103
	v_exp_f32_e32 v109, v109
	v_fma_f32 v97, -v108, v111, 1.0
	v_fma_f32 v96, v97, v111, v111
	v_div_fixup_f32 v96, v96, v108, 1.0
	v_add_f32_e32 v97, 1.0, v109
	v_rcp_f32_e32 v110, v97
	v_mul_f32_e32 v96, v102, v96
	v_mul_f32_e32 v102, v96, v98
	v_fma_f32 v98, -v97, v110, 1.0
	v_fma_f32 v96, v98, v110, v110
	v_div_fixup_f32 v96, v96, v97, 1.0
	v_mul_f32_e32 v98, 0xbfb8aa3b, v92
	v_mul_f32_e32 v96, v103, v96
	v_exp_f32_e32 v103, v98
	v_mul_f32_e32 v99, v96, v99
	v_cvt_pk_bf16_f32 v96, v104, v105
	v_cvt_pk_bf16_f32 v97, v106, v107
	v_cvt_pk_bf16_f32 v98, v100, v101
	v_cvt_pk_bf16_f32 v99, v102, v99
	v_add_f32_e32 v102, 1.0, v103
	v_rcp_f32_e32 v104, v102
	v_or_b32_e32 v100, 16, v150
	v_mad_i64_i32 v[100:101], s[26:27], v100, s53, v[112:113]
	v_lshl_add_u64 v[100:101], v[100:101], 0, v[114:115]
	global_store_dwordx4 v[100:101], v[96:99], off
	s_nop 1
	v_mul_f32_e32 v98, 0xbfb8aa3b, v93
	v_exp_f32_e32 v98, v98
	v_fma_f32 v97, -v102, v104, 1.0
	v_fma_f32 v96, v97, v104, v104
	v_div_fixup_f32 v96, v96, v102, 1.0
	v_add_f32_e32 v97, 1.0, v98
	v_rcp_f32_e32 v99, v97
	v_mul_f32_e32 v92, v92, v96
	v_mul_f32_e32 v88, v92, v88
	v_mul_f32_e32 v100, 0xbfb8aa3b, v94
	v_exp_f32_e32 v100, v100
	v_fma_f32 v96, -v97, v99, 1.0
	v_fma_f32 v92, v96, v99, v99
	v_div_fixup_f32 v92, v92, v97, 1.0
	v_add_f32_e32 v96, 1.0, v100
	v_rcp_f32_e32 v99, v96
	v_mul_f32_e32 v92, v93, v92
	v_mul_f32_e32 v89, v92, v89
	v_mul_f32_e32 v97, 0xbfb8aa3b, v95
	v_exp_f32_e32 v97, v97
	v_fma_f32 v93, -v96, v99, 1.0
	v_fma_f32 v92, v93, v99, v99
	v_div_fixup_f32 v92, v92, v96, 1.0
	v_add_f32_e32 v93, 1.0, v97
	v_rcp_f32_e32 v98, v93
	v_mul_f32_e32 v92, v94, v92
	v_mul_f32_e32 v90, v92, v90
	v_mul_f32_e32 v96, 0xbfb8aa3b, v84
	v_exp_f32_e32 v96, v96
	v_fma_f32 v94, -v93, v98, 1.0
	v_fma_f32 v92, v94, v98, v98
	v_div_fixup_f32 v92, v92, v93, 1.0
	v_add_f32_e32 v94, 1.0, v96
	v_rcp_f32_e32 v97, v94
	v_mul_f32_e32 v92, v95, v92
	v_mul_f32_e32 v91, v92, v91
	v_mul_f32_e32 v95, 0xbfb8aa3b, v85
	v_exp_f32_e32 v95, v95
	v_fma_f32 v93, -v94, v97, 1.0
	v_fma_f32 v92, v93, v97, v97
	v_div_fixup_f32 v92, v92, v94, 1.0
	v_add_f32_e32 v93, 1.0, v95
	v_rcp_f32_e32 v96, v93
	v_mul_f32_e32 v84, v84, v92
	v_mul_f32_e32 v84, v84, v80
	v_mul_f32_e32 v94, 0xbfb8aa3b, v86
	v_exp_f32_e32 v94, v94
	v_fma_f32 v92, -v93, v96, 1.0
	v_fma_f32 v80, v92, v96, v96
	v_div_fixup_f32 v80, v80, v93, 1.0
	v_add_f32_e32 v92, 1.0, v94
	v_rcp_f32_e32 v95, v92
	v_mul_f32_e32 v80, v85, v80
	v_mul_f32_e32 v85, v80, v81
	v_mul_f32_e32 v93, 0xbfb8aa3b, v87
	v_exp_f32_e32 v93, v93
	v_fma_f32 v81, -v92, v95, 1.0
	v_fma_f32 v80, v81, v95, v95
	v_div_fixup_f32 v80, v80, v92, 1.0
	v_add_f32_e32 v81, 1.0, v93
	v_rcp_f32_e32 v94, v81
	v_mul_f32_e32 v80, v86, v80
	v_mul_f32_e32 v86, v80, v82
	v_fma_f32 v82, -v81, v94, 1.0
	v_fma_f32 v80, v82, v94, v94
	v_div_fixup_f32 v80, v80, v81, 1.0
	v_mul_f32_e32 v82, 0xbfb8aa3b, v76
	v_mul_f32_e32 v80, v87, v80
	v_exp_f32_e32 v87, v82
	v_mul_f32_e32 v83, v80, v83
	v_cvt_pk_bf16_f32 v80, v88, v89
	v_cvt_pk_bf16_f32 v81, v90, v91
	v_cvt_pk_bf16_f32 v82, v84, v85
	v_cvt_pk_bf16_f32 v83, v86, v83
	v_add_f32_e32 v86, 1.0, v87
	v_rcp_f32_e32 v88, v86
	v_or_b32_e32 v84, 32, v150
	v_mad_i64_i32 v[84:85], s[26:27], v84, s53, v[112:113]
	v_lshl_add_u64 v[84:85], v[84:85], 0, v[114:115]
	global_store_dwordx4 v[84:85], v[80:83], off
	s_nop 1
	v_mul_f32_e32 v82, 0xbfb8aa3b, v77
	v_exp_f32_e32 v82, v82
	v_fma_f32 v81, -v86, v88, 1.0
	v_fma_f32 v80, v81, v88, v88
	v_div_fixup_f32 v80, v80, v86, 1.0
	v_add_f32_e32 v81, 1.0, v82
	v_rcp_f32_e32 v83, v81
	v_mul_f32_e32 v76, v76, v80
	v_mul_f32_e32 v72, v76, v72
	v_mul_f32_e32 v84, 0xbfb8aa3b, v78
; __device__ __forceinline__ unsigned cvt_pk_bf16(float lo, float hi) { unsigned r; asm volatile("v_cvt_pk_bf16_f32 %0, %1, %2" : "=v"(r) : "v"(lo), "v"(hi)); return r; }
; __device__ __forceinline__ float sigmoidf_(float x) { return 1.0f / (1.0f + __expf(-x)); }
;     __device__ __forceinline__ void operator()(const f32x4 (&acc)[2][2][4][2], const Unit& u, int wr, int wc, int fr, int fq) const {
;     ...
;             for (int m = 0; m < 4; ++m) { float hv[8];
; #pragma unroll
;                 for (int n = 0; n < 2; ++n)
; #pragma unroll
;                     for (int i = 0; i < 4; ++i) { const float gt = acc[ai][0][m][n][i], up = acc[ai][1][m][n][i]; hv[4 * n + i] = gt * sigmoidf_(gt) * up; }
;                 u32x4 o; o[0] = cvt_pk_bf16(hv[0], hv[1]); o[1] = cvt_pk_bf16(hv[2], hv[3]); o[2] = cvt_pk_bf16(hv[4], hv[5]); o[3] = cvt_pk_bf16(hv[6], hv[7]);
;                 *(u32x4*)(O + (size_t)(row0 + ai * 128 + m * 16) * 5632 + col0) = o; }
	v_exp_f32_e32 v84, v84
	v_fma_f32 v80, -v81, v83, 1.0
	v_fma_f32 v76, v80, v83, v83
	v_div_fixup_f32 v76, v76, v81, 1.0
	v_add_f32_e32 v80, 1.0, v84
	v_rcp_f32_e32 v83, v80
	v_mul_f32_e32 v76, v77, v76
	v_mul_f32_e32 v73, v76, v73
	v_mul_f32_e32 v81, 0xbfb8aa3b, v79
	v_exp_f32_e32 v81, v81
	v_fma_f32 v77, -v80, v83, 1.0
	v_fma_f32 v76, v77, v83, v83
	v_div_fixup_f32 v76, v76, v80, 1.0
	v_add_f32_e32 v77, 1.0, v81
	v_rcp_f32_e32 v82, v77
	v_mul_f32_e32 v76, v78, v76
	v_mul_f32_e32 v74, v76, v74
	v_mul_f32_e32 v80, 0xbfb8aa3b, v68
	v_exp_f32_e32 v80, v80
	v_fma_f32 v78, -v77, v82, 1.0
	v_fma_f32 v76, v78, v82, v82
	v_div_fixup_f32 v76, v76, v77, 1.0
	v_add_f32_e32 v78, 1.0, v80
	v_rcp_f32_e32 v81, v78
	v_mul_f32_e32 v76, v79, v76
	v_mul_f32_e32 v75, v76, v75
	v_mul_f32_e32 v79, 0xbfb8aa3b, v69
	v_exp_f32_e32 v79, v79
	v_fma_f32 v77, -v78, v81, 1.0
	v_fma_f32 v76, v77, v81, v81
	v_div_fixup_f32 v76, v76, v78, 1.0
	v_add_f32_e32 v77, 1.0, v79
	v_rcp_f32_e32 v80, v77
	v_mul_f32_e32 v68, v68, v76
	v_mul_f32_e32 v68, v68, v64
	v_mul_f32_e32 v78, 0xbfb8aa3b, v70
	v_exp_f32_e32 v78, v78
	v_fma_f32 v76, -v77, v80, 1.0
	v_fma_f32 v64, v76, v80, v80
	v_div_fixup_f32 v64, v64, v77, 1.0
	v_add_f32_e32 v76, 1.0, v78
	v_rcp_f32_e32 v79, v76
	v_mul_f32_e32 v64, v69, v64
	v_mul_f32_e32 v69, v64, v65
	v_mul_f32_e32 v77, 0xbfb8aa3b, v71
	v_exp_f32_e32 v77, v77
	v_fma_f32 v65, -v76, v79, 1.0
	v_fma_f32 v64, v65, v79, v79
	v_div_fixup_f32 v64, v64, v76, 1.0
	v_add_f32_e32 v65, 1.0, v77
	v_rcp_f32_e32 v78, v65
	v_mul_f32_e32 v64, v70, v64
	v_mul_f32_e32 v70, v64, v66
	v_fma_f32 v66, -v65, v78, 1.0
	v_fma_f32 v64, v66, v78, v78
	v_div_fixup_f32 v64, v64, v65, 1.0
	v_mul_f32_e32 v64, v71, v64
	v_mul_f32_e32 v67, v64, v67
	v_cvt_pk_bf16_f32 v64, v72, v73
	v_cvt_pk_bf16_f32 v65, v74, v75
	v_cvt_pk_bf16_f32 v66, v68, v69
	v_mul_f32_e32 v68, 0xbfb8aa3b, v60
	v_cvt_pk_bf16_f32 v67, v70, v67
	v_exp_f32_e32 v70, v68
	v_or_b32_e32 v68, 48, v150
	v_mad_i64_i32 v[68:69], s[26:27], v68, s53, v[112:113]
	v_add_f32_e32 v70, 1.0, v70
	v_rcp_f32_e32 v72, v70
	v_lshl_add_u64 v[68:69], v[68:69], 0, v[114:115]
	global_store_dwordx4 v[68:69], v[64:67], off
	s_nop 1
	v_mul_f32_e32 v67, 0xbfb8aa3b, v61
	v_exp_f32_e32 v67, v67
	v_fma_f32 v66, -v70, v72, 1.0
	v_fma_f32 v65, v66, v72, v72
	v_div_fixup_f32 v65, v65, v70, 1.0
	v_add_f32_e32 v66, 1.0, v67
	v_rcp_f32_e32 v68, v66
	v_mul_f32_e32 v60, v60, v65
	v_mul_f32_e32 v56, v60, v56
	v_add_u32_e32 v64, 0x80, v150
	v_mul_f32_e32 v69, 0xbfb8aa3b, v62
	v_exp_f32_e32 v69, v69
	v_fma_f32 v65, -v66, v68, 1.0
	v_fma_f32 v60, v65, v68, v68
	v_div_fixup_f32 v60, v60, v66, 1.0
	v_add_f32_e32 v65, 1.0, v69
	v_rcp_f32_e32 v68, v65
	v_mul_f32_e32 v60, v61, v60
	v_mul_f32_e32 v57, v60, v57
	v_mul_f32_e32 v66, 0xbfb8aa3b, v63
	v_exp_f32_e32 v66, v66
	v_fma_f32 v61, -v65, v68, 1.0
	v_fma_f32 v60, v61, v68, v68
	v_div_fixup_f32 v60, v60, v65, 1.0
	v_add_f32_e32 v61, 1.0, v66
	v_rcp_f32_e32 v67, v61
	v_mul_f32_e32 v60, v62, v60
	v_mul_f32_e32 v58, v60, v58
	v_mul_f32_e32 v65, 0xbfb8aa3b, v52
	v_exp_f32_e32 v65, v65
	v_fma_f32 v62, -v61, v67, 1.0
	v_fma_f32 v60, v62, v67, v67
	v_div_fixup_f32 v60, v60, v61, 1.0
	v_add_f32_e32 v62, 1.0, v65
	v_rcp_f32_e32 v66, v62
	v_mul_f32_e32 v60, v63, v60
	v_mul_f32_e32 v59, v60, v59
	v_mul_f32_e32 v63, 0xbfb8aa3b, v53
	v_exp_f32_e32 v63, v63
	v_fma_f32 v61, -v62, v66, 1.0
	v_fma_f32 v60, v61, v66, v66
	v_div_fixup_f32 v60, v60, v62, 1.0
	v_add_f32_e32 v61, 1.0, v63
	v_rcp_f32_e32 v65, v61
	v_mul_f32_e32 v52, v52, v60
	v_mul_f32_e32 v52, v52, v48
	v_mul_f32_e32 v62, 0xbfb8aa3b, v54
	v_exp_f32_e32 v62, v62
	v_fma_f32 v60, -v61, v65, 1.0
	v_fma_f32 v48, v60, v65, v65
	v_div_fixup_f32 v48, v48, v61, 1.0
	v_add_f32_e32 v60, 1.0, v62
	v_rcp_f32_e32 v63, v60
	v_mul_f32_e32 v48, v53, v48
	v_mul_f32_e32 v53, v48, v49
	v_mul_f32_e32 v61, 0xbfb8aa3b, v55
	v_exp_f32_e32 v61, v61
	v_fma_f32 v49, -v60, v63, 1.0
	v_fma_f32 v48, v49, v63, v63
	v_div_fixup_f32 v48, v48, v60, 1.0
	v_add_f32_e32 v49, 1.0, v61
	v_rcp_f32_e32 v62, v49
	v_mul_f32_e32 v48, v54, v48
	v_mul_f32_e32 v54, v48, v50
	v_fma_f32 v50, -v49, v62, 1.0
	v_fma_f32 v48, v50, v62, v62
	v_div_fixup_f32 v48, v48, v49, 1.0
	v_mul_f32_e32 v49, 0xbfb8aa3b, v44
	v_mul_f32_e32 v48, v55, v48
	v_exp_f32_e32 v55, v49
	v_mul_f32_e32 v51, v48, v51
	v_cvt_pk_bf16_f32 v48, v56, v57
	v_cvt_pk_bf16_f32 v49, v58, v59
	v_cvt_pk_bf16_f32 v50, v52, v53
	v_cvt_pk_bf16_f32 v51, v54, v51
	v_add_f32_e32 v54, 1.0, v55
	v_rcp_f32_e32 v56, v54
	v_mad_i64_i32 v[52:53], s[26:27], v64, s53, v[112:113]
	v_lshl_add_u64 v[52:53], v[52:53], 0, v[114:115]
	global_store_dwordx4 v[52:53], v[48:51], off
	s_nop 1
	v_mul_f32_e32 v50, 0xbfb8aa3b, v45
	v_exp_f32_e32 v50, v50
	v_fma_f32 v49, -v54, v56, 1.0
	v_fma_f32 v48, v49, v56, v56
	v_div_fixup_f32 v48, v48, v54, 1.0
	v_add_f32_e32 v49, 1.0, v50
	v_rcp_f32_e32 v51, v49
	v_mul_f32_e32 v44, v44, v48
	v_mul_f32_e32 v40, v44, v40
	v_mul_f32_e32 v52, 0xbfb8aa3b, v46
	v_exp_f32_e32 v52, v52
	v_fma_f32 v48, -v49, v51, 1.0
	v_fma_f32 v44, v48, v51, v51
	v_div_fixup_f32 v44, v44, v49, 1.0
	v_add_f32_e32 v48, 1.0, v52
	v_rcp_f32_e32 v51, v48
	v_mul_f32_e32 v44, v45, v44
	v_mul_f32_e32 v41, v44, v41
	v_mul_f32_e32 v49, 0xbfb8aa3b, v47
	v_exp_f32_e32 v49, v49
	v_fma_f32 v45, -v48, v51, 1.0
	v_fma_f32 v44, v45, v51, v51
	v_div_fixup_f32 v44, v44, v48, 1.0
	v_add_f32_e32 v45, 1.0, v49
	v_rcp_f32_e32 v50, v45
	v_mul_f32_e32 v44, v46, v44
	v_mul_f32_e32 v42, v44, v42
	v_mul_f32_e32 v48, 0xbfb8aa3b, v36
	v_exp_f32_e32 v48, v48
	v_fma_f32 v46, -v45, v50, 1.0
	v_fma_f32 v44, v46, v50, v50
	v_div_fixup_f32 v44, v44, v45, 1.0
	v_add_f32_e32 v46, 1.0, v48
	v_rcp_f32_e32 v49, v46
; __device__ __forceinline__ unsigned cvt_pk_bf16(float lo, float hi) { unsigned r; asm volatile("v_cvt_pk_bf16_f32 %0, %1, %2" : "=v"(r) : "v"(lo), "v"(hi)); return r; }
; __device__ __forceinline__ float sigmoidf_(float x) { return 1.0f / (1.0f + __expf(-x)); }
; #define PG8_WAIT_V(n) asm volatile("s_waitcnt vmcnt(" #n ")" ::: "memory")
; #define PG8_BAR __builtin_amdgcn_s_barrier()
; template <class Epi>
; __device__ __forceinline__ void gemm_phase(LAS unsigned char* lds, const Gemm g, const StaticOrder& S, const Epi& E) {
;     ...
;         if (!has_next) break;
; #pragma unroll
;         for (int a = 0; a < 2; ++a)
; #pragma unroll
;             for (int b = 0; b < 2; ++b)
; #pragma unroll
;                 for (int m = 0; m < 4; ++m)
; #pragma unroll
;                     for (int n = 0; n < 2; ++n) acc[a][b][m][n] = (f32x4){0.f, 0.f, 0.f, 0.f};
;         cur = nxt; cA = nA; cB = nB; ++ui;
;     }
;     PG8_WAIT_V(0);
;     if (wr == 0) PG8_BAR;
;     PG8_BAR;
;     __device__ __forceinline__ void operator()(const f32x4 (&acc)[2][2][4][2], const Unit& u, int wr, int wc, int fr, int fq) const {
;     ...
;             for (int m = 0; m < 4; ++m) { float hv[8];
; #pragma unroll
;                 for (int n = 0; n < 2; ++n)
; #pragma unroll
;                     for (int i = 0; i < 4; ++i) { const float gt = acc[ai][0][m][n][i], up = acc[ai][1][m][n][i]; hv[4 * n + i] = gt * sigmoidf_(gt) * up; }
;                 u32x4 o; o[0] = cvt_pk_bf16(hv[0], hv[1]); o[1] = cvt_pk_bf16(hv[2], hv[3]); o[2] = cvt_pk_bf16(hv[4], hv[5]); o[3] = cvt_pk_bf16(hv[6], hv[7]);
;                 *(u32x4*)(O + (size_t)(row0 + ai * 128 + m * 16) * 5632 + col0) = o; }
	v_mul_f32_e32 v44, v47, v44
	v_mul_f32_e32 v43, v44, v43
	v_mul_f32_e32 v47, 0xbfb8aa3b, v37
	v_exp_f32_e32 v47, v47
	v_fma_f32 v45, -v46, v49, 1.0
	v_fma_f32 v44, v45, v49, v49
	v_div_fixup_f32 v44, v44, v46, 1.0
	v_add_f32_e32 v45, 1.0, v47
	v_rcp_f32_e32 v48, v45
	v_mul_f32_e32 v36, v36, v44
	v_mul_f32_e32 v36, v36, v32
	v_mul_f32_e32 v46, 0xbfb8aa3b, v38
	v_exp_f32_e32 v46, v46
	v_fma_f32 v44, -v45, v48, 1.0
	v_fma_f32 v32, v44, v48, v48
	v_div_fixup_f32 v32, v32, v45, 1.0
	v_add_f32_e32 v44, 1.0, v46
	v_rcp_f32_e32 v47, v44
	v_mul_f32_e32 v32, v37, v32
	v_mul_f32_e32 v37, v32, v33
	v_mul_f32_e32 v45, 0xbfb8aa3b, v39
	v_exp_f32_e32 v45, v45
	v_fma_f32 v33, -v44, v47, 1.0
	v_fma_f32 v32, v33, v47, v47
	v_div_fixup_f32 v32, v32, v44, 1.0
	v_add_f32_e32 v33, 1.0, v45
	v_rcp_f32_e32 v46, v33
	v_mul_f32_e32 v32, v38, v32
	v_mul_f32_e32 v38, v32, v34
	v_fma_f32 v34, -v33, v46, 1.0
	v_fma_f32 v32, v34, v46, v46
	v_div_fixup_f32 v32, v32, v33, 1.0
	v_mul_f32_e32 v34, 0xbfb8aa3b, v28
	v_mul_f32_e32 v32, v39, v32
	v_exp_f32_e32 v39, v34
	v_mul_f32_e32 v35, v32, v35
	v_cvt_pk_bf16_f32 v32, v40, v41
	v_cvt_pk_bf16_f32 v33, v42, v43
	v_cvt_pk_bf16_f32 v34, v36, v37
	v_cvt_pk_bf16_f32 v35, v38, v35
	v_add_f32_e32 v38, 1.0, v39
	v_rcp_f32_e32 v40, v38
	v_add_u32_e32 v36, 0x90, v150
	v_mad_i64_i32 v[36:37], s[26:27], v36, s53, v[112:113]
	v_lshl_add_u64 v[36:37], v[36:37], 0, v[114:115]
	global_store_dwordx4 v[36:37], v[32:35], off
	s_nop 1
	v_mul_f32_e32 v34, 0xbfb8aa3b, v29
	v_exp_f32_e32 v34, v34
	v_fma_f32 v33, -v38, v40, 1.0
	v_fma_f32 v32, v33, v40, v40
	v_div_fixup_f32 v32, v32, v38, 1.0
	v_add_f32_e32 v33, 1.0, v34
	v_rcp_f32_e32 v35, v33
	v_mul_f32_e32 v28, v28, v32
	v_mul_f32_e32 v24, v28, v24
	v_mul_f32_e32 v36, 0xbfb8aa3b, v30
	v_exp_f32_e32 v36, v36
	v_fma_f32 v32, -v33, v35, 1.0
	v_fma_f32 v28, v32, v35, v35
	v_div_fixup_f32 v28, v28, v33, 1.0
	v_add_f32_e32 v32, 1.0, v36
	v_rcp_f32_e32 v35, v32
	v_mul_f32_e32 v28, v29, v28
	v_mul_f32_e32 v25, v28, v25
	v_mul_f32_e32 v33, 0xbfb8aa3b, v31
	v_exp_f32_e32 v33, v33
	v_fma_f32 v29, -v32, v35, 1.0
	v_fma_f32 v28, v29, v35, v35
	v_div_fixup_f32 v28, v28, v32, 1.0
	v_add_f32_e32 v29, 1.0, v33
	v_rcp_f32_e32 v34, v29
	v_mul_f32_e32 v28, v30, v28
	v_mul_f32_e32 v26, v28, v26
	v_mul_f32_e32 v32, 0xbfb8aa3b, v20
	v_exp_f32_e32 v32, v32
	v_fma_f32 v30, -v29, v34, 1.0
	v_fma_f32 v28, v30, v34, v34
	v_div_fixup_f32 v28, v28, v29, 1.0
	v_add_f32_e32 v30, 1.0, v32
	v_rcp_f32_e32 v33, v30
	v_mul_f32_e32 v28, v31, v28
	v_mul_f32_e32 v27, v28, v27
	v_mul_f32_e32 v31, 0xbfb8aa3b, v21
	v_exp_f32_e32 v31, v31
	v_fma_f32 v29, -v30, v33, 1.0
	v_fma_f32 v28, v29, v33, v33
	v_div_fixup_f32 v28, v28, v30, 1.0
	v_add_f32_e32 v29, 1.0, v31
	v_rcp_f32_e32 v32, v29
	v_mul_f32_e32 v20, v20, v28
	v_mul_f32_e32 v20, v20, v16
	v_mul_f32_e32 v30, 0xbfb8aa3b, v22
	v_exp_f32_e32 v30, v30
	v_fma_f32 v28, -v29, v32, 1.0
	v_fma_f32 v16, v28, v32, v32
	v_div_fixup_f32 v16, v16, v29, 1.0
	v_add_f32_e32 v28, 1.0, v30
	v_rcp_f32_e32 v31, v28
	v_mul_f32_e32 v16, v21, v16
	v_mul_f32_e32 v21, v16, v17
	v_mul_f32_e32 v29, 0xbfb8aa3b, v23
	v_exp_f32_e32 v29, v29
	v_fma_f32 v17, -v28, v31, 1.0
	v_fma_f32 v16, v17, v31, v31
	v_div_fixup_f32 v16, v16, v28, 1.0
	v_add_f32_e32 v17, 1.0, v29
	v_rcp_f32_e32 v30, v17
	v_mul_f32_e32 v16, v22, v16
	v_mul_f32_e32 v22, v16, v18
	v_fma_f32 v18, -v17, v30, 1.0
	v_fma_f32 v16, v18, v30, v30
	v_div_fixup_f32 v16, v16, v17, 1.0
	v_mul_f32_e32 v18, 0xbfb8aa3b, v12
	v_mul_f32_e32 v16, v23, v16
	v_exp_f32_e32 v23, v18
	v_mul_f32_e32 v19, v16, v19
	v_cvt_pk_bf16_f32 v16, v24, v25
	v_cvt_pk_bf16_f32 v17, v26, v27
	v_cvt_pk_bf16_f32 v18, v20, v21
	v_cvt_pk_bf16_f32 v19, v22, v19
	v_add_f32_e32 v22, 1.0, v23
	v_rcp_f32_e32 v24, v22
	v_add_u32_e32 v20, 0xa0, v150
	v_mad_i64_i32 v[20:21], s[26:27], v20, s53, v[112:113]
	v_lshl_add_u64 v[20:21], v[20:21], 0, v[114:115]
	global_store_dwordx4 v[20:21], v[16:19], off
	s_nop 1
	v_mul_f32_e32 v18, 0xbfb8aa3b, v13
	v_exp_f32_e32 v18, v18
	v_fma_f32 v17, -v22, v24, 1.0
	v_fma_f32 v16, v17, v24, v24
	v_div_fixup_f32 v16, v16, v22, 1.0
	v_add_f32_e32 v17, 1.0, v18
	v_rcp_f32_e32 v19, v17
	v_mul_f32_e32 v12, v12, v16
	v_mul_f32_e32 v8, v12, v8
	v_mul_f32_e32 v20, 0xbfb8aa3b, v14
	v_exp_f32_e32 v20, v20
	v_fma_f32 v16, -v17, v19, 1.0
	v_fma_f32 v12, v16, v19, v19
	v_div_fixup_f32 v12, v12, v17, 1.0
	v_add_f32_e32 v16, 1.0, v20
	v_rcp_f32_e32 v19, v16
	v_mul_f32_e32 v12, v13, v12
	v_mul_f32_e32 v9, v12, v9
	v_mul_f32_e32 v17, 0xbfb8aa3b, v15
	v_exp_f32_e32 v17, v17
	v_fma_f32 v13, -v16, v19, 1.0
	v_fma_f32 v12, v13, v19, v19
	v_div_fixup_f32 v12, v12, v16, 1.0
	v_add_f32_e32 v13, 1.0, v17
	v_rcp_f32_e32 v18, v13
	v_mul_f32_e32 v12, v14, v12
	v_mul_f32_e32 v10, v12, v10
	v_mul_f32_e32 v16, 0xbfb8aa3b, v4
	v_exp_f32_e32 v16, v16
	v_fma_f32 v14, -v13, v18, 1.0
	v_fma_f32 v12, v14, v18, v18
	v_div_fixup_f32 v12, v12, v13, 1.0
	v_add_f32_e32 v14, 1.0, v16
	v_rcp_f32_e32 v17, v14
	v_mul_f32_e32 v12, v15, v12
	v_mul_f32_e32 v11, v12, v11
	v_mul_f32_e32 v15, 0xbfb8aa3b, v5
	v_exp_f32_e32 v15, v15
	v_fma_f32 v13, -v14, v17, 1.0
	v_fma_f32 v12, v13, v17, v17
	v_div_fixup_f32 v12, v12, v14, 1.0
	v_add_f32_e32 v13, 1.0, v15
	v_rcp_f32_e32 v16, v13
	v_mul_f32_e32 v4, v4, v12
	v_mul_f32_e32 v4, v4, v0
	v_mul_f32_e32 v14, 0xbfb8aa3b, v6
	v_exp_f32_e32 v14, v14
	v_fma_f32 v12, -v13, v16, 1.0
	v_fma_f32 v0, v12, v16, v16
	v_div_fixup_f32 v0, v0, v13, 1.0
	v_add_f32_e32 v12, 1.0, v14
	v_rcp_f32_e32 v15, v12
	v_mul_f32_e32 v0, v5, v0
	v_mul_f32_e32 v5, v0, v1
	v_mul_f32_e32 v13, 0xbfb8aa3b, v7
	v_exp_f32_e32 v13, v13
	v_fma_f32 v1, -v12, v15, 1.0
	v_fma_f32 v0, v1, v15, v15
	v_div_fixup_f32 v0, v0, v12, 1.0
	v_add_f32_e32 v1, 1.0, v13
	v_rcp_f32_e32 v14, v1
	v_mul_f32_e32 v0, v6, v0
	v_mul_f32_e32 v6, v0, v2
	v_fma_f32 v2, -v1, v14, 1.0
	v_fma_f32 v0, v2, v14, v14
	v_div_fixup_f32 v0, v0, v1, 1.0
	v_mul_f32_e32 v0, v7, v0
	v_mul_f32_e32 v3, v0, v3
	v_cvt_pk_bf16_f32 v0, v8, v9
	v_cvt_pk_bf16_f32 v1, v10, v11
	v_cvt_pk_bf16_f32 v2, v4, v5
	v_add_u32_e32 v4, 0xb0, v150
	v_mad_i64_i32 v[4:5], s[26:27], v4, s53, v[112:113]
	v_lshl_add_u64 v[4:5], v[4:5], 0, v[114:115]
	s_and_b64 vcc, exec, s[4:5]
	s_mov_b64 s[26:27], s[14:15]
	v_cvt_pk_bf16_f32 v3, v6, v3
	global_store_dwordx4 v[4:5], v[0:3], off
	s_cbranch_vccz .LBB0_1766
	s_waitcnt vmcnt(0)
	s_cmpk_gt_u32 s2, 0xff
	s_cbranch_scc1 .LBB0_1773
	s_barrier

; #define AT_STOREK(buf) do { _Pragma("unroll") for (int i_ = 0; i_ < 2; ++i_) { const int id_ = tid + 512 * i_; \
;             *(u32x4*)(sKt + (buf) * 8704 + (id_ >> 4) * 136 + (id_ & 15) * 8) = kr[i_]; } } while (0)
; #define AT_STOREV(buf) do { _Pragma("unroll") for (int i_ = 0; i_ < 2; ++i_) { const int id_ = tid + 512 * i_; \
;             *(u32x4*)(sVt + (buf) * 9216 + (id_ >> 3) * 72 + (id_ & 7) * 8) = vr[i_]; } } while (0)
; #define AT_LDV(set, vb) do { _Pragma("unroll") for (int kb = 0; kb < 2; ++kb) _Pragma("unroll") for (int s2 = 0; s2 < 2; ++s2) \
;                     vf[set][kb * 2 + s2] = *(const bf16x8*)(sVt + buf * 9216 + (32 * (vb) + ql) * 72 + 32 * kb + 16 * s2 + 8 * g); } while (0)
; __device__ __forceinline__ void phase_attn(const Params& p, unsigned char* lds) {
;     ...
;                 AT_LDV(0, 0);
; #pragma unroll
;                 for (int vb = 0; vb < 4; ++vb) {
;                     if (vb < 3) AT_LDV((vb + 1) & 1, vb + 1);
;                     __builtin_amdgcn_sched_barrier(0);
;                     __builtin_amdgcn_s_setprio(2);
; #pragma unroll
;                     for (int kb = 0; kb < 2; ++kb)
; #pragma unroll
;                         for (int s2 = 0; s2 < 2; ++s2) ot[vb] = __builtin_amdgcn_mfma_f32_32x32x16_bf16(vf[vb & 1][kb * 2 + s2], P[kb][s2], ot[vb], 0, 0, 0);
;                     __builtin_amdgcn_s_setprio(0);
;                     __builtin_amdgcn_sched_barrier(0);
;                 }
;     ...
;             }
;             if (kt + 1 < 64) { AT_STOREK(buf ^ 1); AT_STOREV(buf ^ 1); }
;             __syncthreads();
;         }
;     ...
;         lsum += __shfl_xor(lsum, 32);
;         const float inv = 1.0f / lsum;
;         if (cmap == 1) {
; #pragma unroll
;             for (int vb = 0; vb < 4; ++vb)
; #pragma unroll
;                 for (int i = 0; i < 16; ++i) ex[(vb * 16 + i) * 256 + qsub * 64 + lane] = ot[vb][i] * inv;
.Lat_norescale_10:
	ds_read_b128 v[172:175], v147 offset:34816
	ds_read_b128 v[176:179], v147 offset:34848
	ds_read_b128 v[180:183], v147 offset:34880
	ds_read_b128 v[184:187], v147 offset:34912
	ds_read_b128 v[188:191], v147 offset:39424
	ds_read_b128 v[192:195], v147 offset:39456
	ds_read_b128 v[228:231], v147 offset:39488
	ds_read_b128 v[232:235], v147 offset:39520
	v_add_f32_e32 v128, v128, v236
	s_waitcnt lgkmcnt(7)
	v_mfma_f32_32x32x16_bf16 v[48:63], v[172:175], v[196:199], v[48:63]
	s_waitcnt lgkmcnt(6)
	v_mfma_f32_32x32x16_bf16 v[48:63], v[176:179], v[200:203], v[48:63]
	s_waitcnt lgkmcnt(5)
	v_mfma_f32_32x32x16_bf16 v[48:63], v[180:183], v[212:215], v[48:63]
	s_waitcnt lgkmcnt(4)
	v_mfma_f32_32x32x16_bf16 v[48:63], v[184:187], v[216:219], v[48:63]
	ds_read_b128 v[172:175], v147 offset:44032
	ds_read_b128 v[176:179], v147 offset:44064
	ds_read_b128 v[180:183], v147 offset:44096
	ds_read_b128 v[184:187], v147 offset:44128
	s_waitcnt lgkmcnt(7)
	v_mfma_f32_32x32x16_bf16 v[32:47], v[188:191], v[196:199], v[32:47]
	s_waitcnt lgkmcnt(6)
	v_mfma_f32_32x32x16_bf16 v[32:47], v[192:195], v[200:203], v[32:47]
	s_waitcnt lgkmcnt(5)
	v_mfma_f32_32x32x16_bf16 v[32:47], v[228:231], v[212:215], v[32:47]
	s_waitcnt lgkmcnt(4)
	v_mfma_f32_32x32x16_bf16 v[32:47], v[232:235], v[216:219], v[32:47]
	ds_read_b128 v[188:191], v147 offset:48640
	ds_read_b128 v[192:195], v147 offset:48672
	ds_read_b128 v[228:231], v147 offset:48704
	ds_read_b128 v[232:235], v147 offset:48736
	s_waitcnt lgkmcnt(7)
	v_mfma_f32_32x32x16_bf16 v[16:31], v[172:175], v[196:199], v[16:31]
	s_waitcnt lgkmcnt(6)
	v_mfma_f32_32x32x16_bf16 v[16:31], v[176:179], v[200:203], v[16:31]
	s_waitcnt lgkmcnt(5)
	v_mfma_f32_32x32x16_bf16 v[16:31], v[180:183], v[212:215], v[16:31]
	s_waitcnt lgkmcnt(4)
	v_mfma_f32_32x32x16_bf16 v[16:31], v[184:187], v[216:219], v[16:31]
	s_waitcnt lgkmcnt(3)
	v_mfma_f32_32x32x16_bf16 v[0:15], v[188:191], v[196:199], v[0:15]
	s_waitcnt lgkmcnt(2)
	v_mfma_f32_32x32x16_bf16 v[0:15], v[192:195], v[200:203], v[0:15]
	s_waitcnt lgkmcnt(1)
	v_mfma_f32_32x32x16_bf16 v[0:15], v[228:231], v[212:215], v[0:15]
	s_waitcnt lgkmcnt(0)
	v_mfma_f32_32x32x16_bf16 v[0:15], v[232:235], v[216:219], v[0:15]
	v_mov_b32_e32 v64, v128
	ds_bpermute_b32 v65, v158, v64
	s_waitcnt lgkmcnt(0)
	s_barrier
	v_add_f32_e32 v64, v64, v65
	v_rcp_f32_e32 v66, v64
	s_nop 0
	v_fma_f32 v68, -v64, v66, 1.0
	v_fma_f32 v65, v68, v66, v66
	v_div_fixup_f32 v64, v65, v64, 1.0
	s_and_saveexec_b64 s[20:21], s[4:5]
	s_cbranch_execz .LBB0_2029
	v_mul_f32_e32 v65, v48, v64
	v_mul_f32_e32 v66, v49, v64
	ds_write2st64_b32 v160, v65, v66 offset1:4
	v_mul_f32_e32 v65, v50, v64
	v_mul_f32_e32 v66, v51, v64
	ds_write2st64_b32 v160, v65, v66 offset0:8 offset1:12
	v_mul_f32_e32 v65, v52, v64
	v_mul_f32_e32 v66, v53, v64
	ds_write2st64_b32 v160, v65, v66 offset0:16 offset1:20
	v_mul_f32_e32 v65, v54, v64
	v_mul_f32_e32 v66, v55, v64
	ds_write2st64_b32 v160, v65, v66 offset0:24 offset1:28
	v_mul_f32_e32 v65, v56, v64
	v_mul_f32_e32 v66, v57, v64
	ds_write2st64_b32 v160, v65, v66 offset0:32 offset1:36
	v_mul_f32_e32 v65, v58, v64
	v_mul_f32_e32 v66, v59, v64
	ds_write2st64_b32 v160, v65, v66 offset0:40 offset1:44
	v_mul_f32_e32 v65, v60, v64
	v_mul_f32_e32 v66, v61, v64
	ds_write2st64_b32 v160, v65, v66 offset0:48 offset1:52
	v_mul_f32_e32 v65, v62, v64
	v_mul_f32_e32 v66, v63, v64
	ds_write2st64_b32 v160, v65, v66 offset0:56 offset1:60
	v_mul_f32_e32 v65, v32, v64
	v_mul_f32_e32 v66, v33, v64
	ds_write2st64_b32 v160, v65, v66 offset0:64 offset1:68
	v_mul_f32_e32 v65, v34, v64
	v_mul_f32_e32 v66, v35, v64
	ds_write2st64_b32 v160, v65, v66 offset0:72 offset1:76
	v_mul_f32_e32 v65, v36, v64
	v_mul_f32_e32 v66, v37, v64
	ds_write2st64_b32 v160, v65, v66 offset0:80 offset1:84
	v_mul_f32_e32 v65, v38, v64
	v_mul_f32_e32 v66, v39, v64
	ds_write2st64_b32 v160, v65, v66 offset0:88 offset1:92
	v_mul_f32_e32 v65, v40, v64
	v_mul_f32_e32 v66, v41, v64
	ds_write2st64_b32 v160, v65, v66 offset0:96 offset1:100
	v_mul_f32_e32 v65, v42, v64
	v_mul_f32_e32 v66, v43, v64
	ds_write2st64_b32 v160, v65, v66 offset0:104 offset1:108
	v_mul_f32_e32 v65, v44, v64
	v_mul_f32_e32 v66, v45, v64
	ds_write2st64_b32 v160, v65, v66 offset0:112 offset1:116
	v_mul_f32_e32 v65, v46, v64
	v_mul_f32_e32 v66, v47, v64
	ds_write2st64_b32 v160, v65, v66 offset0:120 offset1:124
	v_mul_f32_e32 v65, v16, v64
	v_mul_f32_e32 v66, v17, v64
	ds_write2st64_b32 v160, v65, v66 offset0:128 offset1:132
	v_mul_f32_e32 v65, v18, v64
	v_mul_f32_e32 v66, v19, v64
	ds_write2st64_b32 v160, v65, v66 offset0:136 offset1:140
	v_mul_f32_e32 v65, v20, v64
	v_mul_f32_e32 v66, v21, v64
	ds_write2st64_b32 v160, v65, v66 offset0:144 offset1:148
	v_mul_f32_e32 v65, v22, v64
	v_mul_f32_e32 v66, v23, v64
	ds_write2st64_b32 v160, v65, v66 offset0:152 offset1:156
	v_mul_f32_e32 v65, v24, v64
	v_mul_f32_e32 v66, v25, v64
	ds_write2st64_b32 v160, v65, v66 offset0:160 offset1:164
	v_mul_f32_e32 v65, v26, v64
	v_mul_f32_e32 v66, v27, v64
	ds_write2st64_b32 v160, v65, v66 offset0:168 offset1:172
	v_mul_f32_e32 v65, v28, v64
	v_mul_f32_e32 v66, v29, v64
	ds_write2st64_b32 v160, v65, v66 offset0:176 offset1:180
	v_mul_f32_e32 v65, v30, v64
	v_mul_f32_e32 v66, v31, v64
	ds_write2st64_b32 v160, v65, v66 offset0:184 offset1:188
	v_mul_f32_e32 v65, v0, v64
	v_mul_f32_e32 v66, v1, v64
	ds_write2st64_b32 v160, v65, v66 offset0:192 offset1:196
	v_mul_f32_e32 v65, v2, v64
	v_mul_f32_e32 v66, v3, v64
	ds_write2st64_b32 v160, v65, v66 offset0:200 offset1:204
	v_mul_f32_e32 v65, v4, v64
	v_mul_f32_e32 v66, v5, v64
	ds_write2st64_b32 v160, v65, v66 offset0:208 offset1:212
	v_mul_f32_e32 v65, v6, v64
	v_mul_f32_e32 v66, v7, v64
	ds_write2st64_b32 v160, v65, v66 offset0:216 offset1:220
	v_mul_f32_e32 v65, v8, v64
	v_mul_f32_e32 v66, v9, v64
	ds_write2st64_b32 v160, v65, v66 offset0:224 offset1:228
	v_mul_f32_e32 v65, v10, v64
	v_mul_f32_e32 v66, v11, v64
	ds_write2st64_b32 v160, v65, v66 offset0:232 offset1:236
	v_mul_f32_e32 v65, v12, v64
	v_mul_f32_e32 v66, v13, v64
	ds_write2st64_b32 v160, v65, v66 offset0:240 offset1:244
	v_mul_f32_e32 v65, v14, v64
	v_mul_f32_e32 v66, v15, v64
	ds_write2st64_b32 v160, v65, v66 offset0:248 offset1:252

; #define PG8_STAGE(bufoff, gbase, voff) do { _Pragma("unroll") for (int _i = 0; _i < 2; ++_i) \
;         __builtin_amdgcn_global_load_lds((const unsigned*)((const char*)(gbase) + (voff)[_i]), (LAS unsigned*)(lds + (bufoff) + ldsw + _i * 8192), 16, 0, 0); } while (0)
; #define PG8_LDA(dst, b, h) do { _Pragma("unroll") for (int m = 0; m < 4; ++m) _Pragma("unroll") for (int k = 0; k < 2; ++k) dst[m][k] = *(const LAS bf16x8*)(lds + PG8_SA(b, h) + aoff + m * 2048 + k * 1024); } while (0)
; #define PG8_LDB(dst, b, h) do { _Pragma("unroll") for (int n = 0; n < 2; ++n) _Pragma("unroll") for (int k = 0; k < 2; ++k) dst[n][k] = *(const LAS bf16x8*)(lds + PG8_SB(b, h) + boff + n * 2048 + k * 1024); } while (0)
; #define PG8_MMA(ai, bj, At, Bt) do { __builtin_amdgcn_s_setprio(1); _Pragma("unroll") for (int m = 0; m < 4; ++m) _Pragma("unroll") for (int n = 0; n < 2; ++n) _Pragma("unroll") for (int k = 0; k < 2; ++k) \
;         acc[ai][bj][m][n] = __builtin_amdgcn_mfma_f32_16x16x32_bf16(Bt[n][k], At[m][k], acc[ai][bj][m][n], 0, 0, 0); __builtin_amdgcn_s_setprio(0); } while (0)
; #define PG8_WAIT_V(n) asm volatile("s_waitcnt vmcnt(" #n ")" ::: "memory")
; #define PG8_WAIT_L(n) asm volatile("s_waitcnt lgkmcnt(" #n ")" ::: "memory")
; #define PG8_BAR __builtin_amdgcn_s_barrier()
; #define PG8_SCHED __builtin_amdgcn_sched_barrier(0)
; template <class Epi>
; __device__ __forceinline__ void gemm_phase(LAS unsigned char* lds, const Gemm g, const StaticOrder& S, const Epi& E) {
;     ...
;             PG8_LDB(B0, 0, 0); PG8_SCHED; PG8_LDA(At, 0, 0); PG8_STAGE(PG8_SA(1, 1), a1 + hstep, voffA);
;             PG8_WAIT_L(8); PG8_BAR; PG8_WAIT_L(0); PG8_MMA(0, 0, At, B0); PG8_BAR; PG8_SCHED;
;             PG8_LDB(B1, 0, 1); PG8_STAGE(PG8_SB(0, 0), b2, voffB);
;             PG8_BAR; PG8_WAIT_L(0); PG8_MMA(0, 1, At, B1); PG8_BAR;
;             PG8_LDA(At, 0, 1); PG8_STAGE(PG8_SA(0, 0), a2, voffA);
;             PG8_BAR; PG8_WAIT_L(0); PG8_MMA(1, 0, At, B0); PG8_BAR; PG8_SCHED;
;             PG8_STAGE(PG8_SB(0, 1), b2 + hstep, voffB);
;             PG8_WAIT_V(6); PG8_BAR; PG8_MMA(1, 1, At, B1); PG8_BAR;
.LBB0_2209:
	ds_read_b128 v[150:153], v147
	ds_read_b128 v[154:157], v147 offset:1024
	ds_read_b128 v[158:161], v147 offset:2048
	ds_read_b128 v[162:165], v147 offset:3072
	s_add_u32 s22, s20, 0xfff80080
	s_addc_u32 s23, s21, -1
	s_cmp_eq_u32 s55, 28
	s_cselect_b32 s27, s11, s23
	s_cselect_b32 s26, s51, s22
	s_cselect_b32 s23, s7, s54
	s_cselect_b32 s22, s52, s53
	v_lshl_add_u64 v[200:201], s[20:21], 0, v[136:137]
	s_add_i32 m0, s17, 0xc000
	ds_read_b128 v[166:169], v148
	ds_read_b128 v[172:175], v148 offset:1024
	ds_read_b128 v[176:179], v148 offset:2048
	ds_read_b128 v[180:183], v148 offset:3072
	ds_read_b128 v[184:187], v148 offset:4096
	ds_read_b128 v[188:191], v148 offset:5120
	ds_read_b128 v[192:195], v148 offset:6144
	ds_read_b128 v[196:199], v148 offset:7168
	global_load_lds_dwordx4 v[200:201], off
	v_lshl_add_u64 v[200:201], s[20:21], 0, v[138:139]
	s_add_i32 m0, s17, 0xe000
	s_nop 0
	global_load_lds_dwordx4 v[200:201], off
	s_waitcnt lgkmcnt(8)
	s_barrier
	s_waitcnt lgkmcnt(0)
	s_setprio 1
	s_waitcnt lgkmcnt(0)
	v_mfma_f32_16x16x32_bf16 v[124:127], v[150:153], v[166:169], v[124:127]
	v_mfma_f32_16x16x32_bf16 v[116:119], v[158:161], v[166:169], v[116:119]
	v_mfma_f32_16x16x32_bf16 v[108:111], v[150:153], v[176:179], v[108:111]
	v_mfma_f32_16x16x32_bf16 v[100:103], v[158:161], v[176:179], v[100:103]
	v_mfma_f32_16x16x32_bf16 v[92:95], v[150:153], v[184:187], v[92:95]
	v_mfma_f32_16x16x32_bf16 v[84:87], v[158:161], v[184:187], v[84:87]
	v_mfma_f32_16x16x32_bf16 v[76:79], v[150:153], v[192:195], v[76:79]
	v_mfma_f32_16x16x32_bf16 v[68:71], v[158:161], v[192:195], v[68:71]
	v_mfma_f32_16x16x32_bf16 v[124:127], v[154:157], v[172:175], v[124:127]
	v_mfma_f32_16x16x32_bf16 v[116:119], v[162:165], v[172:175], v[116:119]
	v_mfma_f32_16x16x32_bf16 v[108:111], v[154:157], v[180:183], v[108:111]
	v_mfma_f32_16x16x32_bf16 v[100:103], v[162:165], v[180:183], v[100:103]
	v_mfma_f32_16x16x32_bf16 v[92:95], v[154:157], v[188:191], v[92:95]
	v_mfma_f32_16x16x32_bf16 v[84:87], v[162:165], v[188:191], v[84:87]
	v_mfma_f32_16x16x32_bf16 v[76:79], v[154:157], v[196:199], v[76:79]
	v_mfma_f32_16x16x32_bf16 v[68:71], v[162:165], v[196:199], v[68:71]
	s_setprio 0
	s_barrier
	s_add_i32 s56, s43, s31
	v_lshl_add_u64 v[216:217], s[22:23], 0, v[132:133]
	s_mov_b32 m0, s56
	ds_read_b128 v[200:203], v149
	ds_read_b128 v[204:207], v149 offset:1024
	ds_read_b128 v[208:211], v149 offset:2048
	ds_read_b128 v[212:215], v149 offset:3072
	global_load_lds_dwordx4 v[216:217], off
	v_lshl_add_u64 v[218:219], s[22:23], 0, v[128:129]
	s_add_i32 m0, s56, 0x2000
	s_nop 0
	global_load_lds_dwordx4 v[218:219], off
	s_barrier
	s_waitcnt lgkmcnt(0)
	s_setprio 1
	s_waitcnt lgkmcnt(0)
	v_mfma_f32_16x16x32_bf16 v[120:123], v[200:203], v[166:169], v[120:123]
	v_mfma_f32_16x16x32_bf16 v[112:115], v[208:211], v[166:169], v[112:115]
	v_mfma_f32_16x16x32_bf16 v[104:107], v[200:203], v[176:179], v[104:107]
	v_mfma_f32_16x16x32_bf16 v[96:99], v[208:211], v[176:179], v[96:99]
	v_mfma_f32_16x16x32_bf16 v[88:91], v[200:203], v[184:187], v[88:91]
	v_mfma_f32_16x16x32_bf16 v[80:83], v[208:211], v[184:187], v[80:83]
	v_mfma_f32_16x16x32_bf16 v[72:75], v[200:203], v[192:195], v[72:75]
	v_mfma_f32_16x16x32_bf16 v[64:67], v[208:211], v[192:195], v[64:67]
	v_mfma_f32_16x16x32_bf16 v[120:123], v[204:207], v[172:175], v[120:123]
	v_mfma_f32_16x16x32_bf16 v[112:115], v[212:215], v[172:175], v[112:115]
	v_mfma_f32_16x16x32_bf16 v[104:107], v[204:207], v[180:183], v[104:107]
	v_mfma_f32_16x16x32_bf16 v[96:99], v[212:215], v[180:183], v[96:99]
	v_mfma_f32_16x16x32_bf16 v[88:91], v[204:207], v[188:191], v[88:91]
	v_mfma_f32_16x16x32_bf16 v[80:83], v[212:215], v[188:191], v[80:83]
	v_mfma_f32_16x16x32_bf16 v[72:75], v[204:207], v[196:199], v[72:75]
	v_mfma_f32_16x16x32_bf16 v[64:67], v[212:215], v[196:199], v[64:67]
	s_setprio 0
	s_mov_b32 m0, s17
	v_lshl_add_u64 v[220:221], s[26:27], 0, v[134:135]
	s_barrier
	ds_read_b128 v[166:169], v148 offset:16384
	ds_read_b128 v[172:175], v148 offset:17408
	ds_read_b128 v[176:179], v148 offset:18432
	ds_read_b128 v[180:183], v148 offset:19456
	ds_read_b128 v[184:187], v148 offset:20480
	ds_read_b128 v[188:191], v148 offset:21504
	ds_read_b128 v[192:195], v148 offset:22528
	ds_read_b128 v[196:199], v148 offset:23552
	global_load_lds_dwordx4 v[220:221], off
	v_lshl_add_u64 v[222:223], s[26:27], 0, v[130:131]
	s_mov_b32 m0, s36
	s_nop 0
	global_load_lds_dwordx4 v[222:223], off
	s_barrier
	s_waitcnt lgkmcnt(0)
	s_setprio 1
	s_waitcnt lgkmcnt(0)
	v_mfma_f32_16x16x32_bf16 v[60:63], v[150:153], v[166:169], v[60:63]
	v_mfma_f32_16x16x32_bf16 v[52:55], v[158:161], v[166:169], v[52:55]
	v_mfma_f32_16x16x32_bf16 v[44:47], v[150:153], v[176:179], v[44:47]
	v_mfma_f32_16x16x32_bf16 v[36:39], v[158:161], v[176:179], v[36:39]
	v_mfma_f32_16x16x32_bf16 v[28:31], v[150:153], v[184:187], v[28:31]
	v_mfma_f32_16x16x32_bf16 v[20:23], v[158:161], v[184:187], v[20:23]
	v_mfma_f32_16x16x32_bf16 v[12:15], v[150:153], v[192:195], v[12:15]
	v_mfma_f32_16x16x32_bf16 v[4:7], v[158:161], v[192:195], v[4:7]
	v_mfma_f32_16x16x32_bf16 v[60:63], v[154:157], v[172:175], v[60:63]
	v_mfma_f32_16x16x32_bf16 v[52:55], v[162:165], v[172:175], v[52:55]
	v_mfma_f32_16x16x32_bf16 v[44:47], v[154:157], v[180:183], v[44:47]
	v_mfma_f32_16x16x32_bf16 v[36:39], v[162:165], v[180:183], v[36:39]
	v_mfma_f32_16x16x32_bf16 v[28:31], v[154:157], v[188:191], v[28:31]
	v_mfma_f32_16x16x32_bf16 v[20:23], v[162:165], v[188:191], v[20:23]
	v_mfma_f32_16x16x32_bf16 v[12:15], v[154:157], v[196:199], v[12:15]
	v_mfma_f32_16x16x32_bf16 v[4:7], v[162:165], v[196:199], v[4:7]
	s_setprio 0
	s_barrier
; #define PG8_STAGE(bufoff, gbase, voff) do { _Pragma("unroll") for (int _i = 0; _i < 2; ++_i) \
;         __builtin_amdgcn_global_load_lds((const unsigned*)((const char*)(gbase) + (voff)[_i]), (LAS unsigned*)(lds + (bufoff) + ldsw + _i * 8192), 16, 0, 0); } while (0)
; #define PG8_LDA(dst, b, h) do { _Pragma("unroll") for (int m = 0; m < 4; ++m) _Pragma("unroll") for (int k = 0; k < 2; ++k) dst[m][k] = *(const LAS bf16x8*)(lds + PG8_SA(b, h) + aoff + m * 2048 + k * 1024); } while (0)
; #define PG8_LDB(dst, b, h) do { _Pragma("unroll") for (int n = 0; n < 2; ++n) _Pragma("unroll") for (int k = 0; k < 2; ++k) dst[n][k] = *(const LAS bf16x8*)(lds + PG8_SB(b, h) + boff + n * 2048 + k * 1024); } while (0)
; #define PG8_MMA(ai, bj, At, Bt) do { __builtin_amdgcn_s_setprio(1); _Pragma("unroll") for (int m = 0; m < 4; ++m) _Pragma("unroll") for (int n = 0; n < 2; ++n) _Pragma("unroll") for (int k = 0; k < 2; ++k) \
;         acc[ai][bj][m][n] = __builtin_amdgcn_mfma_f32_16x16x32_bf16(Bt[n][k], At[m][k], acc[ai][bj][m][n], 0, 0, 0); __builtin_amdgcn_s_setprio(0); } while (0)
; #define PG8_WAIT_V(n) asm volatile("s_waitcnt vmcnt(" #n ")" ::: "memory")
; #define PG8_BAR __builtin_amdgcn_s_barrier()
; template <class Epi>
; __device__ __forceinline__ void gemm_phase(LAS unsigned char* lds, const Gemm g, const StaticOrder& S, const Epi& E) {
;     ...
;             PG8_LDB(B1, 0, 1); PG8_STAGE(PG8_SB(0, 0), b2, voffB);
;             PG8_BAR; PG8_WAIT_L(0); PG8_MMA(0, 1, At, B1); PG8_BAR;
;             PG8_LDA(At, 0, 1); PG8_STAGE(PG8_SA(0, 0), a2, voffA);
;             PG8_BAR; PG8_WAIT_L(0); PG8_MMA(1, 0, At, B0); PG8_BAR; PG8_SCHED;
;             PG8_STAGE(PG8_SB(0, 1), b2 + hstep, voffB);
;             PG8_WAIT_V(6); PG8_BAR; PG8_MMA(1, 1, At, B1); PG8_BAR;
;             PG8_LDB(B0, 1, 0); PG8_SCHED; PG8_LDA(At, 1, 0); PG8_STAGE(PG8_SA(0, 1), a2 + hstep, voffA);
;             PG8_WAIT_L(8); PG8_BAR; PG8_WAIT_L(0); PG8_MMA(0, 0, At, B0); PG8_BAR; PG8_SCHED;
;             PG8_LDB(B1, 1, 1); PG8_STAGE(PG8_SB(1, 0), b3, voffB);
;             PG8_BAR; PG8_WAIT_L(0); PG8_MMA(0, 1, At, B1); PG8_BAR;
;             PG8_LDA(At, 1, 1); PG8_STAGE(PG8_SA(1, 0), a3, voffA);
;             PG8_BAR; PG8_WAIT_L(0); PG8_MMA(1, 0, At, B0); PG8_BAR; PG8_SCHED;
;             PG8_STAGE(PG8_SB(1, 1), b3 + hstep, voffB);
;             PG8_WAIT_V(6); PG8_BAR; PG8_MMA(1, 1, At, B1); PG8_BAR;
	s_add_u32 s56, s22, 0x80000
	s_addc_u32 s57, s23, 0
	s_add_i32 s58, s48, s31
	v_lshl_add_u64 v[150:151], s[56:57], 0, v[132:133]
	s_mov_b32 m0, s58
	s_nop 0
	global_load_lds_dwordx4 v[150:151], off
	v_lshl_add_u64 v[150:151], s[56:57], 0, v[128:129]
	s_add_i32 m0, s58, 0x2000
	s_nop 0
	global_load_lds_dwordx4 v[150:151], off
	s_waitcnt vmcnt(6)
	s_barrier
	s_setprio 1
	v_mfma_f32_16x16x32_bf16 v[56:59], v[200:203], v[166:169], v[56:59]
	v_mfma_f32_16x16x32_bf16 v[48:51], v[208:211], v[166:169], v[48:51]
	v_mfma_f32_16x16x32_bf16 v[40:43], v[200:203], v[176:179], v[40:43]
	v_mfma_f32_16x16x32_bf16 v[32:35], v[208:211], v[176:179], v[32:35]
	v_mfma_f32_16x16x32_bf16 v[24:27], v[200:203], v[184:187], v[24:27]
	v_mfma_f32_16x16x32_bf16 v[16:19], v[208:211], v[184:187], v[16:19]
	v_mfma_f32_16x16x32_bf16 v[8:11], v[200:203], v[192:195], v[8:11]
	v_mfma_f32_16x16x32_bf16 v[0:3], v[208:211], v[192:195], v[0:3]
	v_mfma_f32_16x16x32_bf16 v[56:59], v[204:207], v[172:175], v[56:59]
	v_mfma_f32_16x16x32_bf16 v[48:51], v[212:215], v[172:175], v[48:51]
	v_mfma_f32_16x16x32_bf16 v[40:43], v[204:207], v[180:183], v[40:43]
	v_mfma_f32_16x16x32_bf16 v[32:35], v[212:215], v[180:183], v[32:35]
	v_mfma_f32_16x16x32_bf16 v[24:27], v[204:207], v[188:191], v[24:27]
	v_mfma_f32_16x16x32_bf16 v[16:19], v[212:215], v[188:191], v[16:19]
	v_mfma_f32_16x16x32_bf16 v[8:11], v[204:207], v[196:199], v[8:11]
	v_mfma_f32_16x16x32_bf16 v[0:3], v[212:215], v[196:199], v[0:3]
	s_setprio 0
	s_add_i32 s56, 0, 0x18000
	v_add_u32_e32 v162, s56, v145
	s_barrier
	ds_read_b128 v[150:153], v162
	ds_read_b128 v[154:157], v162 offset:1024
	ds_read_b128 v[158:161], v162 offset:2048
	ds_read_b128 v[162:165], v162 offset:3072
	s_add_u32 s26, s26, 0x80000
	s_addc_u32 s27, s27, 0
	s_mov_b32 m0, s37
	v_lshl_add_u64 v[200:201], s[26:27], 0, v[134:135]
	ds_read_b128 v[166:169], v148 offset:32768
	ds_read_b128 v[172:175], v148 offset:33792
	ds_read_b128 v[176:179], v148 offset:34816
	ds_read_b128 v[180:183], v148 offset:35840
	ds_read_b128 v[184:187], v148 offset:36864
	ds_read_b128 v[188:191], v148 offset:37888
	ds_read_b128 v[192:195], v148 offset:38912
	ds_read_b128 v[196:199], v148 offset:39936
	global_load_lds_dwordx4 v[200:201], off
	v_lshl_add_u64 v[200:201], s[26:27], 0, v[130:131]
	s_mov_b32 m0, s38
	s_nop 0
	global_load_lds_dwordx4 v[200:201], off
	s_waitcnt lgkmcnt(8)
	s_barrier
	s_waitcnt lgkmcnt(0)
	s_setprio 1
	s_waitcnt lgkmcnt(0)
	v_mfma_f32_16x16x32_bf16 v[124:127], v[150:153], v[166:169], v[124:127]
	v_mfma_f32_16x16x32_bf16 v[116:119], v[158:161], v[166:169], v[116:119]
	v_mfma_f32_16x16x32_bf16 v[108:111], v[150:153], v[176:179], v[108:111]
	v_mfma_f32_16x16x32_bf16 v[100:103], v[158:161], v[176:179], v[100:103]
	v_mfma_f32_16x16x32_bf16 v[92:95], v[150:153], v[184:187], v[92:95]
	v_mfma_f32_16x16x32_bf16 v[84:87], v[158:161], v[184:187], v[84:87]
	v_mfma_f32_16x16x32_bf16 v[76:79], v[150:153], v[192:195], v[76:79]
	v_mfma_f32_16x16x32_bf16 v[68:71], v[158:161], v[192:195], v[68:71]
	v_mfma_f32_16x16x32_bf16 v[124:127], v[154:157], v[172:175], v[124:127]
	v_mfma_f32_16x16x32_bf16 v[116:119], v[162:165], v[172:175], v[116:119]
	v_mfma_f32_16x16x32_bf16 v[108:111], v[154:157], v[180:183], v[108:111]
	v_mfma_f32_16x16x32_bf16 v[100:103], v[162:165], v[180:183], v[100:103]
	v_mfma_f32_16x16x32_bf16 v[92:95], v[154:157], v[188:191], v[92:95]
	v_mfma_f32_16x16x32_bf16 v[84:87], v[162:165], v[188:191], v[84:87]
	v_mfma_f32_16x16x32_bf16 v[76:79], v[154:157], v[196:199], v[76:79]
	v_mfma_f32_16x16x32_bf16 v[68:71], v[162:165], v[196:199], v[68:71]
	s_setprio 0
	s_barrier
	s_add_i32 s26, 0, 0x1c000
	s_add_i32 s27, s56, s31
	v_add_u32_e32 v171, s26, v145
	v_lshl_add_u64 v[216:217], v[216:217], 0, s[0:1]
	s_mov_b32 m0, s27
	ds_read_b128 v[200:203], v171
	ds_read_b128 v[204:207], v171 offset:1024
	ds_read_b128 v[208:211], v171 offset:2048
	ds_read_b128 v[212:215], v171 offset:3072
	global_load_lds_dwordx4 v[216:217], off
	v_lshl_add_u64 v[216:217], v[218:219], 0, s[0:1]
	s_add_i32 m0, s27, 0x2000
	s_nop 0
	global_load_lds_dwordx4 v[216:217], off
	s_barrier
	s_waitcnt lgkmcnt(0)
	s_setprio 1
	s_waitcnt lgkmcnt(0)
	v_mfma_f32_16x16x32_bf16 v[120:123], v[200:203], v[166:169], v[120:123]
	v_mfma_f32_16x16x32_bf16 v[112:115], v[208:211], v[166:169], v[112:115]
	v_mfma_f32_16x16x32_bf16 v[104:107], v[200:203], v[176:179], v[104:107]
	v_mfma_f32_16x16x32_bf16 v[96:99], v[208:211], v[176:179], v[96:99]
	v_mfma_f32_16x16x32_bf16 v[88:91], v[200:203], v[184:187], v[88:91]
	v_mfma_f32_16x16x32_bf16 v[80:83], v[208:211], v[184:187], v[80:83]
	v_mfma_f32_16x16x32_bf16 v[72:75], v[200:203], v[192:195], v[72:75]
	v_mfma_f32_16x16x32_bf16 v[64:67], v[208:211], v[192:195], v[64:67]
	v_mfma_f32_16x16x32_bf16 v[120:123], v[204:207], v[172:175], v[120:123]
	v_mfma_f32_16x16x32_bf16 v[112:115], v[212:215], v[172:175], v[112:115]
	v_mfma_f32_16x16x32_bf16 v[104:107], v[204:207], v[180:183], v[104:107]
	v_mfma_f32_16x16x32_bf16 v[96:99], v[212:215], v[180:183], v[96:99]
	v_mfma_f32_16x16x32_bf16 v[88:91], v[204:207], v[188:191], v[88:91]
	v_mfma_f32_16x16x32_bf16 v[80:83], v[212:215], v[188:191], v[80:83]
	v_mfma_f32_16x16x32_bf16 v[72:75], v[204:207], v[196:199], v[72:75]
	v_mfma_f32_16x16x32_bf16 v[64:67], v[212:215], v[196:199], v[64:67]
	s_setprio 0
	s_mov_b32 m0, s40
	v_lshl_add_u64 v[216:217], v[220:221], 0, s[0:1]
	s_barrier
	ds_read_b128 v[166:169], v148 offset:49152
	ds_read_b128 v[172:175], v148 offset:50176
	ds_read_b128 v[176:179], v148 offset:51200
	ds_read_b128 v[180:183], v148 offset:52224
	ds_read_b128 v[184:187], v148 offset:53248
	ds_read_b128 v[188:191], v148 offset:54272
	ds_read_b128 v[192:195], v148 offset:55296
	ds_read_b128 v[196:199], v148 offset:56320
	global_load_lds_dwordx4 v[216:217], off
	v_lshl_add_u64 v[216:217], v[222:223], 0, s[0:1]
	s_mov_b32 m0, s41
	s_nop 0
	global_load_lds_dwordx4 v[216:217], off
	s_barrier
; __device__ __forceinline__ unsigned cvt_pk_bf16(float lo, float hi) { unsigned r; asm volatile("v_cvt_pk_bf16_f32 %0, %1, %2" : "=v"(r) : "v"(lo), "v"(hi)); return r; }
; __device__ __forceinline__ float sigmoidf_(float x) { return 1.0f / (1.0f + __expf(-x)); }
; #define PG8_STAGE(bufoff, gbase, voff) do { _Pragma("unroll") for (int _i = 0; _i < 2; ++_i) \
;         __builtin_amdgcn_global_load_lds((const unsigned*)((const char*)(gbase) + (voff)[_i]), (LAS unsigned*)(lds + (bufoff) + ldsw + _i * 8192), 16, 0, 0); } while (0)
; #define PG8_LDA(dst, b, h) do { _Pragma("unroll") for (int m = 0; m < 4; ++m) _Pragma("unroll") for (int k = 0; k < 2; ++k) dst[m][k] = *(const LAS bf16x8*)(lds + PG8_SA(b, h) + aoff + m * 2048 + k * 1024); } while (0)
; #define PG8_MMA(ai, bj, At, Bt) do { __builtin_amdgcn_s_setprio(1); _Pragma("unroll") for (int m = 0; m < 4; ++m) _Pragma("unroll") for (int n = 0; n < 2; ++n) _Pragma("unroll") for (int k = 0; k < 2; ++k) \
;         acc[ai][bj][m][n] = __builtin_amdgcn_mfma_f32_16x16x32_bf16(Bt[n][k], At[m][k], acc[ai][bj][m][n], 0, 0, 0); __builtin_amdgcn_s_setprio(0); } while (0)
; #define PG8_WAIT_V(n) asm volatile("s_waitcnt vmcnt(" #n ")" ::: "memory")
; #define PG8_WAIT_L(n) asm volatile("s_waitcnt lgkmcnt(" #n ")" ::: "memory")
; #define PG8_BAR __builtin_amdgcn_s_barrier()
; template <class Epi>
; __device__ __forceinline__ void gemm_phase(LAS unsigned char* lds, const Gemm g, const StaticOrder& S, const Epi& E) {
;     ...
;             PG8_BAR; PG8_WAIT_L(0); PG8_MMA(0, 1, At, B1); PG8_BAR;
;             PG8_LDA(At, 1, 1); PG8_STAGE(PG8_SA(1, 0), a3, voffA);
;             PG8_BAR; PG8_WAIT_L(0); PG8_MMA(1, 0, At, B0); PG8_BAR; PG8_SCHED;
;             PG8_STAGE(PG8_SB(1, 1), b3 + hstep, voffB);
;             PG8_WAIT_V(6); PG8_BAR; PG8_MMA(1, 1, At, B1); PG8_BAR;
;     __device__ __forceinline__ void operator()(const f32x4 (&acc)[2][2][4][2], const Unit& u, int wr, int wc, int fr, int fq) const {
;     ...
;                     for (int i = 0; i < 4; ++i) { const float gt = acc[ai][0][m][n][i], up = acc[ai][1][m][n][i]; hv[4 * n + i] = gt * sigmoidf_(gt) * up; }
;                 u32x4 o; o[0] = cvt_pk_bf16(hv[0], hv[1]); o[1] = cvt_pk_bf16(hv[2], hv[3]); o[2] = cvt_pk_bf16(hv[4], hv[5]); o[3] = cvt_pk_bf16(hv[6], hv[7]);
;                 *(u32x4*)(O + (size_t)(row0 + ai * 128 + m * 16) * 5632 + col0) = o; }
	s_waitcnt lgkmcnt(0)
	s_setprio 1
	s_waitcnt lgkmcnt(0)
	v_mfma_f32_16x16x32_bf16 v[60:63], v[150:153], v[166:169], v[60:63]
	v_mfma_f32_16x16x32_bf16 v[52:55], v[158:161], v[166:169], v[52:55]
	v_mfma_f32_16x16x32_bf16 v[44:47], v[150:153], v[176:179], v[44:47]
	v_mfma_f32_16x16x32_bf16 v[36:39], v[158:161], v[176:179], v[36:39]
	v_mfma_f32_16x16x32_bf16 v[28:31], v[150:153], v[184:187], v[28:31]
	v_mfma_f32_16x16x32_bf16 v[20:23], v[158:161], v[184:187], v[20:23]
	v_mfma_f32_16x16x32_bf16 v[12:15], v[150:153], v[192:195], v[12:15]
	v_mfma_f32_16x16x32_bf16 v[4:7], v[158:161], v[192:195], v[4:7]
	v_mfma_f32_16x16x32_bf16 v[60:63], v[154:157], v[172:175], v[60:63]
	v_mfma_f32_16x16x32_bf16 v[52:55], v[162:165], v[172:175], v[52:55]
	v_mfma_f32_16x16x32_bf16 v[44:47], v[154:157], v[180:183], v[44:47]
	v_mfma_f32_16x16x32_bf16 v[36:39], v[162:165], v[180:183], v[36:39]
	v_mfma_f32_16x16x32_bf16 v[28:31], v[154:157], v[188:191], v[28:31]
	v_mfma_f32_16x16x32_bf16 v[20:23], v[162:165], v[188:191], v[20:23]
	v_mfma_f32_16x16x32_bf16 v[12:15], v[154:157], v[196:199], v[12:15]
	v_mfma_f32_16x16x32_bf16 v[4:7], v[162:165], v[196:199], v[4:7]
	s_setprio 0
	s_barrier
	s_add_u32 s22, s22, 0x80080
	s_addc_u32 s23, s23, 0
	s_add_i32 s26, s26, s31
	v_lshl_add_u64 v[150:151], s[22:23], 0, v[132:133]
	s_mov_b32 m0, s26
	s_nop 0
	global_load_lds_dwordx4 v[150:151], off
	v_lshl_add_u64 v[150:151], s[22:23], 0, v[128:129]
	s_add_i32 m0, s26, 0x2000
	s_nop 0
	global_load_lds_dwordx4 v[150:151], off
	s_waitcnt vmcnt(6)
	s_barrier
	s_setprio 1
	v_mfma_f32_16x16x32_bf16 v[56:59], v[200:203], v[166:169], v[56:59]
	v_mfma_f32_16x16x32_bf16 v[48:51], v[208:211], v[166:169], v[48:51]
	v_mfma_f32_16x16x32_bf16 v[40:43], v[200:203], v[176:179], v[40:43]
	v_mfma_f32_16x16x32_bf16 v[32:35], v[208:211], v[176:179], v[32:35]
	v_mfma_f32_16x16x32_bf16 v[24:27], v[200:203], v[184:187], v[24:27]
	v_mfma_f32_16x16x32_bf16 v[16:19], v[208:211], v[184:187], v[16:19]
	v_mfma_f32_16x16x32_bf16 v[8:11], v[200:203], v[192:195], v[8:11]
	v_mfma_f32_16x16x32_bf16 v[0:3], v[208:211], v[192:195], v[0:3]
	v_mfma_f32_16x16x32_bf16 v[56:59], v[204:207], v[172:175], v[56:59]
	v_mfma_f32_16x16x32_bf16 v[48:51], v[212:215], v[172:175], v[48:51]
	v_mfma_f32_16x16x32_bf16 v[40:43], v[204:207], v[180:183], v[40:43]
	v_mfma_f32_16x16x32_bf16 v[32:35], v[212:215], v[180:183], v[32:35]
	v_mfma_f32_16x16x32_bf16 v[24:27], v[204:207], v[188:191], v[24:27]
	v_mfma_f32_16x16x32_bf16 v[16:19], v[212:215], v[188:191], v[16:19]
	v_mfma_f32_16x16x32_bf16 v[8:11], v[204:207], v[196:199], v[8:11]
	v_mfma_f32_16x16x32_bf16 v[0:3], v[212:215], v[196:199], v[0:3]
	s_setprio 0
	s_add_i32 s55, s55, 2
	s_add_u32 s20, s20, 0x100
	s_addc_u32 s21, s21, 0
	s_add_u32 s53, s53, 0x100
	s_addc_u32 s54, s54, 0
	s_cmp_gt_u32 s55, 29
	s_barrier
	s_cbranch_scc0 .LBB0_2209
	v_mul_f32_e32 v150, 0xbfb8aa3b, v124
	v_exp_f32_e32 v151, v150
	v_lshl_or_b32 v152, s50, 7, v146
	v_lshl_add_u32 v150, s16, 8, v144
	v_ashrrev_i32_e32 v153, 31, v152
	v_add_f32_e32 v151, 1.0, v151
	v_rcp_f32_e32 v155, v151
	s_mov_b32 s50, s6
	v_mul_f32_e32 v158, 0xbfb8aa3b, v125
	v_exp_f32_e32 v158, v158
	v_fma_f32 v157, -v151, v155, 1.0
	v_fma_f32 v154, v157, v155, v155
	v_div_fixup_f32 v151, v154, v151, 1.0
	v_add_f32_e32 v155, 1.0, v158
	v_rcp_f32_e32 v157, v155
	v_mul_f32_e32 v124, v124, v151
	v_mul_f32_e32 v120, v124, v120
	s_mov_b32 s16, s10
	v_mul_f32_e32 v154, 0xbfb8aa3b, v126
	v_exp_f32_e32 v154, v154
	v_fma_f32 v151, -v155, v157, 1.0
	v_fma_f32 v124, v151, v157, v157
	v_div_fixup_f32 v124, v124, v155, 1.0
	v_add_f32_e32 v151, 1.0, v154
	v_rcp_f32_e32 v156, v151
	v_mul_f32_e32 v124, v125, v124
	v_mul_f32_e32 v121, v124, v121
	s_mov_b64 s[22:23], s[14:15]
	v_mul_f32_e32 v155, 0xbfb8aa3b, v127
	v_exp_f32_e32 v155, v155
	v_fma_f32 v125, -v151, v156, 1.0
	v_fma_f32 v124, v125, v156, v156
	v_div_fixup_f32 v124, v124, v151, 1.0
	v_add_f32_e32 v125, 1.0, v155
	v_rcp_f32_e32 v155, v125
	v_mul_f32_e32 v124, v126, v124
	v_mul_f32_e32 v122, v124, v122
	v_mul_f32_e32 v151, 0xbfb8aa3b, v116
	v_exp_f32_e32 v151, v151
	v_fma_f32 v126, -v125, v155, 1.0
	v_fma_f32 v124, v126, v155, v155
	v_div_fixup_f32 v124, v124, v125, 1.0
	v_add_f32_e32 v126, 1.0, v151
	v_rcp_f32_e32 v154, v126
	v_mul_f32_e32 v124, v127, v124
	v_mul_f32_e32 v123, v124, v123
	v_mul_f32_e32 v127, 0xbfb8aa3b, v117
	v_exp_f32_e32 v127, v127
	v_fma_f32 v125, -v126, v154, 1.0
	v_fma_f32 v124, v125, v154, v154
	v_div_fixup_f32 v124, v124, v126, 1.0
	v_add_f32_e32 v125, 1.0, v127
	v_rcp_f32_e32 v151, v125
	v_mul_f32_e32 v116, v116, v124
	v_mul_f32_e32 v112, v116, v112
	v_mul_f32_e32 v126, 0xbfb8aa3b, v118
	v_exp_f32_e32 v126, v126
	v_fma_f32 v124, -v125, v151, 1.0
	v_fma_f32 v116, v124, v151, v151
	v_div_fixup_f32 v116, v116, v125, 1.0
	v_add_f32_e32 v124, 1.0, v126
	v_rcp_f32_e32 v127, v124
	v_mul_f32_e32 v116, v117, v116
	v_mul_f32_e32 v113, v116, v113
	v_mul_f32_e32 v125, 0xbfb8aa3b, v119
	v_exp_f32_e32 v125, v125
	v_fma_f32 v117, -v124, v127, 1.0
	v_fma_f32 v116, v117, v127, v127
	v_div_fixup_f32 v116, v116, v124, 1.0
	v_add_f32_e32 v117, 1.0, v125
	v_rcp_f32_e32 v126, v117
	v_mul_f32_e32 v116, v118, v116
	v_mul_f32_e32 v114, v116, v114
	v_fma_f32 v118, -v117, v126, 1.0
	v_fma_f32 v116, v118, v126, v126
	v_div_fixup_f32 v116, v116, v117, 1.0
	v_mul_f32_e32 v116, v119, v116
	v_mul_f32_e32 v115, v116, v115
	v_cvt_pk_bf16_f32 v116, v120, v121
	v_cvt_pk_bf16_f32 v117, v122, v123
	v_cvt_pk_bf16_f32 v118, v112, v113
	v_mul_f32_e32 v112, 0xbfb8aa3b, v108
	v_cvt_pk_bf16_f32 v119, v114, v115
	v_exp_f32_e32 v114, v112
	v_mov_b64_e32 v[112:113], s[96:97]
	v_mad_i64_i32 v[120:121], s[20:21], v150, s49, v[112:113]
; __device__ __forceinline__ unsigned cvt_pk_bf16(float lo, float hi) { unsigned r; asm volatile("v_cvt_pk_bf16_f32 %0, %1, %2" : "=v"(r) : "v"(lo), "v"(hi)); return r; }
; __device__ __forceinline__ float sigmoidf_(float x) { return 1.0f / (1.0f + __expf(-x)); }
;     __device__ __forceinline__ void operator()(const f32x4 (&acc)[2][2][4][2], const Unit& u, int wr, int wc, int fr, int fq) const {
;     ...
;             for (int m = 0; m < 4; ++m) { float hv[8];
; #pragma unroll
;                 for (int n = 0; n < 2; ++n)
; #pragma unroll
;                     for (int i = 0; i < 4; ++i) { const float gt = acc[ai][0][m][n][i], up = acc[ai][1][m][n][i]; hv[4 * n + i] = gt * sigmoidf_(gt) * up; }
;                 u32x4 o; o[0] = cvt_pk_bf16(hv[0], hv[1]); o[1] = cvt_pk_bf16(hv[2], hv[3]); o[2] = cvt_pk_bf16(hv[4], hv[5]); o[3] = cvt_pk_bf16(hv[6], hv[7]);
;                 *(u32x4*)(O + (size_t)(row0 + ai * 128 + m * 16) * 5632 + col0) = o; }
	v_add_f32_e32 v122, 1.0, v114
	v_rcp_f32_e32 v124, v122
	v_lshlrev_b64 v[114:115], 1, v[152:153]
	v_lshl_add_u64 v[120:121], v[120:121], 0, v[114:115]
	global_store_dwordx4 v[120:121], v[116:119], off
	s_nop 1
	v_mul_f32_e32 v118, 0xbfb8aa3b, v109
	v_exp_f32_e32 v118, v118
	v_fma_f32 v117, -v122, v124, 1.0
	v_fma_f32 v116, v117, v124, v124
	v_div_fixup_f32 v116, v116, v122, 1.0
	v_add_f32_e32 v117, 1.0, v118
	v_rcp_f32_e32 v119, v117
	v_mul_f32_e32 v108, v108, v116
	v_mul_f32_e32 v104, v108, v104
	v_mul_f32_e32 v120, 0xbfb8aa3b, v110
	v_exp_f32_e32 v120, v120
	v_fma_f32 v116, -v117, v119, 1.0
	v_fma_f32 v108, v116, v119, v119
	v_div_fixup_f32 v108, v108, v117, 1.0
	v_add_f32_e32 v116, 1.0, v120
	v_rcp_f32_e32 v119, v116
	v_mul_f32_e32 v108, v109, v108
	v_mul_f32_e32 v105, v108, v105
	v_mul_f32_e32 v117, 0xbfb8aa3b, v111
	v_exp_f32_e32 v117, v117
	v_fma_f32 v109, -v116, v119, 1.0
	v_fma_f32 v108, v109, v119, v119
	v_div_fixup_f32 v108, v108, v116, 1.0
	v_add_f32_e32 v109, 1.0, v117
	v_rcp_f32_e32 v118, v109
	v_mul_f32_e32 v108, v110, v108
	v_mul_f32_e32 v106, v108, v106
	v_mul_f32_e32 v116, 0xbfb8aa3b, v100
	v_exp_f32_e32 v116, v116
	v_fma_f32 v110, -v109, v118, 1.0
	v_fma_f32 v108, v110, v118, v118
	v_div_fixup_f32 v108, v108, v109, 1.0
	v_add_f32_e32 v110, 1.0, v116
	v_rcp_f32_e32 v117, v110
	v_mul_f32_e32 v108, v111, v108
	v_mul_f32_e32 v107, v108, v107
	v_mul_f32_e32 v111, 0xbfb8aa3b, v101
	v_exp_f32_e32 v111, v111
	v_fma_f32 v109, -v110, v117, 1.0
	v_fma_f32 v108, v109, v117, v117
	v_div_fixup_f32 v108, v108, v110, 1.0
	v_add_f32_e32 v109, 1.0, v111
	v_rcp_f32_e32 v116, v109
	v_mul_f32_e32 v100, v100, v108
	v_mul_f32_e32 v100, v100, v96
	v_mul_f32_e32 v110, 0xbfb8aa3b, v102
	v_exp_f32_e32 v110, v110
	v_fma_f32 v108, -v109, v116, 1.0
	v_fma_f32 v96, v108, v116, v116
	v_div_fixup_f32 v96, v96, v109, 1.0
	v_add_f32_e32 v108, 1.0, v110
	v_rcp_f32_e32 v111, v108
	v_mul_f32_e32 v96, v101, v96
	v_mul_f32_e32 v101, v96, v97
	v_mul_f32_e32 v109, 0xbfb8aa3b, v103
	v_exp_f32_e32 v109, v109
	v_fma_f32 v97, -v108, v111, 1.0
	v_fma_f32 v96, v97, v111, v111
	v_div_fixup_f32 v96, v96, v108, 1.0
	v_add_f32_e32 v97, 1.0, v109
	v_rcp_f32_e32 v110, v97
	v_mul_f32_e32 v96, v102, v96
	v_mul_f32_e32 v102, v96, v98
	v_fma_f32 v98, -v97, v110, 1.0
	v_fma_f32 v96, v98, v110, v110
	v_div_fixup_f32 v96, v96, v97, 1.0
	v_mul_f32_e32 v98, 0xbfb8aa3b, v92
	v_mul_f32_e32 v96, v103, v96
	v_exp_f32_e32 v103, v98
	v_mul_f32_e32 v99, v96, v99
	v_cvt_pk_bf16_f32 v96, v104, v105
	v_cvt_pk_bf16_f32 v97, v106, v107
	v_cvt_pk_bf16_f32 v98, v100, v101
	v_cvt_pk_bf16_f32 v99, v102, v99
	v_add_f32_e32 v102, 1.0, v103
	v_rcp_f32_e32 v104, v102
	v_or_b32_e32 v100, 16, v150
	v_mad_i64_i32 v[100:101], s[20:21], v100, s49, v[112:113]
	v_lshl_add_u64 v[100:101], v[100:101], 0, v[114:115]
	global_store_dwordx4 v[100:101], v[96:99], off
	s_nop 1
	v_mul_f32_e32 v98, 0xbfb8aa3b, v93
	v_exp_f32_e32 v98, v98
	v_fma_f32 v97, -v102, v104, 1.0
	v_fma_f32 v96, v97, v104, v104
	v_div_fixup_f32 v96, v96, v102, 1.0
	v_add_f32_e32 v97, 1.0, v98
	v_rcp_f32_e32 v99, v97
	v_mul_f32_e32 v92, v92, v96
	v_mul_f32_e32 v88, v92, v88
	v_mul_f32_e32 v100, 0xbfb8aa3b, v94
	v_exp_f32_e32 v100, v100
	v_fma_f32 v96, -v97, v99, 1.0
	v_fma_f32 v92, v96, v99, v99
	v_div_fixup_f32 v92, v92, v97, 1.0
	v_add_f32_e32 v96, 1.0, v100
	v_rcp_f32_e32 v99, v96
	v_mul_f32_e32 v92, v93, v92
	v_mul_f32_e32 v89, v92, v89
	v_mul_f32_e32 v97, 0xbfb8aa3b, v95
	v_exp_f32_e32 v97, v97
	v_fma_f32 v93, -v96, v99, 1.0
	v_fma_f32 v92, v93, v99, v99
	v_div_fixup_f32 v92, v92, v96, 1.0
	v_add_f32_e32 v93, 1.0, v97
	v_rcp_f32_e32 v98, v93
	v_mul_f32_e32 v92, v94, v92
	v_mul_f32_e32 v90, v92, v90
	v_mul_f32_e32 v96, 0xbfb8aa3b, v84
	v_exp_f32_e32 v96, v96
	v_fma_f32 v94, -v93, v98, 1.0
	v_fma_f32 v92, v94, v98, v98
	v_div_fixup_f32 v92, v92, v93, 1.0
	v_add_f32_e32 v94, 1.0, v96
	v_rcp_f32_e32 v97, v94
	v_mul_f32_e32 v92, v95, v92
	v_mul_f32_e32 v91, v92, v91
	v_mul_f32_e32 v95, 0xbfb8aa3b, v85
	v_exp_f32_e32 v95, v95
	v_fma_f32 v93, -v94, v97, 1.0
	v_fma_f32 v92, v93, v97, v97
	v_div_fixup_f32 v92, v92, v94, 1.0
	v_add_f32_e32 v93, 1.0, v95
	v_rcp_f32_e32 v96, v93
	v_mul_f32_e32 v84, v84, v92
	v_mul_f32_e32 v84, v84, v80
	v_mul_f32_e32 v94, 0xbfb8aa3b, v86
	v_exp_f32_e32 v94, v94
	v_fma_f32 v92, -v93, v96, 1.0
	v_fma_f32 v80, v92, v96, v96
	v_div_fixup_f32 v80, v80, v93, 1.0
	v_add_f32_e32 v92, 1.0, v94
	v_rcp_f32_e32 v95, v92
	v_mul_f32_e32 v80, v85, v80
	v_mul_f32_e32 v85, v80, v81
	v_mul_f32_e32 v93, 0xbfb8aa3b, v87
	v_exp_f32_e32 v93, v93
	v_fma_f32 v81, -v92, v95, 1.0
	v_fma_f32 v80, v81, v95, v95
	v_div_fixup_f32 v80, v80, v92, 1.0
	v_add_f32_e32 v81, 1.0, v93
	v_rcp_f32_e32 v94, v81
	v_mul_f32_e32 v80, v86, v80
	v_mul_f32_e32 v86, v80, v82
	v_fma_f32 v82, -v81, v94, 1.0
	v_fma_f32 v80, v82, v94, v94
	v_div_fixup_f32 v80, v80, v81, 1.0
	v_mul_f32_e32 v82, 0xbfb8aa3b, v76
	v_mul_f32_e32 v80, v87, v80
	v_exp_f32_e32 v87, v82
	v_mul_f32_e32 v83, v80, v83
	v_cvt_pk_bf16_f32 v80, v88, v89
	v_cvt_pk_bf16_f32 v81, v90, v91
	v_cvt_pk_bf16_f32 v82, v84, v85
	v_cvt_pk_bf16_f32 v83, v86, v83
	v_add_f32_e32 v86, 1.0, v87
	v_rcp_f32_e32 v88, v86
	v_or_b32_e32 v84, 32, v150
	v_mad_i64_i32 v[84:85], s[20:21], v84, s49, v[112:113]
	v_lshl_add_u64 v[84:85], v[84:85], 0, v[114:115]
	global_store_dwordx4 v[84:85], v[80:83], off
	s_nop 1
	v_mul_f32_e32 v82, 0xbfb8aa3b, v77
	v_exp_f32_e32 v82, v82
	v_fma_f32 v81, -v86, v88, 1.0
	v_fma_f32 v80, v81, v88, v88
	v_div_fixup_f32 v80, v80, v86, 1.0
	v_add_f32_e32 v81, 1.0, v82
	v_rcp_f32_e32 v83, v81
	v_mul_f32_e32 v76, v76, v80
	v_mul_f32_e32 v72, v76, v72
	v_mul_f32_e32 v84, 0xbfb8aa3b, v78
; __device__ __forceinline__ unsigned cvt_pk_bf16(float lo, float hi) { unsigned r; asm volatile("v_cvt_pk_bf16_f32 %0, %1, %2" : "=v"(r) : "v"(lo), "v"(hi)); return r; }
; __device__ __forceinline__ float sigmoidf_(float x) { return 1.0f / (1.0f + __expf(-x)); }
;     __device__ __forceinline__ void operator()(const f32x4 (&acc)[2][2][4][2], const Unit& u, int wr, int wc, int fr, int fq) const {
;     ...
;             for (int m = 0; m < 4; ++m) { float hv[8];
; #pragma unroll
;                 for (int n = 0; n < 2; ++n)
; #pragma unroll
;                     for (int i = 0; i < 4; ++i) { const float gt = acc[ai][0][m][n][i], up = acc[ai][1][m][n][i]; hv[4 * n + i] = gt * sigmoidf_(gt) * up; }
;                 u32x4 o; o[0] = cvt_pk_bf16(hv[0], hv[1]); o[1] = cvt_pk_bf16(hv[2], hv[3]); o[2] = cvt_pk_bf16(hv[4], hv[5]); o[3] = cvt_pk_bf16(hv[6], hv[7]);
;                 *(u32x4*)(O + (size_t)(row0 + ai * 128 + m * 16) * 5632 + col0) = o; }
	v_exp_f32_e32 v84, v84
	v_fma_f32 v80, -v81, v83, 1.0
	v_fma_f32 v76, v80, v83, v83
	v_div_fixup_f32 v76, v76, v81, 1.0
	v_add_f32_e32 v80, 1.0, v84
	v_rcp_f32_e32 v83, v80
	v_mul_f32_e32 v76, v77, v76
	v_mul_f32_e32 v73, v76, v73
	v_mul_f32_e32 v81, 0xbfb8aa3b, v79
	v_exp_f32_e32 v81, v81
	v_fma_f32 v77, -v80, v83, 1.0
	v_fma_f32 v76, v77, v83, v83
	v_div_fixup_f32 v76, v76, v80, 1.0
	v_add_f32_e32 v77, 1.0, v81
	v_rcp_f32_e32 v82, v77
	v_mul_f32_e32 v76, v78, v76
	v_mul_f32_e32 v74, v76, v74
	v_mul_f32_e32 v80, 0xbfb8aa3b, v68
	v_exp_f32_e32 v80, v80
	v_fma_f32 v78, -v77, v82, 1.0
	v_fma_f32 v76, v78, v82, v82
	v_div_fixup_f32 v76, v76, v77, 1.0
	v_add_f32_e32 v78, 1.0, v80
	v_rcp_f32_e32 v81, v78
	v_mul_f32_e32 v76, v79, v76
	v_mul_f32_e32 v75, v76, v75
	v_mul_f32_e32 v79, 0xbfb8aa3b, v69
	v_exp_f32_e32 v79, v79
	v_fma_f32 v77, -v78, v81, 1.0
	v_fma_f32 v76, v77, v81, v81
	v_div_fixup_f32 v76, v76, v78, 1.0
	v_add_f32_e32 v77, 1.0, v79
	v_rcp_f32_e32 v80, v77
	v_mul_f32_e32 v68, v68, v76
	v_mul_f32_e32 v68, v68, v64
	v_mul_f32_e32 v78, 0xbfb8aa3b, v70
	v_exp_f32_e32 v78, v78
	v_fma_f32 v76, -v77, v80, 1.0
	v_fma_f32 v64, v76, v80, v80
	v_div_fixup_f32 v64, v64, v77, 1.0
	v_add_f32_e32 v76, 1.0, v78
	v_rcp_f32_e32 v79, v76
	v_mul_f32_e32 v64, v69, v64
	v_mul_f32_e32 v69, v64, v65
	v_mul_f32_e32 v77, 0xbfb8aa3b, v71
	v_exp_f32_e32 v77, v77
	v_fma_f32 v65, -v76, v79, 1.0
	v_fma_f32 v64, v65, v79, v79
	v_div_fixup_f32 v64, v64, v76, 1.0
	v_add_f32_e32 v65, 1.0, v77
	v_rcp_f32_e32 v78, v65
	v_mul_f32_e32 v64, v70, v64
	v_mul_f32_e32 v70, v64, v66
	v_fma_f32 v66, -v65, v78, 1.0
	v_fma_f32 v64, v66, v78, v78
	v_div_fixup_f32 v64, v64, v65, 1.0
	v_mul_f32_e32 v64, v71, v64
	v_mul_f32_e32 v67, v64, v67
	v_cvt_pk_bf16_f32 v64, v72, v73
	v_cvt_pk_bf16_f32 v65, v74, v75
	v_cvt_pk_bf16_f32 v66, v68, v69
	v_mul_f32_e32 v68, 0xbfb8aa3b, v60
	v_cvt_pk_bf16_f32 v67, v70, v67
	v_exp_f32_e32 v70, v68
	v_or_b32_e32 v68, 48, v150
	v_mad_i64_i32 v[68:69], s[20:21], v68, s49, v[112:113]
	v_add_f32_e32 v70, 1.0, v70
	v_rcp_f32_e32 v72, v70
	v_lshl_add_u64 v[68:69], v[68:69], 0, v[114:115]
	global_store_dwordx4 v[68:69], v[64:67], off
	s_nop 1
	v_mul_f32_e32 v67, 0xbfb8aa3b, v61
	v_exp_f32_e32 v67, v67
	v_fma_f32 v66, -v70, v72, 1.0
	v_fma_f32 v65, v66, v72, v72
	v_div_fixup_f32 v65, v65, v70, 1.0
	v_add_f32_e32 v66, 1.0, v67
	v_rcp_f32_e32 v68, v66
	v_mul_f32_e32 v60, v60, v65
	v_mul_f32_e32 v56, v60, v56
	v_add_u32_e32 v64, 0x80, v150
	v_mul_f32_e32 v69, 0xbfb8aa3b, v62
	v_exp_f32_e32 v69, v69
	v_fma_f32 v65, -v66, v68, 1.0
	v_fma_f32 v60, v65, v68, v68
	v_div_fixup_f32 v60, v60, v66, 1.0
	v_add_f32_e32 v65, 1.0, v69
	v_rcp_f32_e32 v68, v65
	v_mul_f32_e32 v60, v61, v60
	v_mul_f32_e32 v57, v60, v57
	v_mul_f32_e32 v66, 0xbfb8aa3b, v63
	v_exp_f32_e32 v66, v66
	v_fma_f32 v61, -v65, v68, 1.0
	v_fma_f32 v60, v61, v68, v68
	v_div_fixup_f32 v60, v60, v65, 1.0
	v_add_f32_e32 v61, 1.0, v66
	v_rcp_f32_e32 v67, v61
	v_mul_f32_e32 v60, v62, v60
	v_mul_f32_e32 v58, v60, v58
	v_mul_f32_e32 v65, 0xbfb8aa3b, v52
	v_exp_f32_e32 v65, v65
	v_fma_f32 v62, -v61, v67, 1.0
	v_fma_f32 v60, v62, v67, v67
	v_div_fixup_f32 v60, v60, v61, 1.0
	v_add_f32_e32 v62, 1.0, v65
	v_rcp_f32_e32 v66, v62
	v_mul_f32_e32 v60, v63, v60
	v_mul_f32_e32 v59, v60, v59
	v_mul_f32_e32 v63, 0xbfb8aa3b, v53
	v_exp_f32_e32 v63, v63
	v_fma_f32 v61, -v62, v66, 1.0
	v_fma_f32 v60, v61, v66, v66
	v_div_fixup_f32 v60, v60, v62, 1.0
	v_add_f32_e32 v61, 1.0, v63
	v_rcp_f32_e32 v65, v61
	v_mul_f32_e32 v52, v52, v60
	v_mul_f32_e32 v52, v52, v48
	v_mul_f32_e32 v62, 0xbfb8aa3b, v54
	v_exp_f32_e32 v62, v62
	v_fma_f32 v60, -v61, v65, 1.0
	v_fma_f32 v48, v60, v65, v65
	v_div_fixup_f32 v48, v48, v61, 1.0
	v_add_f32_e32 v60, 1.0, v62
	v_rcp_f32_e32 v63, v60
	v_mul_f32_e32 v48, v53, v48
	v_mul_f32_e32 v53, v48, v49
	v_mul_f32_e32 v61, 0xbfb8aa3b, v55
	v_exp_f32_e32 v61, v61
	v_fma_f32 v49, -v60, v63, 1.0
	v_fma_f32 v48, v49, v63, v63
	v_div_fixup_f32 v48, v48, v60, 1.0
	v_add_f32_e32 v49, 1.0, v61
	v_rcp_f32_e32 v62, v49
	v_mul_f32_e32 v48, v54, v48
	v_mul_f32_e32 v54, v48, v50
	v_fma_f32 v50, -v49, v62, 1.0
	v_fma_f32 v48, v50, v62, v62
	v_div_fixup_f32 v48, v48, v49, 1.0
	v_mul_f32_e32 v49, 0xbfb8aa3b, v44
	v_mul_f32_e32 v48, v55, v48
	v_exp_f32_e32 v55, v49
	v_mul_f32_e32 v51, v48, v51
	v_cvt_pk_bf16_f32 v48, v56, v57
	v_cvt_pk_bf16_f32 v49, v58, v59
	v_cvt_pk_bf16_f32 v50, v52, v53
	v_cvt_pk_bf16_f32 v51, v54, v51
	v_add_f32_e32 v54, 1.0, v55
	v_rcp_f32_e32 v56, v54
	v_mad_i64_i32 v[52:53], s[20:21], v64, s49, v[112:113]
	v_lshl_add_u64 v[52:53], v[52:53], 0, v[114:115]
	global_store_dwordx4 v[52:53], v[48:51], off
	s_nop 1
	v_mul_f32_e32 v50, 0xbfb8aa3b, v45
	v_exp_f32_e32 v50, v50
	v_fma_f32 v49, -v54, v56, 1.0
	v_fma_f32 v48, v49, v56, v56
	v_div_fixup_f32 v48, v48, v54, 1.0
	v_add_f32_e32 v49, 1.0, v50
	v_rcp_f32_e32 v51, v49
	v_mul_f32_e32 v44, v44, v48
	v_mul_f32_e32 v40, v44, v40
	v_mul_f32_e32 v52, 0xbfb8aa3b, v46
	v_exp_f32_e32 v52, v52
	v_fma_f32 v48, -v49, v51, 1.0
	v_fma_f32 v44, v48, v51, v51
	v_div_fixup_f32 v44, v44, v49, 1.0
	v_add_f32_e32 v48, 1.0, v52
	v_rcp_f32_e32 v51, v48
	v_mul_f32_e32 v44, v45, v44
	v_mul_f32_e32 v41, v44, v41
	v_mul_f32_e32 v49, 0xbfb8aa3b, v47
	v_exp_f32_e32 v49, v49
	v_fma_f32 v45, -v48, v51, 1.0
	v_fma_f32 v44, v45, v51, v51
	v_div_fixup_f32 v44, v44, v48, 1.0
	v_add_f32_e32 v45, 1.0, v49
	v_rcp_f32_e32 v50, v45
	v_mul_f32_e32 v44, v46, v44
	v_mul_f32_e32 v42, v44, v42
	v_mul_f32_e32 v48, 0xbfb8aa3b, v36
	v_exp_f32_e32 v48, v48
	v_fma_f32 v46, -v45, v50, 1.0
	v_fma_f32 v44, v46, v50, v50
	v_div_fixup_f32 v44, v44, v45, 1.0
	v_add_f32_e32 v46, 1.0, v48
	v_rcp_f32_e32 v49, v46
; __device__ __forceinline__ unsigned cvt_pk_bf16(float lo, float hi) { unsigned r; asm volatile("v_cvt_pk_bf16_f32 %0, %1, %2" : "=v"(r) : "v"(lo), "v"(hi)); return r; }
; __device__ __forceinline__ float sigmoidf_(float x) { return 1.0f / (1.0f + __expf(-x)); }
; #define PG8_WAIT_V(n) asm volatile("s_waitcnt vmcnt(" #n ")" ::: "memory")
; #define PG8_BAR __builtin_amdgcn_s_barrier()
; template <class Epi>
; __device__ __forceinline__ void gemm_phase(LAS unsigned char* lds, const Gemm g, const StaticOrder& S, const Epi& E) {
;     ...
;         }
;         E(acc, cur, wr, wc, fr, fq);
;         if (!has_next) break;
; #pragma unroll
;         for (int a = 0; a < 2; ++a)
; #pragma unroll
;             for (int b = 0; b < 2; ++b)
; #pragma unroll
;                 for (int m = 0; m < 4; ++m)
; #pragma unroll
;                     for (int n = 0; n < 2; ++n) acc[a][b][m][n] = (f32x4){0.f, 0.f, 0.f, 0.f};
;         cur = nxt; cA = nA; cB = nB; ++ui;
;     }
;     PG8_WAIT_V(0);
;     if (wr == 0) PG8_BAR;
;     PG8_BAR;
;     __device__ __forceinline__ void operator()(const f32x4 (&acc)[2][2][4][2], const Unit& u, int wr, int wc, int fr, int fq) const {
;     ...
;             for (int m = 0; m < 4; ++m) { float hv[8];
; #pragma unroll
;                 for (int n = 0; n < 2; ++n)
; #pragma unroll
;                     for (int i = 0; i < 4; ++i) { const float gt = acc[ai][0][m][n][i], up = acc[ai][1][m][n][i]; hv[4 * n + i] = gt * sigmoidf_(gt) * up; }
;                 u32x4 o; o[0] = cvt_pk_bf16(hv[0], hv[1]); o[1] = cvt_pk_bf16(hv[2], hv[3]); o[2] = cvt_pk_bf16(hv[4], hv[5]); o[3] = cvt_pk_bf16(hv[6], hv[7]);
;                 *(u32x4*)(O + (size_t)(row0 + ai * 128 + m * 16) * 5632 + col0) = o; }
	v_mul_f32_e32 v44, v47, v44
	v_mul_f32_e32 v43, v44, v43
	v_mul_f32_e32 v47, 0xbfb8aa3b, v37
	v_exp_f32_e32 v47, v47
	v_fma_f32 v45, -v46, v49, 1.0
	v_fma_f32 v44, v45, v49, v49
	v_div_fixup_f32 v44, v44, v46, 1.0
	v_add_f32_e32 v45, 1.0, v47
	v_rcp_f32_e32 v48, v45
	v_mul_f32_e32 v36, v36, v44
	v_mul_f32_e32 v36, v36, v32
	v_mul_f32_e32 v46, 0xbfb8aa3b, v38
	v_exp_f32_e32 v46, v46
	v_fma_f32 v44, -v45, v48, 1.0
	v_fma_f32 v32, v44, v48, v48
	v_div_fixup_f32 v32, v32, v45, 1.0
	v_add_f32_e32 v44, 1.0, v46
	v_rcp_f32_e32 v47, v44
	v_mul_f32_e32 v32, v37, v32
	v_mul_f32_e32 v37, v32, v33
	v_mul_f32_e32 v45, 0xbfb8aa3b, v39
	v_exp_f32_e32 v45, v45
	v_fma_f32 v33, -v44, v47, 1.0
	v_fma_f32 v32, v33, v47, v47
	v_div_fixup_f32 v32, v32, v44, 1.0
	v_add_f32_e32 v33, 1.0, v45
	v_rcp_f32_e32 v46, v33
	v_mul_f32_e32 v32, v38, v32
	v_mul_f32_e32 v38, v32, v34
	v_fma_f32 v34, -v33, v46, 1.0
	v_fma_f32 v32, v34, v46, v46
	v_div_fixup_f32 v32, v32, v33, 1.0
	v_mul_f32_e32 v34, 0xbfb8aa3b, v28
	v_mul_f32_e32 v32, v39, v32
	v_exp_f32_e32 v39, v34
	v_mul_f32_e32 v35, v32, v35
	v_cvt_pk_bf16_f32 v32, v40, v41
	v_cvt_pk_bf16_f32 v33, v42, v43
	v_cvt_pk_bf16_f32 v34, v36, v37
	v_cvt_pk_bf16_f32 v35, v38, v35
	v_add_f32_e32 v38, 1.0, v39
	v_rcp_f32_e32 v40, v38
	v_add_u32_e32 v36, 0x90, v150
	v_mad_i64_i32 v[36:37], s[20:21], v36, s49, v[112:113]
	v_lshl_add_u64 v[36:37], v[36:37], 0, v[114:115]
	global_store_dwordx4 v[36:37], v[32:35], off
	s_nop 1
	v_mul_f32_e32 v34, 0xbfb8aa3b, v29
	v_exp_f32_e32 v34, v34
	v_fma_f32 v33, -v38, v40, 1.0
	v_fma_f32 v32, v33, v40, v40
	v_div_fixup_f32 v32, v32, v38, 1.0
	v_add_f32_e32 v33, 1.0, v34
	v_rcp_f32_e32 v35, v33
	v_mul_f32_e32 v28, v28, v32
	v_mul_f32_e32 v24, v28, v24
	v_mul_f32_e32 v36, 0xbfb8aa3b, v30
	v_exp_f32_e32 v36, v36
	v_fma_f32 v32, -v33, v35, 1.0
	v_fma_f32 v28, v32, v35, v35
	v_div_fixup_f32 v28, v28, v33, 1.0
	v_add_f32_e32 v32, 1.0, v36
	v_rcp_f32_e32 v35, v32
	v_mul_f32_e32 v28, v29, v28
	v_mul_f32_e32 v25, v28, v25
	v_mul_f32_e32 v33, 0xbfb8aa3b, v31
	v_exp_f32_e32 v33, v33
	v_fma_f32 v29, -v32, v35, 1.0
	v_fma_f32 v28, v29, v35, v35
	v_div_fixup_f32 v28, v28, v32, 1.0
	v_add_f32_e32 v29, 1.0, v33
	v_rcp_f32_e32 v34, v29
	v_mul_f32_e32 v28, v30, v28
	v_mul_f32_e32 v26, v28, v26
	v_mul_f32_e32 v32, 0xbfb8aa3b, v20
	v_exp_f32_e32 v32, v32
	v_fma_f32 v30, -v29, v34, 1.0
	v_fma_f32 v28, v30, v34, v34
	v_div_fixup_f32 v28, v28, v29, 1.0
	v_add_f32_e32 v30, 1.0, v32
	v_rcp_f32_e32 v33, v30
	v_mul_f32_e32 v28, v31, v28
	v_mul_f32_e32 v27, v28, v27
	v_mul_f32_e32 v31, 0xbfb8aa3b, v21
	v_exp_f32_e32 v31, v31
	v_fma_f32 v29, -v30, v33, 1.0
	v_fma_f32 v28, v29, v33, v33
	v_div_fixup_f32 v28, v28, v30, 1.0
	v_add_f32_e32 v29, 1.0, v31
	v_rcp_f32_e32 v32, v29
	v_mul_f32_e32 v20, v20, v28
	v_mul_f32_e32 v20, v20, v16
	v_mul_f32_e32 v30, 0xbfb8aa3b, v22
	v_exp_f32_e32 v30, v30
	v_fma_f32 v28, -v29, v32, 1.0
	v_fma_f32 v16, v28, v32, v32
	v_div_fixup_f32 v16, v16, v29, 1.0
	v_add_f32_e32 v28, 1.0, v30
	v_rcp_f32_e32 v31, v28
	v_mul_f32_e32 v16, v21, v16
	v_mul_f32_e32 v21, v16, v17
	v_mul_f32_e32 v29, 0xbfb8aa3b, v23
	v_exp_f32_e32 v29, v29
	v_fma_f32 v17, -v28, v31, 1.0
	v_fma_f32 v16, v17, v31, v31
	v_div_fixup_f32 v16, v16, v28, 1.0
	v_add_f32_e32 v17, 1.0, v29
	v_rcp_f32_e32 v30, v17
	v_mul_f32_e32 v16, v22, v16
	v_mul_f32_e32 v22, v16, v18
	v_fma_f32 v18, -v17, v30, 1.0
	v_fma_f32 v16, v18, v30, v30
	v_div_fixup_f32 v16, v16, v17, 1.0
	v_mul_f32_e32 v18, 0xbfb8aa3b, v12
	v_mul_f32_e32 v16, v23, v16
	v_exp_f32_e32 v23, v18
	v_mul_f32_e32 v19, v16, v19
	v_cvt_pk_bf16_f32 v16, v24, v25
	v_cvt_pk_bf16_f32 v17, v26, v27
	v_cvt_pk_bf16_f32 v18, v20, v21
	v_cvt_pk_bf16_f32 v19, v22, v19
	v_add_f32_e32 v22, 1.0, v23
	v_rcp_f32_e32 v24, v22
	v_add_u32_e32 v20, 0xa0, v150
	v_mad_i64_i32 v[20:21], s[20:21], v20, s49, v[112:113]
	v_lshl_add_u64 v[20:21], v[20:21], 0, v[114:115]
	global_store_dwordx4 v[20:21], v[16:19], off
	s_nop 1
	v_mul_f32_e32 v18, 0xbfb8aa3b, v13
	v_exp_f32_e32 v18, v18
	v_fma_f32 v17, -v22, v24, 1.0
	v_fma_f32 v16, v17, v24, v24
	v_div_fixup_f32 v16, v16, v22, 1.0
	v_add_f32_e32 v17, 1.0, v18
	v_rcp_f32_e32 v19, v17
	v_mul_f32_e32 v12, v12, v16
	v_mul_f32_e32 v8, v12, v8
	v_mul_f32_e32 v20, 0xbfb8aa3b, v14
	v_exp_f32_e32 v20, v20
	v_fma_f32 v16, -v17, v19, 1.0
	v_fma_f32 v12, v16, v19, v19
	v_div_fixup_f32 v12, v12, v17, 1.0
	v_add_f32_e32 v16, 1.0, v20
	v_rcp_f32_e32 v19, v16
	v_mul_f32_e32 v12, v13, v12
	v_mul_f32_e32 v9, v12, v9
	v_mul_f32_e32 v17, 0xbfb8aa3b, v15
	v_exp_f32_e32 v17, v17
	v_fma_f32 v13, -v16, v19, 1.0
	v_fma_f32 v12, v13, v19, v19
	v_div_fixup_f32 v12, v12, v16, 1.0
	v_add_f32_e32 v13, 1.0, v17
	v_rcp_f32_e32 v18, v13
	v_mul_f32_e32 v12, v14, v12
	v_mul_f32_e32 v10, v12, v10
	v_mul_f32_e32 v16, 0xbfb8aa3b, v4
	v_exp_f32_e32 v16, v16
	v_fma_f32 v14, -v13, v18, 1.0
	v_fma_f32 v12, v14, v18, v18
	v_div_fixup_f32 v12, v12, v13, 1.0
	v_add_f32_e32 v14, 1.0, v16
	v_rcp_f32_e32 v17, v14
	v_mul_f32_e32 v12, v15, v12
	v_mul_f32_e32 v11, v12, v11
	v_mul_f32_e32 v15, 0xbfb8aa3b, v5
	v_exp_f32_e32 v15, v15
	v_fma_f32 v13, -v14, v17, 1.0
	v_fma_f32 v12, v13, v17, v17
	v_div_fixup_f32 v12, v12, v14, 1.0
	v_add_f32_e32 v13, 1.0, v15
	v_rcp_f32_e32 v16, v13
	v_mul_f32_e32 v4, v4, v12
	v_mul_f32_e32 v4, v4, v0
	v_mul_f32_e32 v14, 0xbfb8aa3b, v6
	v_exp_f32_e32 v14, v14
	v_fma_f32 v12, -v13, v16, 1.0
	v_fma_f32 v0, v12, v16, v16
	v_div_fixup_f32 v0, v0, v13, 1.0
	v_add_f32_e32 v12, 1.0, v14
	v_rcp_f32_e32 v15, v12
	v_mul_f32_e32 v0, v5, v0
	v_mul_f32_e32 v5, v0, v1
	v_mul_f32_e32 v13, 0xbfb8aa3b, v7
	v_exp_f32_e32 v13, v13
	v_fma_f32 v1, -v12, v15, 1.0
	v_fma_f32 v0, v1, v15, v15
	v_div_fixup_f32 v0, v0, v12, 1.0
	v_add_f32_e32 v1, 1.0, v13
	v_rcp_f32_e32 v14, v1
	v_mul_f32_e32 v0, v6, v0
	v_mul_f32_e32 v6, v0, v2
	v_fma_f32 v2, -v1, v14, 1.0
	v_fma_f32 v0, v2, v14, v14
	v_div_fixup_f32 v0, v0, v1, 1.0
	v_mul_f32_e32 v0, v7, v0
	v_mul_f32_e32 v3, v0, v3
	v_cvt_pk_bf16_f32 v0, v8, v9
	v_cvt_pk_bf16_f32 v1, v10, v11
	v_cvt_pk_bf16_f32 v2, v4, v5
	v_add_u32_e32 v4, 0xb0, v150
	v_mad_i64_i32 v[4:5], s[20:21], v4, s49, v[112:113]
	v_lshl_add_u64 v[4:5], v[4:5], 0, v[114:115]
	s_and_b64 vcc, exec, s[4:5]
	s_mov_b64 s[20:21], s[12:13]
	v_cvt_pk_bf16_f32 v3, v6, v3
	global_store_dwordx4 v[4:5], v[0:3], off
	s_cbranch_vccz .LBB0_2206
	s_waitcnt vmcnt(0)
	v_readlane_b32 s36, v241, 18
	s_cmpk_gt_u32 s2, 0xff
	v_readlane_b32 s44, v241, 26
	v_readlane_b32 s45, v241, 27
	v_readlane_b32 s46, v241, 28
	v_readlane_b32 s47, v241, 29
	v_readlane_b32 s37, v241, 19
	v_readlane_b32 s38, v241, 20
	v_readlane_b32 s39, v241, 21
	v_readlane_b32 s40, v241, 22
	v_readlane_b32 s41, v241, 23
	v_readlane_b32 s42, v241, 24
	v_readlane_b32 s43, v241, 25
	v_readlane_b32 s48, v241, 30
	v_readlane_b32 s49, v241, 31
	v_readlane_b32 s50, v241, 32
	v_readlane_b32 s51, v241, 33
	s_cbranch_scc1 .LBB0_2213
	s_barrier
